# v46 + K-loop hand-off: setprio raise before / drop after the barrier, repeated lgkmcnt(0) removed; stray in-loop lgkmcnt(0) hoisted to preheader in two K-loops
# speedup vs baseline: 1.0074x; 1.0074x over previous
; #define PG8_STAGE(bufoff, gbase, voff) do { _Pragma("unroll") for (int _i = 0; _i < 2; ++_i) \
;         __builtin_amdgcn_global_load_lds((const unsigned*)((const char*)(gbase) + (voff)[_i]), (PG8_LAS unsigned*)(lds + (bufoff) + ldsw + _i * 8192), 16, 0, 0); } while (0)
; #define PG8_LDA(dst, b, h) do { _Pragma("unroll") for (int m = 0; m < 4; ++m) _Pragma("unroll") for (int k = 0; k < 2; ++k) dst[m][k] = *(const PG8_LAS bf16x8*)(lds + PG8_SA(b, h) + aoff + m * 2048 + k * 1024); } while (0)
; #define PG8_LDB(dst, b, h) do { _Pragma("unroll") for (int n = 0; n < 2; ++n) _Pragma("unroll") for (int k = 0; k < 2; ++k) dst[n][k] = *(const PG8_LAS bf16x8*)(lds + PG8_SB(b, h) + boff + n * 2048 + k * 1024); } while (0)
; #define PG8_MMA(ai, bj, At, Bt) do { __builtin_amdgcn_s_setprio(1); _Pragma("unroll") for (int m = 0; m < 4; ++m) _Pragma("unroll") for (int n = 0; n < 2; ++n) _Pragma("unroll") for (int k = 0; k < 2; ++k) \
;         acc[ai][bj][m][n] = __builtin_amdgcn_mfma_f32_16x16x32_bf16(Bt[n][k], At[m][k], acc[ai][bj][m][n], 0, 0, 0); __builtin_amdgcn_s_setprio(0); } while (0)
; #define PG8_WAIT_V(n) asm volatile("s_waitcnt vmcnt(" #n ")" ::: "memory")
; #define PG8_WAIT_L(n) asm volatile("s_waitcnt lgkmcnt(" #n ")" ::: "memory")
; #define PG8_BAR __builtin_amdgcn_s_barrier()
; #define PG8_SCHED __builtin_amdgcn_sched_barrier(0)
;     ...
;             PG8_LDB(B0, 0, 0); PG8_LDB(B1, 0, 1); PG8_SCHED; PG8_LDA(At, 0, 0); PG8_STAGE(PG8_SA(1, 1), a1 + hstep, voffA);
;             PG8_WAIT_V(8); PG8_WAIT_L(0); PG8_BAR; PG8_MMA(0, 0, At, B0); PG8_MMA(0, 1, At, B1); PG8_BAR; PG8_SCHED;
;             PG8_LDA(At, 0, 1); PG8_STAGE(PG8_SB(0, 0), b2, voffB); PG8_STAGE(PG8_SB(0, 1), b2 + hstep, voffB); PG8_STAGE(PG8_SA(0, 0), a2, voffA);
;             PG8_WAIT_V(8); PG8_WAIT_L(0); PG8_BAR; PG8_MMA(1, 0, At, B0); PG8_MMA(1, 1, At, B1); PG8_BAR; PG8_SCHED;
.LBB0_198:
	s_add_u32 s48, s60, 0xfff80080
	s_addc_u32 s49, s61, -1
	s_add_i32 s87, 0, 0x10000
	s_cmp_eq_u32 s86, 28
	s_cselect_b32 s69, s25, s49
	s_cselect_b32 s68, s81, s48
	v_add_u32_e32 v157, s87, v155
	s_cselect_b32 s63, s15, s85
	s_cselect_b32 s62, s83, s84
	s_add_i32 s48, 0, 0x14000
	ds_read_b128 v[142:145], v157
	ds_read_b128 v[146:149], v157 offset:1024
	ds_read_b128 v[150:153], v157 offset:2048
	ds_read_b128 v[158:161], v157 offset:3072
	v_add_u32_e32 v157, s48, v155
	ds_read_b128 v[162:165], v157
	ds_read_b128 v[166:169], v157 offset:1024
	ds_read_b128 v[170:173], v157 offset:2048
	ds_read_b128 v[174:177], v157 offset:3072
	v_lshl_add_u64 v[198:199], s[60:61], 0, v[138:139]
	s_add_i32 m0, s20, 0xc000
	ds_read_b128 v[178:181], v156
	ds_read_b128 v[182:185], v156 offset:1024
	ds_read_b128 v[186:189], v156 offset:2048
	ds_read_b128 v[190:193], v156 offset:3072
	ds_read_b128 v[194:197], v156 offset:4096
	ds_read_b128 v[210:213], v156 offset:5120
	ds_read_b128 v[214:217], v156 offset:6144
	ds_read_b128 v[218:221], v156 offset:7168
	global_load_lds_dwordx4 v[198:199], off
	v_lshl_add_u64 v[198:199], s[60:61], 0, v[140:141]
	s_add_i32 m0, s20, 0xe000
	s_nop 0
	global_load_lds_dwordx4 v[198:199], off
	s_waitcnt vmcnt(8)
	s_waitcnt lgkmcnt(0)
	s_setprio 1
	s_barrier
	v_mfma_f32_16x16x32_bf16 v[128:131], v[142:145], v[178:181], v[128:131]
	v_mfma_f32_16x16x32_bf16 v[124:127], v[150:153], v[178:181], v[124:127]
	v_mfma_f32_16x16x32_bf16 v[112:115], v[142:145], v[186:189], v[112:115]
	v_mfma_f32_16x16x32_bf16 v[108:111], v[150:153], v[186:189], v[108:111]
	v_mfma_f32_16x16x32_bf16 v[96:99], v[142:145], v[194:197], v[96:99]
	v_mfma_f32_16x16x32_bf16 v[92:95], v[150:153], v[194:197], v[92:95]
	v_mfma_f32_16x16x32_bf16 v[80:83], v[142:145], v[214:217], v[80:83]
	v_mfma_f32_16x16x32_bf16 v[76:79], v[150:153], v[214:217], v[76:79]
	v_mfma_f32_16x16x32_bf16 v[128:131], v[146:149], v[182:185], v[128:131]
	v_mfma_f32_16x16x32_bf16 v[124:127], v[158:161], v[182:185], v[124:127]
	v_mfma_f32_16x16x32_bf16 v[112:115], v[146:149], v[190:193], v[112:115]
	v_mfma_f32_16x16x32_bf16 v[108:111], v[158:161], v[190:193], v[108:111]
	v_mfma_f32_16x16x32_bf16 v[96:99], v[146:149], v[210:213], v[96:99]
	v_mfma_f32_16x16x32_bf16 v[92:95], v[158:161], v[210:213], v[92:95]
	v_mfma_f32_16x16x32_bf16 v[80:83], v[146:149], v[218:221], v[80:83]
	v_mfma_f32_16x16x32_bf16 v[76:79], v[158:161], v[218:221], v[76:79]
	s_setprio 0
	s_setprio 1
	v_mfma_f32_16x16x32_bf16 v[120:123], v[162:165], v[178:181], v[120:123]
	v_mfma_f32_16x16x32_bf16 v[116:119], v[170:173], v[178:181], v[116:119]
	v_mfma_f32_16x16x32_bf16 v[104:107], v[162:165], v[186:189], v[104:107]
	v_mfma_f32_16x16x32_bf16 v[100:103], v[170:173], v[186:189], v[100:103]
	v_mfma_f32_16x16x32_bf16 v[88:91], v[162:165], v[194:197], v[88:91]
	v_mfma_f32_16x16x32_bf16 v[84:87], v[170:173], v[194:197], v[84:87]
	v_mfma_f32_16x16x32_bf16 v[72:75], v[162:165], v[214:217], v[72:75]
	v_mfma_f32_16x16x32_bf16 v[68:71], v[170:173], v[214:217], v[68:71]
	v_mfma_f32_16x16x32_bf16 v[120:123], v[166:169], v[182:185], v[120:123]
	v_mfma_f32_16x16x32_bf16 v[116:119], v[174:177], v[182:185], v[116:119]
	v_mfma_f32_16x16x32_bf16 v[104:107], v[166:169], v[190:193], v[104:107]
	v_mfma_f32_16x16x32_bf16 v[100:103], v[174:177], v[190:193], v[100:103]
	v_mfma_f32_16x16x32_bf16 v[88:91], v[166:169], v[210:213], v[88:91]
	v_mfma_f32_16x16x32_bf16 v[84:87], v[174:177], v[210:213], v[84:87]
	v_mfma_f32_16x16x32_bf16 v[72:75], v[166:169], v[218:221], v[72:75]
	v_mfma_f32_16x16x32_bf16 v[68:71], v[174:177], v[218:221], v[68:71]
	s_barrier
	s_setprio 0
	s_add_i32 s49, s87, s1
	v_lshl_add_u64 v[198:199], s[62:63], 0, v[200:201]
	s_mov_b32 m0, s49
	ds_read_b128 v[178:181], v156 offset:16384
	ds_read_b128 v[182:185], v156 offset:17408
	ds_read_b128 v[186:189], v156 offset:18432
	ds_read_b128 v[190:193], v156 offset:19456
	ds_read_b128 v[194:197], v156 offset:20480
	ds_read_b128 v[210:213], v156 offset:21504
	ds_read_b128 v[214:217], v156 offset:22528
	ds_read_b128 v[218:221], v156 offset:23552
	global_load_lds_dwordx4 v[198:199], off
	s_add_i32 m0, s49, 0x2000
	s_add_u32 s88, s62, 0x80000
	v_lshl_add_u64 v[206:207], s[62:63], 0, v[132:133]
	s_addc_u32 s89, s63, 0
	s_add_i32 s48, s48, s1
	global_load_lds_dwordx4 v[206:207], off
	v_lshl_add_u64 v[208:209], s[88:89], 0, v[200:201]
	s_mov_b32 m0, s48
	v_lshl_add_u64 v[222:223], s[68:69], 0, v[134:135]
	global_load_lds_dwordx4 v[208:209], off
	v_lshl_add_u64 v[208:209], s[88:89], 0, v[132:133]
	s_add_i32 m0, s48, 0x2000
	s_nop 0
	global_load_lds_dwordx4 v[208:209], off
	v_lshl_add_u64 v[208:209], s[68:69], 0, v[136:137]
	s_mov_b32 m0, s20
	s_nop 0
	global_load_lds_dwordx4 v[208:209], off
	s_mov_b32 m0, s21
	s_nop 0
	global_load_lds_dwordx4 v[222:223], off
	s_waitcnt vmcnt(8)
	s_waitcnt lgkmcnt(0)
	s_setprio 1
	s_barrier
; #define PG8_STAGE(bufoff, gbase, voff) do { _Pragma("unroll") for (int _i = 0; _i < 2; ++_i) \
;         __builtin_amdgcn_global_load_lds((const unsigned*)((const char*)(gbase) + (voff)[_i]), (PG8_LAS unsigned*)(lds + (bufoff) + ldsw + _i * 8192), 16, 0, 0); } while (0)
; #define PG8_LDA(dst, b, h) do { _Pragma("unroll") for (int m = 0; m < 4; ++m) _Pragma("unroll") for (int k = 0; k < 2; ++k) dst[m][k] = *(const PG8_LAS bf16x8*)(lds + PG8_SA(b, h) + aoff + m * 2048 + k * 1024); } while (0)
; #define PG8_LDB(dst, b, h) do { _Pragma("unroll") for (int n = 0; n < 2; ++n) _Pragma("unroll") for (int k = 0; k < 2; ++k) dst[n][k] = *(const PG8_LAS bf16x8*)(lds + PG8_SB(b, h) + boff + n * 2048 + k * 1024); } while (0)
; #define PG8_MMA(ai, bj, At, Bt) do { __builtin_amdgcn_s_setprio(1); _Pragma("unroll") for (int m = 0; m < 4; ++m) _Pragma("unroll") for (int n = 0; n < 2; ++n) _Pragma("unroll") for (int k = 0; k < 2; ++k) \
;         acc[ai][bj][m][n] = __builtin_amdgcn_mfma_f32_16x16x32_bf16(Bt[n][k], At[m][k], acc[ai][bj][m][n], 0, 0, 0); __builtin_amdgcn_s_setprio(0); } while (0)
; #define PG8_WAIT_V(n) asm volatile("s_waitcnt vmcnt(" #n ")" ::: "memory")
; #define PG8_WAIT_L(n) asm volatile("s_waitcnt lgkmcnt(" #n ")" ::: "memory")
; #define PG8_BAR __builtin_amdgcn_s_barrier()
; #define PG8_SCHED __builtin_amdgcn_sched_barrier(0)
;     ...
;             PG8_WAIT_V(8); PG8_WAIT_L(0); PG8_BAR; PG8_MMA(1, 0, At, B0); PG8_MMA(1, 1, At, B1); PG8_BAR; PG8_SCHED;
;             PG8_LDB(B0, 1, 0); PG8_LDB(B1, 1, 1); PG8_SCHED; PG8_LDA(At, 1, 0); PG8_STAGE(PG8_SA(0, 1), a2 + hstep, voffA);
;             PG8_WAIT_V(8); PG8_WAIT_L(0); PG8_BAR; PG8_MMA(0, 0, At, B0); PG8_MMA(0, 1, At, B1); PG8_BAR; PG8_SCHED;
	v_mfma_f32_16x16x32_bf16 v[64:67], v[142:145], v[178:181], v[64:67]
	v_mfma_f32_16x16x32_bf16 v[60:63], v[150:153], v[178:181], v[60:63]
	v_mfma_f32_16x16x32_bf16 v[48:51], v[142:145], v[186:189], v[48:51]
	v_mfma_f32_16x16x32_bf16 v[44:47], v[150:153], v[186:189], v[44:47]
	v_mfma_f32_16x16x32_bf16 v[32:35], v[142:145], v[194:197], v[32:35]
	v_mfma_f32_16x16x32_bf16 v[28:31], v[150:153], v[194:197], v[28:31]
	v_mfma_f32_16x16x32_bf16 v[16:19], v[142:145], v[214:217], v[16:19]
	v_mfma_f32_16x16x32_bf16 v[12:15], v[150:153], v[214:217], v[12:15]
	v_mfma_f32_16x16x32_bf16 v[64:67], v[146:149], v[182:185], v[64:67]
	v_mfma_f32_16x16x32_bf16 v[60:63], v[158:161], v[182:185], v[60:63]
	v_mfma_f32_16x16x32_bf16 v[48:51], v[146:149], v[190:193], v[48:51]
	v_mfma_f32_16x16x32_bf16 v[44:47], v[158:161], v[190:193], v[44:47]
	v_mfma_f32_16x16x32_bf16 v[32:35], v[146:149], v[210:213], v[32:35]
	v_mfma_f32_16x16x32_bf16 v[28:31], v[158:161], v[210:213], v[28:31]
	v_mfma_f32_16x16x32_bf16 v[16:19], v[146:149], v[218:221], v[16:19]
	v_mfma_f32_16x16x32_bf16 v[12:15], v[158:161], v[218:221], v[12:15]
	s_setprio 0
	s_setprio 1
	v_mfma_f32_16x16x32_bf16 v[56:59], v[162:165], v[178:181], v[56:59]
	v_mfma_f32_16x16x32_bf16 v[52:55], v[170:173], v[178:181], v[52:55]
	v_mfma_f32_16x16x32_bf16 v[40:43], v[162:165], v[186:189], v[40:43]
	v_mfma_f32_16x16x32_bf16 v[36:39], v[170:173], v[186:189], v[36:39]
	v_mfma_f32_16x16x32_bf16 v[24:27], v[162:165], v[194:197], v[24:27]
	v_mfma_f32_16x16x32_bf16 v[20:23], v[170:173], v[194:197], v[20:23]
	v_mfma_f32_16x16x32_bf16 v[8:11], v[162:165], v[214:217], v[8:11]
	v_mfma_f32_16x16x32_bf16 v[4:7], v[170:173], v[214:217], v[4:7]
	v_mfma_f32_16x16x32_bf16 v[56:59], v[166:169], v[182:185], v[56:59]
	v_mfma_f32_16x16x32_bf16 v[52:55], v[174:177], v[182:185], v[52:55]
	v_mfma_f32_16x16x32_bf16 v[40:43], v[166:169], v[190:193], v[40:43]
	v_mfma_f32_16x16x32_bf16 v[36:39], v[174:177], v[190:193], v[36:39]
	v_mfma_f32_16x16x32_bf16 v[24:27], v[166:169], v[210:213], v[24:27]
	v_mfma_f32_16x16x32_bf16 v[20:23], v[174:177], v[210:213], v[20:23]
	v_mfma_f32_16x16x32_bf16 v[8:11], v[166:169], v[218:221], v[8:11]
	v_mfma_f32_16x16x32_bf16 v[4:7], v[174:177], v[218:221], v[4:7]
	s_barrier
	s_setprio 0
	s_add_i32 s48, 0, 0x18000
	v_add_u32_e32 v157, s48, v155
	s_add_i32 s49, 0, 0x1c000
	ds_read_b128 v[142:145], v157
	ds_read_b128 v[146:149], v157 offset:1024
	ds_read_b128 v[150:153], v157 offset:2048
	ds_read_b128 v[158:161], v157 offset:3072
	v_add_u32_e32 v157, s49, v155
	ds_read_b128 v[162:165], v157
	ds_read_b128 v[166:169], v157 offset:1024
	ds_read_b128 v[170:173], v157 offset:2048
	ds_read_b128 v[174:177], v157 offset:3072
	s_add_u32 s68, s68, 0x80000
	s_addc_u32 s69, s69, 0
	s_mov_b32 m0, s23
	v_lshl_add_u64 v[224:225], s[68:69], 0, v[136:137]
	ds_read_b128 v[178:181], v156 offset:32768
	ds_read_b128 v[182:185], v156 offset:33792
	ds_read_b128 v[186:189], v156 offset:34816
	ds_read_b128 v[190:193], v156 offset:35840
	ds_read_b128 v[194:197], v156 offset:36864
	ds_read_b128 v[210:213], v156 offset:37888
	ds_read_b128 v[214:217], v156 offset:38912
	ds_read_b128 v[218:221], v156 offset:39936
	global_load_lds_dwordx4 v[224:225], off
	v_lshl_add_u64 v[224:225], s[68:69], 0, v[134:135]
	s_mov_b32 m0, s42
	s_nop 0
	global_load_lds_dwordx4 v[224:225], off
	s_waitcnt vmcnt(8)
	s_waitcnt lgkmcnt(0)
	s_setprio 1
	s_barrier
	v_mfma_f32_16x16x32_bf16 v[128:131], v[142:145], v[178:181], v[128:131]
	v_mfma_f32_16x16x32_bf16 v[124:127], v[150:153], v[178:181], v[124:127]
	v_mfma_f32_16x16x32_bf16 v[112:115], v[142:145], v[186:189], v[112:115]
	v_mfma_f32_16x16x32_bf16 v[108:111], v[150:153], v[186:189], v[108:111]
	v_mfma_f32_16x16x32_bf16 v[96:99], v[142:145], v[194:197], v[96:99]
	v_mfma_f32_16x16x32_bf16 v[92:95], v[150:153], v[194:197], v[92:95]
	v_mfma_f32_16x16x32_bf16 v[80:83], v[142:145], v[214:217], v[80:83]
	v_mfma_f32_16x16x32_bf16 v[76:79], v[150:153], v[214:217], v[76:79]
	v_mfma_f32_16x16x32_bf16 v[128:131], v[146:149], v[182:185], v[128:131]
	v_mfma_f32_16x16x32_bf16 v[124:127], v[158:161], v[182:185], v[124:127]
	v_mfma_f32_16x16x32_bf16 v[112:115], v[146:149], v[190:193], v[112:115]
	v_mfma_f32_16x16x32_bf16 v[108:111], v[158:161], v[190:193], v[108:111]
	v_mfma_f32_16x16x32_bf16 v[96:99], v[146:149], v[210:213], v[96:99]
	v_mfma_f32_16x16x32_bf16 v[92:95], v[158:161], v[210:213], v[92:95]
	v_mfma_f32_16x16x32_bf16 v[80:83], v[146:149], v[218:221], v[80:83]
	v_mfma_f32_16x16x32_bf16 v[76:79], v[158:161], v[218:221], v[76:79]
	s_setprio 0
	s_setprio 1
	v_mfma_f32_16x16x32_bf16 v[120:123], v[162:165], v[178:181], v[120:123]
	v_mfma_f32_16x16x32_bf16 v[116:119], v[170:173], v[178:181], v[116:119]
	v_mfma_f32_16x16x32_bf16 v[104:107], v[162:165], v[186:189], v[104:107]
	v_mfma_f32_16x16x32_bf16 v[100:103], v[170:173], v[186:189], v[100:103]
	v_mfma_f32_16x16x32_bf16 v[88:91], v[162:165], v[194:197], v[88:91]
	v_mfma_f32_16x16x32_bf16 v[84:87], v[170:173], v[194:197], v[84:87]
	v_mfma_f32_16x16x32_bf16 v[72:75], v[162:165], v[214:217], v[72:75]
	v_mfma_f32_16x16x32_bf16 v[68:71], v[170:173], v[214:217], v[68:71]
	v_mfma_f32_16x16x32_bf16 v[120:123], v[166:169], v[182:185], v[120:123]
	v_mfma_f32_16x16x32_bf16 v[116:119], v[174:177], v[182:185], v[116:119]
	v_mfma_f32_16x16x32_bf16 v[104:107], v[166:169], v[190:193], v[104:107]
	v_mfma_f32_16x16x32_bf16 v[100:103], v[174:177], v[190:193], v[100:103]
	v_mfma_f32_16x16x32_bf16 v[88:91], v[166:169], v[210:213], v[88:91]
	v_mfma_f32_16x16x32_bf16 v[84:87], v[174:177], v[210:213], v[84:87]
	v_mfma_f32_16x16x32_bf16 v[72:75], v[166:169], v[218:221], v[72:75]
	v_mfma_f32_16x16x32_bf16 v[68:71], v[174:177], v[218:221], v[68:71]
	s_barrier
; #define PG8_STAGE(bufoff, gbase, voff) do { _Pragma("unroll") for (int _i = 0; _i < 2; ++_i) \
;         __builtin_amdgcn_global_load_lds((const unsigned*)((const char*)(gbase) + (voff)[_i]), (PG8_LAS unsigned*)(lds + (bufoff) + ldsw + _i * 8192), 16, 0, 0); } while (0)
; #define PG8_LDA(dst, b, h) do { _Pragma("unroll") for (int m = 0; m < 4; ++m) _Pragma("unroll") for (int k = 0; k < 2; ++k) dst[m][k] = *(const PG8_LAS bf16x8*)(lds + PG8_SA(b, h) + aoff + m * 2048 + k * 1024); } while (0)
; #define PG8_MMA(ai, bj, At, Bt) do { __builtin_amdgcn_s_setprio(1); _Pragma("unroll") for (int m = 0; m < 4; ++m) _Pragma("unroll") for (int n = 0; n < 2; ++n) _Pragma("unroll") for (int k = 0; k < 2; ++k) \
;         acc[ai][bj][m][n] = __builtin_amdgcn_mfma_f32_16x16x32_bf16(Bt[n][k], At[m][k], acc[ai][bj][m][n], 0, 0, 0); __builtin_amdgcn_s_setprio(0); } while (0)
; #define PG8_WAIT_V(n) asm volatile("s_waitcnt vmcnt(" #n ")" ::: "memory")
; #define PG8_WAIT_L(n) asm volatile("s_waitcnt lgkmcnt(" #n ")" ::: "memory")
; #define PG8_BAR __builtin_amdgcn_s_barrier()
; #define PG8_SCHED __builtin_amdgcn_sched_barrier(0)
;     ...
;         for (int t = 0; t < nt; t += 2) {
;     ...
;             PG8_WAIT_V(8); PG8_WAIT_L(0); PG8_BAR; PG8_MMA(0, 0, At, B0); PG8_MMA(0, 1, At, B1); PG8_BAR; PG8_SCHED;
;             PG8_LDA(At, 1, 1); PG8_STAGE(PG8_SB(1, 0), b3, voffB); PG8_STAGE(PG8_SB(1, 1), b3 + hstep, voffB); PG8_STAGE(PG8_SA(1, 0), a3, voffA);
;             PG8_WAIT_V(8); PG8_WAIT_L(0); PG8_BAR; PG8_MMA(1, 0, At, B0); PG8_MMA(1, 1, At, B1); PG8_BAR; PG8_SCHED;
	s_setprio 0
	s_add_i32 s48, s48, s1
	v_lshl_add_u64 v[198:199], v[198:199], 0, s[66:67]
	s_mov_b32 m0, s48
	ds_read_b128 v[178:181], v156 offset:49152
	ds_read_b128 v[182:185], v156 offset:50176
	ds_read_b128 v[186:189], v156 offset:51200
	ds_read_b128 v[190:193], v156 offset:52224
	ds_read_b128 v[194:197], v156 offset:53248
	ds_read_b128 v[210:213], v156 offset:54272
	ds_read_b128 v[214:217], v156 offset:55296
	ds_read_b128 v[218:221], v156 offset:56320
	global_load_lds_dwordx4 v[198:199], off
	s_add_i32 m0, s48, 0x2000
	s_add_u32 s62, s62, 0x80080
	v_lshl_add_u64 v[198:199], v[206:207], 0, s[66:67]
	s_addc_u32 s63, s63, 0
	s_add_i32 s48, s49, s1
	global_load_lds_dwordx4 v[198:199], off
	v_lshl_add_u64 v[198:199], s[62:63], 0, v[200:201]
	s_mov_b32 m0, s48
	s_nop 0
	global_load_lds_dwordx4 v[198:199], off
	v_lshl_add_u64 v[198:199], s[62:63], 0, v[132:133]
	s_add_i32 m0, s48, 0x2000
	s_nop 0
	global_load_lds_dwordx4 v[198:199], off
	v_lshl_add_u64 v[198:199], v[208:209], 0, s[66:67]
	s_mov_b32 m0, s55
	s_nop 0
	global_load_lds_dwordx4 v[198:199], off
	v_lshl_add_u64 v[198:199], v[222:223], 0, s[66:67]
	s_mov_b32 m0, s56
	s_nop 0
	global_load_lds_dwordx4 v[198:199], off
	s_waitcnt vmcnt(8)
	s_waitcnt lgkmcnt(0)
	s_setprio 1
	s_barrier
	v_mfma_f32_16x16x32_bf16 v[64:67], v[142:145], v[178:181], v[64:67]
	v_mfma_f32_16x16x32_bf16 v[60:63], v[150:153], v[178:181], v[60:63]
	v_mfma_f32_16x16x32_bf16 v[48:51], v[142:145], v[186:189], v[48:51]
	v_mfma_f32_16x16x32_bf16 v[44:47], v[150:153], v[186:189], v[44:47]
	v_mfma_f32_16x16x32_bf16 v[32:35], v[142:145], v[194:197], v[32:35]
	v_mfma_f32_16x16x32_bf16 v[28:31], v[150:153], v[194:197], v[28:31]
	v_mfma_f32_16x16x32_bf16 v[16:19], v[142:145], v[214:217], v[16:19]
	v_mfma_f32_16x16x32_bf16 v[12:15], v[150:153], v[214:217], v[12:15]
	v_mfma_f32_16x16x32_bf16 v[64:67], v[146:149], v[182:185], v[64:67]
	v_mfma_f32_16x16x32_bf16 v[60:63], v[158:161], v[182:185], v[60:63]
	v_mfma_f32_16x16x32_bf16 v[48:51], v[146:149], v[190:193], v[48:51]
	v_mfma_f32_16x16x32_bf16 v[44:47], v[158:161], v[190:193], v[44:47]
	v_mfma_f32_16x16x32_bf16 v[32:35], v[146:149], v[210:213], v[32:35]
	v_mfma_f32_16x16x32_bf16 v[28:31], v[158:161], v[210:213], v[28:31]
	v_mfma_f32_16x16x32_bf16 v[16:19], v[146:149], v[218:221], v[16:19]
	v_mfma_f32_16x16x32_bf16 v[12:15], v[158:161], v[218:221], v[12:15]
	s_setprio 0
	s_setprio 1
	v_mfma_f32_16x16x32_bf16 v[56:59], v[162:165], v[178:181], v[56:59]
	v_mfma_f32_16x16x32_bf16 v[52:55], v[170:173], v[178:181], v[52:55]
	v_mfma_f32_16x16x32_bf16 v[40:43], v[162:165], v[186:189], v[40:43]
	v_mfma_f32_16x16x32_bf16 v[36:39], v[170:173], v[186:189], v[36:39]
	v_mfma_f32_16x16x32_bf16 v[24:27], v[162:165], v[194:197], v[24:27]
	v_mfma_f32_16x16x32_bf16 v[20:23], v[170:173], v[194:197], v[20:23]
	v_mfma_f32_16x16x32_bf16 v[8:11], v[162:165], v[214:217], v[8:11]
	v_mfma_f32_16x16x32_bf16 v[4:7], v[170:173], v[214:217], v[4:7]
	v_mfma_f32_16x16x32_bf16 v[56:59], v[166:169], v[182:185], v[56:59]
	v_mfma_f32_16x16x32_bf16 v[52:55], v[174:177], v[182:185], v[52:55]
	v_mfma_f32_16x16x32_bf16 v[40:43], v[166:169], v[190:193], v[40:43]
	v_mfma_f32_16x16x32_bf16 v[36:39], v[174:177], v[190:193], v[36:39]
	v_mfma_f32_16x16x32_bf16 v[24:27], v[166:169], v[210:213], v[24:27]
	v_mfma_f32_16x16x32_bf16 v[20:23], v[174:177], v[210:213], v[20:23]
	v_mfma_f32_16x16x32_bf16 v[8:11], v[166:169], v[218:221], v[8:11]
	v_mfma_f32_16x16x32_bf16 v[4:7], v[174:177], v[218:221], v[4:7]
	s_barrier
	s_setprio 0
	s_add_i32 s86, s86, 2
	s_add_u32 s60, s60, 0x100
	s_addc_u32 s61, s61, 0
	s_add_u32 s84, s84, 0x100
	s_addc_u32 s85, s85, 0
	s_cmp_gt_u32 s86, 29
	s_cbranch_scc0 .LBB0_198
	s_and_b64 vcc, exec, s[12:13]
	s_cbranch_vccz .LBB0_201
	s_barrier

; #define PG8_STAGE(bufoff, gbase, voff) do { _Pragma("unroll") for (int _i = 0; _i < 2; ++_i) \
;         __builtin_amdgcn_global_load_lds((const unsigned*)((const char*)(gbase) + (voff)[_i]), (PG8_LAS unsigned*)(lds + (bufoff) + ldsw + _i * 8192), 16, 0, 0); } while (0)
; #define PG8_LDA(dst, b, h) do { _Pragma("unroll") for (int m = 0; m < 4; ++m) _Pragma("unroll") for (int k = 0; k < 2; ++k) dst[m][k] = *(const PG8_LAS bf16x8*)(lds + PG8_SA(b, h) + aoff + m * 2048 + k * 1024); } while (0)
; #define PG8_LDB(dst, b, h) do { _Pragma("unroll") for (int n = 0; n < 2; ++n) _Pragma("unroll") for (int k = 0; k < 2; ++k) dst[n][k] = *(const PG8_LAS bf16x8*)(lds + PG8_SB(b, h) + boff + n * 2048 + k * 1024); } while (0)
; #define PG8_MMA(ai, bj, At, Bt) do { __builtin_amdgcn_s_setprio(1); _Pragma("unroll") for (int m = 0; m < 4; ++m) _Pragma("unroll") for (int n = 0; n < 2; ++n) _Pragma("unroll") for (int k = 0; k < 2; ++k) \
;         acc[ai][bj][m][n] = __builtin_amdgcn_mfma_f32_16x16x32_bf16(Bt[n][k], At[m][k], acc[ai][bj][m][n], 0, 0, 0); __builtin_amdgcn_s_setprio(0); } while (0)
; #define PG8_WAIT_V(n) asm volatile("s_waitcnt vmcnt(" #n ")" ::: "memory")
; #define PG8_WAIT_L(n) asm volatile("s_waitcnt lgkmcnt(" #n ")" ::: "memory")
; #define PG8_BAR __builtin_amdgcn_s_barrier()
; #define PG8_SCHED __builtin_amdgcn_sched_barrier(0)
;     ...
;             if constexpr (SP2) {
;             PG8_LDB(B0, 0, 0); PG8_LDB(B1, 0, 1); PG8_SCHED; PG8_LDA(At, 0, 0); PG8_STAGE(PG8_SA(1, 1), a1 + hstep, voffA);
;             PG8_WAIT_V(8); PG8_WAIT_L(0); PG8_BAR; PG8_MMA(0, 0, At, B0); PG8_MMA(0, 1, At, B1); PG8_BAR; PG8_SCHED;
;             PG8_LDA(At, 0, 1); PG8_STAGE(PG8_SB(0, 0), b2, voffB); PG8_STAGE(PG8_SB(0, 1), b2 + hstep, voffB); PG8_STAGE(PG8_SA(0, 0), a2, voffA);
;             PG8_WAIT_V(8); PG8_WAIT_L(0); PG8_BAR; PG8_MMA(1, 0, At, B0); PG8_MMA(1, 1, At, B1); PG8_BAR; PG8_SCHED;
.LBB0_279:
	s_add_u32 s10, s56, s6
	s_addc_u32 s11, s73, s7
	s_add_u32 s10, s10, 0x1d800100
	s_addc_u32 s11, s11, 0
	s_add_u32 s48, s0, s6
	s_addc_u32 s49, s50, s7
	s_add_i32 s52, 0, 0x10000
	s_cmpk_eq_i32 s6, 0xf00
	s_cselect_b32 s13, s55, s11
	s_cselect_b32 s12, s54, s10
	v_add_u32_e32 v145, s52, v143
	s_cselect_b32 s11, s5, s49
	s_cselect_b32 s10, s4, s48
	s_add_i32 s48, 0, 0x14000
	ds_read_b128 v[146:149], v145
	ds_read_b128 v[150:153], v145 offset:1024
	ds_read_b128 v[154:157], v145 offset:2048
	ds_read_b128 v[158:161], v145 offset:3072
	v_add_u32_e32 v145, s48, v143
	ds_read_b128 v[162:165], v145
	ds_read_b128 v[166:169], v145 offset:1024
	ds_read_b128 v[170:173], v145 offset:2048
	ds_read_b128 v[174:177], v145 offset:3072
	v_lshl_add_u64 v[198:199], v[138:139], 0, s[6:7]
	s_add_i32 m0, s15, 0xc000
	ds_read_b128 v[178:181], v144
	ds_read_b128 v[182:185], v144 offset:1024
	ds_read_b128 v[186:189], v144 offset:2048
	ds_read_b128 v[190:193], v144 offset:3072
	ds_read_b128 v[194:197], v144 offset:4096
	ds_read_b128 v[210:213], v144 offset:5120
	ds_read_b128 v[214:217], v144 offset:6144
	ds_read_b128 v[218:221], v144 offset:7168
	global_load_lds_dwordx4 v[198:199], off
	v_lshl_add_u64 v[198:199], v[140:141], 0, s[6:7]
	s_add_i32 m0, s15, 0xe000
	s_nop 0
	global_load_lds_dwordx4 v[198:199], off
	s_waitcnt vmcnt(8)
	s_waitcnt lgkmcnt(0)
	s_setprio 1
	s_barrier
	v_mfma_f32_16x16x32_bf16 v[128:131], v[146:149], v[178:181], v[128:131]
	v_mfma_f32_16x16x32_bf16 v[124:127], v[154:157], v[178:181], v[124:127]
	v_mfma_f32_16x16x32_bf16 v[112:115], v[146:149], v[186:189], v[112:115]
	v_mfma_f32_16x16x32_bf16 v[108:111], v[154:157], v[186:189], v[108:111]
	v_mfma_f32_16x16x32_bf16 v[96:99], v[146:149], v[194:197], v[96:99]
	v_mfma_f32_16x16x32_bf16 v[92:95], v[154:157], v[194:197], v[92:95]
	v_mfma_f32_16x16x32_bf16 v[80:83], v[146:149], v[214:217], v[80:83]
	v_mfma_f32_16x16x32_bf16 v[76:79], v[154:157], v[214:217], v[76:79]
	v_mfma_f32_16x16x32_bf16 v[128:131], v[150:153], v[182:185], v[128:131]
	v_mfma_f32_16x16x32_bf16 v[124:127], v[158:161], v[182:185], v[124:127]
	v_mfma_f32_16x16x32_bf16 v[112:115], v[150:153], v[190:193], v[112:115]
	v_mfma_f32_16x16x32_bf16 v[108:111], v[158:161], v[190:193], v[108:111]
	v_mfma_f32_16x16x32_bf16 v[96:99], v[150:153], v[210:213], v[96:99]
	v_mfma_f32_16x16x32_bf16 v[92:95], v[158:161], v[210:213], v[92:95]
	v_mfma_f32_16x16x32_bf16 v[80:83], v[150:153], v[218:221], v[80:83]
	v_mfma_f32_16x16x32_bf16 v[76:79], v[158:161], v[218:221], v[76:79]
	s_setprio 0
	s_setprio 1
	v_mfma_f32_16x16x32_bf16 v[120:123], v[162:165], v[178:181], v[120:123]
	v_mfma_f32_16x16x32_bf16 v[116:119], v[170:173], v[178:181], v[116:119]
	v_mfma_f32_16x16x32_bf16 v[104:107], v[162:165], v[186:189], v[104:107]
	v_mfma_f32_16x16x32_bf16 v[100:103], v[170:173], v[186:189], v[100:103]
	v_mfma_f32_16x16x32_bf16 v[88:91], v[162:165], v[194:197], v[88:91]
	v_mfma_f32_16x16x32_bf16 v[84:87], v[170:173], v[194:197], v[84:87]
	v_mfma_f32_16x16x32_bf16 v[72:75], v[162:165], v[214:217], v[72:75]
	v_mfma_f32_16x16x32_bf16 v[68:71], v[170:173], v[214:217], v[68:71]
	v_mfma_f32_16x16x32_bf16 v[120:123], v[166:169], v[182:185], v[120:123]
	v_mfma_f32_16x16x32_bf16 v[116:119], v[174:177], v[182:185], v[116:119]
	v_mfma_f32_16x16x32_bf16 v[104:107], v[166:169], v[190:193], v[104:107]
	v_mfma_f32_16x16x32_bf16 v[100:103], v[174:177], v[190:193], v[100:103]
	v_mfma_f32_16x16x32_bf16 v[88:91], v[166:169], v[210:213], v[88:91]
	v_mfma_f32_16x16x32_bf16 v[84:87], v[174:177], v[210:213], v[84:87]
	v_mfma_f32_16x16x32_bf16 v[72:75], v[166:169], v[218:221], v[72:75]
	v_mfma_f32_16x16x32_bf16 v[68:71], v[174:177], v[218:221], v[68:71]
	s_barrier
	s_setprio 0
	s_add_i32 s49, s52, s14
	v_lshl_add_u64 v[198:199], s[10:11], 0, v[200:201]
	s_mov_b32 m0, s49
	ds_read_b128 v[178:181], v144 offset:16384
	ds_read_b128 v[182:185], v144 offset:17408
	ds_read_b128 v[186:189], v144 offset:18432
	ds_read_b128 v[190:193], v144 offset:19456
	ds_read_b128 v[194:197], v144 offset:20480
	ds_read_b128 v[210:213], v144 offset:21504
	ds_read_b128 v[214:217], v144 offset:22528
	ds_read_b128 v[218:221], v144 offset:23552
	global_load_lds_dwordx4 v[198:199], off
	s_add_i32 m0, s49, 0x2000
	s_add_u32 s52, s10, 0x80000
	v_lshl_add_u64 v[206:207], s[10:11], 0, v[136:137]
	s_addc_u32 s53, s11, 0
	s_add_i32 s48, s48, s14
	global_load_lds_dwordx4 v[206:207], off
	v_lshl_add_u64 v[208:209], s[52:53], 0, v[200:201]
	s_mov_b32 m0, s48
	v_lshl_add_u64 v[222:223], s[12:13], 0, v[134:135]
	global_load_lds_dwordx4 v[208:209], off
	v_lshl_add_u64 v[208:209], s[52:53], 0, v[136:137]
	s_add_i32 m0, s48, 0x2000
	s_nop 0
	global_load_lds_dwordx4 v[208:209], off
	v_lshl_add_u64 v[208:209], s[12:13], 0, v[132:133]
	s_mov_b32 m0, s15
	s_nop 0
	global_load_lds_dwordx4 v[208:209], off
	s_mov_b32 m0, s20
	s_nop 0
	global_load_lds_dwordx4 v[222:223], off
	s_waitcnt vmcnt(8)
	s_waitcnt lgkmcnt(0)
	s_setprio 1
	s_barrier
; #define PG8_STAGE(bufoff, gbase, voff) do { _Pragma("unroll") for (int _i = 0; _i < 2; ++_i) \
;         __builtin_amdgcn_global_load_lds((const unsigned*)((const char*)(gbase) + (voff)[_i]), (PG8_LAS unsigned*)(lds + (bufoff) + ldsw + _i * 8192), 16, 0, 0); } while (0)
; #define PG8_LDA(dst, b, h) do { _Pragma("unroll") for (int m = 0; m < 4; ++m) _Pragma("unroll") for (int k = 0; k < 2; ++k) dst[m][k] = *(const PG8_LAS bf16x8*)(lds + PG8_SA(b, h) + aoff + m * 2048 + k * 1024); } while (0)
; #define PG8_LDB(dst, b, h) do { _Pragma("unroll") for (int n = 0; n < 2; ++n) _Pragma("unroll") for (int k = 0; k < 2; ++k) dst[n][k] = *(const PG8_LAS bf16x8*)(lds + PG8_SB(b, h) + boff + n * 2048 + k * 1024); } while (0)
; #define PG8_MMA(ai, bj, At, Bt) do { __builtin_amdgcn_s_setprio(1); _Pragma("unroll") for (int m = 0; m < 4; ++m) _Pragma("unroll") for (int n = 0; n < 2; ++n) _Pragma("unroll") for (int k = 0; k < 2; ++k) \
;         acc[ai][bj][m][n] = __builtin_amdgcn_mfma_f32_16x16x32_bf16(Bt[n][k], At[m][k], acc[ai][bj][m][n], 0, 0, 0); __builtin_amdgcn_s_setprio(0); } while (0)
; #define PG8_WAIT_V(n) asm volatile("s_waitcnt vmcnt(" #n ")" ::: "memory")
; #define PG8_WAIT_L(n) asm volatile("s_waitcnt lgkmcnt(" #n ")" ::: "memory")
; #define PG8_BAR __builtin_amdgcn_s_barrier()
; #define PG8_SCHED __builtin_amdgcn_sched_barrier(0)
;     ...
;             PG8_WAIT_V(8); PG8_WAIT_L(0); PG8_BAR; PG8_MMA(1, 0, At, B0); PG8_MMA(1, 1, At, B1); PG8_BAR; PG8_SCHED;
;             PG8_LDB(B0, 1, 0); PG8_LDB(B1, 1, 1); PG8_SCHED; PG8_LDA(At, 1, 0); PG8_STAGE(PG8_SA(0, 1), a2 + hstep, voffA);
;             PG8_WAIT_V(8); PG8_WAIT_L(0); PG8_BAR; PG8_MMA(0, 0, At, B0); PG8_MMA(0, 1, At, B1); PG8_BAR; PG8_SCHED;
	v_mfma_f32_16x16x32_bf16 v[64:67], v[146:149], v[178:181], v[64:67]
	v_mfma_f32_16x16x32_bf16 v[60:63], v[154:157], v[178:181], v[60:63]
	v_mfma_f32_16x16x32_bf16 v[48:51], v[146:149], v[186:189], v[48:51]
	v_mfma_f32_16x16x32_bf16 v[44:47], v[154:157], v[186:189], v[44:47]
	v_mfma_f32_16x16x32_bf16 v[32:35], v[146:149], v[194:197], v[32:35]
	v_mfma_f32_16x16x32_bf16 v[28:31], v[154:157], v[194:197], v[28:31]
	v_mfma_f32_16x16x32_bf16 v[16:19], v[146:149], v[214:217], v[16:19]
	v_mfma_f32_16x16x32_bf16 v[12:15], v[154:157], v[214:217], v[12:15]
	v_mfma_f32_16x16x32_bf16 v[64:67], v[150:153], v[182:185], v[64:67]
	v_mfma_f32_16x16x32_bf16 v[60:63], v[158:161], v[182:185], v[60:63]
	v_mfma_f32_16x16x32_bf16 v[48:51], v[150:153], v[190:193], v[48:51]
	v_mfma_f32_16x16x32_bf16 v[44:47], v[158:161], v[190:193], v[44:47]
	v_mfma_f32_16x16x32_bf16 v[32:35], v[150:153], v[210:213], v[32:35]
	v_mfma_f32_16x16x32_bf16 v[28:31], v[158:161], v[210:213], v[28:31]
	v_mfma_f32_16x16x32_bf16 v[16:19], v[150:153], v[218:221], v[16:19]
	v_mfma_f32_16x16x32_bf16 v[12:15], v[158:161], v[218:221], v[12:15]
	s_setprio 0
	s_setprio 1
	v_mfma_f32_16x16x32_bf16 v[56:59], v[162:165], v[178:181], v[56:59]
	v_mfma_f32_16x16x32_bf16 v[52:55], v[170:173], v[178:181], v[52:55]
	v_mfma_f32_16x16x32_bf16 v[40:43], v[162:165], v[186:189], v[40:43]
	v_mfma_f32_16x16x32_bf16 v[36:39], v[170:173], v[186:189], v[36:39]
	v_mfma_f32_16x16x32_bf16 v[24:27], v[162:165], v[194:197], v[24:27]
	v_mfma_f32_16x16x32_bf16 v[20:23], v[170:173], v[194:197], v[20:23]
	v_mfma_f32_16x16x32_bf16 v[8:11], v[162:165], v[214:217], v[8:11]
	v_mfma_f32_16x16x32_bf16 v[4:7], v[170:173], v[214:217], v[4:7]
	v_mfma_f32_16x16x32_bf16 v[56:59], v[166:169], v[182:185], v[56:59]
	v_mfma_f32_16x16x32_bf16 v[52:55], v[174:177], v[182:185], v[52:55]
	v_mfma_f32_16x16x32_bf16 v[40:43], v[166:169], v[190:193], v[40:43]
	v_mfma_f32_16x16x32_bf16 v[36:39], v[174:177], v[190:193], v[36:39]
	v_mfma_f32_16x16x32_bf16 v[24:27], v[166:169], v[210:213], v[24:27]
	v_mfma_f32_16x16x32_bf16 v[20:23], v[174:177], v[210:213], v[20:23]
	v_mfma_f32_16x16x32_bf16 v[8:11], v[166:169], v[218:221], v[8:11]
	v_mfma_f32_16x16x32_bf16 v[4:7], v[174:177], v[218:221], v[4:7]
	s_barrier
	s_setprio 0
	s_add_i32 s48, 0, 0x18000
	v_add_u32_e32 v145, s48, v143
	s_add_i32 s49, 0, 0x1c000
	ds_read_b128 v[146:149], v145
	ds_read_b128 v[150:153], v145 offset:1024
	ds_read_b128 v[154:157], v145 offset:2048
	ds_read_b128 v[158:161], v145 offset:3072
	v_add_u32_e32 v145, s49, v143
	ds_read_b128 v[162:165], v145
	ds_read_b128 v[166:169], v145 offset:1024
	ds_read_b128 v[170:173], v145 offset:2048
	ds_read_b128 v[174:177], v145 offset:3072
	s_add_u32 s12, s12, 0x80000
	s_addc_u32 s13, s13, 0
	s_mov_b32 m0, s21
	v_lshl_add_u64 v[224:225], s[12:13], 0, v[132:133]
	ds_read_b128 v[178:181], v144 offset:32768
	ds_read_b128 v[182:185], v144 offset:33792
	ds_read_b128 v[186:189], v144 offset:34816
	ds_read_b128 v[190:193], v144 offset:35840
	ds_read_b128 v[194:197], v144 offset:36864
	ds_read_b128 v[210:213], v144 offset:37888
	ds_read_b128 v[214:217], v144 offset:38912
	ds_read_b128 v[218:221], v144 offset:39936
	global_load_lds_dwordx4 v[224:225], off
	v_lshl_add_u64 v[224:225], s[12:13], 0, v[134:135]
	s_mov_b32 m0, s23
	s_nop 0
	global_load_lds_dwordx4 v[224:225], off
	s_waitcnt vmcnt(8)
	s_waitcnt lgkmcnt(0)
	s_setprio 1
	s_barrier
	v_mfma_f32_16x16x32_bf16 v[128:131], v[146:149], v[178:181], v[128:131]
	v_mfma_f32_16x16x32_bf16 v[124:127], v[154:157], v[178:181], v[124:127]
	v_mfma_f32_16x16x32_bf16 v[112:115], v[146:149], v[186:189], v[112:115]
	v_mfma_f32_16x16x32_bf16 v[108:111], v[154:157], v[186:189], v[108:111]
	v_mfma_f32_16x16x32_bf16 v[96:99], v[146:149], v[194:197], v[96:99]
	v_mfma_f32_16x16x32_bf16 v[92:95], v[154:157], v[194:197], v[92:95]
	v_mfma_f32_16x16x32_bf16 v[80:83], v[146:149], v[214:217], v[80:83]
	v_mfma_f32_16x16x32_bf16 v[76:79], v[154:157], v[214:217], v[76:79]
	v_mfma_f32_16x16x32_bf16 v[128:131], v[150:153], v[182:185], v[128:131]
	v_mfma_f32_16x16x32_bf16 v[124:127], v[158:161], v[182:185], v[124:127]
	v_mfma_f32_16x16x32_bf16 v[112:115], v[150:153], v[190:193], v[112:115]
	v_mfma_f32_16x16x32_bf16 v[108:111], v[158:161], v[190:193], v[108:111]
	v_mfma_f32_16x16x32_bf16 v[96:99], v[150:153], v[210:213], v[96:99]
	v_mfma_f32_16x16x32_bf16 v[92:95], v[158:161], v[210:213], v[92:95]
	v_mfma_f32_16x16x32_bf16 v[80:83], v[150:153], v[218:221], v[80:83]
	v_mfma_f32_16x16x32_bf16 v[76:79], v[158:161], v[218:221], v[76:79]
	s_setprio 0
	s_setprio 1
	v_mfma_f32_16x16x32_bf16 v[120:123], v[162:165], v[178:181], v[120:123]
	v_mfma_f32_16x16x32_bf16 v[116:119], v[170:173], v[178:181], v[116:119]
	v_mfma_f32_16x16x32_bf16 v[104:107], v[162:165], v[186:189], v[104:107]
	v_mfma_f32_16x16x32_bf16 v[100:103], v[170:173], v[186:189], v[100:103]
	v_mfma_f32_16x16x32_bf16 v[88:91], v[162:165], v[194:197], v[88:91]
	v_mfma_f32_16x16x32_bf16 v[84:87], v[170:173], v[194:197], v[84:87]
	v_mfma_f32_16x16x32_bf16 v[72:75], v[162:165], v[214:217], v[72:75]
	v_mfma_f32_16x16x32_bf16 v[68:71], v[170:173], v[214:217], v[68:71]
	v_mfma_f32_16x16x32_bf16 v[120:123], v[166:169], v[182:185], v[120:123]
	v_mfma_f32_16x16x32_bf16 v[116:119], v[174:177], v[182:185], v[116:119]
	v_mfma_f32_16x16x32_bf16 v[104:107], v[166:169], v[190:193], v[104:107]
	v_mfma_f32_16x16x32_bf16 v[100:103], v[174:177], v[190:193], v[100:103]
	v_mfma_f32_16x16x32_bf16 v[88:91], v[166:169], v[210:213], v[88:91]
	v_mfma_f32_16x16x32_bf16 v[84:87], v[174:177], v[210:213], v[84:87]
	v_mfma_f32_16x16x32_bf16 v[72:75], v[166:169], v[218:221], v[72:75]
	v_mfma_f32_16x16x32_bf16 v[68:71], v[174:177], v[218:221], v[68:71]
	s_barrier
; #define PG8_STAGE(bufoff, gbase, voff) do { _Pragma("unroll") for (int _i = 0; _i < 2; ++_i) \
;         __builtin_amdgcn_global_load_lds((const unsigned*)((const char*)(gbase) + (voff)[_i]), (PG8_LAS unsigned*)(lds + (bufoff) + ldsw + _i * 8192), 16, 0, 0); } while (0)
; #define PG8_LDA(dst, b, h) do { _Pragma("unroll") for (int m = 0; m < 4; ++m) _Pragma("unroll") for (int k = 0; k < 2; ++k) dst[m][k] = *(const PG8_LAS bf16x8*)(lds + PG8_SA(b, h) + aoff + m * 2048 + k * 1024); } while (0)
; #define PG8_MMA(ai, bj, At, Bt) do { __builtin_amdgcn_s_setprio(1); _Pragma("unroll") for (int m = 0; m < 4; ++m) _Pragma("unroll") for (int n = 0; n < 2; ++n) _Pragma("unroll") for (int k = 0; k < 2; ++k) \
;         acc[ai][bj][m][n] = __builtin_amdgcn_mfma_f32_16x16x32_bf16(Bt[n][k], At[m][k], acc[ai][bj][m][n], 0, 0, 0); __builtin_amdgcn_s_setprio(0); } while (0)
; #define PG8_WAIT_V(n) asm volatile("s_waitcnt vmcnt(" #n ")" ::: "memory")
; #define PG8_WAIT_L(n) asm volatile("s_waitcnt lgkmcnt(" #n ")" ::: "memory")
; #define PG8_BAR __builtin_amdgcn_s_barrier()
; #define PG8_SCHED __builtin_amdgcn_sched_barrier(0)
;     ...
;             PG8_WAIT_V(8); PG8_WAIT_L(0); PG8_BAR; PG8_MMA(0, 0, At, B0); PG8_MMA(0, 1, At, B1); PG8_BAR; PG8_SCHED;
;             PG8_LDA(At, 1, 1); PG8_STAGE(PG8_SB(1, 0), b3, voffB); PG8_STAGE(PG8_SB(1, 1), b3 + hstep, voffB); PG8_STAGE(PG8_SA(1, 0), a3, voffA);
;             PG8_WAIT_V(8); PG8_WAIT_L(0); PG8_BAR; PG8_MMA(1, 0, At, B0); PG8_MMA(1, 1, At, B1); PG8_BAR; PG8_SCHED;
;     ...
;         if constexpr (ALIGN_EPI) { if (wr == 0) PG8_BAR; }
	s_setprio 0
	s_add_i32 s12, s48, s14
	v_lshl_add_u64 v[198:199], v[198:199], 0, s[66:67]
	s_mov_b32 m0, s12
	ds_read_b128 v[178:181], v144 offset:49152
	ds_read_b128 v[182:185], v144 offset:50176
	ds_read_b128 v[186:189], v144 offset:51200
	ds_read_b128 v[190:193], v144 offset:52224
	ds_read_b128 v[194:197], v144 offset:53248
	ds_read_b128 v[210:213], v144 offset:54272
	ds_read_b128 v[214:217], v144 offset:55296
	ds_read_b128 v[218:221], v144 offset:56320
	global_load_lds_dwordx4 v[198:199], off
	s_add_i32 m0, s12, 0x2000
	s_add_u32 s10, s10, 0x80080
	v_lshl_add_u64 v[198:199], v[206:207], 0, s[66:67]
	s_addc_u32 s11, s11, 0
	s_add_i32 s12, s49, s14
	global_load_lds_dwordx4 v[198:199], off
	v_lshl_add_u64 v[198:199], s[10:11], 0, v[200:201]
	s_mov_b32 m0, s12
	s_nop 0
	global_load_lds_dwordx4 v[198:199], off
	v_lshl_add_u64 v[198:199], s[10:11], 0, v[136:137]
	s_add_i32 m0, s12, 0x2000
	s_nop 0
	global_load_lds_dwordx4 v[198:199], off
	v_lshl_add_u64 v[198:199], v[208:209], 0, s[66:67]
	s_mov_b32 m0, s42
	s_nop 0
	global_load_lds_dwordx4 v[198:199], off
	v_lshl_add_u64 v[198:199], v[222:223], 0, s[66:67]
	s_mov_b32 m0, s44
	s_nop 0
	global_load_lds_dwordx4 v[198:199], off
	s_waitcnt vmcnt(8)
	s_waitcnt lgkmcnt(0)
	s_setprio 1
	s_barrier
	v_mfma_f32_16x16x32_bf16 v[64:67], v[146:149], v[178:181], v[64:67]
	v_mfma_f32_16x16x32_bf16 v[60:63], v[154:157], v[178:181], v[60:63]
	v_mfma_f32_16x16x32_bf16 v[48:51], v[146:149], v[186:189], v[48:51]
	v_mfma_f32_16x16x32_bf16 v[44:47], v[154:157], v[186:189], v[44:47]
	v_mfma_f32_16x16x32_bf16 v[32:35], v[146:149], v[194:197], v[32:35]
	v_mfma_f32_16x16x32_bf16 v[28:31], v[154:157], v[194:197], v[28:31]
	v_mfma_f32_16x16x32_bf16 v[16:19], v[146:149], v[214:217], v[16:19]
	v_mfma_f32_16x16x32_bf16 v[12:15], v[154:157], v[214:217], v[12:15]
	v_mfma_f32_16x16x32_bf16 v[64:67], v[150:153], v[182:185], v[64:67]
	v_mfma_f32_16x16x32_bf16 v[60:63], v[158:161], v[182:185], v[60:63]
	v_mfma_f32_16x16x32_bf16 v[48:51], v[150:153], v[190:193], v[48:51]
	v_mfma_f32_16x16x32_bf16 v[44:47], v[158:161], v[190:193], v[44:47]
	v_mfma_f32_16x16x32_bf16 v[32:35], v[150:153], v[210:213], v[32:35]
	v_mfma_f32_16x16x32_bf16 v[28:31], v[158:161], v[210:213], v[28:31]
	v_mfma_f32_16x16x32_bf16 v[16:19], v[150:153], v[218:221], v[16:19]
	v_mfma_f32_16x16x32_bf16 v[12:15], v[158:161], v[218:221], v[12:15]
	s_setprio 0
	s_setprio 1
	v_mfma_f32_16x16x32_bf16 v[56:59], v[162:165], v[178:181], v[56:59]
	v_mfma_f32_16x16x32_bf16 v[52:55], v[170:173], v[178:181], v[52:55]
	v_mfma_f32_16x16x32_bf16 v[40:43], v[162:165], v[186:189], v[40:43]
	v_mfma_f32_16x16x32_bf16 v[36:39], v[170:173], v[186:189], v[36:39]
	v_mfma_f32_16x16x32_bf16 v[24:27], v[162:165], v[194:197], v[24:27]
	v_mfma_f32_16x16x32_bf16 v[20:23], v[170:173], v[194:197], v[20:23]
	v_mfma_f32_16x16x32_bf16 v[8:11], v[162:165], v[214:217], v[8:11]
	v_mfma_f32_16x16x32_bf16 v[4:7], v[170:173], v[214:217], v[4:7]
	v_mfma_f32_16x16x32_bf16 v[56:59], v[166:169], v[182:185], v[56:59]
	v_mfma_f32_16x16x32_bf16 v[52:55], v[174:177], v[182:185], v[52:55]
	v_mfma_f32_16x16x32_bf16 v[40:43], v[166:169], v[190:193], v[40:43]
	v_mfma_f32_16x16x32_bf16 v[36:39], v[174:177], v[190:193], v[36:39]
	v_mfma_f32_16x16x32_bf16 v[24:27], v[166:169], v[210:213], v[24:27]
	v_mfma_f32_16x16x32_bf16 v[20:23], v[174:177], v[210:213], v[20:23]
	v_mfma_f32_16x16x32_bf16 v[8:11], v[166:169], v[218:221], v[8:11]
	v_mfma_f32_16x16x32_bf16 v[4:7], v[174:177], v[218:221], v[4:7]
	s_barrier
	s_setprio 0
	s_add_i32 s51, s51, 2
	s_add_u32 s6, s6, 0x100
	s_addc_u32 s7, s7, 0
	s_cmp_gt_u32 s51, 29
	s_cbranch_scc0 .LBB0_279
	s_cmpk_lt_u32 s1, 0x100
	s_cbranch_scc0 .LBB0_282
	s_barrier

;     __device__ __forceinline__ bool next(int i, Unit& u) const { if (i >= n) return false; u.pm = pm; u.pn = pn0 + i; return true; }
;     __device__ __forceinline__ bool next(int i, Unit& u) const { if (i) return false; u.pm = pm; u.pn = pn; return true; }
; #define PG8_STAGE(bufoff, gbase, voff) do { _Pragma("unroll") for (int _i = 0; _i < 2; ++_i) \
;         __builtin_amdgcn_global_load_lds((const unsigned*)((const char*)(gbase) + (voff)[_i]), (PG8_LAS unsigned*)(lds + (bufoff) + ldsw + _i * 8192), 16, 0, 0); } while (0)
; #define PG8_LDA(dst, b, h) do { _Pragma("unroll") for (int m = 0; m < 4; ++m) _Pragma("unroll") for (int k = 0; k < 2; ++k) dst[m][k] = *(const PG8_LAS bf16x8*)(lds + PG8_SA(b, h) + aoff + m * 2048 + k * 1024); } while (0)
; #define PG8_LDB(dst, b, h) do { _Pragma("unroll") for (int n = 0; n < 2; ++n) _Pragma("unroll") for (int k = 0; k < 2; ++k) dst[n][k] = *(const PG8_LAS bf16x8*)(lds + PG8_SB(b, h) + boff + n * 2048 + k * 1024); } while (0)
; #define PG8_WAIT_V(n) asm volatile("s_waitcnt vmcnt(" #n ")" ::: "memory")
; #define PG8_BAR __builtin_amdgcn_s_barrier()
;     ...
;         const bool has_next = S.next(ui + 1, nxt);
;         const char* nA = has_next ? (const char*)g.A + (size_t)nxt.pm * tstep : cA; const char* nB = has_next ? (const char*)g.Bt + (size_t)nxt.pn * tstep : cB;
;         for (int t = 0; t < nt; t += 2) {
;             const bool last = (t == nt - 2);
;             const char* a1 = cA + (size_t)(t + 1) * kstep;
;             const char* a2 = last ? nA : cA + (size_t)(t + 2) * kstep; const char* b2 = last ? nB : cB + (size_t)(t + 2) * kstep;
;             const char* a3 = a2 + kstep; const char* b3 = b2 + kstep;
;             if (last && has_next) S.a_ready(nxt);
;             if (t == 0) E.pre_issue(pre, cur, tid, ui); else if (t == 2) E.pre_finish(pre, tid, ui);
;             if constexpr (SP2) {
;             PG8_LDB(B0, 0, 0); PG8_LDB(B1, 0, 1); PG8_SCHED; PG8_LDA(At, 0, 0); PG8_STAGE(PG8_SA(1, 1), a1 + hstep, voffA);
;             PG8_WAIT_V(8); PG8_WAIT_L(0); PG8_BAR; PG8_MMA(0, 0, At, B0); PG8_MMA(0, 1, At, B1); PG8_BAR; PG8_SCHED;
;             PG8_LDA(At, 0, 1); PG8_STAGE(PG8_SB(0, 0), b2, voffB); PG8_STAGE(PG8_SB(0, 1), b2 + hstep, voffB); PG8_STAGE(PG8_SA(0, 0), a2, voffA);
;             PG8_WAIT_V(8); PG8_WAIT_L(0); PG8_BAR; PG8_MMA(1, 0, At, B0); PG8_MMA(1, 1, At, B1); PG8_BAR; PG8_SCHED;
.LBB0_290:
	s_add_u32 s48, s24, 0xfffe0080
	s_addc_u32 s49, s25, -1
	s_add_i32 s84, 0, 0x10000
	s_cmp_eq_u32 s83, 4
	s_cselect_b32 s61, s68, s49
	s_cselect_b32 s60, s69, s48
	v_add_u32_e32 v146, s84, v149
	s_cselect_b32 s51, s70, s81
	s_cselect_b32 s50, s71, s73
	s_add_i32 s48, 0, 0x14000
	ds_read_b128 v[142:145], v146
	ds_read_b128 v[152:155], v146 offset:1024
	ds_read_b128 v[156:159], v146 offset:2048
	ds_read_b128 v[160:163], v146 offset:3072
	v_add_u32_e32 v146, s48, v149
	ds_read_b128 v[164:167], v146
	ds_read_b128 v[168:171], v146 offset:1024
	ds_read_b128 v[172:175], v146 offset:2048
	ds_read_b128 v[176:179], v146 offset:3072
	v_lshl_add_u64 v[146:147], s[24:25], 0, v[140:141]
	s_add_i32 m0, s23, 0xc000
	ds_read_b128 v[180:183], v150
	ds_read_b128 v[184:187], v150 offset:1024
	ds_read_b128 v[188:191], v150 offset:2048
	ds_read_b128 v[192:195], v150 offset:3072
	ds_read_b128 v[196:199], v150 offset:4096
	ds_read_b128 v[210:213], v150 offset:5120
	ds_read_b128 v[214:217], v150 offset:6144
	ds_read_b128 v[218:221], v150 offset:7168
	global_load_lds_dwordx4 v[146:147], off
	v_lshl_add_u64 v[146:147], s[24:25], 0, v[138:139]
	s_add_i32 m0, s23, 0xe000
	s_nop 0
	global_load_lds_dwordx4 v[146:147], off
	s_waitcnt vmcnt(8)
	s_waitcnt lgkmcnt(0)
	s_setprio 1
	s_barrier
	v_mfma_f32_16x16x32_bf16 v[128:131], v[142:145], v[180:183], v[128:131]
	v_mfma_f32_16x16x32_bf16 v[124:127], v[156:159], v[180:183], v[124:127]
	v_mfma_f32_16x16x32_bf16 v[112:115], v[142:145], v[188:191], v[112:115]
	v_mfma_f32_16x16x32_bf16 v[108:111], v[156:159], v[188:191], v[108:111]
	v_mfma_f32_16x16x32_bf16 v[96:99], v[142:145], v[196:199], v[96:99]
	v_mfma_f32_16x16x32_bf16 v[92:95], v[156:159], v[196:199], v[92:95]
	v_mfma_f32_16x16x32_bf16 v[80:83], v[142:145], v[214:217], v[80:83]
	v_mfma_f32_16x16x32_bf16 v[76:79], v[156:159], v[214:217], v[76:79]
	v_mfma_f32_16x16x32_bf16 v[128:131], v[152:155], v[184:187], v[128:131]
	v_mfma_f32_16x16x32_bf16 v[124:127], v[160:163], v[184:187], v[124:127]
	v_mfma_f32_16x16x32_bf16 v[112:115], v[152:155], v[192:195], v[112:115]
	v_mfma_f32_16x16x32_bf16 v[108:111], v[160:163], v[192:195], v[108:111]
	v_mfma_f32_16x16x32_bf16 v[96:99], v[152:155], v[210:213], v[96:99]
	v_mfma_f32_16x16x32_bf16 v[92:95], v[160:163], v[210:213], v[92:95]
	v_mfma_f32_16x16x32_bf16 v[80:83], v[152:155], v[218:221], v[80:83]
	v_mfma_f32_16x16x32_bf16 v[76:79], v[160:163], v[218:221], v[76:79]
	s_setprio 0
	s_setprio 1
	v_mfma_f32_16x16x32_bf16 v[120:123], v[164:167], v[180:183], v[120:123]
	v_mfma_f32_16x16x32_bf16 v[116:119], v[172:175], v[180:183], v[116:119]
	v_mfma_f32_16x16x32_bf16 v[104:107], v[164:167], v[188:191], v[104:107]
	v_mfma_f32_16x16x32_bf16 v[100:103], v[172:175], v[188:191], v[100:103]
	v_mfma_f32_16x16x32_bf16 v[88:91], v[164:167], v[196:199], v[88:91]
	v_mfma_f32_16x16x32_bf16 v[84:87], v[172:175], v[196:199], v[84:87]
	v_mfma_f32_16x16x32_bf16 v[72:75], v[164:167], v[214:217], v[72:75]
	v_mfma_f32_16x16x32_bf16 v[68:71], v[172:175], v[214:217], v[68:71]
	v_mfma_f32_16x16x32_bf16 v[120:123], v[168:171], v[184:187], v[120:123]
	v_mfma_f32_16x16x32_bf16 v[116:119], v[176:179], v[184:187], v[116:119]
	v_mfma_f32_16x16x32_bf16 v[104:107], v[168:171], v[192:195], v[104:107]
	v_mfma_f32_16x16x32_bf16 v[100:103], v[176:179], v[192:195], v[100:103]
	v_mfma_f32_16x16x32_bf16 v[88:91], v[168:171], v[210:213], v[88:91]
	v_mfma_f32_16x16x32_bf16 v[84:87], v[176:179], v[210:213], v[84:87]
	v_mfma_f32_16x16x32_bf16 v[72:75], v[168:171], v[218:221], v[72:75]
	v_mfma_f32_16x16x32_bf16 v[68:71], v[176:179], v[218:221], v[68:71]
	s_barrier
	s_setprio 0
	s_add_i32 s49, s84, s21
	v_lshl_add_u64 v[146:147], s[50:51], 0, v[200:201]
	s_mov_b32 m0, s49
	ds_read_b128 v[180:183], v150 offset:16384
	ds_read_b128 v[184:187], v150 offset:17408
	ds_read_b128 v[188:191], v150 offset:18432
	ds_read_b128 v[192:195], v150 offset:19456
	ds_read_b128 v[196:199], v150 offset:20480
	ds_read_b128 v[210:213], v150 offset:21504
	ds_read_b128 v[214:217], v150 offset:22528
	ds_read_b128 v[218:221], v150 offset:23552
	global_load_lds_dwordx4 v[146:147], off
	s_add_i32 m0, s49, 0x2000
	s_add_u32 s84, s50, 0x20000
	v_lshl_add_u64 v[206:207], s[50:51], 0, v[132:133]
	s_addc_u32 s85, s51, 0
	s_add_i32 s48, s48, s21
	global_load_lds_dwordx4 v[206:207], off
	v_lshl_add_u64 v[208:209], s[84:85], 0, v[200:201]
	s_mov_b32 m0, s48
	v_lshl_add_u64 v[222:223], s[60:61], 0, v[134:135]
	global_load_lds_dwordx4 v[208:209], off
	v_lshl_add_u64 v[208:209], s[84:85], 0, v[132:133]
	s_add_i32 m0, s48, 0x2000
	s_nop 0
	global_load_lds_dwordx4 v[208:209], off
	v_lshl_add_u64 v[208:209], s[60:61], 0, v[136:137]
	s_mov_b32 m0, s23
	s_nop 0
	global_load_lds_dwordx4 v[208:209], off
	s_mov_b32 m0, s42
	s_nop 0
	global_load_lds_dwordx4 v[222:223], off
	s_waitcnt vmcnt(8)
	s_waitcnt lgkmcnt(0)
	s_setprio 1
	s_barrier
; #define PG8_STAGE(bufoff, gbase, voff) do { _Pragma("unroll") for (int _i = 0; _i < 2; ++_i) \
;         __builtin_amdgcn_global_load_lds((const unsigned*)((const char*)(gbase) + (voff)[_i]), (PG8_LAS unsigned*)(lds + (bufoff) + ldsw + _i * 8192), 16, 0, 0); } while (0)
; #define PG8_LDA(dst, b, h) do { _Pragma("unroll") for (int m = 0; m < 4; ++m) _Pragma("unroll") for (int k = 0; k < 2; ++k) dst[m][k] = *(const PG8_LAS bf16x8*)(lds + PG8_SA(b, h) + aoff + m * 2048 + k * 1024); } while (0)
; #define PG8_LDB(dst, b, h) do { _Pragma("unroll") for (int n = 0; n < 2; ++n) _Pragma("unroll") for (int k = 0; k < 2; ++k) dst[n][k] = *(const PG8_LAS bf16x8*)(lds + PG8_SB(b, h) + boff + n * 2048 + k * 1024); } while (0)
; #define PG8_MMA(ai, bj, At, Bt) do { __builtin_amdgcn_s_setprio(1); _Pragma("unroll") for (int m = 0; m < 4; ++m) _Pragma("unroll") for (int n = 0; n < 2; ++n) _Pragma("unroll") for (int k = 0; k < 2; ++k) \
;         acc[ai][bj][m][n] = __builtin_amdgcn_mfma_f32_16x16x32_bf16(Bt[n][k], At[m][k], acc[ai][bj][m][n], 0, 0, 0); __builtin_amdgcn_s_setprio(0); } while (0)
; #define PG8_WAIT_V(n) asm volatile("s_waitcnt vmcnt(" #n ")" ::: "memory")
; #define PG8_WAIT_L(n) asm volatile("s_waitcnt lgkmcnt(" #n ")" ::: "memory")
; #define PG8_BAR __builtin_amdgcn_s_barrier()
; #define PG8_SCHED __builtin_amdgcn_sched_barrier(0)
;     ...
;             PG8_WAIT_V(8); PG8_WAIT_L(0); PG8_BAR; PG8_MMA(1, 0, At, B0); PG8_MMA(1, 1, At, B1); PG8_BAR; PG8_SCHED;
;             PG8_LDB(B0, 1, 0); PG8_LDB(B1, 1, 1); PG8_SCHED; PG8_LDA(At, 1, 0); PG8_STAGE(PG8_SA(0, 1), a2 + hstep, voffA);
;             PG8_WAIT_V(8); PG8_WAIT_L(0); PG8_BAR; PG8_MMA(0, 0, At, B0); PG8_MMA(0, 1, At, B1); PG8_BAR; PG8_SCHED;
	v_mfma_f32_16x16x32_bf16 v[64:67], v[142:145], v[180:183], v[64:67]
	v_mfma_f32_16x16x32_bf16 v[60:63], v[156:159], v[180:183], v[60:63]
	v_mfma_f32_16x16x32_bf16 v[48:51], v[142:145], v[188:191], v[48:51]
	v_mfma_f32_16x16x32_bf16 v[44:47], v[156:159], v[188:191], v[44:47]
	v_mfma_f32_16x16x32_bf16 v[32:35], v[142:145], v[196:199], v[32:35]
	v_mfma_f32_16x16x32_bf16 v[28:31], v[156:159], v[196:199], v[28:31]
	v_mfma_f32_16x16x32_bf16 v[16:19], v[142:145], v[214:217], v[16:19]
	v_mfma_f32_16x16x32_bf16 v[12:15], v[156:159], v[214:217], v[12:15]
	v_mfma_f32_16x16x32_bf16 v[64:67], v[152:155], v[184:187], v[64:67]
	v_mfma_f32_16x16x32_bf16 v[60:63], v[160:163], v[184:187], v[60:63]
	v_mfma_f32_16x16x32_bf16 v[48:51], v[152:155], v[192:195], v[48:51]
	v_mfma_f32_16x16x32_bf16 v[44:47], v[160:163], v[192:195], v[44:47]
	v_mfma_f32_16x16x32_bf16 v[32:35], v[152:155], v[210:213], v[32:35]
	v_mfma_f32_16x16x32_bf16 v[28:31], v[160:163], v[210:213], v[28:31]
	v_mfma_f32_16x16x32_bf16 v[16:19], v[152:155], v[218:221], v[16:19]
	v_mfma_f32_16x16x32_bf16 v[12:15], v[160:163], v[218:221], v[12:15]
	s_setprio 0
	s_setprio 1
	v_mfma_f32_16x16x32_bf16 v[56:59], v[164:167], v[180:183], v[56:59]
	v_mfma_f32_16x16x32_bf16 v[52:55], v[172:175], v[180:183], v[52:55]
	v_mfma_f32_16x16x32_bf16 v[40:43], v[164:167], v[188:191], v[40:43]
	v_mfma_f32_16x16x32_bf16 v[36:39], v[172:175], v[188:191], v[36:39]
	v_mfma_f32_16x16x32_bf16 v[24:27], v[164:167], v[196:199], v[24:27]
	v_mfma_f32_16x16x32_bf16 v[20:23], v[172:175], v[196:199], v[20:23]
	v_mfma_f32_16x16x32_bf16 v[8:11], v[164:167], v[214:217], v[8:11]
	v_mfma_f32_16x16x32_bf16 v[4:7], v[172:175], v[214:217], v[4:7]
	v_mfma_f32_16x16x32_bf16 v[56:59], v[168:171], v[184:187], v[56:59]
	v_mfma_f32_16x16x32_bf16 v[52:55], v[176:179], v[184:187], v[52:55]
	v_mfma_f32_16x16x32_bf16 v[40:43], v[168:171], v[192:195], v[40:43]
	v_mfma_f32_16x16x32_bf16 v[36:39], v[176:179], v[192:195], v[36:39]
	v_mfma_f32_16x16x32_bf16 v[24:27], v[168:171], v[210:213], v[24:27]
	v_mfma_f32_16x16x32_bf16 v[20:23], v[176:179], v[210:213], v[20:23]
	v_mfma_f32_16x16x32_bf16 v[8:11], v[168:171], v[218:221], v[8:11]
	v_mfma_f32_16x16x32_bf16 v[4:7], v[176:179], v[218:221], v[4:7]
	s_barrier
	s_setprio 0
	s_add_i32 s48, 0, 0x18000
	v_add_u32_e32 v151, s48, v149
	s_add_i32 s49, 0, 0x1c000
	ds_read_b128 v[142:145], v151
	ds_read_b128 v[152:155], v151 offset:1024
	ds_read_b128 v[156:159], v151 offset:2048
	ds_read_b128 v[160:163], v151 offset:3072
	v_add_u32_e32 v151, s49, v149
	ds_read_b128 v[164:167], v151
	ds_read_b128 v[168:171], v151 offset:1024
	ds_read_b128 v[172:175], v151 offset:2048
	ds_read_b128 v[176:179], v151 offset:3072
	s_add_u32 s60, s60, 0x20000
	s_addc_u32 s61, s61, 0
	s_mov_b32 m0, s44
	v_lshl_add_u64 v[224:225], s[60:61], 0, v[136:137]
	ds_read_b128 v[180:183], v150 offset:32768
	ds_read_b128 v[184:187], v150 offset:33792
	ds_read_b128 v[188:191], v150 offset:34816
	ds_read_b128 v[192:195], v150 offset:35840
	ds_read_b128 v[196:199], v150 offset:36864
	ds_read_b128 v[210:213], v150 offset:37888
	ds_read_b128 v[214:217], v150 offset:38912
	ds_read_b128 v[218:221], v150 offset:39936
	global_load_lds_dwordx4 v[224:225], off
	v_lshl_add_u64 v[224:225], s[60:61], 0, v[134:135]
	s_mov_b32 m0, s52
	s_nop 0
	global_load_lds_dwordx4 v[224:225], off
	s_waitcnt vmcnt(8)
	s_waitcnt lgkmcnt(0)
	s_setprio 1
	s_barrier
	v_mfma_f32_16x16x32_bf16 v[128:131], v[142:145], v[180:183], v[128:131]
	v_mfma_f32_16x16x32_bf16 v[124:127], v[156:159], v[180:183], v[124:127]
	v_mfma_f32_16x16x32_bf16 v[112:115], v[142:145], v[188:191], v[112:115]
	v_mfma_f32_16x16x32_bf16 v[108:111], v[156:159], v[188:191], v[108:111]
	v_mfma_f32_16x16x32_bf16 v[96:99], v[142:145], v[196:199], v[96:99]
	v_mfma_f32_16x16x32_bf16 v[92:95], v[156:159], v[196:199], v[92:95]
	v_mfma_f32_16x16x32_bf16 v[80:83], v[142:145], v[214:217], v[80:83]
	v_mfma_f32_16x16x32_bf16 v[76:79], v[156:159], v[214:217], v[76:79]
	v_mfma_f32_16x16x32_bf16 v[128:131], v[152:155], v[184:187], v[128:131]
	v_mfma_f32_16x16x32_bf16 v[124:127], v[160:163], v[184:187], v[124:127]
	v_mfma_f32_16x16x32_bf16 v[112:115], v[152:155], v[192:195], v[112:115]
	v_mfma_f32_16x16x32_bf16 v[108:111], v[160:163], v[192:195], v[108:111]
	v_mfma_f32_16x16x32_bf16 v[96:99], v[152:155], v[210:213], v[96:99]
	v_mfma_f32_16x16x32_bf16 v[92:95], v[160:163], v[210:213], v[92:95]
	v_mfma_f32_16x16x32_bf16 v[80:83], v[152:155], v[218:221], v[80:83]
	v_mfma_f32_16x16x32_bf16 v[76:79], v[160:163], v[218:221], v[76:79]
	s_setprio 0
	s_setprio 1
	v_mfma_f32_16x16x32_bf16 v[120:123], v[164:167], v[180:183], v[120:123]
	v_mfma_f32_16x16x32_bf16 v[116:119], v[172:175], v[180:183], v[116:119]
	v_mfma_f32_16x16x32_bf16 v[104:107], v[164:167], v[188:191], v[104:107]
	v_mfma_f32_16x16x32_bf16 v[100:103], v[172:175], v[188:191], v[100:103]
	v_mfma_f32_16x16x32_bf16 v[88:91], v[164:167], v[196:199], v[88:91]
	v_mfma_f32_16x16x32_bf16 v[84:87], v[172:175], v[196:199], v[84:87]
	v_mfma_f32_16x16x32_bf16 v[72:75], v[164:167], v[214:217], v[72:75]
	v_mfma_f32_16x16x32_bf16 v[68:71], v[172:175], v[214:217], v[68:71]
	v_mfma_f32_16x16x32_bf16 v[120:123], v[168:171], v[184:187], v[120:123]
	v_mfma_f32_16x16x32_bf16 v[116:119], v[176:179], v[184:187], v[116:119]
	v_mfma_f32_16x16x32_bf16 v[104:107], v[168:171], v[192:195], v[104:107]
	v_mfma_f32_16x16x32_bf16 v[100:103], v[176:179], v[192:195], v[100:103]
	v_mfma_f32_16x16x32_bf16 v[88:91], v[168:171], v[210:213], v[88:91]
	v_mfma_f32_16x16x32_bf16 v[84:87], v[176:179], v[210:213], v[84:87]
	v_mfma_f32_16x16x32_bf16 v[72:75], v[168:171], v[218:221], v[72:75]
	v_mfma_f32_16x16x32_bf16 v[68:71], v[176:179], v[218:221], v[68:71]
	s_barrier
; #define PG8_G __attribute__((address_space(1)))
; __device__ __forceinline__ u32x4 pack8bf(const f32x4 a, const f32x4 b) { u32x4 w; w.x = cvt_pk_bf16(a[0], a[1]); w.y = cvt_pk_bf16(a[2], a[3]); w.z = cvt_pk_bf16(b[0], b[1]); w.w = cvt_pk_bf16(b[2], b[3]); return w; }
; #define PG8_STAGE(bufoff, gbase, voff) do { _Pragma("unroll") for (int _i = 0; _i < 2; ++_i) \
;         __builtin_amdgcn_global_load_lds((const unsigned*)((const char*)(gbase) + (voff)[_i]), (PG8_LAS unsigned*)(lds + (bufoff) + ldsw + _i * 8192), 16, 0, 0); } while (0)
; #define PG8_LDA(dst, b, h) do { _Pragma("unroll") for (int m = 0; m < 4; ++m) _Pragma("unroll") for (int k = 0; k < 2; ++k) dst[m][k] = *(const PG8_LAS bf16x8*)(lds + PG8_SA(b, h) + aoff + m * 2048 + k * 1024); } while (0)
; #define PG8_MMA(ai, bj, At, Bt) do { __builtin_amdgcn_s_setprio(1); _Pragma("unroll") for (int m = 0; m < 4; ++m) _Pragma("unroll") for (int n = 0; n < 2; ++n) _Pragma("unroll") for (int k = 0; k < 2; ++k) \
;         acc[ai][bj][m][n] = __builtin_amdgcn_mfma_f32_16x16x32_bf16(Bt[n][k], At[m][k], acc[ai][bj][m][n], 0, 0, 0); __builtin_amdgcn_s_setprio(0); } while (0)
; #define PG8_WAIT_V(n) asm volatile("s_waitcnt vmcnt(" #n ")" ::: "memory")
;     __device__ __forceinline__ void operator()(const f32x4 (&acc)[2][2][4][2], const Unit& u, int wr, int wc, int fr_, int fq_, int ui) const {
;     ...
;         const int row0 = u.pm * BM + wr * 64 + fr, dim0 = wc * 32 + 8 * fq;
;         float r[2][4]; load_rs(r, rsl, wr, fr);
; #pragma unroll
;         for (int ai = 0; ai < 2; ++ai)
; #pragma unroll
;             for (int m = 0; m < 4; ++m) { const int row = row0 + ai * HALF + m * 16, b = row >> 12, s = row & 4095;
;                 const size_t o = (((size_t)b * 16 + u.pn) * 4096 + s) * 128 + dim0;
;                 *(PG8_G u32x4*)(KH + o) = pack8bf(acc[ai][0][m][0] * r[ai][m], acc[ai][0][m][1] * r[ai][m]); *(PG8_G u32x4*)(VH + o) = pack8bf(acc[ai][1][m][0] * r[ai][m], acc[ai][1][m][1] * r[ai][m]); }
;     ...
;             PG8_WAIT_V(8); PG8_WAIT_L(0); PG8_BAR; PG8_MMA(0, 0, At, B0); PG8_MMA(0, 1, At, B1); PG8_BAR; PG8_SCHED;
;             PG8_LDA(At, 1, 1); PG8_STAGE(PG8_SB(1, 0), b3, voffB); PG8_STAGE(PG8_SB(1, 1), b3 + hstep, voffB); PG8_STAGE(PG8_SA(1, 0), a3, voffA);
;             PG8_WAIT_V(8); PG8_WAIT_L(0); PG8_BAR; PG8_MMA(1, 0, At, B0); PG8_MMA(1, 1, At, B1); PG8_BAR; PG8_SCHED;
	s_setprio 0
	s_add_i32 s48, s48, s21
	v_lshl_add_u64 v[146:147], v[146:147], 0, s[66:67]
	s_mov_b32 m0, s48
	ds_read_b128 v[180:183], v150 offset:49152
	ds_read_b128 v[184:187], v150 offset:50176
	ds_read_b128 v[188:191], v150 offset:51200
	ds_read_b128 v[192:195], v150 offset:52224
	ds_read_b128 v[196:199], v150 offset:53248
	ds_read_b128 v[210:213], v150 offset:54272
	ds_read_b128 v[214:217], v150 offset:55296
	ds_read_b128 v[218:221], v150 offset:56320
	global_load_lds_dwordx4 v[146:147], off
	s_add_i32 m0, s48, 0x2000
	s_add_u32 s50, s50, 0x20080
	v_lshl_add_u64 v[146:147], v[206:207], 0, s[66:67]
	s_addc_u32 s51, s51, 0
	s_add_i32 s48, s49, s21
	global_load_lds_dwordx4 v[146:147], off
	v_lshl_add_u64 v[146:147], s[50:51], 0, v[200:201]
	s_mov_b32 m0, s48
	s_nop 0
	global_load_lds_dwordx4 v[146:147], off
	v_lshl_add_u64 v[146:147], s[50:51], 0, v[132:133]
	s_add_i32 m0, s48, 0x2000
	s_nop 0
	global_load_lds_dwordx4 v[146:147], off
	v_lshl_add_u64 v[146:147], v[208:209], 0, s[66:67]
	s_mov_b32 m0, s54
	s_nop 0
	global_load_lds_dwordx4 v[146:147], off
	v_lshl_add_u64 v[146:147], v[222:223], 0, s[66:67]
	s_mov_b32 m0, s55
	s_nop 0
	global_load_lds_dwordx4 v[146:147], off
	s_waitcnt vmcnt(8)
	s_waitcnt lgkmcnt(0)
	s_setprio 1
	s_barrier
	v_mfma_f32_16x16x32_bf16 v[64:67], v[142:145], v[180:183], v[64:67]
	v_mfma_f32_16x16x32_bf16 v[60:63], v[156:159], v[180:183], v[60:63]
	v_mfma_f32_16x16x32_bf16 v[48:51], v[142:145], v[188:191], v[48:51]
	v_mfma_f32_16x16x32_bf16 v[44:47], v[156:159], v[188:191], v[44:47]
	v_mfma_f32_16x16x32_bf16 v[32:35], v[142:145], v[196:199], v[32:35]
	v_mfma_f32_16x16x32_bf16 v[28:31], v[156:159], v[196:199], v[28:31]
	v_mfma_f32_16x16x32_bf16 v[16:19], v[142:145], v[214:217], v[16:19]
	v_mfma_f32_16x16x32_bf16 v[12:15], v[156:159], v[214:217], v[12:15]
	v_mfma_f32_16x16x32_bf16 v[64:67], v[152:155], v[184:187], v[64:67]
	v_mfma_f32_16x16x32_bf16 v[60:63], v[160:163], v[184:187], v[60:63]
	v_mfma_f32_16x16x32_bf16 v[48:51], v[152:155], v[192:195], v[48:51]
	v_mfma_f32_16x16x32_bf16 v[44:47], v[160:163], v[192:195], v[44:47]
	v_mfma_f32_16x16x32_bf16 v[32:35], v[152:155], v[210:213], v[32:35]
	v_mfma_f32_16x16x32_bf16 v[28:31], v[160:163], v[210:213], v[28:31]
	v_mfma_f32_16x16x32_bf16 v[16:19], v[152:155], v[218:221], v[16:19]
	v_mfma_f32_16x16x32_bf16 v[12:15], v[160:163], v[218:221], v[12:15]
	s_setprio 0
	s_setprio 1
	v_mfma_f32_16x16x32_bf16 v[56:59], v[164:167], v[180:183], v[56:59]
	v_mfma_f32_16x16x32_bf16 v[52:55], v[172:175], v[180:183], v[52:55]
	v_mfma_f32_16x16x32_bf16 v[40:43], v[164:167], v[188:191], v[40:43]
	v_mfma_f32_16x16x32_bf16 v[36:39], v[172:175], v[188:191], v[36:39]
	v_mfma_f32_16x16x32_bf16 v[24:27], v[164:167], v[196:199], v[24:27]
	v_mfma_f32_16x16x32_bf16 v[20:23], v[172:175], v[196:199], v[20:23]
	v_mfma_f32_16x16x32_bf16 v[8:11], v[164:167], v[214:217], v[8:11]
	v_mfma_f32_16x16x32_bf16 v[4:7], v[172:175], v[214:217], v[4:7]
	v_mfma_f32_16x16x32_bf16 v[56:59], v[168:171], v[184:187], v[56:59]
	v_mfma_f32_16x16x32_bf16 v[52:55], v[176:179], v[184:187], v[52:55]
	v_mfma_f32_16x16x32_bf16 v[40:43], v[168:171], v[192:195], v[40:43]
	v_mfma_f32_16x16x32_bf16 v[36:39], v[176:179], v[192:195], v[36:39]
	v_mfma_f32_16x16x32_bf16 v[24:27], v[168:171], v[210:213], v[24:27]
	v_mfma_f32_16x16x32_bf16 v[20:23], v[176:179], v[210:213], v[20:23]
	v_mfma_f32_16x16x32_bf16 v[8:11], v[168:171], v[218:221], v[8:11]
	v_mfma_f32_16x16x32_bf16 v[4:7], v[176:179], v[218:221], v[4:7]
	s_barrier
	s_setprio 0
	s_add_i32 s83, s83, 2
	s_add_u32 s73, s73, 0x100
	s_addc_u32 s81, s81, 0
	s_add_u32 s24, s24, 0x100
	s_addc_u32 s25, s25, 0
	s_cmp_gt_u32 s83, 5
	s_cbranch_scc0 .LBB0_290
	v_mov_b32_e32 v142, v148
	v_mov_b32_e32 v143, v3
	v_readlane_b32 s84, v255, 29
	s_add_i32 s24, s63, s84
	v_add_u32_e32 v151, s56, v143
	v_ashrrev_i32_e32 v156, 12, v151
	s_ashr_i32 s25, s24, 31
	v_ashrrev_i32_e32 v157, 31, v156
	s_lshl_b64 s[24:25], s[24:25], 12
	v_lshlrev_b64 v[156:157], 16, v[156:157]
	v_lshl_add_u32 v143, v143, 2, s58
	v_lshl_add_u64 v[156:157], v[156:157], 0, s[24:25]
	v_lshl_add_u32 v142, v142, 3, s53
	ds_read2_b32 v[152:153], v143 offset1:16
	ds_read2_b32 v[154:155], v143 offset0:32 offset1:48
	ds_read2_b32 v[146:147], v143 offset0:128 offset1:144
	ds_read2_b32 v[144:145], v143 offset0:160 offset1:176
	v_and_or_b32 v156, v151, s17, v156
	v_ashrrev_i32_e32 v143, 31, v142
	v_lshlrev_b64 v[156:157], 7, v[156:157]
	v_lshl_add_u64 v[156:157], v[156:157], 0, v[142:143]
	s_waitcnt lgkmcnt(0)
; #define PG8_G __attribute__((address_space(1)))
; __device__ __forceinline__ u32x4 pack8bf(const f32x4 a, const f32x4 b) { u32x4 w; w.x = cvt_pk_bf16(a[0], a[1]); w.y = cvt_pk_bf16(a[2], a[3]); w.z = cvt_pk_bf16(b[0], b[1]); w.w = cvt_pk_bf16(b[2], b[3]); return w; }
;     __device__ __forceinline__ void operator()(const f32x4 (&acc)[2][2][4][2], const Unit& u, int wr, int wc, int fr_, int fq_, int ui) const {
;     ...
;             for (int m = 0; m < 4; ++m) { const int row = row0 + ai * HALF + m * 16, b = row >> 12, s = row & 4095;
;                 const size_t o = (((size_t)b * 16 + u.pn) * 4096 + s) * 128 + dim0;
;                 *(PG8_G u32x4*)(KH + o) = pack8bf(acc[ai][0][m][0] * r[ai][m], acc[ai][0][m][1] * r[ai][m]); *(PG8_G u32x4*)(VH + o) = pack8bf(acc[ai][1][m][0] * r[ai][m], acc[ai][1][m][1] * r[ai][m]); }
	v_pk_mul_f32 v[128:129], v[128:129], v[152:153] op_sel_hi:[1,0]
	v_pk_mul_f32 v[130:131], v[130:131], v[152:153] op_sel_hi:[1,0]
	v_pk_mul_f32 v[158:159], v[126:127], v[152:153] op_sel_hi:[1,0]
	v_pk_mul_f32 v[126:127], v[124:125], v[152:153] op_sel_hi:[1,0]
	v_cvt_pk_bf16_f32 v124, v128, v129
	v_lshlrev_b64 v[128:129], 1, v[156:157]
	v_cvt_pk_bf16_f32 v125, v130, v131
	v_lshl_add_u64 v[130:131], s[12:13], 0, v[128:129]
	v_cvt_pk_bf16_f32 v126, v126, v127
	v_cvt_pk_bf16_f32 v127, v158, v159
	global_store_dwordx4 v[130:131], v[124:127], off
	v_pk_mul_f32 v[120:121], v[120:121], v[152:153] op_sel_hi:[1,0]
	v_pk_mul_f32 v[122:123], v[122:123], v[152:153] op_sel_hi:[1,0]
	v_pk_mul_f32 v[124:125], v[118:119], v[152:153] op_sel_hi:[1,0]
	v_pk_mul_f32 v[118:119], v[116:117], v[152:153] op_sel_hi:[1,0]
	v_cvt_pk_bf16_f32 v116, v120, v121
	v_cvt_pk_bf16_f32 v117, v122, v123
	v_lshl_add_u64 v[120:121], s[14:15], 0, v[128:129]
	v_cvt_pk_bf16_f32 v118, v118, v119
	v_cvt_pk_bf16_f32 v119, v124, v125
	global_store_dwordx4 v[120:121], v[116:119], off
	v_pk_mul_f32 v[96:97], v[96:97], v[154:155] op_sel_hi:[1,0]
	v_pk_mul_f32 v[98:99], v[98:99], v[154:155] op_sel_hi:[1,0]
	v_add_u32_e32 v118, 16, v151
	v_ashrrev_i32_e32 v116, 12, v118
	v_ashrrev_i32_e32 v117, 31, v116
	v_lshlrev_b64 v[116:117], 16, v[116:117]
	v_lshl_add_u64 v[116:117], v[116:117], 0, s[24:25]
	v_and_or_b32 v116, v118, s17, v116
	v_lshlrev_b64 v[116:117], 7, v[116:117]
	v_mov_b32_e32 v118, v153
	v_lshl_add_u64 v[116:117], v[116:117], 0, v[142:143]
	v_pk_mul_f32 v[112:113], v[112:113], v[118:119] op_sel_hi:[1,0]
	v_pk_mul_f32 v[114:115], v[114:115], v[118:119] op_sel_hi:[1,0]
	v_pk_mul_f32 v[120:121], v[110:111], v[118:119] op_sel_hi:[1,0]
	v_pk_mul_f32 v[110:111], v[108:109], v[118:119] op_sel_hi:[1,0]
	v_cvt_pk_bf16_f32 v108, v112, v113
	v_lshlrev_b64 v[112:113], 1, v[116:117]
	v_cvt_pk_bf16_f32 v109, v114, v115
	v_lshl_add_u64 v[114:115], s[12:13], 0, v[112:113]
	v_cvt_pk_bf16_f32 v110, v110, v111
	v_cvt_pk_bf16_f32 v111, v120, v121
	global_store_dwordx4 v[114:115], v[108:111], off
	v_pk_mul_f32 v[104:105], v[104:105], v[118:119] op_sel_hi:[1,0]
	v_pk_mul_f32 v[106:107], v[106:107], v[118:119] op_sel_hi:[1,0]
	v_pk_mul_f32 v[108:109], v[102:103], v[118:119] op_sel_hi:[1,0]
	v_pk_mul_f32 v[102:103], v[100:101], v[118:119] op_sel_hi:[1,0]
	v_cvt_pk_bf16_f32 v100, v104, v105
	v_cvt_pk_bf16_f32 v101, v106, v107
	v_lshl_add_u64 v[104:105], s[14:15], 0, v[112:113]
	v_cvt_pk_bf16_f32 v102, v102, v103
	v_cvt_pk_bf16_f32 v103, v108, v109
	global_store_dwordx4 v[104:105], v[100:103], off
	v_pk_mul_f32 v[88:89], v[88:89], v[154:155] op_sel_hi:[1,0]
	v_pk_mul_f32 v[90:91], v[90:91], v[154:155] op_sel_hi:[1,0]
	v_add_u32_e32 v102, 32, v151
	v_ashrrev_i32_e32 v100, 12, v102
	v_ashrrev_i32_e32 v101, 31, v100
	v_lshlrev_b64 v[100:101], 16, v[100:101]
	v_lshl_add_u64 v[100:101], v[100:101], 0, s[24:25]
	v_and_or_b32 v100, v102, s17, v100
	v_lshlrev_b64 v[100:101], 7, v[100:101]
	v_lshl_add_u64 v[100:101], v[100:101], 0, v[142:143]
	v_pk_mul_f32 v[102:103], v[94:95], v[154:155] op_sel_hi:[1,0]
	v_pk_mul_f32 v[94:95], v[92:93], v[154:155] op_sel_hi:[1,0]
	v_cvt_pk_bf16_f32 v92, v96, v97
	v_lshlrev_b64 v[96:97], 1, v[100:101]
	v_cvt_pk_bf16_f32 v93, v98, v99
	v_lshl_add_u64 v[98:99], s[12:13], 0, v[96:97]
	v_cvt_pk_bf16_f32 v94, v94, v95
	v_cvt_pk_bf16_f32 v95, v102, v103
	global_store_dwordx4 v[98:99], v[92:95], off
	v_pk_mul_f32 v[64:65], v[64:65], v[146:147] op_sel_hi:[1,0]
	v_pk_mul_f32 v[66:67], v[66:67], v[146:147] op_sel_hi:[1,0]
	v_pk_mul_f32 v[92:93], v[86:87], v[154:155] op_sel_hi:[1,0]
	v_pk_mul_f32 v[86:87], v[84:85], v[154:155] op_sel_hi:[1,0]
	v_cvt_pk_bf16_f32 v84, v88, v89
	v_cvt_pk_bf16_f32 v85, v90, v91
	v_lshl_add_u64 v[88:89], s[14:15], 0, v[96:97]
	v_cvt_pk_bf16_f32 v86, v86, v87
	v_cvt_pk_bf16_f32 v87, v92, v93
	global_store_dwordx4 v[88:89], v[84:87], off
	v_pk_mul_f32 v[56:57], v[56:57], v[146:147] op_sel_hi:[1,0]
	v_pk_mul_f32 v[58:59], v[58:59], v[146:147] op_sel_hi:[1,0]
	v_add_u32_e32 v86, 48, v151
	v_ashrrev_i32_e32 v84, 12, v86
	v_ashrrev_i32_e32 v85, 31, v84
	v_lshlrev_b64 v[84:85], 16, v[84:85]
	v_lshl_add_u64 v[84:85], v[84:85], 0, s[24:25]
	v_and_or_b32 v84, v86, s17, v84
	v_lshlrev_b64 v[84:85], 7, v[84:85]
	v_mov_b32_e32 v86, v155
	v_lshl_add_u64 v[84:85], v[84:85], 0, v[142:143]
	v_pk_mul_f32 v[80:81], v[80:81], v[86:87] op_sel_hi:[1,0]
	v_pk_mul_f32 v[82:83], v[82:83], v[86:87] op_sel_hi:[1,0]
	v_pk_mul_f32 v[88:89], v[78:79], v[86:87] op_sel_hi:[1,0]
	v_pk_mul_f32 v[78:79], v[76:77], v[86:87] op_sel_hi:[1,0]
	v_cvt_pk_bf16_f32 v76, v80, v81
	v_lshlrev_b64 v[80:81], 1, v[84:85]
	v_cvt_pk_bf16_f32 v77, v82, v83
	v_lshl_add_u64 v[82:83], s[12:13], 0, v[80:81]
	v_cvt_pk_bf16_f32 v78, v78, v79
	v_cvt_pk_bf16_f32 v79, v88, v89
	global_store_dwordx4 v[82:83], v[76:79], off
	v_pk_mul_f32 v[72:73], v[72:73], v[86:87] op_sel_hi:[1,0]
	v_pk_mul_f32 v[74:75], v[74:75], v[86:87] op_sel_hi:[1,0]
	v_pk_mul_f32 v[76:77], v[70:71], v[86:87] op_sel_hi:[1,0]
	v_pk_mul_f32 v[70:71], v[68:69], v[86:87] op_sel_hi:[1,0]
	v_cvt_pk_bf16_f32 v68, v72, v73
	v_cvt_pk_bf16_f32 v69, v74, v75
	v_lshl_add_u64 v[72:73], s[14:15], 0, v[80:81]
; #define PG8_G __attribute__((address_space(1)))
; __device__ __forceinline__ u32x4 pack8bf(const f32x4 a, const f32x4 b) { u32x4 w; w.x = cvt_pk_bf16(a[0], a[1]); w.y = cvt_pk_bf16(a[2], a[3]); w.z = cvt_pk_bf16(b[0], b[1]); w.w = cvt_pk_bf16(b[2], b[3]); return w; }
; #define PG8_WAIT_V(n) asm volatile("s_waitcnt vmcnt(" #n ")" ::: "memory")
; #define PG8_BAR __builtin_amdgcn_s_barrier()
;     __device__ __forceinline__ void operator()(const f32x4 (&acc)[2][2][4][2], const Unit& u, int wr, int wc, int fr_, int fq_, int ui) const {
;     ...
;             for (int m = 0; m < 4; ++m) { const int row = row0 + ai * HALF + m * 16, b = row >> 12, s = row & 4095;
;                 const size_t o = (((size_t)b * 16 + u.pn) * 4096 + s) * 128 + dim0;
;                 *(PG8_G u32x4*)(KH + o) = pack8bf(acc[ai][0][m][0] * r[ai][m], acc[ai][0][m][1] * r[ai][m]); *(PG8_G u32x4*)(VH + o) = pack8bf(acc[ai][1][m][0] * r[ai][m], acc[ai][1][m][1] * r[ai][m]); }
;     ...
;         if (!has_next) break;
;     ...
;     PG8_WAIT_V(0);
;     if constexpr (!ALIGN_EPI) { if (wr == 0) PG8_BAR; }
	v_cvt_pk_bf16_f32 v70, v70, v71
	v_cvt_pk_bf16_f32 v71, v76, v77
	global_store_dwordx4 v[72:73], v[68:71], off
	v_pk_mul_f32 v[32:33], v[32:33], v[144:145] op_sel_hi:[1,0]
	v_pk_mul_f32 v[34:35], v[34:35], v[144:145] op_sel_hi:[1,0]
	v_add_u32_e32 v70, 0x80, v151
	v_ashrrev_i32_e32 v68, 12, v70
	v_ashrrev_i32_e32 v69, 31, v68
	v_lshlrev_b64 v[68:69], 16, v[68:69]
	v_lshl_add_u64 v[68:69], v[68:69], 0, s[24:25]
	v_and_or_b32 v68, v70, s17, v68
	v_lshlrev_b64 v[68:69], 7, v[68:69]
	v_lshl_add_u64 v[68:69], v[68:69], 0, v[142:143]
	v_pk_mul_f32 v[70:71], v[62:63], v[146:147] op_sel_hi:[1,0]
	v_pk_mul_f32 v[62:63], v[60:61], v[146:147] op_sel_hi:[1,0]
	v_cvt_pk_bf16_f32 v60, v64, v65
	v_lshlrev_b64 v[64:65], 1, v[68:69]
	v_cvt_pk_bf16_f32 v61, v66, v67
	v_lshl_add_u64 v[66:67], s[12:13], 0, v[64:65]
	v_cvt_pk_bf16_f32 v62, v62, v63
	v_cvt_pk_bf16_f32 v63, v70, v71
	global_store_dwordx4 v[66:67], v[60:63], off
	v_pk_mul_f32 v[24:25], v[24:25], v[144:145] op_sel_hi:[1,0]
	v_pk_mul_f32 v[26:27], v[26:27], v[144:145] op_sel_hi:[1,0]
	v_pk_mul_f32 v[60:61], v[54:55], v[146:147] op_sel_hi:[1,0]
	v_pk_mul_f32 v[54:55], v[52:53], v[146:147] op_sel_hi:[1,0]
	v_cvt_pk_bf16_f32 v52, v56, v57
	v_cvt_pk_bf16_f32 v53, v58, v59
	v_lshl_add_u64 v[56:57], s[14:15], 0, v[64:65]
	v_cvt_pk_bf16_f32 v54, v54, v55
	v_cvt_pk_bf16_f32 v55, v60, v61
	global_store_dwordx4 v[56:57], v[52:55], off
	s_cmp_eq_u32 s62, 8
	s_mov_b32 s63, s62
	v_add_u32_e32 v54, 0x90, v151
	v_ashrrev_i32_e32 v52, 12, v54
	v_ashrrev_i32_e32 v53, 31, v52
	v_lshlrev_b64 v[52:53], 16, v[52:53]
	v_lshl_add_u64 v[52:53], v[52:53], 0, s[24:25]
	v_and_or_b32 v52, v54, s17, v52
	v_lshlrev_b64 v[52:53], 7, v[52:53]
	v_mov_b32_e32 v54, v147
	v_lshl_add_u64 v[52:53], v[52:53], 0, v[142:143]
	v_pk_mul_f32 v[48:49], v[48:49], v[54:55] op_sel_hi:[1,0]
	v_pk_mul_f32 v[50:51], v[50:51], v[54:55] op_sel_hi:[1,0]
	v_pk_mul_f32 v[56:57], v[46:47], v[54:55] op_sel_hi:[1,0]
	v_pk_mul_f32 v[46:47], v[44:45], v[54:55] op_sel_hi:[1,0]
	v_cvt_pk_bf16_f32 v44, v48, v49
	v_lshlrev_b64 v[48:49], 1, v[52:53]
	v_cvt_pk_bf16_f32 v45, v50, v51
	v_lshl_add_u64 v[50:51], s[12:13], 0, v[48:49]
	v_cvt_pk_bf16_f32 v46, v46, v47
	v_cvt_pk_bf16_f32 v47, v56, v57
	global_store_dwordx4 v[50:51], v[44:47], off
	v_pk_mul_f32 v[40:41], v[40:41], v[54:55] op_sel_hi:[1,0]
	v_pk_mul_f32 v[42:43], v[42:43], v[54:55] op_sel_hi:[1,0]
	v_pk_mul_f32 v[44:45], v[38:39], v[54:55] op_sel_hi:[1,0]
	v_pk_mul_f32 v[38:39], v[36:37], v[54:55] op_sel_hi:[1,0]
	v_cvt_pk_bf16_f32 v36, v40, v41
	v_cvt_pk_bf16_f32 v37, v42, v43
	v_lshl_add_u64 v[40:41], s[14:15], 0, v[48:49]
	v_cvt_pk_bf16_f32 v38, v38, v39
	v_cvt_pk_bf16_f32 v39, v44, v45
	global_store_dwordx4 v[40:41], v[36:39], off
	v_readlane_b32 s85, v255, 30
	s_nop 0
	v_add_u32_e32 v38, 0xa0, v151
	v_ashrrev_i32_e32 v36, 12, v38
	v_ashrrev_i32_e32 v37, 31, v36
	v_lshlrev_b64 v[36:37], 16, v[36:37]
	v_lshl_add_u64 v[36:37], v[36:37], 0, s[24:25]
	v_and_or_b32 v36, v38, s17, v36
	v_lshlrev_b64 v[36:37], 7, v[36:37]
	v_lshl_add_u64 v[36:37], v[36:37], 0, v[142:143]
	v_pk_mul_f32 v[38:39], v[30:31], v[144:145] op_sel_hi:[1,0]
	v_pk_mul_f32 v[30:31], v[28:29], v[144:145] op_sel_hi:[1,0]
	v_cvt_pk_bf16_f32 v28, v32, v33
	v_lshlrev_b64 v[32:33], 1, v[36:37]
	v_cvt_pk_bf16_f32 v29, v34, v35
	v_lshl_add_u64 v[34:35], s[12:13], 0, v[32:33]
	v_cvt_pk_bf16_f32 v30, v30, v31
	v_cvt_pk_bf16_f32 v31, v38, v39
	global_store_dwordx4 v[34:35], v[28:31], off
	s_nop 1
	v_pk_mul_f32 v[28:29], v[22:23], v[144:145] op_sel_hi:[1,0]
	v_pk_mul_f32 v[22:23], v[20:21], v[144:145] op_sel_hi:[1,0]
	v_cvt_pk_bf16_f32 v20, v24, v25
	v_cvt_pk_bf16_f32 v21, v26, v27
	v_lshl_add_u64 v[24:25], s[14:15], 0, v[32:33]
	v_cvt_pk_bf16_f32 v22, v22, v23
	v_cvt_pk_bf16_f32 v23, v28, v29
	global_store_dwordx4 v[24:25], v[20:23], off
	s_nop 1
	v_add_u32_e32 v22, 0xb0, v151
	v_ashrrev_i32_e32 v20, 12, v22
	v_ashrrev_i32_e32 v21, 31, v20
	v_lshlrev_b64 v[20:21], 16, v[20:21]
	v_lshl_add_u64 v[20:21], v[20:21], 0, s[24:25]
	v_and_or_b32 v20, v22, s17, v20
	v_lshlrev_b64 v[20:21], 7, v[20:21]
	v_mov_b32_e32 v22, v145
	v_lshl_add_u64 v[20:21], v[20:21], 0, v[142:143]
	v_pk_mul_f32 v[16:17], v[16:17], v[22:23] op_sel_hi:[1,0]
	v_pk_mul_f32 v[18:19], v[18:19], v[22:23] op_sel_hi:[1,0]
	v_pk_mul_f32 v[24:25], v[14:15], v[22:23] op_sel_hi:[1,0]
	v_pk_mul_f32 v[14:15], v[12:13], v[22:23] op_sel_hi:[1,0]
	v_cvt_pk_bf16_f32 v12, v16, v17
	v_lshlrev_b64 v[16:17], 1, v[20:21]
	v_cvt_pk_bf16_f32 v13, v18, v19
	v_lshl_add_u64 v[18:19], s[12:13], 0, v[16:17]
	v_pk_mul_f32 v[8:9], v[8:9], v[22:23] op_sel_hi:[1,0]
	v_cvt_pk_bf16_f32 v14, v14, v15
	v_cvt_pk_bf16_f32 v15, v24, v25
	global_store_dwordx4 v[18:19], v[12:15], off
	v_pk_mul_f32 v[10:11], v[10:11], v[22:23] op_sel_hi:[1,0]
	s_nop 0
	v_pk_mul_f32 v[12:13], v[6:7], v[22:23] op_sel_hi:[1,0]
	v_pk_mul_f32 v[6:7], v[4:5], v[22:23] op_sel_hi:[1,0]
	v_cvt_pk_bf16_f32 v4, v8, v9
	v_lshl_add_u64 v[8:9], s[14:15], 0, v[16:17]
	v_cvt_pk_bf16_f32 v5, v10, v11
	v_cvt_pk_bf16_f32 v6, v6, v7
	v_cvt_pk_bf16_f32 v7, v12, v13
	global_store_dwordx4 v[8:9], v[4:7], off
	s_cbranch_scc0 .LBB0_289
	s_waitcnt vmcnt(0)
	s_cmpk_gt_u32 s20, 0xff
	s_cbranch_scc1 .LBB0_294
	s_barrier

;     __device__ __forceinline__ bool next(int i, Unit& u) const { if (i >= n) return false; u.pm = pm; u.pn = pn0 + i; return true; }
;     __device__ __forceinline__ bool next(int i, Unit& u) const { if (i) return false; u.pm = pm; u.pn = pn; return true; }
; #define PG8_STAGE(bufoff, gbase, voff) do { _Pragma("unroll") for (int _i = 0; _i < 2; ++_i) \
;         __builtin_amdgcn_global_load_lds((const unsigned*)((const char*)(gbase) + (voff)[_i]), (PG8_LAS unsigned*)(lds + (bufoff) + ldsw + _i * 8192), 16, 0, 0); } while (0)
; #define PG8_LDA(dst, b, h) do { _Pragma("unroll") for (int m = 0; m < 4; ++m) _Pragma("unroll") for (int k = 0; k < 2; ++k) dst[m][k] = *(const PG8_LAS bf16x8*)(lds + PG8_SA(b, h) + aoff + m * 2048 + k * 1024); } while (0)
; #define PG8_LDB(dst, b, h) do { _Pragma("unroll") for (int n = 0; n < 2; ++n) _Pragma("unroll") for (int k = 0; k < 2; ++k) dst[n][k] = *(const PG8_LAS bf16x8*)(lds + PG8_SB(b, h) + boff + n * 2048 + k * 1024); } while (0)
; #define PG8_BAR __builtin_amdgcn_s_barrier()
;     ...
;         const bool has_next = S.next(ui + 1, nxt);
;         const char* nA = has_next ? (const char*)g.A + (size_t)nxt.pm * tstep : cA; const char* nB = has_next ? (const char*)g.Bt + (size_t)nxt.pn * tstep : cB;
;         for (int t = 0; t < nt; t += 2) {
;             const bool last = (t == nt - 2);
;             const char* a1 = cA + (size_t)(t + 1) * kstep;
;             const char* a2 = last ? nA : cA + (size_t)(t + 2) * kstep; const char* b2 = last ? nB : cB + (size_t)(t + 2) * kstep;
;             const char* a3 = a2 + kstep; const char* b3 = b2 + kstep;
;             if (last && has_next) S.a_ready(nxt);
;             if (t == 0) E.pre_issue(pre, cur, tid, ui); else if (t == 2) E.pre_finish(pre, tid, ui);
;             if constexpr (SP2) {
;             PG8_LDB(B0, 0, 0); PG8_LDB(B1, 0, 1); PG8_SCHED; PG8_LDA(At, 0, 0); PG8_STAGE(PG8_SA(1, 1), a1 + hstep, voffA);
;             PG8_WAIT_V(8); PG8_WAIT_L(0); PG8_BAR; PG8_MMA(0, 0, At, B0); PG8_MMA(0, 1, At, B1); PG8_BAR; PG8_SCHED;
;     ...
; #pragma unroll
;         for (int a = 0; a < 2; ++a)
; #pragma unroll
;             for (int b = 0; b < 2; ++b)
; #pragma unroll
;                 for (int m = 0; m < 4; ++m)
; #pragma unroll
;                     for (int n = 0; n < 2; ++n) acc[a][b][m][n] = (f32x4){0.f, 0.f, 0.f, 0.f};
;         cur = nxt; cA = nA; cB = nB; ++ui;
.LBB0_300:
	s_mov_b32 s20, s79
	s_add_i32 s79, s79, 1
	s_mov_b64 s[24:25], s[4:5]
	s_cmp_lt_u32 s79, s21
	v_readlane_b32 s4, v254, 30
	s_mov_b64 s[14:15], s[6:7]
	s_mov_b32 s6, s83
	s_cselect_b64 s[50:51], -1, 0
	s_add_i32 s83, s79, s4
	s_and_b64 s[4:5], s[50:51], exec
	v_readlane_b32 s5, v254, 23
	s_cselect_b32 s4, s83, s6
	s_cselect_b32 s6, s5, s5
	s_ashr_i32 s7, s6, 31
	s_lshl_b64 s[6:7], s[6:7], 18
	s_add_u32 s6, s76, s6
	s_addc_u32 s7, s77, s7
	s_and_b64 s[52:53], s[50:51], exec
	s_cselect_b32 s21, s7, s15
	s_cselect_b32 s23, s6, s14
	s_ashr_i32 s5, s4, 31
	s_lshl_b64 s[4:5], s[4:5], 18
	s_add_u32 s4, s58, s4
	s_addc_u32 s5, s59, s5
	s_and_b64 s[50:51], s[50:51], exec
	s_cselect_b32 s42, s5, s25
	s_cselect_b32 s44, s4, s24
	s_add_u32 s52, s24, 0x100
	s_addc_u32 s53, s25, 0
	s_add_u32 s14, s14, 0x20080
	v_mov_b32_e32 v4, 0
	s_addc_u32 s15, s15, 0
	s_mov_b32 s54, -2
	v_mov_b32_e32 v5, v4
	v_mov_b32_e32 v6, v4
	v_mov_b32_e32 v7, v4
	v_mov_b32_e32 v8, v4
	v_mov_b32_e32 v9, v4
	v_mov_b32_e32 v10, v4
	v_mov_b32_e32 v11, v4
	v_mov_b32_e32 v16, v4
	v_mov_b32_e32 v17, v4
	v_mov_b32_e32 v18, v4
	v_mov_b32_e32 v19, v4
	v_mov_b32_e32 v24, v4
	v_mov_b32_e32 v25, v4
	v_mov_b32_e32 v26, v4
	v_mov_b32_e32 v27, v4
	v_mov_b32_e32 v32, v4
	v_mov_b32_e32 v33, v4
	v_mov_b32_e32 v34, v4
	v_mov_b32_e32 v35, v4
	v_mov_b32_e32 v40, v4
	v_mov_b32_e32 v41, v4
	v_mov_b32_e32 v42, v4
	v_mov_b32_e32 v43, v4
	v_mov_b32_e32 v48, v4
	v_mov_b32_e32 v49, v4
	v_mov_b32_e32 v50, v4
	v_mov_b32_e32 v51, v4
	v_mov_b32_e32 v56, v4
	v_mov_b32_e32 v57, v4
	v_mov_b32_e32 v58, v4
	v_mov_b32_e32 v59, v4
	v_mov_b32_e32 v12, v4
	v_mov_b32_e32 v13, v4
	v_mov_b32_e32 v14, v4
	v_mov_b32_e32 v15, v4
	v_mov_b32_e32 v20, v4
	v_mov_b32_e32 v21, v4
	v_mov_b32_e32 v22, v4
	v_mov_b32_e32 v23, v4
	v_mov_b32_e32 v28, v4
	v_mov_b32_e32 v29, v4
	v_mov_b32_e32 v30, v4
	v_mov_b32_e32 v31, v4
	v_mov_b32_e32 v36, v4
	v_mov_b32_e32 v37, v4
	v_mov_b32_e32 v38, v4
	v_mov_b32_e32 v39, v4
	v_mov_b32_e32 v44, v4
	v_mov_b32_e32 v45, v4
	v_mov_b32_e32 v46, v4
	v_mov_b32_e32 v47, v4
	v_mov_b32_e32 v52, v4
	v_mov_b32_e32 v53, v4
	v_mov_b32_e32 v54, v4
	v_mov_b32_e32 v55, v4
	v_mov_b32_e32 v60, v4
	v_mov_b32_e32 v61, v4
	v_mov_b32_e32 v62, v4
	v_mov_b32_e32 v63, v4
	v_mov_b32_e32 v64, v4
	v_mov_b32_e32 v65, v4
	v_mov_b32_e32 v66, v4
	v_mov_b32_e32 v67, v4
	v_mov_b32_e32 v68, v4
	v_mov_b32_e32 v69, v4
	v_mov_b32_e32 v70, v4
	v_mov_b32_e32 v71, v4
	v_mov_b32_e32 v72, v4
	v_mov_b32_e32 v73, v4
	v_mov_b32_e32 v74, v4
	v_mov_b32_e32 v75, v4
	v_mov_b32_e32 v80, v4
	v_mov_b32_e32 v81, v4
	v_mov_b32_e32 v82, v4
	v_mov_b32_e32 v83, v4
	v_mov_b32_e32 v88, v4
	v_mov_b32_e32 v89, v4
	v_mov_b32_e32 v90, v4
	v_mov_b32_e32 v91, v4
	v_mov_b32_e32 v96, v4
	v_mov_b32_e32 v97, v4
	v_mov_b32_e32 v98, v4
	v_mov_b32_e32 v99, v4
	v_mov_b32_e32 v104, v4
	v_mov_b32_e32 v105, v4
	v_mov_b32_e32 v106, v4
	v_mov_b32_e32 v107, v4
	v_mov_b32_e32 v112, v4
	v_mov_b32_e32 v113, v4
	v_mov_b32_e32 v114, v4
	v_mov_b32_e32 v115, v4
	v_mov_b32_e32 v120, v4
	v_mov_b32_e32 v121, v4
	v_mov_b32_e32 v122, v4
	v_mov_b32_e32 v123, v4
	v_mov_b32_e32 v76, v4
	v_mov_b32_e32 v77, v4
	v_mov_b32_e32 v78, v4
	v_mov_b32_e32 v79, v4
	v_mov_b32_e32 v84, v4
	v_mov_b32_e32 v85, v4
	v_mov_b32_e32 v86, v4
	v_mov_b32_e32 v87, v4
	v_mov_b32_e32 v92, v4
	v_mov_b32_e32 v93, v4
	v_mov_b32_e32 v94, v4
	v_mov_b32_e32 v95, v4
	v_mov_b32_e32 v100, v4
	v_mov_b32_e32 v101, v4
	v_mov_b32_e32 v102, v4
	v_mov_b32_e32 v103, v4
	v_mov_b32_e32 v108, v4
	v_mov_b32_e32 v109, v4
	v_mov_b32_e32 v110, v4
	v_mov_b32_e32 v111, v4
	v_mov_b32_e32 v116, v4
	v_mov_b32_e32 v117, v4
	v_mov_b32_e32 v118, v4
	v_mov_b32_e32 v119, v4
	v_mov_b32_e32 v124, v4
	v_mov_b32_e32 v125, v4
	v_mov_b32_e32 v126, v4
	v_mov_b32_e32 v127, v4
	v_mov_b32_e32 v128, v4
	v_mov_b32_e32 v129, v4
	v_mov_b32_e32 v130, v4
	v_mov_b32_e32 v131, v4
	s_waitcnt lgkmcnt(0)
.LBB0_301:
	s_add_u32 s24, s14, 0xfffe0080
	s_addc_u32 s25, s15, -1
	s_add_i32 s48, 0, 0x10000
	s_cmp_eq_u32 s54, 4
	s_cselect_b32 s51, s21, s25
	s_cselect_b32 s50, s23, s24
	s_cselect_b32 s25, s42, s53
	s_cselect_b32 s24, s44, s52
	s_add_i32 s49, 0, 0x14000
	v_add_u32_e32 v154, s48, v173
	v_add_u32_e32 v170, s49, v173
	ds_read_b128 v[132:135], v154
	ds_read_b128 v[146:149], v154 offset:1024
	ds_read_b128 v[150:153], v154 offset:2048
	ds_read_b128 v[154:157], v154 offset:3072
	ds_read_b128 v[158:161], v170
	ds_read_b128 v[162:165], v170 offset:1024
	ds_read_b128 v[166:169], v170 offset:2048
	ds_read_b128 v[176:179], v170 offset:3072
	v_lshl_add_u64 v[170:171], s[14:15], 0, v[144:145]
	s_add_i32 m0, s62, 0xc000
	ds_read_b128 v[180:183], v174
	ds_read_b128 v[184:187], v174 offset:1024
	ds_read_b128 v[188:191], v174 offset:2048
	ds_read_b128 v[192:195], v174 offset:3072
	ds_read_b128 v[196:199], v174 offset:4096
	ds_read_b128 v[210:213], v174 offset:5120
	ds_read_b128 v[214:217], v174 offset:6144
	ds_read_b128 v[218:221], v174 offset:7168
	global_load_lds_dwordx4 v[170:171], off
	v_lshl_add_u64 v[170:171], s[14:15], 0, v[142:143]
	s_add_i32 m0, s62, 0xe000
	s_nop 0
	global_load_lds_dwordx4 v[170:171], off
	s_waitcnt vmcnt(8)
	s_waitcnt lgkmcnt(0)
	s_setprio 1
	s_barrier
; #define PG8_STAGE(bufoff, gbase, voff) do { _Pragma("unroll") for (int _i = 0; _i < 2; ++_i) \
;         __builtin_amdgcn_global_load_lds((const unsigned*)((const char*)(gbase) + (voff)[_i]), (PG8_LAS unsigned*)(lds + (bufoff) + ldsw + _i * 8192), 16, 0, 0); } while (0)
; #define PG8_LDA(dst, b, h) do { _Pragma("unroll") for (int m = 0; m < 4; ++m) _Pragma("unroll") for (int k = 0; k < 2; ++k) dst[m][k] = *(const PG8_LAS bf16x8*)(lds + PG8_SA(b, h) + aoff + m * 2048 + k * 1024); } while (0)
; #define PG8_MMA(ai, bj, At, Bt) do { __builtin_amdgcn_s_setprio(1); _Pragma("unroll") for (int m = 0; m < 4; ++m) _Pragma("unroll") for (int n = 0; n < 2; ++n) _Pragma("unroll") for (int k = 0; k < 2; ++k) \
;         acc[ai][bj][m][n] = __builtin_amdgcn_mfma_f32_16x16x32_bf16(Bt[n][k], At[m][k], acc[ai][bj][m][n], 0, 0, 0); __builtin_amdgcn_s_setprio(0); } while (0)
; #define PG8_WAIT_V(n) asm volatile("s_waitcnt vmcnt(" #n ")" ::: "memory")
; #define PG8_WAIT_L(n) asm volatile("s_waitcnt lgkmcnt(" #n ")" ::: "memory")
; #define PG8_BAR __builtin_amdgcn_s_barrier()
; #define PG8_SCHED __builtin_amdgcn_sched_barrier(0)
;     ...
;             PG8_WAIT_V(8); PG8_WAIT_L(0); PG8_BAR; PG8_MMA(0, 0, At, B0); PG8_MMA(0, 1, At, B1); PG8_BAR; PG8_SCHED;
;             PG8_LDA(At, 0, 1); PG8_STAGE(PG8_SB(0, 0), b2, voffB); PG8_STAGE(PG8_SB(0, 1), b2 + hstep, voffB); PG8_STAGE(PG8_SA(0, 0), a2, voffA);
;             PG8_WAIT_V(8); PG8_WAIT_L(0); PG8_BAR; PG8_MMA(1, 0, At, B0); PG8_MMA(1, 1, At, B1); PG8_BAR; PG8_SCHED;
	v_mfma_f32_16x16x32_bf16 v[128:131], v[132:135], v[180:183], v[128:131]
	v_mfma_f32_16x16x32_bf16 v[124:127], v[150:153], v[180:183], v[124:127]
	v_mfma_f32_16x16x32_bf16 v[116:119], v[132:135], v[188:191], v[116:119]
	v_mfma_f32_16x16x32_bf16 v[108:111], v[150:153], v[188:191], v[108:111]
	v_mfma_f32_16x16x32_bf16 v[100:103], v[132:135], v[196:199], v[100:103]
	v_mfma_f32_16x16x32_bf16 v[92:95], v[150:153], v[196:199], v[92:95]
	v_mfma_f32_16x16x32_bf16 v[84:87], v[132:135], v[214:217], v[84:87]
	v_mfma_f32_16x16x32_bf16 v[76:79], v[150:153], v[214:217], v[76:79]
	v_mfma_f32_16x16x32_bf16 v[128:131], v[146:149], v[184:187], v[128:131]
	v_mfma_f32_16x16x32_bf16 v[124:127], v[154:157], v[184:187], v[124:127]
	v_mfma_f32_16x16x32_bf16 v[116:119], v[146:149], v[192:195], v[116:119]
	v_mfma_f32_16x16x32_bf16 v[108:111], v[154:157], v[192:195], v[108:111]
	v_mfma_f32_16x16x32_bf16 v[100:103], v[146:149], v[210:213], v[100:103]
	v_mfma_f32_16x16x32_bf16 v[92:95], v[154:157], v[210:213], v[92:95]
	v_mfma_f32_16x16x32_bf16 v[84:87], v[146:149], v[218:221], v[84:87]
	v_mfma_f32_16x16x32_bf16 v[76:79], v[154:157], v[218:221], v[76:79]
	s_setprio 0
	s_setprio 1
	v_mfma_f32_16x16x32_bf16 v[120:123], v[158:161], v[180:183], v[120:123]
	v_mfma_f32_16x16x32_bf16 v[112:115], v[166:169], v[180:183], v[112:115]
	v_mfma_f32_16x16x32_bf16 v[104:107], v[158:161], v[188:191], v[104:107]
	v_mfma_f32_16x16x32_bf16 v[96:99], v[166:169], v[188:191], v[96:99]
	v_mfma_f32_16x16x32_bf16 v[88:91], v[158:161], v[196:199], v[88:91]
	v_mfma_f32_16x16x32_bf16 v[80:83], v[166:169], v[196:199], v[80:83]
	v_mfma_f32_16x16x32_bf16 v[72:75], v[158:161], v[214:217], v[72:75]
	v_mfma_f32_16x16x32_bf16 v[68:71], v[166:169], v[214:217], v[68:71]
	v_mfma_f32_16x16x32_bf16 v[120:123], v[162:165], v[184:187], v[120:123]
	v_mfma_f32_16x16x32_bf16 v[112:115], v[176:179], v[184:187], v[112:115]
	v_mfma_f32_16x16x32_bf16 v[104:107], v[162:165], v[192:195], v[104:107]
	v_mfma_f32_16x16x32_bf16 v[96:99], v[176:179], v[192:195], v[96:99]
	v_mfma_f32_16x16x32_bf16 v[88:91], v[162:165], v[210:213], v[88:91]
	v_mfma_f32_16x16x32_bf16 v[80:83], v[176:179], v[210:213], v[80:83]
	v_mfma_f32_16x16x32_bf16 v[72:75], v[162:165], v[218:221], v[72:75]
	v_mfma_f32_16x16x32_bf16 v[68:71], v[176:179], v[218:221], v[68:71]
	s_barrier
	s_setprio 0
	s_add_i32 s48, s48, s61
	v_lshl_add_u64 v[170:171], s[24:25], 0, v[200:201]
	s_mov_b32 m0, s48
	ds_read_b128 v[180:183], v174 offset:16384
	ds_read_b128 v[184:187], v174 offset:17408
	ds_read_b128 v[188:191], v174 offset:18432
	ds_read_b128 v[192:195], v174 offset:19456
	ds_read_b128 v[196:199], v174 offset:20480
	ds_read_b128 v[210:213], v174 offset:21504
	ds_read_b128 v[214:217], v174 offset:22528
	ds_read_b128 v[218:221], v174 offset:23552
	global_load_lds_dwordx4 v[170:171], off
	s_add_i32 m0, s48, 0x2000
	s_add_u32 s84, s24, 0x20000
	v_lshl_add_u64 v[206:207], s[24:25], 0, v[136:137]
	s_addc_u32 s85, s25, 0
	s_add_i32 s48, s49, s61
	global_load_lds_dwordx4 v[206:207], off
	v_lshl_add_u64 v[208:209], s[84:85], 0, v[200:201]
	s_mov_b32 m0, s48
	v_lshl_add_u64 v[222:223], s[50:51], 0, v[138:139]
	global_load_lds_dwordx4 v[208:209], off
	v_lshl_add_u64 v[208:209], s[84:85], 0, v[136:137]
	s_add_i32 m0, s48, 0x2000
	s_nop 0
	global_load_lds_dwordx4 v[208:209], off
	v_lshl_add_u64 v[208:209], s[50:51], 0, v[140:141]
	s_mov_b32 m0, s62
	s_nop 0
	global_load_lds_dwordx4 v[208:209], off
	s_mov_b32 m0, s63
	s_nop 0
	global_load_lds_dwordx4 v[222:223], off
	s_waitcnt vmcnt(8)
	s_waitcnt lgkmcnt(0)
	s_setprio 1
	s_barrier
	v_mfma_f32_16x16x32_bf16 v[64:67], v[132:135], v[180:183], v[64:67]
	v_mfma_f32_16x16x32_bf16 v[60:63], v[150:153], v[180:183], v[60:63]
	v_mfma_f32_16x16x32_bf16 v[52:55], v[132:135], v[188:191], v[52:55]
	v_mfma_f32_16x16x32_bf16 v[44:47], v[150:153], v[188:191], v[44:47]
	v_mfma_f32_16x16x32_bf16 v[36:39], v[132:135], v[196:199], v[36:39]
	v_mfma_f32_16x16x32_bf16 v[28:31], v[150:153], v[196:199], v[28:31]
	v_mfma_f32_16x16x32_bf16 v[20:23], v[132:135], v[214:217], v[20:23]
	v_mfma_f32_16x16x32_bf16 v[12:15], v[150:153], v[214:217], v[12:15]
	v_mfma_f32_16x16x32_bf16 v[64:67], v[146:149], v[184:187], v[64:67]
	v_mfma_f32_16x16x32_bf16 v[60:63], v[154:157], v[184:187], v[60:63]
	v_mfma_f32_16x16x32_bf16 v[52:55], v[146:149], v[192:195], v[52:55]
	v_mfma_f32_16x16x32_bf16 v[44:47], v[154:157], v[192:195], v[44:47]
	v_mfma_f32_16x16x32_bf16 v[36:39], v[146:149], v[210:213], v[36:39]
	v_mfma_f32_16x16x32_bf16 v[28:31], v[154:157], v[210:213], v[28:31]
	v_mfma_f32_16x16x32_bf16 v[20:23], v[146:149], v[218:221], v[20:23]
	v_mfma_f32_16x16x32_bf16 v[12:15], v[154:157], v[218:221], v[12:15]
	s_setprio 0
	s_setprio 1
	v_mfma_f32_16x16x32_bf16 v[56:59], v[158:161], v[180:183], v[56:59]
	v_mfma_f32_16x16x32_bf16 v[48:51], v[166:169], v[180:183], v[48:51]
	v_mfma_f32_16x16x32_bf16 v[40:43], v[158:161], v[188:191], v[40:43]
	v_mfma_f32_16x16x32_bf16 v[32:35], v[166:169], v[188:191], v[32:35]
	v_mfma_f32_16x16x32_bf16 v[24:27], v[158:161], v[196:199], v[24:27]
	v_mfma_f32_16x16x32_bf16 v[16:19], v[166:169], v[196:199], v[16:19]
	v_mfma_f32_16x16x32_bf16 v[8:11], v[158:161], v[214:217], v[8:11]
	v_mfma_f32_16x16x32_bf16 v[4:7], v[166:169], v[214:217], v[4:7]
	v_mfma_f32_16x16x32_bf16 v[56:59], v[162:165], v[184:187], v[56:59]
	v_mfma_f32_16x16x32_bf16 v[48:51], v[176:179], v[184:187], v[48:51]
	v_mfma_f32_16x16x32_bf16 v[40:43], v[162:165], v[192:195], v[40:43]
	v_mfma_f32_16x16x32_bf16 v[32:35], v[176:179], v[192:195], v[32:35]
	v_mfma_f32_16x16x32_bf16 v[24:27], v[162:165], v[210:213], v[24:27]
	v_mfma_f32_16x16x32_bf16 v[16:19], v[176:179], v[210:213], v[16:19]
	v_mfma_f32_16x16x32_bf16 v[8:11], v[162:165], v[218:221], v[8:11]
	v_mfma_f32_16x16x32_bf16 v[4:7], v[176:179], v[218:221], v[4:7]
	s_barrier
; #define PG8_STAGE(bufoff, gbase, voff) do { _Pragma("unroll") for (int _i = 0; _i < 2; ++_i) \
;         __builtin_amdgcn_global_load_lds((const unsigned*)((const char*)(gbase) + (voff)[_i]), (PG8_LAS unsigned*)(lds + (bufoff) + ldsw + _i * 8192), 16, 0, 0); } while (0)
; #define PG8_LDA(dst, b, h) do { _Pragma("unroll") for (int m = 0; m < 4; ++m) _Pragma("unroll") for (int k = 0; k < 2; ++k) dst[m][k] = *(const PG8_LAS bf16x8*)(lds + PG8_SA(b, h) + aoff + m * 2048 + k * 1024); } while (0)
; #define PG8_LDB(dst, b, h) do { _Pragma("unroll") for (int n = 0; n < 2; ++n) _Pragma("unroll") for (int k = 0; k < 2; ++k) dst[n][k] = *(const PG8_LAS bf16x8*)(lds + PG8_SB(b, h) + boff + n * 2048 + k * 1024); } while (0)
; #define PG8_MMA(ai, bj, At, Bt) do { __builtin_amdgcn_s_setprio(1); _Pragma("unroll") for (int m = 0; m < 4; ++m) _Pragma("unroll") for (int n = 0; n < 2; ++n) _Pragma("unroll") for (int k = 0; k < 2; ++k) \
;         acc[ai][bj][m][n] = __builtin_amdgcn_mfma_f32_16x16x32_bf16(Bt[n][k], At[m][k], acc[ai][bj][m][n], 0, 0, 0); __builtin_amdgcn_s_setprio(0); } while (0)
; #define PG8_WAIT_V(n) asm volatile("s_waitcnt vmcnt(" #n ")" ::: "memory")
; #define PG8_WAIT_L(n) asm volatile("s_waitcnt lgkmcnt(" #n ")" ::: "memory")
; #define PG8_BAR __builtin_amdgcn_s_barrier()
; #define PG8_SCHED __builtin_amdgcn_sched_barrier(0)
;     ...
;             PG8_LDB(B0, 1, 0); PG8_LDB(B1, 1, 1); PG8_SCHED; PG8_LDA(At, 1, 0); PG8_STAGE(PG8_SA(0, 1), a2 + hstep, voffA);
;             PG8_WAIT_V(8); PG8_WAIT_L(0); PG8_BAR; PG8_MMA(0, 0, At, B0); PG8_MMA(0, 1, At, B1); PG8_BAR; PG8_SCHED;
;             PG8_LDA(At, 1, 1); PG8_STAGE(PG8_SB(1, 0), b3, voffB); PG8_STAGE(PG8_SB(1, 1), b3 + hstep, voffB); PG8_STAGE(PG8_SA(1, 0), a3, voffA);
;             PG8_WAIT_V(8); PG8_WAIT_L(0); PG8_BAR; PG8_MMA(1, 0, At, B0); PG8_MMA(1, 1, At, B1); PG8_BAR; PG8_SCHED;
	s_setprio 0
	s_add_i32 s48, 0, 0x18000
	s_add_i32 s49, 0, 0x1c000
	v_add_u32_e32 v154, s48, v173
	v_add_u32_e32 v175, s49, v173
	ds_read_b128 v[132:135], v154
	ds_read_b128 v[146:149], v154 offset:1024
	ds_read_b128 v[150:153], v154 offset:2048
	ds_read_b128 v[154:157], v154 offset:3072
	ds_read_b128 v[158:161], v175
	ds_read_b128 v[162:165], v175 offset:1024
	ds_read_b128 v[166:169], v175 offset:2048
	ds_read_b128 v[176:179], v175 offset:3072
	s_add_u32 s50, s50, 0x20000
	s_addc_u32 s51, s51, 0
	s_mov_b32 m0, s68
	v_lshl_add_u64 v[224:225], s[50:51], 0, v[140:141]
	ds_read_b128 v[180:183], v174 offset:32768
	ds_read_b128 v[184:187], v174 offset:33792
	ds_read_b128 v[188:191], v174 offset:34816
	ds_read_b128 v[192:195], v174 offset:35840
	ds_read_b128 v[196:199], v174 offset:36864
	ds_read_b128 v[210:213], v174 offset:37888
	ds_read_b128 v[214:217], v174 offset:38912
	ds_read_b128 v[218:221], v174 offset:39936
	global_load_lds_dwordx4 v[224:225], off
	v_lshl_add_u64 v[224:225], s[50:51], 0, v[138:139]
	s_mov_b32 m0, s69
	s_nop 0
	global_load_lds_dwordx4 v[224:225], off
	s_waitcnt vmcnt(8)
	s_waitcnt lgkmcnt(0)
	s_setprio 1
	s_barrier
	v_mfma_f32_16x16x32_bf16 v[128:131], v[132:135], v[180:183], v[128:131]
	v_mfma_f32_16x16x32_bf16 v[124:127], v[150:153], v[180:183], v[124:127]
	v_mfma_f32_16x16x32_bf16 v[116:119], v[132:135], v[188:191], v[116:119]
	v_mfma_f32_16x16x32_bf16 v[108:111], v[150:153], v[188:191], v[108:111]
	v_mfma_f32_16x16x32_bf16 v[100:103], v[132:135], v[196:199], v[100:103]
	v_mfma_f32_16x16x32_bf16 v[92:95], v[150:153], v[196:199], v[92:95]
	v_mfma_f32_16x16x32_bf16 v[84:87], v[132:135], v[214:217], v[84:87]
	v_mfma_f32_16x16x32_bf16 v[76:79], v[150:153], v[214:217], v[76:79]
	v_mfma_f32_16x16x32_bf16 v[128:131], v[146:149], v[184:187], v[128:131]
	v_mfma_f32_16x16x32_bf16 v[124:127], v[154:157], v[184:187], v[124:127]
	v_mfma_f32_16x16x32_bf16 v[116:119], v[146:149], v[192:195], v[116:119]
	v_mfma_f32_16x16x32_bf16 v[108:111], v[154:157], v[192:195], v[108:111]
	v_mfma_f32_16x16x32_bf16 v[100:103], v[146:149], v[210:213], v[100:103]
	v_mfma_f32_16x16x32_bf16 v[92:95], v[154:157], v[210:213], v[92:95]
	v_mfma_f32_16x16x32_bf16 v[84:87], v[146:149], v[218:221], v[84:87]
	v_mfma_f32_16x16x32_bf16 v[76:79], v[154:157], v[218:221], v[76:79]
	s_setprio 0
	s_setprio 1
	v_mfma_f32_16x16x32_bf16 v[120:123], v[158:161], v[180:183], v[120:123]
	v_mfma_f32_16x16x32_bf16 v[112:115], v[166:169], v[180:183], v[112:115]
	v_mfma_f32_16x16x32_bf16 v[104:107], v[158:161], v[188:191], v[104:107]
	v_mfma_f32_16x16x32_bf16 v[96:99], v[166:169], v[188:191], v[96:99]
	v_mfma_f32_16x16x32_bf16 v[88:91], v[158:161], v[196:199], v[88:91]
	v_mfma_f32_16x16x32_bf16 v[80:83], v[166:169], v[196:199], v[80:83]
	v_mfma_f32_16x16x32_bf16 v[72:75], v[158:161], v[214:217], v[72:75]
	v_mfma_f32_16x16x32_bf16 v[68:71], v[166:169], v[214:217], v[68:71]
	v_mfma_f32_16x16x32_bf16 v[120:123], v[162:165], v[184:187], v[120:123]
	v_mfma_f32_16x16x32_bf16 v[112:115], v[176:179], v[184:187], v[112:115]
	v_mfma_f32_16x16x32_bf16 v[104:107], v[162:165], v[192:195], v[104:107]
	v_mfma_f32_16x16x32_bf16 v[96:99], v[176:179], v[192:195], v[96:99]
	v_mfma_f32_16x16x32_bf16 v[88:91], v[162:165], v[210:213], v[88:91]
	v_mfma_f32_16x16x32_bf16 v[80:83], v[176:179], v[210:213], v[80:83]
	v_mfma_f32_16x16x32_bf16 v[72:75], v[162:165], v[218:221], v[72:75]
	v_mfma_f32_16x16x32_bf16 v[68:71], v[176:179], v[218:221], v[68:71]
	s_barrier
	s_setprio 0
	s_add_i32 s48, s48, s61
	v_lshl_add_u64 v[170:171], v[170:171], 0, s[66:67]
	s_mov_b32 m0, s48
	ds_read_b128 v[180:183], v174 offset:49152
	ds_read_b128 v[184:187], v174 offset:50176
	ds_read_b128 v[188:191], v174 offset:51200
	ds_read_b128 v[192:195], v174 offset:52224
	ds_read_b128 v[196:199], v174 offset:53248
	ds_read_b128 v[210:213], v174 offset:54272
	ds_read_b128 v[214:217], v174 offset:55296
	ds_read_b128 v[218:221], v174 offset:56320
	global_load_lds_dwordx4 v[170:171], off
	s_add_i32 m0, s48, 0x2000
	s_add_u32 s24, s24, 0x20080
	v_lshl_add_u64 v[170:171], v[206:207], 0, s[66:67]
	s_addc_u32 s25, s25, 0
	s_add_i32 s48, s49, s61
	global_load_lds_dwordx4 v[170:171], off
	v_lshl_add_u64 v[170:171], s[24:25], 0, v[200:201]
	s_mov_b32 m0, s48
	s_nop 0
	global_load_lds_dwordx4 v[170:171], off
	v_lshl_add_u64 v[170:171], s[24:25], 0, v[136:137]
	s_add_i32 m0, s48, 0x2000
	s_nop 0
	global_load_lds_dwordx4 v[170:171], off
	v_lshl_add_u64 v[170:171], v[208:209], 0, s[66:67]
	s_mov_b32 m0, s71
	s_nop 0
	global_load_lds_dwordx4 v[170:171], off
	v_lshl_add_u64 v[170:171], v[222:223], 0, s[66:67]
	s_mov_b32 m0, s73
	s_nop 0
	global_load_lds_dwordx4 v[170:171], off
	s_waitcnt vmcnt(8)
	s_waitcnt lgkmcnt(0)
	s_setprio 1
	s_barrier
; #define PG8_G __attribute__((address_space(1)))
; __device__ __forceinline__ u32x4 pack8bf(const f32x4 a, const f32x4 b) { u32x4 w; w.x = cvt_pk_bf16(a[0], a[1]); w.y = cvt_pk_bf16(a[2], a[3]); w.z = cvt_pk_bf16(b[0], b[1]); w.w = cvt_pk_bf16(b[2], b[3]); return w; }
; #define PG8_MMA(ai, bj, At, Bt) do { __builtin_amdgcn_s_setprio(1); _Pragma("unroll") for (int m = 0; m < 4; ++m) _Pragma("unroll") for (int n = 0; n < 2; ++n) _Pragma("unroll") for (int k = 0; k < 2; ++k) \
;         acc[ai][bj][m][n] = __builtin_amdgcn_mfma_f32_16x16x32_bf16(Bt[n][k], At[m][k], acc[ai][bj][m][n], 0, 0, 0); __builtin_amdgcn_s_setprio(0); } while (0)
; #define PG8_WAIT_V(n) asm volatile("s_waitcnt vmcnt(" #n ")" ::: "memory")
; #define PG8_WAIT_L(n) asm volatile("s_waitcnt lgkmcnt(" #n ")" ::: "memory")
;     __device__ __forceinline__ void operator()(const f32x4 (&acc)[2][2][4][2], const Unit& u, int wr, int wc, int fr_, int fq_, int ui) const {
;     ...
;         const int row0 = u.pm * BM + wr * 64 + fr;
;         float r[2][4]; load_rs(r, rsl, wr, fr);
;         if (u.pn < 8) {
;             const int col0 = u.pn * BM + wc * 32 + 8 * fq;
; #pragma unroll
;             for (int ai = 0; ai < 2; ++ai)
; #pragma unroll
;                 for (int m = 0; m < 4; ++m) { bf16_t* rowp = Q + (size_t)(row0 + ai * HALF + m * 16) * 3072 + col0;
; #pragma unroll
;                     for (int bj = 0; bj < 2; ++bj) *(PG8_G u32x4*)(rowp + bj * HALF) = pack8bf(acc[ai][bj][m][0] * r[ai][m], acc[ai][bj][m][1] * r[ai][m]); }
;         } else {
;             const int head = 4 * (u.pn - 8) + wc, i0 = 8 * fq;
; #pragma unroll
;             for (int ai = 0; ai < 2; ++ai)
; #pragma unroll
;                 for (int m = 0; m < 4; ++m) { const int row = row0 + ai * HALF + m * 16;
;                     const f32x4 c0 = *(const PG8_G f32x4*)(cosT + (size_t)row * 32 + i0), c1 = *(const PG8_G f32x4*)(cosT + (size_t)row * 32 + i0 + 4);
;                     const f32x4 s0 = *(const PG8_G f32x4*)(sinT + (size_t)row * 32 + i0), s1 = *(const PG8_G f32x4*)(sinT + (size_t)row * 32 + i0 + 4);
;                     const f32x4 x1a = acc[ai][0][m][0] * r[ai][m], x1b = acc[ai][0][m][1] * r[ai][m], x2a = acc[ai][1][m][0] * r[ai][m], x2b = acc[ai][1][m][1] * r[ai][m];
;     ...
;             PG8_WAIT_V(8); PG8_WAIT_L(0); PG8_BAR; PG8_MMA(1, 0, At, B0); PG8_MMA(1, 1, At, B1); PG8_BAR; PG8_SCHED;
	v_mfma_f32_16x16x32_bf16 v[64:67], v[132:135], v[180:183], v[64:67]
	v_mfma_f32_16x16x32_bf16 v[60:63], v[150:153], v[180:183], v[60:63]
	v_mfma_f32_16x16x32_bf16 v[52:55], v[132:135], v[188:191], v[52:55]
	v_mfma_f32_16x16x32_bf16 v[44:47], v[150:153], v[188:191], v[44:47]
	v_mfma_f32_16x16x32_bf16 v[36:39], v[132:135], v[196:199], v[36:39]
	v_mfma_f32_16x16x32_bf16 v[28:31], v[150:153], v[196:199], v[28:31]
	v_mfma_f32_16x16x32_bf16 v[20:23], v[132:135], v[214:217], v[20:23]
	v_mfma_f32_16x16x32_bf16 v[12:15], v[150:153], v[214:217], v[12:15]
	v_mfma_f32_16x16x32_bf16 v[64:67], v[146:149], v[184:187], v[64:67]
	v_mfma_f32_16x16x32_bf16 v[60:63], v[154:157], v[184:187], v[60:63]
	v_mfma_f32_16x16x32_bf16 v[52:55], v[146:149], v[192:195], v[52:55]
	v_mfma_f32_16x16x32_bf16 v[44:47], v[154:157], v[192:195], v[44:47]
	v_mfma_f32_16x16x32_bf16 v[36:39], v[146:149], v[210:213], v[36:39]
	v_mfma_f32_16x16x32_bf16 v[28:31], v[154:157], v[210:213], v[28:31]
	v_mfma_f32_16x16x32_bf16 v[20:23], v[146:149], v[218:221], v[20:23]
	v_mfma_f32_16x16x32_bf16 v[12:15], v[154:157], v[218:221], v[12:15]
	s_setprio 0
	s_setprio 1
	v_mfma_f32_16x16x32_bf16 v[56:59], v[158:161], v[180:183], v[56:59]
	v_mfma_f32_16x16x32_bf16 v[48:51], v[166:169], v[180:183], v[48:51]
	v_mfma_f32_16x16x32_bf16 v[40:43], v[158:161], v[188:191], v[40:43]
	v_mfma_f32_16x16x32_bf16 v[32:35], v[166:169], v[188:191], v[32:35]
	v_mfma_f32_16x16x32_bf16 v[24:27], v[158:161], v[196:199], v[24:27]
	v_mfma_f32_16x16x32_bf16 v[16:19], v[166:169], v[196:199], v[16:19]
	v_mfma_f32_16x16x32_bf16 v[8:11], v[158:161], v[214:217], v[8:11]
	v_mfma_f32_16x16x32_bf16 v[4:7], v[166:169], v[214:217], v[4:7]
	v_mfma_f32_16x16x32_bf16 v[56:59], v[162:165], v[184:187], v[56:59]
	v_mfma_f32_16x16x32_bf16 v[48:51], v[176:179], v[184:187], v[48:51]
	v_mfma_f32_16x16x32_bf16 v[40:43], v[162:165], v[192:195], v[40:43]
	v_mfma_f32_16x16x32_bf16 v[32:35], v[176:179], v[192:195], v[32:35]
	v_mfma_f32_16x16x32_bf16 v[24:27], v[162:165], v[210:213], v[24:27]
	v_mfma_f32_16x16x32_bf16 v[16:19], v[176:179], v[210:213], v[16:19]
	v_mfma_f32_16x16x32_bf16 v[8:11], v[162:165], v[218:221], v[8:11]
	v_mfma_f32_16x16x32_bf16 v[4:7], v[176:179], v[218:221], v[4:7]
	s_barrier
	s_setprio 0
	s_add_i32 s54, s54, 2
	s_add_u32 s52, s52, 0x100
	s_addc_u32 s53, s53, 0
	s_add_u32 s14, s14, 0x100
	s_addc_u32 s15, s15, 0
	s_cmp_gt_u32 s54, 5
	s_cbranch_scc0 .LBB0_301
	v_mov_b32_e32 v132, v3
	v_mov_b32_e32 v133, v172
	v_readlane_b32 s14, v254, 30
	v_add_u32_e32 v146, s1, v132
	v_lshl_add_u32 v132, v132, 2, s78
	ds_read2_b32 v[164:165], v132 offset1:16
	ds_read2_b32 v[158:159], v132 offset0:32 offset1:48
	ds_read2_b32 v[152:153], v132 offset0:128 offset1:144
	ds_read2_b32 v[148:149], v132 offset0:160 offset1:176
	s_add_i32 s14, s20, s14
	s_lshl_b32 s20, s14, 8
	s_cmp_gt_u32 s14, 7
	v_lshlrev_b32_e32 v168, 3, v133
	v_ashrrev_i32_e32 v147, 31, v146
	s_mov_b64 s[14:15], -1
	v_add_u32_e32 v166, 16, v146
	v_add_u32_e32 v162, 32, v146
	v_add_u32_e32 v160, 48, v146
	v_add_u32_e32 v156, 0x80, v146
	v_add_u32_e32 v154, 0x90, v146
	v_add_u32_e32 v150, 0xa0, v146
	s_cbranch_scc0 .LBB0_304
	v_ashrrev_i32_e32 v169, 31, v168
	v_lshlrev_b64 v[180:181], 7, v[146:147]
	v_lshl_add_u64 v[132:133], s[38:39], 0, v[180:181]
	v_lshlrev_b64 v[170:171], 2, v[168:169]
	v_lshl_add_u64 v[180:181], s[40:41], 0, v[180:181]
	v_lshl_add_u64 v[176:177], v[132:133], 0, v[170:171]
	v_lshl_add_u64 v[184:185], v[180:181], 0, v[170:171]
	global_load_dwordx4 v[132:135], v[176:177], off offset:16
	s_nop 0
	global_load_dwordx4 v[176:179], v[176:177], off
	s_nop 0
	global_load_dwordx4 v[180:183], v[184:185], off offset:16
	s_nop 0
	global_load_dwordx4 v[184:187], v[184:185], off
	s_waitcnt lgkmcnt(0)
	v_pk_mul_f32 v[188:189], v[130:131], v[164:165] op_sel_hi:[1,0]
	v_pk_mul_f32 v[196:197], v[122:123], v[164:165] op_sel_hi:[1,0]
	v_pk_mul_f32 v[190:191], v[128:129], v[164:165] op_sel_hi:[1,0]
	v_pk_mul_f32 v[194:195], v[124:125], v[164:165] op_sel_hi:[1,0]
	v_pk_mul_f32 v[198:199], v[120:121], v[164:165] op_sel_hi:[1,0]
	v_pk_mul_f32 v[208:209], v[112:113], v[164:165] op_sel_hi:[1,0]
	v_pk_mul_f32 v[192:193], v[126:127], v[164:165] op_sel_hi:[1,0]
	v_pk_mul_f32 v[206:207], v[114:115], v[164:165] op_sel_hi:[1,0]
	s_add_i32 s44, s0, s20
	s_mov_b64 s[48:49], 0x1000
	v_ashrrev_i32_e32 v167, 31, v166
	v_ashrrev_i32_e32 v163, 31, v162
	v_ashrrev_i32_e32 v161, 31, v160
	v_ashrrev_i32_e32 v157, 31, v156
	v_ashrrev_i32_e32 v155, 31, v154
	v_ashrrev_i32_e32 v151, 31, v150
	s_waitcnt vmcnt(0)
; #define PG8_G __attribute__((address_space(1)))
; __device__ __forceinline__ u32x4 pack8bf(const f32x4 a, const f32x4 b) { u32x4 w; w.x = cvt_pk_bf16(a[0], a[1]); w.y = cvt_pk_bf16(a[2], a[3]); w.z = cvt_pk_bf16(b[0], b[1]); w.w = cvt_pk_bf16(b[2], b[3]); return w; }
;     __device__ __forceinline__ void operator()(const f32x4 (&acc)[2][2][4][2], const Unit& u, int wr, int wc, int fr_, int fq_, int ui) const {
;     ...
;                 for (int m = 0; m < 4; ++m) { const int row = row0 + ai * HALF + m * 16;
;                     const f32x4 c0 = *(const PG8_G f32x4*)(cosT + (size_t)row * 32 + i0), c1 = *(const PG8_G f32x4*)(cosT + (size_t)row * 32 + i0 + 4);
;                     const f32x4 s0 = *(const PG8_G f32x4*)(sinT + (size_t)row * 32 + i0), s1 = *(const PG8_G f32x4*)(sinT + (size_t)row * 32 + i0 + 4);
;                     const f32x4 x1a = acc[ai][0][m][0] * r[ai][m], x1b = acc[ai][0][m][1] * r[ai][m], x2a = acc[ai][1][m][0] * r[ai][m], x2b = acc[ai][1][m][1] * r[ai][m];
;                     const f32x4 y1a = x1a * c0 - x2a * s0, y1b = x1b * c1 - x2b * s1, y2a = x2a * c0 + x1a * s0, y2b = x2b * c1 + x1b * s1;
;                     bf16_t* dst = Q + (size_t)row * 3072 + 2048 + head * 64 + i0;
;                     *(PG8_G u32x4*)dst = pack8bf(y1a, y1b); *(PG8_G u32x4*)(dst + 32) = pack8bf(y2a, y2b); }
	v_pk_mul_f32 v[216:217], v[208:209], v[180:181]
	v_pk_mul_f32 v[210:211], v[196:197], v[186:187]
	v_pk_mul_f32 v[186:187], v[188:189], v[186:187]
	v_pk_mul_f32 v[212:213], v[198:199], v[184:185]
	v_pk_fma_f32 v[210:211], v[188:189], v[178:179], v[210:211] neg_lo:[0,0,1] neg_hi:[0,0,1]
	v_pk_mul_f32 v[184:185], v[190:191], v[184:185]
	v_pk_fma_f32 v[186:187], v[196:197], v[178:179], v[186:187]
	v_pk_mul_f32 v[178:179], v[194:195], v[180:181]
	v_pk_fma_f32 v[212:213], v[190:191], v[176:177], v[212:213] neg_lo:[0,0,1] neg_hi:[0,0,1]
	v_pk_mul_f32 v[214:215], v[206:207], v[182:183]
	v_pk_fma_f32 v[216:217], v[194:195], v[132:133], v[216:217] neg_lo:[0,0,1] neg_hi:[0,0,1]
	v_pk_fma_f32 v[184:185], v[198:199], v[176:177], v[184:185]
	v_pk_mul_f32 v[176:177], v[192:193], v[182:183]
	v_pk_fma_f32 v[182:183], v[208:209], v[132:133], v[178:179]
	v_mov_b64_e32 v[132:133], s[10:11]
	v_pk_fma_f32 v[214:215], v[192:193], v[134:135], v[214:215] neg_lo:[0,0,1] neg_hi:[0,0,1]
	v_pk_fma_f32 v[180:181], v[206:207], v[134:135], v[176:177]
	v_mad_i64_i32 v[134:135], s[14:15], v146, s26, v[132:133]
	s_lshl_b64 s[14:15], s[44:45], 1
	s_nop 0
	v_lshl_add_u64 v[176:177], v[134:135], 0, s[14:15]
	v_lshlrev_b64 v[134:135], 1, v[168:169]
	v_lshl_add_u64 v[188:189], v[176:177], 0, v[134:135]
	v_lshl_add_u64 v[190:191], v[188:189], 0, s[48:49]
	v_add_co_u32_e32 v188, vcc, s27, v188
	v_cvt_pk_bf16_f32 v176, v212, v213
	v_cvt_pk_bf16_f32 v177, v210, v211
	v_cvt_pk_bf16_f32 v178, v216, v217
	v_cvt_pk_bf16_f32 v179, v214, v215
	s_nop 1
	v_addc_co_u32_e32 v189, vcc, 0, v189, vcc
	global_store_dwordx4 v[188:189], v[176:179], off
	v_mov_b32_e32 v192, v165
	v_pk_mul_f32 v[194:195], v[118:119], v[192:193] op_sel_hi:[1,0]
	v_cvt_pk_bf16_f32 v176, v184, v185
	v_cvt_pk_bf16_f32 v177, v186, v187
	v_lshlrev_b64 v[184:185], 7, v[166:167]
	v_cvt_pk_bf16_f32 v178, v182, v183
	v_cvt_pk_bf16_f32 v179, v180, v181
	global_store_dwordx4 v[190:191], v[176:179], off offset:64
	v_pk_mul_f32 v[196:197], v[116:117], v[192:193] op_sel_hi:[1,0]
	v_pk_mul_f32 v[198:199], v[110:111], v[192:193] op_sel_hi:[1,0]
	v_lshl_add_u64 v[176:177], s[38:39], 0, v[184:185]
	v_lshl_add_u64 v[184:185], s[40:41], 0, v[184:185]
	v_lshl_add_u64 v[180:181], v[176:177], 0, v[170:171]
	v_lshl_add_u64 v[188:189], v[184:185], 0, v[170:171]
	global_load_dwordx4 v[176:179], v[180:181], off offset:16
	s_nop 0
	global_load_dwordx4 v[180:183], v[180:181], off
	s_nop 0
	global_load_dwordx4 v[184:187], v[188:189], off offset:16
	s_nop 0
	global_load_dwordx4 v[188:191], v[188:189], off
	v_pk_mul_f32 v[206:207], v[108:109], v[192:193] op_sel_hi:[1,0]
	v_pk_mul_f32 v[208:209], v[106:107], v[192:193] op_sel_hi:[1,0]
	v_pk_mul_f32 v[210:211], v[104:105], v[192:193] op_sel_hi:[1,0]
	v_pk_mul_f32 v[212:213], v[98:99], v[192:193] op_sel_hi:[1,0]
	v_pk_mul_f32 v[192:193], v[96:97], v[192:193] op_sel_hi:[1,0]
	s_waitcnt vmcnt(1)
	v_pk_mul_f32 v[218:219], v[212:213], v[186:187]
	v_pk_mul_f32 v[220:221], v[192:193], v[184:185]
	v_pk_mul_f32 v[184:185], v[206:207], v[184:185]
	v_pk_fma_f32 v[220:221], v[206:207], v[176:177], v[220:221] neg_lo:[0,0,1] neg_hi:[0,0,1]
	v_pk_fma_f32 v[184:185], v[192:193], v[176:177], v[184:185]
	v_mad_i64_i32 v[176:177], s[24:25], v166, s26, v[132:133]
	s_waitcnt vmcnt(0)
	v_pk_mul_f32 v[216:217], v[210:211], v[188:189]
	v_pk_mul_f32 v[188:189], v[196:197], v[188:189]
	v_lshl_add_u64 v[176:177], v[176:177], 0, s[14:15]
	v_pk_mul_f32 v[214:215], v[208:209], v[190:191]
	v_pk_fma_f32 v[216:217], v[196:197], v[180:181], v[216:217] neg_lo:[0,0,1] neg_hi:[0,0,1]
	v_pk_mul_f32 v[190:191], v[194:195], v[190:191]
	v_pk_fma_f32 v[180:181], v[210:211], v[180:181], v[188:189]
	v_lshl_add_u64 v[188:189], v[176:177], 0, v[134:135]
	v_pk_fma_f32 v[214:215], v[194:195], v[182:183], v[214:215] neg_lo:[0,0,1] neg_hi:[0,0,1]
	v_pk_fma_f32 v[182:183], v[208:209], v[182:183], v[190:191]
	v_pk_mul_f32 v[186:187], v[198:199], v[186:187]
	v_lshl_add_u64 v[190:191], v[188:189], 0, s[48:49]
	v_add_co_u32_e32 v188, vcc, s27, v188
	v_pk_fma_f32 v[218:219], v[198:199], v[178:179], v[218:219] neg_lo:[0,0,1] neg_hi:[0,0,1]
	v_pk_fma_f32 v[186:187], v[212:213], v[178:179], v[186:187]
	v_cvt_pk_bf16_f32 v176, v216, v217
	v_cvt_pk_bf16_f32 v177, v214, v215
	v_cvt_pk_bf16_f32 v178, v220, v221
	v_addc_co_u32_e32 v189, vcc, 0, v189, vcc
	v_cvt_pk_bf16_f32 v179, v218, v219
	global_store_dwordx4 v[188:189], v[176:179], off
	v_pk_mul_f32 v[198:199], v[92:93], v[158:159] op_sel_hi:[1,0]
	v_pk_mul_f32 v[212:213], v[80:81], v[158:159] op_sel_hi:[1,0]
	v_cvt_pk_bf16_f32 v176, v180, v181
	v_cvt_pk_bf16_f32 v177, v182, v183
	v_cvt_pk_bf16_f32 v178, v184, v185
	v_lshlrev_b64 v[184:185], 7, v[162:163]
	v_cvt_pk_bf16_f32 v179, v186, v187
	global_store_dwordx4 v[190:191], v[176:179], off offset:64
	v_pk_mul_f32 v[194:195], v[100:101], v[158:159] op_sel_hi:[1,0]
	v_pk_mul_f32 v[208:209], v[88:89], v[158:159] op_sel_hi:[1,0]
	v_lshl_add_u64 v[176:177], s[38:39], 0, v[184:185]
	v_lshl_add_u64 v[184:185], s[40:41], 0, v[184:185]
	v_lshl_add_u64 v[180:181], v[176:177], 0, v[170:171]
	v_lshl_add_u64 v[188:189], v[184:185], 0, v[170:171]
	global_load_dwordx4 v[176:179], v[180:181], off offset:16
	s_nop 0
	global_load_dwordx4 v[180:183], v[180:181], off
	s_nop 0
	global_load_dwordx4 v[184:187], v[188:189], off offset:16
	s_nop 0
	global_load_dwordx4 v[188:191], v[188:189], off
	v_pk_mul_f32 v[192:193], v[102:103], v[158:159] op_sel_hi:[1,0]
	v_pk_mul_f32 v[206:207], v[90:91], v[158:159] op_sel_hi:[1,0]
	v_pk_mul_f32 v[196:197], v[94:95], v[158:159] op_sel_hi:[1,0]
	v_pk_mul_f32 v[210:211], v[82:83], v[158:159] op_sel_hi:[1,0]
	s_waitcnt vmcnt(1)
; #define PG8_G __attribute__((address_space(1)))
; __device__ __forceinline__ u32x4 pack8bf(const f32x4 a, const f32x4 b) { u32x4 w; w.x = cvt_pk_bf16(a[0], a[1]); w.y = cvt_pk_bf16(a[2], a[3]); w.z = cvt_pk_bf16(b[0], b[1]); w.w = cvt_pk_bf16(b[2], b[3]); return w; }
;     __device__ __forceinline__ void operator()(const f32x4 (&acc)[2][2][4][2], const Unit& u, int wr, int wc, int fr_, int fq_, int ui) const {
;     ...
;                 for (int m = 0; m < 4; ++m) { const int row = row0 + ai * HALF + m * 16;
;                     const f32x4 c0 = *(const PG8_G f32x4*)(cosT + (size_t)row * 32 + i0), c1 = *(const PG8_G f32x4*)(cosT + (size_t)row * 32 + i0 + 4);
;                     const f32x4 s0 = *(const PG8_G f32x4*)(sinT + (size_t)row * 32 + i0), s1 = *(const PG8_G f32x4*)(sinT + (size_t)row * 32 + i0 + 4);
;                     const f32x4 x1a = acc[ai][0][m][0] * r[ai][m], x1b = acc[ai][0][m][1] * r[ai][m], x2a = acc[ai][1][m][0] * r[ai][m], x2b = acc[ai][1][m][1] * r[ai][m];
;                     const f32x4 y1a = x1a * c0 - x2a * s0, y1b = x1b * c1 - x2b * s1, y2a = x2a * c0 + x1a * s0, y2b = x2b * c1 + x1b * s1;
;                     bf16_t* dst = Q + (size_t)row * 3072 + 2048 + head * 64 + i0;
;                     *(PG8_G u32x4*)dst = pack8bf(y1a, y1b); *(PG8_G u32x4*)(dst + 32) = pack8bf(y2a, y2b); }
	v_pk_mul_f32 v[220:221], v[212:213], v[184:185]
	v_pk_mul_f32 v[184:185], v[198:199], v[184:185]
	v_pk_fma_f32 v[220:221], v[198:199], v[176:177], v[220:221] neg_lo:[0,0,1] neg_hi:[0,0,1]
	v_pk_fma_f32 v[184:185], v[212:213], v[176:177], v[184:185]
	v_mad_i64_i32 v[176:177], s[24:25], v162, s26, v[132:133]
	s_waitcnt vmcnt(0)
	v_pk_mul_f32 v[216:217], v[208:209], v[188:189]
	v_pk_mul_f32 v[188:189], v[194:195], v[188:189]
	v_lshl_add_u64 v[176:177], v[176:177], 0, s[14:15]
	v_pk_mul_f32 v[214:215], v[206:207], v[190:191]
	v_pk_fma_f32 v[216:217], v[194:195], v[180:181], v[216:217] neg_lo:[0,0,1] neg_hi:[0,0,1]
	v_pk_mul_f32 v[190:191], v[192:193], v[190:191]
	v_pk_fma_f32 v[180:181], v[208:209], v[180:181], v[188:189]
	v_lshl_add_u64 v[188:189], v[176:177], 0, v[134:135]
	v_pk_fma_f32 v[214:215], v[192:193], v[182:183], v[214:215] neg_lo:[0,0,1] neg_hi:[0,0,1]
	v_pk_mul_f32 v[218:219], v[210:211], v[186:187]
	v_pk_fma_f32 v[182:183], v[206:207], v[182:183], v[190:191]
	v_pk_mul_f32 v[186:187], v[196:197], v[186:187]
	v_lshl_add_u64 v[190:191], v[188:189], 0, s[48:49]
	v_add_co_u32_e32 v188, vcc, s27, v188
	v_pk_fma_f32 v[218:219], v[196:197], v[178:179], v[218:219] neg_lo:[0,0,1] neg_hi:[0,0,1]
	v_pk_fma_f32 v[186:187], v[210:211], v[178:179], v[186:187]
	v_cvt_pk_bf16_f32 v176, v216, v217
	v_cvt_pk_bf16_f32 v177, v214, v215
	v_cvt_pk_bf16_f32 v178, v220, v221
	v_addc_co_u32_e32 v189, vcc, 0, v189, vcc
	v_cvt_pk_bf16_f32 v179, v218, v219
	global_store_dwordx4 v[188:189], v[176:179], off
	v_mov_b32_e32 v192, v159
	v_pk_mul_f32 v[194:195], v[86:87], v[192:193] op_sel_hi:[1,0]
	v_cvt_pk_bf16_f32 v176, v180, v181
	v_cvt_pk_bf16_f32 v177, v182, v183
	v_cvt_pk_bf16_f32 v178, v184, v185
	v_lshlrev_b64 v[184:185], 7, v[160:161]
	v_cvt_pk_bf16_f32 v179, v186, v187
	global_store_dwordx4 v[190:191], v[176:179], off offset:64
	v_pk_mul_f32 v[196:197], v[84:85], v[192:193] op_sel_hi:[1,0]
	v_pk_mul_f32 v[198:199], v[78:79], v[192:193] op_sel_hi:[1,0]
	v_lshl_add_u64 v[176:177], s[38:39], 0, v[184:185]
	v_lshl_add_u64 v[184:185], s[40:41], 0, v[184:185]
	v_lshl_add_u64 v[180:181], v[176:177], 0, v[170:171]
	v_lshl_add_u64 v[188:189], v[184:185], 0, v[170:171]
	global_load_dwordx4 v[176:179], v[180:181], off offset:16
	s_nop 0
	global_load_dwordx4 v[180:183], v[180:181], off
	s_nop 0
	global_load_dwordx4 v[184:187], v[188:189], off offset:16
	s_nop 0
	global_load_dwordx4 v[188:191], v[188:189], off
	v_pk_mul_f32 v[206:207], v[76:77], v[192:193] op_sel_hi:[1,0]
	v_pk_mul_f32 v[208:209], v[74:75], v[192:193] op_sel_hi:[1,0]
	v_pk_mul_f32 v[210:211], v[72:73], v[192:193] op_sel_hi:[1,0]
	v_pk_mul_f32 v[212:213], v[70:71], v[192:193] op_sel_hi:[1,0]
	v_pk_mul_f32 v[192:193], v[68:69], v[192:193] op_sel_hi:[1,0]
	s_waitcnt vmcnt(1)
	v_pk_mul_f32 v[218:219], v[212:213], v[186:187]
	v_pk_mul_f32 v[220:221], v[192:193], v[184:185]
	v_pk_mul_f32 v[184:185], v[206:207], v[184:185]
	v_pk_fma_f32 v[220:221], v[206:207], v[176:177], v[220:221] neg_lo:[0,0,1] neg_hi:[0,0,1]
	v_pk_fma_f32 v[184:185], v[192:193], v[176:177], v[184:185]
	v_mad_i64_i32 v[176:177], s[24:25], v160, s26, v[132:133]
	s_waitcnt vmcnt(0)
	v_pk_mul_f32 v[216:217], v[210:211], v[188:189]
	v_pk_mul_f32 v[188:189], v[196:197], v[188:189]
	v_lshl_add_u64 v[176:177], v[176:177], 0, s[14:15]
	v_pk_mul_f32 v[214:215], v[208:209], v[190:191]
	v_pk_fma_f32 v[216:217], v[196:197], v[180:181], v[216:217] neg_lo:[0,0,1] neg_hi:[0,0,1]
	v_pk_mul_f32 v[190:191], v[194:195], v[190:191]
	v_pk_fma_f32 v[180:181], v[210:211], v[180:181], v[188:189]
	v_lshl_add_u64 v[188:189], v[176:177], 0, v[134:135]
	v_pk_fma_f32 v[214:215], v[194:195], v[182:183], v[214:215] neg_lo:[0,0,1] neg_hi:[0,0,1]
	v_pk_fma_f32 v[182:183], v[208:209], v[182:183], v[190:191]
	v_pk_mul_f32 v[186:187], v[198:199], v[186:187]
	v_lshl_add_u64 v[190:191], v[188:189], 0, s[48:49]
	v_add_co_u32_e32 v188, vcc, s27, v188
	v_pk_fma_f32 v[218:219], v[198:199], v[178:179], v[218:219] neg_lo:[0,0,1] neg_hi:[0,0,1]
	v_pk_fma_f32 v[186:187], v[212:213], v[178:179], v[186:187]
	v_cvt_pk_bf16_f32 v176, v216, v217
	v_cvt_pk_bf16_f32 v177, v214, v215
	v_cvt_pk_bf16_f32 v178, v220, v221
	v_addc_co_u32_e32 v189, vcc, 0, v189, vcc
	v_cvt_pk_bf16_f32 v179, v218, v219
	global_store_dwordx4 v[188:189], v[176:179], off
	v_pk_mul_f32 v[198:199], v[60:61], v[152:153] op_sel_hi:[1,0]
	v_pk_mul_f32 v[212:213], v[48:49], v[152:153] op_sel_hi:[1,0]
	v_cvt_pk_bf16_f32 v176, v180, v181
	v_cvt_pk_bf16_f32 v177, v182, v183
	v_cvt_pk_bf16_f32 v178, v184, v185
	v_lshlrev_b64 v[184:185], 7, v[156:157]
	v_cvt_pk_bf16_f32 v179, v186, v187
	global_store_dwordx4 v[190:191], v[176:179], off offset:64
	v_pk_mul_f32 v[194:195], v[64:65], v[152:153] op_sel_hi:[1,0]
	v_pk_mul_f32 v[208:209], v[56:57], v[152:153] op_sel_hi:[1,0]
	v_lshl_add_u64 v[176:177], s[38:39], 0, v[184:185]
	v_lshl_add_u64 v[184:185], s[40:41], 0, v[184:185]
	v_lshl_add_u64 v[180:181], v[176:177], 0, v[170:171]
	v_lshl_add_u64 v[188:189], v[184:185], 0, v[170:171]
	global_load_dwordx4 v[176:179], v[180:181], off offset:16
	s_nop 0
	global_load_dwordx4 v[180:183], v[180:181], off
	s_nop 0
	global_load_dwordx4 v[184:187], v[188:189], off offset:16
	s_nop 0
	global_load_dwordx4 v[188:191], v[188:189], off
	v_pk_mul_f32 v[192:193], v[66:67], v[152:153] op_sel_hi:[1,0]
	v_pk_mul_f32 v[206:207], v[58:59], v[152:153] op_sel_hi:[1,0]
	v_pk_mul_f32 v[196:197], v[62:63], v[152:153] op_sel_hi:[1,0]
	v_pk_mul_f32 v[210:211], v[50:51], v[152:153] op_sel_hi:[1,0]
	s_waitcnt vmcnt(1)
; #define PG8_G __attribute__((address_space(1)))
; __device__ __forceinline__ u32x4 pack8bf(const f32x4 a, const f32x4 b) { u32x4 w; w.x = cvt_pk_bf16(a[0], a[1]); w.y = cvt_pk_bf16(a[2], a[3]); w.z = cvt_pk_bf16(b[0], b[1]); w.w = cvt_pk_bf16(b[2], b[3]); return w; }
;     __device__ __forceinline__ void operator()(const f32x4 (&acc)[2][2][4][2], const Unit& u, int wr, int wc, int fr_, int fq_, int ui) const {
;     ...
;                 for (int m = 0; m < 4; ++m) { const int row = row0 + ai * HALF + m * 16;
;                     const f32x4 c0 = *(const PG8_G f32x4*)(cosT + (size_t)row * 32 + i0), c1 = *(const PG8_G f32x4*)(cosT + (size_t)row * 32 + i0 + 4);
;                     const f32x4 s0 = *(const PG8_G f32x4*)(sinT + (size_t)row * 32 + i0), s1 = *(const PG8_G f32x4*)(sinT + (size_t)row * 32 + i0 + 4);
;                     const f32x4 x1a = acc[ai][0][m][0] * r[ai][m], x1b = acc[ai][0][m][1] * r[ai][m], x2a = acc[ai][1][m][0] * r[ai][m], x2b = acc[ai][1][m][1] * r[ai][m];
;                     const f32x4 y1a = x1a * c0 - x2a * s0, y1b = x1b * c1 - x2b * s1, y2a = x2a * c0 + x1a * s0, y2b = x2b * c1 + x1b * s1;
;                     bf16_t* dst = Q + (size_t)row * 3072 + 2048 + head * 64 + i0;
;                     *(PG8_G u32x4*)dst = pack8bf(y1a, y1b); *(PG8_G u32x4*)(dst + 32) = pack8bf(y2a, y2b); }
	v_pk_mul_f32 v[220:221], v[212:213], v[184:185]
	v_pk_mul_f32 v[184:185], v[198:199], v[184:185]
	v_pk_fma_f32 v[220:221], v[198:199], v[176:177], v[220:221] neg_lo:[0,0,1] neg_hi:[0,0,1]
	v_pk_fma_f32 v[184:185], v[212:213], v[176:177], v[184:185]
	v_mad_i64_i32 v[176:177], s[24:25], v156, s26, v[132:133]
	s_waitcnt vmcnt(0)
	v_pk_mul_f32 v[216:217], v[208:209], v[188:189]
	v_pk_mul_f32 v[188:189], v[194:195], v[188:189]
	v_lshl_add_u64 v[176:177], v[176:177], 0, s[14:15]
	v_pk_mul_f32 v[214:215], v[206:207], v[190:191]
	v_pk_fma_f32 v[216:217], v[194:195], v[180:181], v[216:217] neg_lo:[0,0,1] neg_hi:[0,0,1]
	v_pk_mul_f32 v[190:191], v[192:193], v[190:191]
	v_pk_fma_f32 v[180:181], v[208:209], v[180:181], v[188:189]
	v_lshl_add_u64 v[188:189], v[176:177], 0, v[134:135]
	v_pk_fma_f32 v[214:215], v[192:193], v[182:183], v[214:215] neg_lo:[0,0,1] neg_hi:[0,0,1]
	v_pk_mul_f32 v[218:219], v[210:211], v[186:187]
	v_pk_fma_f32 v[182:183], v[206:207], v[182:183], v[190:191]
	v_pk_mul_f32 v[186:187], v[196:197], v[186:187]
	v_lshl_add_u64 v[190:191], v[188:189], 0, s[48:49]
	v_add_co_u32_e32 v188, vcc, s27, v188
	v_pk_fma_f32 v[218:219], v[196:197], v[178:179], v[218:219] neg_lo:[0,0,1] neg_hi:[0,0,1]
	v_pk_fma_f32 v[186:187], v[210:211], v[178:179], v[186:187]
	v_cvt_pk_bf16_f32 v176, v216, v217
	v_cvt_pk_bf16_f32 v177, v214, v215
	v_cvt_pk_bf16_f32 v178, v220, v221
	v_addc_co_u32_e32 v189, vcc, 0, v189, vcc
	v_cvt_pk_bf16_f32 v179, v218, v219
	global_store_dwordx4 v[188:189], v[176:179], off
	v_mov_b32_e32 v192, v153
	v_pk_mul_f32 v[194:195], v[54:55], v[192:193] op_sel_hi:[1,0]
	v_cvt_pk_bf16_f32 v176, v180, v181
	v_cvt_pk_bf16_f32 v177, v182, v183
	v_cvt_pk_bf16_f32 v178, v184, v185
	v_lshlrev_b64 v[184:185], 7, v[154:155]
	v_cvt_pk_bf16_f32 v179, v186, v187
	global_store_dwordx4 v[190:191], v[176:179], off offset:64
	v_pk_mul_f32 v[196:197], v[52:53], v[192:193] op_sel_hi:[1,0]
	v_pk_mul_f32 v[198:199], v[46:47], v[192:193] op_sel_hi:[1,0]
	v_lshl_add_u64 v[176:177], s[38:39], 0, v[184:185]
	v_lshl_add_u64 v[184:185], s[40:41], 0, v[184:185]
	v_lshl_add_u64 v[180:181], v[176:177], 0, v[170:171]
	v_lshl_add_u64 v[188:189], v[184:185], 0, v[170:171]
	global_load_dwordx4 v[176:179], v[180:181], off offset:16
	s_nop 0
	global_load_dwordx4 v[180:183], v[180:181], off
	s_nop 0
	global_load_dwordx4 v[184:187], v[188:189], off offset:16
	s_nop 0
	global_load_dwordx4 v[188:191], v[188:189], off
	v_pk_mul_f32 v[206:207], v[44:45], v[192:193] op_sel_hi:[1,0]
	v_pk_mul_f32 v[208:209], v[42:43], v[192:193] op_sel_hi:[1,0]
	v_pk_mul_f32 v[210:211], v[40:41], v[192:193] op_sel_hi:[1,0]
	v_pk_mul_f32 v[212:213], v[34:35], v[192:193] op_sel_hi:[1,0]
	v_pk_mul_f32 v[192:193], v[32:33], v[192:193] op_sel_hi:[1,0]
	s_waitcnt vmcnt(1)
	v_pk_mul_f32 v[218:219], v[212:213], v[186:187]
	v_pk_mul_f32 v[220:221], v[192:193], v[184:185]
	v_pk_mul_f32 v[184:185], v[206:207], v[184:185]
	v_pk_fma_f32 v[220:221], v[206:207], v[176:177], v[220:221] neg_lo:[0,0,1] neg_hi:[0,0,1]
	v_pk_fma_f32 v[184:185], v[192:193], v[176:177], v[184:185]
	v_mad_i64_i32 v[176:177], s[24:25], v154, s26, v[132:133]
	s_waitcnt vmcnt(0)
	v_pk_mul_f32 v[216:217], v[210:211], v[188:189]
	v_pk_mul_f32 v[188:189], v[196:197], v[188:189]
	v_lshl_add_u64 v[176:177], v[176:177], 0, s[14:15]
	v_pk_mul_f32 v[214:215], v[208:209], v[190:191]
	v_pk_fma_f32 v[216:217], v[196:197], v[180:181], v[216:217] neg_lo:[0,0,1] neg_hi:[0,0,1]
	v_pk_mul_f32 v[190:191], v[194:195], v[190:191]
	v_pk_fma_f32 v[180:181], v[210:211], v[180:181], v[188:189]
	v_lshl_add_u64 v[188:189], v[176:177], 0, v[134:135]
	v_pk_fma_f32 v[214:215], v[194:195], v[182:183], v[214:215] neg_lo:[0,0,1] neg_hi:[0,0,1]
	v_pk_fma_f32 v[182:183], v[208:209], v[182:183], v[190:191]
	v_pk_mul_f32 v[186:187], v[198:199], v[186:187]
	v_lshl_add_u64 v[190:191], v[188:189], 0, s[48:49]
	v_add_co_u32_e32 v188, vcc, s27, v188
	v_pk_fma_f32 v[218:219], v[198:199], v[178:179], v[218:219] neg_lo:[0,0,1] neg_hi:[0,0,1]
	v_pk_fma_f32 v[186:187], v[212:213], v[178:179], v[186:187]
	v_cvt_pk_bf16_f32 v176, v216, v217
	v_cvt_pk_bf16_f32 v177, v214, v215
	v_cvt_pk_bf16_f32 v178, v220, v221
	v_addc_co_u32_e32 v189, vcc, 0, v189, vcc
	v_cvt_pk_bf16_f32 v179, v218, v219
	global_store_dwordx4 v[188:189], v[176:179], off
	v_pk_mul_f32 v[198:199], v[28:29], v[148:149] op_sel_hi:[1,0]
	v_pk_mul_f32 v[212:213], v[16:17], v[148:149] op_sel_hi:[1,0]
	v_cvt_pk_bf16_f32 v176, v180, v181
	v_cvt_pk_bf16_f32 v177, v182, v183
	v_cvt_pk_bf16_f32 v178, v184, v185
	v_lshlrev_b64 v[184:185], 7, v[150:151]
	v_cvt_pk_bf16_f32 v179, v186, v187
	global_store_dwordx4 v[190:191], v[176:179], off offset:64
	v_pk_mul_f32 v[194:195], v[36:37], v[148:149] op_sel_hi:[1,0]
	v_pk_mul_f32 v[208:209], v[24:25], v[148:149] op_sel_hi:[1,0]
	v_lshl_add_u64 v[176:177], s[38:39], 0, v[184:185]
	v_lshl_add_u64 v[184:185], s[40:41], 0, v[184:185]
	v_lshl_add_u64 v[180:181], v[176:177], 0, v[170:171]
	v_lshl_add_u64 v[188:189], v[184:185], 0, v[170:171]
	global_load_dwordx4 v[176:179], v[180:181], off offset:16
	s_nop 0
	global_load_dwordx4 v[180:183], v[180:181], off
	s_nop 0
	global_load_dwordx4 v[184:187], v[188:189], off offset:16
	s_nop 0
	global_load_dwordx4 v[188:191], v[188:189], off
	v_pk_mul_f32 v[192:193], v[38:39], v[148:149] op_sel_hi:[1,0]
	v_pk_mul_f32 v[206:207], v[26:27], v[148:149] op_sel_hi:[1,0]
	v_pk_mul_f32 v[196:197], v[30:31], v[148:149] op_sel_hi:[1,0]
	v_pk_mul_f32 v[210:211], v[18:19], v[148:149] op_sel_hi:[1,0]
	s_waitcnt vmcnt(1)
; #define PG8_G __attribute__((address_space(1)))
; __device__ __forceinline__ u32x4 pack8bf(const f32x4 a, const f32x4 b) { u32x4 w; w.x = cvt_pk_bf16(a[0], a[1]); w.y = cvt_pk_bf16(a[2], a[3]); w.z = cvt_pk_bf16(b[0], b[1]); w.w = cvt_pk_bf16(b[2], b[3]); return w; }
;     __device__ __forceinline__ void operator()(const f32x4 (&acc)[2][2][4][2], const Unit& u, int wr, int wc, int fr_, int fq_, int ui) const {
;     ...
;                 for (int m = 0; m < 4; ++m) { const int row = row0 + ai * HALF + m * 16;
;                     const f32x4 c0 = *(const PG8_G f32x4*)(cosT + (size_t)row * 32 + i0), c1 = *(const PG8_G f32x4*)(cosT + (size_t)row * 32 + i0 + 4);
;                     const f32x4 s0 = *(const PG8_G f32x4*)(sinT + (size_t)row * 32 + i0), s1 = *(const PG8_G f32x4*)(sinT + (size_t)row * 32 + i0 + 4);
;                     const f32x4 x1a = acc[ai][0][m][0] * r[ai][m], x1b = acc[ai][0][m][1] * r[ai][m], x2a = acc[ai][1][m][0] * r[ai][m], x2b = acc[ai][1][m][1] * r[ai][m];
;                     const f32x4 y1a = x1a * c0 - x2a * s0, y1b = x1b * c1 - x2b * s1, y2a = x2a * c0 + x1a * s0, y2b = x2b * c1 + x1b * s1;
;                     bf16_t* dst = Q + (size_t)row * 3072 + 2048 + head * 64 + i0;
;                     *(PG8_G u32x4*)dst = pack8bf(y1a, y1b); *(PG8_G u32x4*)(dst + 32) = pack8bf(y2a, y2b); }
	v_pk_mul_f32 v[220:221], v[212:213], v[184:185]
	v_pk_mul_f32 v[184:185], v[198:199], v[184:185]
	v_pk_fma_f32 v[220:221], v[198:199], v[176:177], v[220:221] neg_lo:[0,0,1] neg_hi:[0,0,1]
	v_pk_fma_f32 v[184:185], v[212:213], v[176:177], v[184:185]
	v_mad_i64_i32 v[176:177], s[24:25], v150, s26, v[132:133]
	s_waitcnt vmcnt(0)
	v_pk_mul_f32 v[216:217], v[208:209], v[188:189]
	v_pk_mul_f32 v[188:189], v[194:195], v[188:189]
	v_lshl_add_u64 v[176:177], v[176:177], 0, s[14:15]
	v_pk_mul_f32 v[214:215], v[206:207], v[190:191]
	v_pk_fma_f32 v[216:217], v[194:195], v[180:181], v[216:217] neg_lo:[0,0,1] neg_hi:[0,0,1]
	v_pk_mul_f32 v[190:191], v[192:193], v[190:191]
	v_pk_fma_f32 v[180:181], v[208:209], v[180:181], v[188:189]
	v_lshl_add_u64 v[188:189], v[176:177], 0, v[134:135]
	v_pk_fma_f32 v[214:215], v[192:193], v[182:183], v[214:215] neg_lo:[0,0,1] neg_hi:[0,0,1]
	v_pk_mul_f32 v[218:219], v[210:211], v[186:187]
	v_pk_fma_f32 v[182:183], v[206:207], v[182:183], v[190:191]
	v_pk_mul_f32 v[186:187], v[196:197], v[186:187]
	v_lshl_add_u64 v[190:191], v[188:189], 0, s[48:49]
	v_add_co_u32_e32 v188, vcc, s27, v188
	v_add_u32_e32 v192, 0xb0, v146
	v_pk_fma_f32 v[218:219], v[196:197], v[178:179], v[218:219] neg_lo:[0,0,1] neg_hi:[0,0,1]
	v_pk_fma_f32 v[186:187], v[210:211], v[178:179], v[186:187]
	v_cvt_pk_bf16_f32 v176, v216, v217
	v_cvt_pk_bf16_f32 v177, v214, v215
	v_cvt_pk_bf16_f32 v178, v220, v221
	v_addc_co_u32_e32 v189, vcc, 0, v189, vcc
	v_ashrrev_i32_e32 v193, 31, v192
	v_cvt_pk_bf16_f32 v179, v218, v219
	global_store_dwordx4 v[188:189], v[176:179], off
	v_mad_i64_i32 v[132:133], s[24:25], v192, s26, v[132:133]
	s_nop 0
	v_cvt_pk_bf16_f32 v176, v180, v181
	v_cvt_pk_bf16_f32 v177, v182, v183
	v_cvt_pk_bf16_f32 v178, v184, v185
	v_lshlrev_b64 v[184:185], 7, v[192:193]
	v_cvt_pk_bf16_f32 v179, v186, v187
	global_store_dwordx4 v[190:191], v[176:179], off offset:64
	v_lshl_add_u64 v[132:133], v[132:133], 0, s[14:15]
	s_mov_b64 s[14:15], 0x1040
	v_lshl_add_u64 v[176:177], s[38:39], 0, v[184:185]
	v_lshl_add_u64 v[184:185], s[40:41], 0, v[184:185]
	v_lshl_add_u64 v[180:181], v[176:177], 0, v[170:171]
	v_lshl_add_u64 v[170:171], v[184:185], 0, v[170:171]
	global_load_dwordx4 v[176:179], v[180:181], off offset:16
	s_nop 0
	global_load_dwordx4 v[180:183], v[180:181], off
	s_nop 0
	global_load_dwordx4 v[184:187], v[170:171], off offset:16
	global_load_dwordx4 v[188:191], v[170:171], off
	v_mov_b32_e32 v170, v149
	v_pk_mul_f32 v[194:195], v[22:23], v[170:171] op_sel_hi:[1,0]
	v_pk_mul_f32 v[196:197], v[20:21], v[170:171] op_sel_hi:[1,0]
	v_pk_mul_f32 v[198:199], v[14:15], v[170:171] op_sel_hi:[1,0]
	v_pk_mul_f32 v[206:207], v[12:13], v[170:171] op_sel_hi:[1,0]
	v_pk_mul_f32 v[208:209], v[10:11], v[170:171] op_sel_hi:[1,0]
	v_pk_mul_f32 v[210:211], v[8:9], v[170:171] op_sel_hi:[1,0]
	v_pk_mul_f32 v[212:213], v[6:7], v[170:171] op_sel_hi:[1,0]
	v_pk_mul_f32 v[170:171], v[4:5], v[170:171] op_sel_hi:[1,0]
	s_waitcnt vmcnt(1)
	v_pk_mul_f32 v[218:219], v[212:213], v[186:187]
	v_pk_mul_f32 v[220:221], v[170:171], v[184:185]
	v_pk_mul_f32 v[184:185], v[206:207], v[184:185]
	v_pk_fma_f32 v[220:221], v[206:207], v[176:177], v[220:221] neg_lo:[0,0,1] neg_hi:[0,0,1]
	v_pk_fma_f32 v[170:171], v[170:171], v[176:177], v[184:185]
	v_lshl_add_u64 v[176:177], v[132:133], 0, v[134:135]
	s_waitcnt vmcnt(0)
	v_pk_mul_f32 v[214:215], v[208:209], v[190:191]
	v_pk_mul_f32 v[216:217], v[210:211], v[188:189]
	v_add_co_u32_e32 v184, vcc, s27, v176
	v_pk_fma_f32 v[214:215], v[194:195], v[182:183], v[214:215] neg_lo:[0,0,1] neg_hi:[0,0,1]
	v_pk_fma_f32 v[216:217], v[196:197], v[180:181], v[216:217] neg_lo:[0,0,1] neg_hi:[0,0,1]
	v_pk_fma_f32 v[218:219], v[198:199], v[178:179], v[218:219] neg_lo:[0,0,1] neg_hi:[0,0,1]
	v_pk_mul_f32 v[190:191], v[194:195], v[190:191]
	v_pk_mul_f32 v[188:189], v[196:197], v[188:189]
	v_pk_mul_f32 v[186:187], v[198:199], v[186:187]
	v_cvt_pk_bf16_f32 v132, v216, v217
	v_cvt_pk_bf16_f32 v133, v214, v215
	v_cvt_pk_bf16_f32 v134, v220, v221
	v_cvt_pk_bf16_f32 v135, v218, v219
	v_addc_co_u32_e32 v185, vcc, 0, v177, vcc
	v_pk_fma_f32 v[182:183], v[208:209], v[182:183], v[190:191]
	v_pk_fma_f32 v[180:181], v[210:211], v[180:181], v[188:189]
	v_pk_fma_f32 v[178:179], v[212:213], v[178:179], v[186:187]
	global_store_dwordx4 v[184:185], v[132:135], off
	s_nop 1
	v_cvt_pk_bf16_f32 v132, v180, v181
	v_cvt_pk_bf16_f32 v133, v182, v183
	v_cvt_pk_bf16_f32 v134, v170, v171
	v_cvt_pk_bf16_f32 v135, v178, v179
	v_lshl_add_u64 v[170:171], v[176:177], 0, s[14:15]
	s_mov_b64 s[14:15], 0

;     __device__ __forceinline__ bool next(int i, Unit& u) const { if (i >= n) return false; u.pm = pm; u.pn = pn0 + i; return true; }
;     __device__ __forceinline__ bool next(int i, Unit& u) const { if (i) return false; u.pm = pm; u.pn = pn; return true; }
; #define PG8_STAGE(bufoff, gbase, voff) do { _Pragma("unroll") for (int _i = 0; _i < 2; ++_i) \
;         __builtin_amdgcn_global_load_lds((const unsigned*)((const char*)(gbase) + (voff)[_i]), (PG8_LAS unsigned*)(lds + (bufoff) + ldsw + _i * 8192), 16, 0, 0); } while (0)
; #define PG8_LDA(dst, b, h) do { _Pragma("unroll") for (int m = 0; m < 4; ++m) _Pragma("unroll") for (int k = 0; k < 2; ++k) dst[m][k] = *(const PG8_LAS bf16x8*)(lds + PG8_SA(b, h) + aoff + m * 2048 + k * 1024); } while (0)
; #define PG8_LDB(dst, b, h) do { _Pragma("unroll") for (int n = 0; n < 2; ++n) _Pragma("unroll") for (int k = 0; k < 2; ++k) dst[n][k] = *(const PG8_LAS bf16x8*)(lds + PG8_SB(b, h) + boff + n * 2048 + k * 1024); } while (0)
; #define PG8_WAIT_V(n) asm volatile("s_waitcnt vmcnt(" #n ")" ::: "memory")
; #define PG8_BAR __builtin_amdgcn_s_barrier()
;     ...
;         const bool has_next = S.next(ui + 1, nxt);
;         const char* nA = has_next ? (const char*)g.A + (size_t)nxt.pm * tstep : cA; const char* nB = has_next ? (const char*)g.Bt + (size_t)nxt.pn * tstep : cB;
;         for (int t = 0; t < nt; t += 2) {
;             const bool last = (t == nt - 2);
;             const char* a1 = cA + (size_t)(t + 1) * kstep;
;             const char* a2 = last ? nA : cA + (size_t)(t + 2) * kstep; const char* b2 = last ? nB : cB + (size_t)(t + 2) * kstep;
;             const char* a3 = a2 + kstep; const char* b3 = b2 + kstep;
;             if (last && has_next) S.a_ready(nxt);
;             if (t == 0) E.pre_issue(pre, cur, tid, ui); else if (t == 2) E.pre_finish(pre, tid, ui);
;             if constexpr (SP2) {
;             PG8_LDB(B0, 0, 0); PG8_LDB(B1, 0, 1); PG8_SCHED; PG8_LDA(At, 0, 0); PG8_STAGE(PG8_SA(1, 1), a1 + hstep, voffA);
;             PG8_WAIT_V(8); PG8_WAIT_L(0); PG8_BAR; PG8_MMA(0, 0, At, B0); PG8_MMA(0, 1, At, B1); PG8_BAR; PG8_SCHED;
;             PG8_LDA(At, 0, 1); PG8_STAGE(PG8_SB(0, 0), b2, voffB); PG8_STAGE(PG8_SB(0, 1), b2 + hstep, voffB); PG8_STAGE(PG8_SA(0, 0), a2, voffA);
;             PG8_WAIT_V(8); PG8_WAIT_L(0); PG8_BAR; PG8_MMA(1, 0, At, B0); PG8_MMA(1, 1, At, B1); PG8_BAR; PG8_SCHED;
.LBB0_454:
	s_add_u32 s48, s62, 0xfff80080
	s_addc_u32 s49, s63, -1
	s_add_i32 s82, 0, 0x10000
	s_cmp_eq_u32 s81, 28
	s_cselect_b32 s71, s25, s49
	s_cselect_b32 s70, s76, s48
	s_cselect_b32 s69, s15, s79
	s_cselect_b32 s68, s77, s78
	s_add_i32 s48, 0, 0x14000
	v_add_u32_e32 v136, s82, v233
	v_add_u32_e32 v160, s48, v233
	ds_read_b128 v[108:111], v136
	ds_read_b128 v[112:115], v136 offset:1024
	ds_read_b128 v[128:131], v136 offset:2048
	ds_read_b128 v[136:139], v136 offset:3072
	ds_read_b128 v[148:151], v160
	ds_read_b128 v[152:155], v160 offset:1024
	ds_read_b128 v[156:159], v160 offset:2048
	ds_read_b128 v[160:163], v160 offset:3072
	v_lshl_add_u64 v[198:199], s[62:63], 0, v[196:197]
	s_add_i32 m0, s20, 0xc000
	ds_read_b128 v[164:167], v234
	ds_read_b128 v[168:171], v234 offset:1024
	ds_read_b128 v[172:175], v234 offset:2048
	ds_read_b128 v[176:179], v234 offset:3072
	ds_read_b128 v[180:183], v234 offset:4096
	ds_read_b128 v[184:187], v234 offset:5120
	ds_read_b128 v[206:209], v234 offset:6144
	ds_read_b128 v[210:213], v234 offset:7168
	global_load_lds_dwordx4 v[198:199], off
	v_lshl_add_u64 v[198:199], s[62:63], 0, v[194:195]
	s_add_i32 m0, s20, 0xe000
	s_nop 0
	global_load_lds_dwordx4 v[198:199], off
	s_waitcnt vmcnt(8)
	s_waitcnt lgkmcnt(0)
	s_setprio 1
	s_barrier
	v_mfma_f32_16x16x32_bf16 v[144:147], v[108:111], v[164:167], v[144:147]
	v_mfma_f32_16x16x32_bf16 v[140:143], v[128:131], v[164:167], v[140:143]
	v_mfma_f32_16x16x32_bf16 v[120:123], v[108:111], v[172:175], v[120:123]
	v_mfma_f32_16x16x32_bf16 v[116:119], v[128:131], v[172:175], v[116:119]
	v_mfma_f32_16x16x32_bf16 v[96:99], v[108:111], v[180:183], v[96:99]
	v_mfma_f32_16x16x32_bf16 v[92:95], v[128:131], v[180:183], v[92:95]
	v_mfma_f32_16x16x32_bf16 v[80:83], v[108:111], v[206:209], v[80:83]
	v_mfma_f32_16x16x32_bf16 v[76:79], v[128:131], v[206:209], v[76:79]
	v_mfma_f32_16x16x32_bf16 v[144:147], v[112:115], v[168:171], v[144:147]
	v_mfma_f32_16x16x32_bf16 v[140:143], v[136:139], v[168:171], v[140:143]
	v_mfma_f32_16x16x32_bf16 v[120:123], v[112:115], v[176:179], v[120:123]
	v_mfma_f32_16x16x32_bf16 v[116:119], v[136:139], v[176:179], v[116:119]
	v_mfma_f32_16x16x32_bf16 v[96:99], v[112:115], v[184:187], v[96:99]
	v_mfma_f32_16x16x32_bf16 v[92:95], v[136:139], v[184:187], v[92:95]
	v_mfma_f32_16x16x32_bf16 v[80:83], v[112:115], v[210:213], v[80:83]
	v_mfma_f32_16x16x32_bf16 v[76:79], v[136:139], v[210:213], v[76:79]
	s_setprio 0
	s_setprio 1
	v_mfma_f32_16x16x32_bf16 v[132:135], v[148:151], v[164:167], v[132:135]
	v_mfma_f32_16x16x32_bf16 v[124:127], v[156:159], v[164:167], v[124:127]
	v_mfma_f32_16x16x32_bf16 v[104:107], v[148:151], v[172:175], v[104:107]
	v_mfma_f32_16x16x32_bf16 v[100:103], v[156:159], v[172:175], v[100:103]
	v_mfma_f32_16x16x32_bf16 v[88:91], v[148:151], v[180:183], v[88:91]
	v_mfma_f32_16x16x32_bf16 v[84:87], v[156:159], v[180:183], v[84:87]
	v_mfma_f32_16x16x32_bf16 v[72:75], v[148:151], v[206:209], v[72:75]
	v_mfma_f32_16x16x32_bf16 v[68:71], v[156:159], v[206:209], v[68:71]
	v_mfma_f32_16x16x32_bf16 v[132:135], v[152:155], v[168:171], v[132:135]
	v_mfma_f32_16x16x32_bf16 v[124:127], v[160:163], v[168:171], v[124:127]
	v_mfma_f32_16x16x32_bf16 v[104:107], v[152:155], v[176:179], v[104:107]
	v_mfma_f32_16x16x32_bf16 v[100:103], v[160:163], v[176:179], v[100:103]
	v_mfma_f32_16x16x32_bf16 v[88:91], v[152:155], v[184:187], v[88:91]
	v_mfma_f32_16x16x32_bf16 v[84:87], v[160:163], v[184:187], v[84:87]
	v_mfma_f32_16x16x32_bf16 v[72:75], v[152:155], v[210:213], v[72:75]
	v_mfma_f32_16x16x32_bf16 v[68:71], v[160:163], v[210:213], v[68:71]
	s_barrier
	s_setprio 0
	s_add_i32 s49, s82, s5
	v_lshl_add_u64 v[198:199], s[68:69], 0, v[200:201]
	s_mov_b32 m0, s49
	ds_read_b128 v[164:167], v234 offset:16384
	ds_read_b128 v[168:171], v234 offset:17408
	ds_read_b128 v[172:175], v234 offset:18432
	ds_read_b128 v[176:179], v234 offset:19456
	ds_read_b128 v[180:183], v234 offset:20480
	ds_read_b128 v[184:187], v234 offset:21504
	ds_read_b128 v[206:209], v234 offset:22528
	ds_read_b128 v[210:213], v234 offset:23552
	global_load_lds_dwordx4 v[198:199], off
	s_add_i32 m0, s49, 0x2000
	s_add_u32 s82, s68, 0x80000
	v_lshl_add_u64 v[214:215], s[68:69], 0, v[188:189]
	s_addc_u32 s83, s69, 0
	s_add_i32 s48, s48, s5
	global_load_lds_dwordx4 v[214:215], off
	v_lshl_add_u64 v[216:217], s[82:83], 0, v[200:201]
	s_mov_b32 m0, s48
	v_lshl_add_u64 v[218:219], s[70:71], 0, v[190:191]
	global_load_lds_dwordx4 v[216:217], off
	v_lshl_add_u64 v[216:217], s[82:83], 0, v[188:189]
	s_add_i32 m0, s48, 0x2000
	s_nop 0
	global_load_lds_dwordx4 v[216:217], off
	v_lshl_add_u64 v[216:217], s[70:71], 0, v[192:193]
	s_mov_b32 m0, s20
	s_nop 0
	global_load_lds_dwordx4 v[216:217], off
	s_mov_b32 m0, s21
	s_nop 0
	global_load_lds_dwordx4 v[218:219], off
	s_waitcnt vmcnt(8)
	s_waitcnt lgkmcnt(0)
	s_setprio 1
	s_barrier
; #define PG8_STAGE(bufoff, gbase, voff) do { _Pragma("unroll") for (int _i = 0; _i < 2; ++_i) \
;         __builtin_amdgcn_global_load_lds((const unsigned*)((const char*)(gbase) + (voff)[_i]), (PG8_LAS unsigned*)(lds + (bufoff) + ldsw + _i * 8192), 16, 0, 0); } while (0)
; #define PG8_LDA(dst, b, h) do { _Pragma("unroll") for (int m = 0; m < 4; ++m) _Pragma("unroll") for (int k = 0; k < 2; ++k) dst[m][k] = *(const PG8_LAS bf16x8*)(lds + PG8_SA(b, h) + aoff + m * 2048 + k * 1024); } while (0)
; #define PG8_LDB(dst, b, h) do { _Pragma("unroll") for (int n = 0; n < 2; ++n) _Pragma("unroll") for (int k = 0; k < 2; ++k) dst[n][k] = *(const PG8_LAS bf16x8*)(lds + PG8_SB(b, h) + boff + n * 2048 + k * 1024); } while (0)
; #define PG8_MMA(ai, bj, At, Bt) do { __builtin_amdgcn_s_setprio(1); _Pragma("unroll") for (int m = 0; m < 4; ++m) _Pragma("unroll") for (int n = 0; n < 2; ++n) _Pragma("unroll") for (int k = 0; k < 2; ++k) \
;         acc[ai][bj][m][n] = __builtin_amdgcn_mfma_f32_16x16x32_bf16(Bt[n][k], At[m][k], acc[ai][bj][m][n], 0, 0, 0); __builtin_amdgcn_s_setprio(0); } while (0)
; #define PG8_WAIT_V(n) asm volatile("s_waitcnt vmcnt(" #n ")" ::: "memory")
; #define PG8_WAIT_L(n) asm volatile("s_waitcnt lgkmcnt(" #n ")" ::: "memory")
; #define PG8_BAR __builtin_amdgcn_s_barrier()
; #define PG8_SCHED __builtin_amdgcn_sched_barrier(0)
;     ...
;             PG8_WAIT_V(8); PG8_WAIT_L(0); PG8_BAR; PG8_MMA(1, 0, At, B0); PG8_MMA(1, 1, At, B1); PG8_BAR; PG8_SCHED;
;             PG8_LDB(B0, 1, 0); PG8_LDB(B1, 1, 1); PG8_SCHED; PG8_LDA(At, 1, 0); PG8_STAGE(PG8_SA(0, 1), a2 + hstep, voffA);
;             PG8_WAIT_V(8); PG8_WAIT_L(0); PG8_BAR; PG8_MMA(0, 0, At, B0); PG8_MMA(0, 1, At, B1); PG8_BAR; PG8_SCHED;
	v_mfma_f32_16x16x32_bf16 v[64:67], v[108:111], v[164:167], v[64:67]
	v_mfma_f32_16x16x32_bf16 v[60:63], v[128:131], v[164:167], v[60:63]
	v_mfma_f32_16x16x32_bf16 v[48:51], v[108:111], v[172:175], v[48:51]
	v_mfma_f32_16x16x32_bf16 v[44:47], v[128:131], v[172:175], v[44:47]
	v_mfma_f32_16x16x32_bf16 v[32:35], v[108:111], v[180:183], v[32:35]
	v_mfma_f32_16x16x32_bf16 v[28:31], v[128:131], v[180:183], v[28:31]
	v_mfma_f32_16x16x32_bf16 v[16:19], v[108:111], v[206:209], v[16:19]
	v_mfma_f32_16x16x32_bf16 v[12:15], v[128:131], v[206:209], v[12:15]
	v_mfma_f32_16x16x32_bf16 v[64:67], v[112:115], v[168:171], v[64:67]
	v_mfma_f32_16x16x32_bf16 v[60:63], v[136:139], v[168:171], v[60:63]
	v_mfma_f32_16x16x32_bf16 v[48:51], v[112:115], v[176:179], v[48:51]
	v_mfma_f32_16x16x32_bf16 v[44:47], v[136:139], v[176:179], v[44:47]
	v_mfma_f32_16x16x32_bf16 v[32:35], v[112:115], v[184:187], v[32:35]
	v_mfma_f32_16x16x32_bf16 v[28:31], v[136:139], v[184:187], v[28:31]
	v_mfma_f32_16x16x32_bf16 v[16:19], v[112:115], v[210:213], v[16:19]
	v_mfma_f32_16x16x32_bf16 v[12:15], v[136:139], v[210:213], v[12:15]
	s_setprio 0
	s_setprio 1
	v_mfma_f32_16x16x32_bf16 v[56:59], v[148:151], v[164:167], v[56:59]
	v_mfma_f32_16x16x32_bf16 v[52:55], v[156:159], v[164:167], v[52:55]
	v_mfma_f32_16x16x32_bf16 v[40:43], v[148:151], v[172:175], v[40:43]
	v_mfma_f32_16x16x32_bf16 v[36:39], v[156:159], v[172:175], v[36:39]
	v_mfma_f32_16x16x32_bf16 v[24:27], v[148:151], v[180:183], v[24:27]
	v_mfma_f32_16x16x32_bf16 v[20:23], v[156:159], v[180:183], v[20:23]
	v_mfma_f32_16x16x32_bf16 v[8:11], v[148:151], v[206:209], v[8:11]
	v_mfma_f32_16x16x32_bf16 v[4:7], v[156:159], v[206:209], v[4:7]
	v_mfma_f32_16x16x32_bf16 v[56:59], v[152:155], v[168:171], v[56:59]
	v_mfma_f32_16x16x32_bf16 v[52:55], v[160:163], v[168:171], v[52:55]
	v_mfma_f32_16x16x32_bf16 v[40:43], v[152:155], v[176:179], v[40:43]
	v_mfma_f32_16x16x32_bf16 v[36:39], v[160:163], v[176:179], v[36:39]
	v_mfma_f32_16x16x32_bf16 v[24:27], v[152:155], v[184:187], v[24:27]
	v_mfma_f32_16x16x32_bf16 v[20:23], v[160:163], v[184:187], v[20:23]
	v_mfma_f32_16x16x32_bf16 v[8:11], v[152:155], v[210:213], v[8:11]
	v_mfma_f32_16x16x32_bf16 v[4:7], v[160:163], v[210:213], v[4:7]
	s_barrier
	s_setprio 0
	s_add_i32 s48, 0, 0x18000
	s_add_i32 s49, 0, 0x1c000
	v_add_u32_e32 v136, s48, v233
	v_add_u32_e32 v160, s49, v233
	ds_read_b128 v[108:111], v136
	ds_read_b128 v[112:115], v136 offset:1024
	ds_read_b128 v[128:131], v136 offset:2048
	ds_read_b128 v[136:139], v136 offset:3072
	ds_read_b128 v[148:151], v160
	ds_read_b128 v[152:155], v160 offset:1024
	ds_read_b128 v[156:159], v160 offset:2048
	ds_read_b128 v[160:163], v160 offset:3072
	s_add_u32 s70, s70, 0x80000
	s_addc_u32 s71, s71, 0
	s_mov_b32 m0, s23
	v_lshl_add_u64 v[220:221], s[70:71], 0, v[192:193]
	ds_read_b128 v[164:167], v234 offset:32768
	ds_read_b128 v[168:171], v234 offset:33792
	ds_read_b128 v[172:175], v234 offset:34816
	ds_read_b128 v[176:179], v234 offset:35840
	ds_read_b128 v[180:183], v234 offset:36864
	ds_read_b128 v[184:187], v234 offset:37888
	ds_read_b128 v[206:209], v234 offset:38912
	ds_read_b128 v[210:213], v234 offset:39936
	global_load_lds_dwordx4 v[220:221], off
	v_lshl_add_u64 v[220:221], s[70:71], 0, v[190:191]
	s_mov_b32 m0, s42
	s_nop 0
	global_load_lds_dwordx4 v[220:221], off
	s_waitcnt vmcnt(8)
	s_waitcnt lgkmcnt(0)
	s_setprio 1
	s_barrier
	v_mfma_f32_16x16x32_bf16 v[144:147], v[108:111], v[164:167], v[144:147]
	v_mfma_f32_16x16x32_bf16 v[140:143], v[128:131], v[164:167], v[140:143]
	v_mfma_f32_16x16x32_bf16 v[120:123], v[108:111], v[172:175], v[120:123]
	v_mfma_f32_16x16x32_bf16 v[116:119], v[128:131], v[172:175], v[116:119]
	v_mfma_f32_16x16x32_bf16 v[96:99], v[108:111], v[180:183], v[96:99]
	v_mfma_f32_16x16x32_bf16 v[92:95], v[128:131], v[180:183], v[92:95]
	v_mfma_f32_16x16x32_bf16 v[80:83], v[108:111], v[206:209], v[80:83]
	v_mfma_f32_16x16x32_bf16 v[76:79], v[128:131], v[206:209], v[76:79]
	v_mfma_f32_16x16x32_bf16 v[144:147], v[112:115], v[168:171], v[144:147]
	v_mfma_f32_16x16x32_bf16 v[140:143], v[136:139], v[168:171], v[140:143]
	v_mfma_f32_16x16x32_bf16 v[120:123], v[112:115], v[176:179], v[120:123]
	v_mfma_f32_16x16x32_bf16 v[116:119], v[136:139], v[176:179], v[116:119]
	v_mfma_f32_16x16x32_bf16 v[96:99], v[112:115], v[184:187], v[96:99]
	v_mfma_f32_16x16x32_bf16 v[92:95], v[136:139], v[184:187], v[92:95]
	v_mfma_f32_16x16x32_bf16 v[80:83], v[112:115], v[210:213], v[80:83]
	v_mfma_f32_16x16x32_bf16 v[76:79], v[136:139], v[210:213], v[76:79]
	s_setprio 0
	s_setprio 1
	v_mfma_f32_16x16x32_bf16 v[132:135], v[148:151], v[164:167], v[132:135]
	v_mfma_f32_16x16x32_bf16 v[124:127], v[156:159], v[164:167], v[124:127]
	v_mfma_f32_16x16x32_bf16 v[104:107], v[148:151], v[172:175], v[104:107]
	v_mfma_f32_16x16x32_bf16 v[100:103], v[156:159], v[172:175], v[100:103]
	v_mfma_f32_16x16x32_bf16 v[88:91], v[148:151], v[180:183], v[88:91]
	v_mfma_f32_16x16x32_bf16 v[84:87], v[156:159], v[180:183], v[84:87]
	v_mfma_f32_16x16x32_bf16 v[72:75], v[148:151], v[206:209], v[72:75]
	v_mfma_f32_16x16x32_bf16 v[68:71], v[156:159], v[206:209], v[68:71]
	v_mfma_f32_16x16x32_bf16 v[132:135], v[152:155], v[168:171], v[132:135]
	v_mfma_f32_16x16x32_bf16 v[124:127], v[160:163], v[168:171], v[124:127]
	v_mfma_f32_16x16x32_bf16 v[104:107], v[152:155], v[176:179], v[104:107]
	v_mfma_f32_16x16x32_bf16 v[100:103], v[160:163], v[176:179], v[100:103]
	v_mfma_f32_16x16x32_bf16 v[88:91], v[152:155], v[184:187], v[88:91]
	v_mfma_f32_16x16x32_bf16 v[84:87], v[160:163], v[184:187], v[84:87]
	v_mfma_f32_16x16x32_bf16 v[72:75], v[152:155], v[210:213], v[72:75]
	v_mfma_f32_16x16x32_bf16 v[68:71], v[160:163], v[210:213], v[68:71]
	s_barrier
; #define PG8_STAGE(bufoff, gbase, voff) do { _Pragma("unroll") for (int _i = 0; _i < 2; ++_i) \
;         __builtin_amdgcn_global_load_lds((const unsigned*)((const char*)(gbase) + (voff)[_i]), (PG8_LAS unsigned*)(lds + (bufoff) + ldsw + _i * 8192), 16, 0, 0); } while (0)
; #define PG8_LDA(dst, b, h) do { _Pragma("unroll") for (int m = 0; m < 4; ++m) _Pragma("unroll") for (int k = 0; k < 2; ++k) dst[m][k] = *(const PG8_LAS bf16x8*)(lds + PG8_SA(b, h) + aoff + m * 2048 + k * 1024); } while (0)
; #define PG8_MMA(ai, bj, At, Bt) do { __builtin_amdgcn_s_setprio(1); _Pragma("unroll") for (int m = 0; m < 4; ++m) _Pragma("unroll") for (int n = 0; n < 2; ++n) _Pragma("unroll") for (int k = 0; k < 2; ++k) \
;         acc[ai][bj][m][n] = __builtin_amdgcn_mfma_f32_16x16x32_bf16(Bt[n][k], At[m][k], acc[ai][bj][m][n], 0, 0, 0); __builtin_amdgcn_s_setprio(0); } while (0)
; #define PG8_WAIT_V(n) asm volatile("s_waitcnt vmcnt(" #n ")" ::: "memory")
; #define PG8_WAIT_L(n) asm volatile("s_waitcnt lgkmcnt(" #n ")" ::: "memory")
; #define PG8_BAR __builtin_amdgcn_s_barrier()
; #define PG8_SCHED __builtin_amdgcn_sched_barrier(0)
;     ...
;             PG8_WAIT_V(8); PG8_WAIT_L(0); PG8_BAR; PG8_MMA(0, 0, At, B0); PG8_MMA(0, 1, At, B1); PG8_BAR; PG8_SCHED;
;             PG8_LDA(At, 1, 1); PG8_STAGE(PG8_SB(1, 0), b3, voffB); PG8_STAGE(PG8_SB(1, 1), b3 + hstep, voffB); PG8_STAGE(PG8_SA(1, 0), a3, voffA);
;             PG8_WAIT_V(8); PG8_WAIT_L(0); PG8_BAR; PG8_MMA(1, 0, At, B0); PG8_MMA(1, 1, At, B1); PG8_BAR; PG8_SCHED;
;     ...
;         if constexpr (ALIGN_EPI) { if (wr == 0) PG8_BAR; }
	s_setprio 0
	s_add_i32 s48, s48, s5
	v_lshl_add_u64 v[198:199], v[198:199], 0, s[66:67]
	s_mov_b32 m0, s48
	ds_read_b128 v[164:167], v234 offset:49152
	ds_read_b128 v[168:171], v234 offset:50176
	ds_read_b128 v[172:175], v234 offset:51200
	ds_read_b128 v[176:179], v234 offset:52224
	ds_read_b128 v[180:183], v234 offset:53248
	ds_read_b128 v[184:187], v234 offset:54272
	ds_read_b128 v[206:209], v234 offset:55296
	ds_read_b128 v[210:213], v234 offset:56320
	global_load_lds_dwordx4 v[198:199], off
	s_add_i32 m0, s48, 0x2000
	s_add_u32 s68, s68, 0x80080
	v_lshl_add_u64 v[198:199], v[214:215], 0, s[66:67]
	s_addc_u32 s69, s69, 0
	s_add_i32 s48, s49, s5
	global_load_lds_dwordx4 v[198:199], off
	v_lshl_add_u64 v[198:199], s[68:69], 0, v[200:201]
	s_mov_b32 m0, s48
	s_nop 0
	global_load_lds_dwordx4 v[198:199], off
	v_lshl_add_u64 v[198:199], s[68:69], 0, v[188:189]
	s_add_i32 m0, s48, 0x2000
	s_nop 0
	global_load_lds_dwordx4 v[198:199], off
	v_lshl_add_u64 v[198:199], v[216:217], 0, s[66:67]
	s_mov_b32 m0, s55
	s_nop 0
	global_load_lds_dwordx4 v[198:199], off
	v_lshl_add_u64 v[198:199], v[218:219], 0, s[66:67]
	s_mov_b32 m0, s56
	s_nop 0
	global_load_lds_dwordx4 v[198:199], off
	s_waitcnt vmcnt(8)
	s_waitcnt lgkmcnt(0)
	s_setprio 1
	s_barrier
	v_mfma_f32_16x16x32_bf16 v[64:67], v[108:111], v[164:167], v[64:67]
	v_mfma_f32_16x16x32_bf16 v[60:63], v[128:131], v[164:167], v[60:63]
	v_mfma_f32_16x16x32_bf16 v[48:51], v[108:111], v[172:175], v[48:51]
	v_mfma_f32_16x16x32_bf16 v[44:47], v[128:131], v[172:175], v[44:47]
	v_mfma_f32_16x16x32_bf16 v[32:35], v[108:111], v[180:183], v[32:35]
	v_mfma_f32_16x16x32_bf16 v[28:31], v[128:131], v[180:183], v[28:31]
	v_mfma_f32_16x16x32_bf16 v[16:19], v[108:111], v[206:209], v[16:19]
	v_mfma_f32_16x16x32_bf16 v[12:15], v[128:131], v[206:209], v[12:15]
	v_mfma_f32_16x16x32_bf16 v[64:67], v[112:115], v[168:171], v[64:67]
	v_mfma_f32_16x16x32_bf16 v[60:63], v[136:139], v[168:171], v[60:63]
	v_mfma_f32_16x16x32_bf16 v[48:51], v[112:115], v[176:179], v[48:51]
	v_mfma_f32_16x16x32_bf16 v[44:47], v[136:139], v[176:179], v[44:47]
	v_mfma_f32_16x16x32_bf16 v[32:35], v[112:115], v[184:187], v[32:35]
	v_mfma_f32_16x16x32_bf16 v[28:31], v[136:139], v[184:187], v[28:31]
	v_mfma_f32_16x16x32_bf16 v[16:19], v[112:115], v[210:213], v[16:19]
	v_mfma_f32_16x16x32_bf16 v[12:15], v[136:139], v[210:213], v[12:15]
	s_setprio 0
	s_setprio 1
	v_mfma_f32_16x16x32_bf16 v[56:59], v[148:151], v[164:167], v[56:59]
	v_mfma_f32_16x16x32_bf16 v[52:55], v[156:159], v[164:167], v[52:55]
	v_mfma_f32_16x16x32_bf16 v[40:43], v[148:151], v[172:175], v[40:43]
	v_mfma_f32_16x16x32_bf16 v[36:39], v[156:159], v[172:175], v[36:39]
	v_mfma_f32_16x16x32_bf16 v[24:27], v[148:151], v[180:183], v[24:27]
	v_mfma_f32_16x16x32_bf16 v[20:23], v[156:159], v[180:183], v[20:23]
	v_mfma_f32_16x16x32_bf16 v[8:11], v[148:151], v[206:209], v[8:11]
	v_mfma_f32_16x16x32_bf16 v[4:7], v[156:159], v[206:209], v[4:7]
	v_mfma_f32_16x16x32_bf16 v[56:59], v[152:155], v[168:171], v[56:59]
	v_mfma_f32_16x16x32_bf16 v[52:55], v[160:163], v[168:171], v[52:55]
	v_mfma_f32_16x16x32_bf16 v[40:43], v[152:155], v[176:179], v[40:43]
	v_mfma_f32_16x16x32_bf16 v[36:39], v[160:163], v[176:179], v[36:39]
	v_mfma_f32_16x16x32_bf16 v[24:27], v[152:155], v[184:187], v[24:27]
	v_mfma_f32_16x16x32_bf16 v[20:23], v[160:163], v[184:187], v[20:23]
	v_mfma_f32_16x16x32_bf16 v[8:11], v[152:155], v[210:213], v[8:11]
	v_mfma_f32_16x16x32_bf16 v[4:7], v[160:163], v[210:213], v[4:7]
	s_barrier
	s_setprio 0
	s_add_i32 s81, s81, 2
	s_add_u32 s78, s78, 0x100
	s_addc_u32 s79, s79, 0
	s_add_u32 s62, s62, 0x100
	s_addc_u32 s63, s63, 0
	s_cmp_gt_u32 s81, 29
	s_cbranch_scc0 .LBB0_454
	s_and_b64 vcc, exec, s[12:13]
	s_cbranch_vccz .LBB0_457
	s_barrier

;     __device__ __forceinline__ bool next(int i, Unit& u) const { if (i >= n) return false; u.pm = pm; u.pn = pn0 + i; return true; }
;     __device__ __forceinline__ bool next(int i, Unit& u) const { if (i) return false; u.pm = pm; u.pn = pn; return true; }
; #define PG8_STAGE(bufoff, gbase, voff) do { _Pragma("unroll") for (int _i = 0; _i < 2; ++_i) \
;         __builtin_amdgcn_global_load_lds((const unsigned*)((const char*)(gbase) + (voff)[_i]), (PG8_LAS unsigned*)(lds + (bufoff) + ldsw + _i * 8192), 16, 0, 0); } while (0)
; #define PG8_LDA(dst, b, h) do { _Pragma("unroll") for (int m = 0; m < 4; ++m) _Pragma("unroll") for (int k = 0; k < 2; ++k) dst[m][k] = *(const PG8_LAS bf16x8*)(lds + PG8_SA(b, h) + aoff + m * 2048 + k * 1024); } while (0)
; #define PG8_LDB(dst, b, h) do { _Pragma("unroll") for (int n = 0; n < 2; ++n) _Pragma("unroll") for (int k = 0; k < 2; ++k) dst[n][k] = *(const PG8_LAS bf16x8*)(lds + PG8_SB(b, h) + boff + n * 2048 + k * 1024); } while (0)
; #define PG8_WAIT_V(n) asm volatile("s_waitcnt vmcnt(" #n ")" ::: "memory")
; #define PG8_BAR __builtin_amdgcn_s_barrier()
;     ...
;         const bool has_next = S.next(ui + 1, nxt);
;         const char* nA = has_next ? (const char*)g.A + (size_t)nxt.pm * tstep : cA; const char* nB = has_next ? (const char*)g.Bt + (size_t)nxt.pn * tstep : cB;
;         for (int t = 0; t < nt; t += 2) {
;             const bool last = (t == nt - 2);
;             const char* a1 = cA + (size_t)(t + 1) * kstep;
;             const char* a2 = last ? nA : cA + (size_t)(t + 2) * kstep; const char* b2 = last ? nB : cB + (size_t)(t + 2) * kstep;
;             const char* a3 = a2 + kstep; const char* b3 = b2 + kstep;
;             if (last && has_next) S.a_ready(nxt);
;             if (t == 0) E.pre_issue(pre, cur, tid, ui); else if (t == 2) E.pre_finish(pre, tid, ui);
;             if constexpr (SP2) {
;             PG8_LDB(B0, 0, 0); PG8_LDB(B1, 0, 1); PG8_SCHED; PG8_LDA(At, 0, 0); PG8_STAGE(PG8_SA(1, 1), a1 + hstep, voffA);
;             PG8_WAIT_V(8); PG8_WAIT_L(0); PG8_BAR; PG8_MMA(0, 0, At, B0); PG8_MMA(0, 1, At, B1); PG8_BAR; PG8_SCHED;
;             PG8_LDA(At, 0, 1); PG8_STAGE(PG8_SB(0, 0), b2, voffB); PG8_STAGE(PG8_SB(0, 1), b2 + hstep, voffB); PG8_STAGE(PG8_SA(0, 0), a2, voffA);
;             PG8_WAIT_V(8); PG8_WAIT_L(0); PG8_BAR; PG8_MMA(1, 0, At, B0); PG8_MMA(1, 1, At, B1); PG8_BAR; PG8_SCHED;
.LBB0_542:
	s_add_u32 s12, s10, 0xfff80080
	s_addc_u32 s13, s11, -1
	s_add_i32 s48, 0, 0x10000
	s_cmp_eq_u32 s89, 28
	s_cselect_b32 s15, s25, s13
	s_cselect_b32 s14, s69, s12
	v_add_u32_e32 v100, s48, v221
	s_cselect_b32 s13, s76, s83
	s_cselect_b32 s12, s77, s82
	s_add_i32 s49, 0, 0x14000
	ds_read_b128 v[106:109], v100
	ds_read_b128 v[110:113], v100 offset:1024
	ds_read_b128 v[114:117], v100 offset:2048
	ds_read_b128 v[118:121], v100 offset:3072
	v_add_u32_e32 v100, s49, v221
	ds_read_b128 v[122:125], v100
	ds_read_b128 v[126:129], v100 offset:1024
	ds_read_b128 v[130:133], v100 offset:2048
	ds_read_b128 v[134:137], v100 offset:3072
	v_lshl_add_u64 v[100:101], s[10:11], 0, v[190:191]
	s_add_i32 m0, s1, 0xc000
	ds_read_b128 v[166:169], v222
	ds_read_b128 v[170:173], v222 offset:1024
	ds_read_b128 v[174:177], v222 offset:2048
	ds_read_b128 v[178:181], v222 offset:3072
	ds_read_b128 v[194:197], v222 offset:4096
	ds_read_b128 v[206:209], v222 offset:5120
	ds_read_b128 v[210:213], v222 offset:6144
	ds_read_b128 v[214:217], v222 offset:7168
	global_load_lds_dwordx4 v[100:101], off
	v_lshl_add_u64 v[100:101], s[10:11], 0, v[192:193]
	s_add_i32 m0, s1, 0xe000
	s_nop 0
	global_load_lds_dwordx4 v[100:101], off
	s_waitcnt vmcnt(8)
	s_waitcnt lgkmcnt(0)
	s_setprio 1
	s_barrier
	v_mfma_f32_16x16x32_bf16 v[4:7], v[106:109], v[166:169], v[4:7]
	v_mfma_f32_16x16x32_bf16 v[72:75], v[114:117], v[166:169], v[72:75]
	v_mfma_f32_16x16x32_bf16 v[162:165], v[106:109], v[174:177], v[162:165]
	v_mfma_f32_16x16x32_bf16 v[60:63], v[114:117], v[174:177], v[60:63]
	v_mfma_f32_16x16x32_bf16 v[158:161], v[106:109], v[194:197], v[158:161]
	v_mfma_f32_16x16x32_bf16 v[56:59], v[114:117], v[194:197], v[56:59]
	v_mfma_f32_16x16x32_bf16 v[96:99], v[106:109], v[210:213], v[96:99]
	v_mfma_f32_16x16x32_bf16 v[76:79], v[114:117], v[210:213], v[76:79]
	v_mfma_f32_16x16x32_bf16 v[4:7], v[110:113], v[170:173], v[4:7]
	v_mfma_f32_16x16x32_bf16 v[72:75], v[118:121], v[170:173], v[72:75]
	v_mfma_f32_16x16x32_bf16 v[162:165], v[110:113], v[178:181], v[162:165]
	v_mfma_f32_16x16x32_bf16 v[60:63], v[118:121], v[178:181], v[60:63]
	v_mfma_f32_16x16x32_bf16 v[158:161], v[110:113], v[206:209], v[158:161]
	v_mfma_f32_16x16x32_bf16 v[56:59], v[118:121], v[206:209], v[56:59]
	v_mfma_f32_16x16x32_bf16 v[96:99], v[110:113], v[214:217], v[96:99]
	v_mfma_f32_16x16x32_bf16 v[76:79], v[118:121], v[214:217], v[76:79]
	s_setprio 0
	s_setprio 1
	v_mfma_f32_16x16x32_bf16 v[8:11], v[122:125], v[166:169], v[8:11]
	v_mfma_f32_16x16x32_bf16 v[64:67], v[130:133], v[166:169], v[64:67]
	v_mfma_f32_16x16x32_bf16 v[154:157], v[122:125], v[174:177], v[154:157]
	v_mfma_f32_16x16x32_bf16 v[52:55], v[130:133], v[174:177], v[52:55]
	v_mfma_f32_16x16x32_bf16 v[150:153], v[122:125], v[194:197], v[150:153]
	v_mfma_f32_16x16x32_bf16 v[48:51], v[130:133], v[194:197], v[48:51]
	v_mfma_f32_16x16x32_bf16 v[92:95], v[122:125], v[210:213], v[92:95]
	v_mfma_f32_16x16x32_bf16 v[68:71], v[130:133], v[210:213], v[68:71]
	v_mfma_f32_16x16x32_bf16 v[8:11], v[126:129], v[170:173], v[8:11]
	v_mfma_f32_16x16x32_bf16 v[64:67], v[134:137], v[170:173], v[64:67]
	v_mfma_f32_16x16x32_bf16 v[154:157], v[126:129], v[178:181], v[154:157]
	v_mfma_f32_16x16x32_bf16 v[52:55], v[134:137], v[178:181], v[52:55]
	v_mfma_f32_16x16x32_bf16 v[150:153], v[126:129], v[206:209], v[150:153]
	v_mfma_f32_16x16x32_bf16 v[48:51], v[134:137], v[206:209], v[48:51]
	v_mfma_f32_16x16x32_bf16 v[92:95], v[126:129], v[214:217], v[92:95]
	v_mfma_f32_16x16x32_bf16 v[68:71], v[134:137], v[214:217], v[68:71]
	s_barrier
	s_setprio 0
	s_add_i32 s48, s48, s0
	v_lshl_add_u64 v[198:199], s[12:13], 0, v[186:187]
	s_mov_b32 m0, s48
	ds_read_b128 v[166:169], v222 offset:16384
	ds_read_b128 v[170:173], v222 offset:17408
	ds_read_b128 v[174:177], v222 offset:18432
	ds_read_b128 v[178:181], v222 offset:19456
	ds_read_b128 v[194:197], v222 offset:20480
	ds_read_b128 v[206:209], v222 offset:21504
	ds_read_b128 v[210:213], v222 offset:22528
	ds_read_b128 v[214:217], v222 offset:23552
	global_load_lds_dwordx4 v[198:199], off
	s_add_i32 m0, s48, 0x2000
	s_add_u32 vcc_lo, s12, 0x80000
	v_lshl_add_u64 v[218:219], s[12:13], 0, v[182:183]
	s_addc_u32 vcc_hi, s13, 0
	s_add_i32 s48, s49, s0
	global_load_lds_dwordx4 v[218:219], off
	v_lshl_add_u64 v[100:101], vcc, 0, v[186:187]
	s_mov_b32 m0, s48
	v_lshl_add_u64 v[224:225], s[14:15], 0, v[188:189]
	global_load_lds_dwordx4 v[100:101], off
	v_lshl_add_u64 v[100:101], vcc, 0, v[182:183]
	s_add_i32 m0, s48, 0x2000
	v_lshl_add_u64 v[232:233], s[14:15], 0, v[184:185]
	global_load_lds_dwordx4 v[100:101], off
	s_mov_b32 m0, s1
	s_nop 0
	global_load_lds_dwordx4 v[224:225], off
	s_mov_b32 m0, s4
	s_nop 0
	global_load_lds_dwordx4 v[232:233], off
	s_waitcnt vmcnt(8)
	s_waitcnt lgkmcnt(0)
	s_setprio 1
	s_barrier
; #define PG8_STAGE(bufoff, gbase, voff) do { _Pragma("unroll") for (int _i = 0; _i < 2; ++_i) \
;         __builtin_amdgcn_global_load_lds((const unsigned*)((const char*)(gbase) + (voff)[_i]), (PG8_LAS unsigned*)(lds + (bufoff) + ldsw + _i * 8192), 16, 0, 0); } while (0)
; #define PG8_LDA(dst, b, h) do { _Pragma("unroll") for (int m = 0; m < 4; ++m) _Pragma("unroll") for (int k = 0; k < 2; ++k) dst[m][k] = *(const PG8_LAS bf16x8*)(lds + PG8_SA(b, h) + aoff + m * 2048 + k * 1024); } while (0)
; #define PG8_LDB(dst, b, h) do { _Pragma("unroll") for (int n = 0; n < 2; ++n) _Pragma("unroll") for (int k = 0; k < 2; ++k) dst[n][k] = *(const PG8_LAS bf16x8*)(lds + PG8_SB(b, h) + boff + n * 2048 + k * 1024); } while (0)
; #define PG8_MMA(ai, bj, At, Bt) do { __builtin_amdgcn_s_setprio(1); _Pragma("unroll") for (int m = 0; m < 4; ++m) _Pragma("unroll") for (int n = 0; n < 2; ++n) _Pragma("unroll") for (int k = 0; k < 2; ++k) \
;         acc[ai][bj][m][n] = __builtin_amdgcn_mfma_f32_16x16x32_bf16(Bt[n][k], At[m][k], acc[ai][bj][m][n], 0, 0, 0); __builtin_amdgcn_s_setprio(0); } while (0)
; #define PG8_WAIT_V(n) asm volatile("s_waitcnt vmcnt(" #n ")" ::: "memory")
; #define PG8_WAIT_L(n) asm volatile("s_waitcnt lgkmcnt(" #n ")" ::: "memory")
; #define PG8_BAR __builtin_amdgcn_s_barrier()
; #define PG8_SCHED __builtin_amdgcn_sched_barrier(0)
;     ...
;             PG8_WAIT_V(8); PG8_WAIT_L(0); PG8_BAR; PG8_MMA(1, 0, At, B0); PG8_MMA(1, 1, At, B1); PG8_BAR; PG8_SCHED;
;             PG8_LDB(B0, 1, 0); PG8_LDB(B1, 1, 1); PG8_SCHED; PG8_LDA(At, 1, 0); PG8_STAGE(PG8_SA(0, 1), a2 + hstep, voffA);
;             PG8_WAIT_V(8); PG8_WAIT_L(0); PG8_BAR; PG8_MMA(0, 0, At, B0); PG8_MMA(0, 1, At, B1); PG8_BAR; PG8_SCHED;
	v_mfma_f32_16x16x32_bf16 v[146:149], v[106:109], v[166:169], v[146:149]
	v_mfma_f32_16x16x32_bf16 v[44:47], v[114:117], v[166:169], v[44:47]
	v_mfma_f32_16x16x32_bf16 v[142:145], v[106:109], v[174:177], v[142:145]
	v_mfma_f32_16x16x32_bf16 v[40:43], v[114:117], v[174:177], v[40:43]
	v_mfma_f32_16x16x32_bf16 v[138:141], v[106:109], v[194:197], v[138:141]
	v_mfma_f32_16x16x32_bf16 v[36:39], v[114:117], v[194:197], v[36:39]
	v_mfma_f32_16x16x32_bf16 v[80:83], v[106:109], v[210:213], v[80:83]
	v_mfma_f32_16x16x32_bf16 v[20:23], v[114:117], v[210:213], v[20:23]
	v_mfma_f32_16x16x32_bf16 v[146:149], v[110:113], v[170:173], v[146:149]
	v_mfma_f32_16x16x32_bf16 v[44:47], v[118:121], v[170:173], v[44:47]
	v_mfma_f32_16x16x32_bf16 v[142:145], v[110:113], v[178:181], v[142:145]
	v_mfma_f32_16x16x32_bf16 v[40:43], v[118:121], v[178:181], v[40:43]
	v_mfma_f32_16x16x32_bf16 v[138:141], v[110:113], v[206:209], v[138:141]
	v_mfma_f32_16x16x32_bf16 v[36:39], v[118:121], v[206:209], v[36:39]
	v_mfma_f32_16x16x32_bf16 v[80:83], v[110:113], v[214:217], v[80:83]
	v_mfma_f32_16x16x32_bf16 v[20:23], v[118:121], v[214:217], v[20:23]
	s_setprio 0
	s_setprio 1
	v_mfma_f32_16x16x32_bf16 v[100:103], v[122:125], v[166:169], v[102:105]
	v_mfma_f32_16x16x32_bf16 v[32:35], v[130:133], v[166:169], v[32:35]
	v_mfma_f32_16x16x32_bf16 v[88:91], v[122:125], v[174:177], v[88:91]
	v_mfma_f32_16x16x32_bf16 v[28:31], v[130:133], v[174:177], v[28:31]
	v_mfma_f32_16x16x32_bf16 v[84:87], v[122:125], v[194:197], v[84:87]
	v_mfma_f32_16x16x32_bf16 v[24:27], v[130:133], v[194:197], v[24:27]
	v_mfma_f32_16x16x32_bf16 v[16:19], v[122:125], v[210:213], v[16:19]
	v_mfma_f32_16x16x32_bf16 v[12:15], v[130:133], v[210:213], v[12:15]
	v_mfma_f32_16x16x32_bf16 v[100:103], v[126:129], v[170:173], v[100:103]
	v_mfma_f32_16x16x32_bf16 v[32:35], v[134:137], v[170:173], v[32:35]
	v_mfma_f32_16x16x32_bf16 v[88:91], v[126:129], v[178:181], v[88:91]
	v_mfma_f32_16x16x32_bf16 v[28:31], v[134:137], v[178:181], v[28:31]
	v_mfma_f32_16x16x32_bf16 v[84:87], v[126:129], v[206:209], v[84:87]
	v_mfma_f32_16x16x32_bf16 v[24:27], v[134:137], v[206:209], v[24:27]
	v_mfma_f32_16x16x32_bf16 v[16:19], v[126:129], v[214:217], v[16:19]
	v_mfma_f32_16x16x32_bf16 v[12:15], v[134:137], v[214:217], v[12:15]
	s_barrier
	s_setprio 0
	s_add_i32 s48, 0, 0x18000
	s_add_i32 s49, 0, 0x1c000
	v_add_u32_e32 v116, s48, v221
	v_add_u32_e32 v132, s49, v221
	ds_read_b128 v[104:107], v116
	ds_read_b128 v[108:111], v116 offset:1024
	ds_read_b128 v[112:115], v116 offset:2048
	ds_read_b128 v[116:119], v116 offset:3072
	ds_read_b128 v[120:123], v132
	ds_read_b128 v[124:127], v132 offset:1024
	ds_read_b128 v[128:131], v132 offset:2048
	ds_read_b128 v[132:135], v132 offset:3072
	s_add_u32 s14, s14, 0x80000
	s_addc_u32 s15, s15, 0
	s_mov_b32 m0, s5
	v_lshl_add_u64 v[136:137], s[14:15], 0, v[188:189]
	ds_read_b128 v[166:169], v222 offset:32768
	ds_read_b128 v[170:173], v222 offset:33792
	ds_read_b128 v[174:177], v222 offset:34816
	ds_read_b128 v[178:181], v222 offset:35840
	ds_read_b128 v[194:197], v222 offset:36864
	ds_read_b128 v[206:209], v222 offset:37888
	ds_read_b128 v[210:213], v222 offset:38912
	ds_read_b128 v[214:217], v222 offset:39936
	global_load_lds_dwordx4 v[136:137], off
	v_lshl_add_u64 v[136:137], s[14:15], 0, v[184:185]
	s_mov_b32 m0, s44
	s_nop 0
	global_load_lds_dwordx4 v[136:137], off
	s_waitcnt vmcnt(8)
	s_waitcnt lgkmcnt(0)
	s_setprio 1
	s_barrier
	v_mfma_f32_16x16x32_bf16 v[4:7], v[104:107], v[166:169], v[4:7]
	v_mfma_f32_16x16x32_bf16 v[72:75], v[112:115], v[166:169], v[72:75]
	v_mfma_f32_16x16x32_bf16 v[162:165], v[104:107], v[174:177], v[162:165]
	v_mfma_f32_16x16x32_bf16 v[60:63], v[112:115], v[174:177], v[60:63]
	v_mfma_f32_16x16x32_bf16 v[158:161], v[104:107], v[194:197], v[158:161]
	v_mfma_f32_16x16x32_bf16 v[56:59], v[112:115], v[194:197], v[56:59]
	v_mfma_f32_16x16x32_bf16 v[96:99], v[104:107], v[210:213], v[96:99]
	v_mfma_f32_16x16x32_bf16 v[76:79], v[112:115], v[210:213], v[76:79]
	v_mfma_f32_16x16x32_bf16 v[4:7], v[108:111], v[170:173], v[4:7]
	v_mfma_f32_16x16x32_bf16 v[72:75], v[116:119], v[170:173], v[72:75]
	v_mfma_f32_16x16x32_bf16 v[162:165], v[108:111], v[178:181], v[162:165]
	v_mfma_f32_16x16x32_bf16 v[60:63], v[116:119], v[178:181], v[60:63]
	v_mfma_f32_16x16x32_bf16 v[158:161], v[108:111], v[206:209], v[158:161]
	v_mfma_f32_16x16x32_bf16 v[56:59], v[116:119], v[206:209], v[56:59]
	v_mfma_f32_16x16x32_bf16 v[96:99], v[108:111], v[214:217], v[96:99]
	v_mfma_f32_16x16x32_bf16 v[76:79], v[116:119], v[214:217], v[76:79]
	s_setprio 0
	s_setprio 1
	v_mfma_f32_16x16x32_bf16 v[8:11], v[120:123], v[166:169], v[8:11]
	v_mfma_f32_16x16x32_bf16 v[64:67], v[128:131], v[166:169], v[64:67]
	v_mfma_f32_16x16x32_bf16 v[154:157], v[120:123], v[174:177], v[154:157]
	v_mfma_f32_16x16x32_bf16 v[52:55], v[128:131], v[174:177], v[52:55]
	v_mfma_f32_16x16x32_bf16 v[150:153], v[120:123], v[194:197], v[150:153]
	v_mfma_f32_16x16x32_bf16 v[48:51], v[128:131], v[194:197], v[48:51]
	v_mfma_f32_16x16x32_bf16 v[92:95], v[120:123], v[210:213], v[92:95]
	v_mfma_f32_16x16x32_bf16 v[68:71], v[128:131], v[210:213], v[68:71]
	v_mfma_f32_16x16x32_bf16 v[8:11], v[124:127], v[170:173], v[8:11]
	v_mfma_f32_16x16x32_bf16 v[64:67], v[132:135], v[170:173], v[64:67]
	v_mfma_f32_16x16x32_bf16 v[154:157], v[124:127], v[178:181], v[154:157]
	v_mfma_f32_16x16x32_bf16 v[52:55], v[132:135], v[178:181], v[52:55]
	v_mfma_f32_16x16x32_bf16 v[150:153], v[124:127], v[206:209], v[150:153]
	v_mfma_f32_16x16x32_bf16 v[48:51], v[132:135], v[206:209], v[48:51]
	v_mfma_f32_16x16x32_bf16 v[92:95], v[124:127], v[214:217], v[92:95]
	v_mfma_f32_16x16x32_bf16 v[68:71], v[132:135], v[214:217], v[68:71]
	s_barrier
; #define PG8_STAGE(bufoff, gbase, voff) do { _Pragma("unroll") for (int _i = 0; _i < 2; ++_i) \
;         __builtin_amdgcn_global_load_lds((const unsigned*)((const char*)(gbase) + (voff)[_i]), (PG8_LAS unsigned*)(lds + (bufoff) + ldsw + _i * 8192), 16, 0, 0); } while (0)
; #define PG8_LDA(dst, b, h) do { _Pragma("unroll") for (int m = 0; m < 4; ++m) _Pragma("unroll") for (int k = 0; k < 2; ++k) dst[m][k] = *(const PG8_LAS bf16x8*)(lds + PG8_SA(b, h) + aoff + m * 2048 + k * 1024); } while (0)
; #define PG8_MMA(ai, bj, At, Bt) do { __builtin_amdgcn_s_setprio(1); _Pragma("unroll") for (int m = 0; m < 4; ++m) _Pragma("unroll") for (int n = 0; n < 2; ++n) _Pragma("unroll") for (int k = 0; k < 2; ++k) \
;         acc[ai][bj][m][n] = __builtin_amdgcn_mfma_f32_16x16x32_bf16(Bt[n][k], At[m][k], acc[ai][bj][m][n], 0, 0, 0); __builtin_amdgcn_s_setprio(0); } while (0)
; #define PG8_WAIT_V(n) asm volatile("s_waitcnt vmcnt(" #n ")" ::: "memory")
; #define PG8_WAIT_L(n) asm volatile("s_waitcnt lgkmcnt(" #n ")" ::: "memory")
; #define PG8_BAR __builtin_amdgcn_s_barrier()
; #define PG8_SCHED __builtin_amdgcn_sched_barrier(0)
;     ...
;             PG8_WAIT_V(8); PG8_WAIT_L(0); PG8_BAR; PG8_MMA(0, 0, At, B0); PG8_MMA(0, 1, At, B1); PG8_BAR; PG8_SCHED;
;             PG8_LDA(At, 1, 1); PG8_STAGE(PG8_SB(1, 0), b3, voffB); PG8_STAGE(PG8_SB(1, 1), b3 + hstep, voffB); PG8_STAGE(PG8_SA(1, 0), a3, voffA);
;             PG8_WAIT_V(8); PG8_WAIT_L(0); PG8_BAR; PG8_MMA(1, 0, At, B0); PG8_MMA(1, 1, At, B1); PG8_BAR; PG8_SCHED;
;     ...
;         if constexpr (ALIGN_EPI) { if (wr == 0) PG8_BAR; }
	s_setprio 0
	s_add_i32 s14, s48, s0
	v_lshl_add_u64 v[136:137], v[198:199], 0, s[66:67]
	s_mov_b32 m0, s14
	ds_read_b128 v[166:169], v222 offset:49152
	ds_read_b128 v[170:173], v222 offset:50176
	ds_read_b128 v[174:177], v222 offset:51200
	ds_read_b128 v[178:181], v222 offset:52224
	ds_read_b128 v[194:197], v222 offset:53248
	ds_read_b128 v[206:209], v222 offset:54272
	ds_read_b128 v[210:213], v222 offset:55296
	ds_read_b128 v[214:217], v222 offset:56320
	global_load_lds_dwordx4 v[136:137], off
	s_add_i32 m0, s14, 0x2000
	s_add_u32 s12, s12, 0x80080
	v_lshl_add_u64 v[136:137], v[218:219], 0, s[66:67]
	s_addc_u32 s13, s13, 0
	s_add_i32 s14, s49, s0
	global_load_lds_dwordx4 v[136:137], off
	v_lshl_add_u64 v[136:137], s[12:13], 0, v[186:187]
	s_mov_b32 m0, s14
	s_nop 0
	global_load_lds_dwordx4 v[136:137], off
	v_lshl_add_u64 v[136:137], s[12:13], 0, v[182:183]
	s_add_i32 m0, s14, 0x2000
	s_nop 0
	global_load_lds_dwordx4 v[136:137], off
	v_lshl_add_u64 v[136:137], v[224:225], 0, s[66:67]
	s_mov_b32 m0, s81
	s_nop 0
	global_load_lds_dwordx4 v[136:137], off
	v_lshl_add_u64 v[136:137], v[232:233], 0, s[66:67]
	s_mov_b32 m0, s42
	s_nop 0
	global_load_lds_dwordx4 v[136:137], off
	s_waitcnt vmcnt(8)
	s_waitcnt lgkmcnt(0)
	s_setprio 1
	s_barrier
	v_mfma_f32_16x16x32_bf16 v[146:149], v[104:107], v[166:169], v[146:149]
	v_mfma_f32_16x16x32_bf16 v[44:47], v[112:115], v[166:169], v[44:47]
	v_mfma_f32_16x16x32_bf16 v[142:145], v[104:107], v[174:177], v[142:145]
	v_mfma_f32_16x16x32_bf16 v[40:43], v[112:115], v[174:177], v[40:43]
	v_mfma_f32_16x16x32_bf16 v[136:139], v[104:107], v[194:197], v[138:141]
	v_mfma_f32_16x16x32_bf16 v[36:39], v[112:115], v[194:197], v[36:39]
	v_mfma_f32_16x16x32_bf16 v[80:83], v[104:107], v[210:213], v[80:83]
	v_mfma_f32_16x16x32_bf16 v[20:23], v[112:115], v[210:213], v[20:23]
	v_mfma_f32_16x16x32_bf16 v[146:149], v[108:111], v[170:173], v[146:149]
	v_mfma_f32_16x16x32_bf16 v[44:47], v[116:119], v[170:173], v[44:47]
	v_mfma_f32_16x16x32_bf16 v[142:145], v[108:111], v[178:181], v[142:145]
	v_mfma_f32_16x16x32_bf16 v[40:43], v[116:119], v[178:181], v[40:43]
	v_mfma_f32_16x16x32_bf16 v[138:141], v[108:111], v[206:209], v[136:139]
	v_mfma_f32_16x16x32_bf16 v[36:39], v[116:119], v[206:209], v[36:39]
	v_mfma_f32_16x16x32_bf16 v[80:83], v[108:111], v[214:217], v[80:83]
	v_mfma_f32_16x16x32_bf16 v[20:23], v[116:119], v[214:217], v[20:23]
	s_setprio 0
	s_setprio 1
	v_mfma_f32_16x16x32_bf16 v[100:103], v[120:123], v[166:169], v[100:103]
	v_mfma_f32_16x16x32_bf16 v[32:35], v[128:131], v[166:169], v[32:35]
	v_mfma_f32_16x16x32_bf16 v[88:91], v[120:123], v[174:177], v[88:91]
	v_mfma_f32_16x16x32_bf16 v[28:31], v[128:131], v[174:177], v[28:31]
	v_mfma_f32_16x16x32_bf16 v[84:87], v[120:123], v[194:197], v[84:87]
	v_mfma_f32_16x16x32_bf16 v[24:27], v[128:131], v[194:197], v[24:27]
	v_mfma_f32_16x16x32_bf16 v[16:19], v[120:123], v[210:213], v[16:19]
	v_mfma_f32_16x16x32_bf16 v[12:15], v[128:131], v[210:213], v[12:15]
	v_mfma_f32_16x16x32_bf16 v[102:105], v[124:127], v[170:173], v[100:103]
	v_mfma_f32_16x16x32_bf16 v[32:35], v[132:135], v[170:173], v[32:35]
	v_mfma_f32_16x16x32_bf16 v[88:91], v[124:127], v[178:181], v[88:91]
	v_mfma_f32_16x16x32_bf16 v[28:31], v[132:135], v[178:181], v[28:31]
	v_mfma_f32_16x16x32_bf16 v[84:87], v[124:127], v[206:209], v[84:87]
	v_mfma_f32_16x16x32_bf16 v[24:27], v[132:135], v[206:209], v[24:27]
	v_mfma_f32_16x16x32_bf16 v[16:19], v[124:127], v[214:217], v[16:19]
	v_mfma_f32_16x16x32_bf16 v[12:15], v[132:135], v[214:217], v[12:15]
	s_barrier
	s_setprio 0
	s_add_i32 s89, s89, 2
	s_add_u32 s10, s10, 0x100
	s_addc_u32 s11, s11, 0
	s_add_u32 s82, s82, 0x100
	s_addc_u32 s83, s83, 0
	s_cmp_gt_u32 s89, 29
	s_cbranch_scc0 .LBB0_542
	s_and_b64 vcc, exec, s[70:71]
	s_cbranch_vccz .LBB0_545
	s_barrier

;     __device__ __forceinline__ bool next(int i, Unit& u) const { if (i >= n) return false; u.pm = pm; u.pn = pn0 + i; return true; }
;     __device__ __forceinline__ bool next(int i, Unit& u) const { if (i) return false; u.pm = pm; u.pn = pn; return true; }
; #define PG8_STAGE(bufoff, gbase, voff) do { _Pragma("unroll") for (int _i = 0; _i < 2; ++_i) \
;         __builtin_amdgcn_global_load_lds((const unsigned*)((const char*)(gbase) + (voff)[_i]), (PG8_LAS unsigned*)(lds + (bufoff) + ldsw + _i * 8192), 16, 0, 0); } while (0)
; #define PG8_LDA(dst, b, h) do { _Pragma("unroll") for (int m = 0; m < 4; ++m) _Pragma("unroll") for (int k = 0; k < 2; ++k) dst[m][k] = *(const PG8_LAS bf16x8*)(lds + PG8_SA(b, h) + aoff + m * 2048 + k * 1024); } while (0)
; #define PG8_LDB(dst, b, h) do { _Pragma("unroll") for (int n = 0; n < 2; ++n) _Pragma("unroll") for (int k = 0; k < 2; ++k) dst[n][k] = *(const PG8_LAS bf16x8*)(lds + PG8_SB(b, h) + boff + n * 2048 + k * 1024); } while (0)
; #define PG8_WAIT_V(n) asm volatile("s_waitcnt vmcnt(" #n ")" ::: "memory")
; #define PG8_BAR __builtin_amdgcn_s_barrier()
;     ...
;         const bool has_next = S.next(ui + 1, nxt);
;         const char* nA = has_next ? (const char*)g.A + (size_t)nxt.pm * tstep : cA; const char* nB = has_next ? (const char*)g.Bt + (size_t)nxt.pn * tstep : cB;
;         for (int t = 0; t < nt; t += 2) {
;             const bool last = (t == nt - 2);
;             const char* a1 = cA + (size_t)(t + 1) * kstep;
;             const char* a2 = last ? nA : cA + (size_t)(t + 2) * kstep; const char* b2 = last ? nB : cB + (size_t)(t + 2) * kstep;
;             const char* a3 = a2 + kstep; const char* b3 = b2 + kstep;
;             if (last && has_next) S.a_ready(nxt);
;             if (t == 0) E.pre_issue(pre, cur, tid, ui); else if (t == 2) E.pre_finish(pre, tid, ui);
;             if constexpr (SP2) {
;             PG8_LDB(B0, 0, 0); PG8_LDB(B1, 0, 1); PG8_SCHED; PG8_LDA(At, 0, 0); PG8_STAGE(PG8_SA(1, 1), a1 + hstep, voffA);
;             PG8_WAIT_V(8); PG8_WAIT_L(0); PG8_BAR; PG8_MMA(0, 0, At, B0); PG8_MMA(0, 1, At, B1); PG8_BAR; PG8_SCHED;
;             PG8_LDA(At, 0, 1); PG8_STAGE(PG8_SB(0, 0), b2, voffB); PG8_STAGE(PG8_SB(0, 1), b2 + hstep, voffB); PG8_STAGE(PG8_SA(0, 0), a2, voffA);
;             PG8_WAIT_V(8); PG8_WAIT_L(0); PG8_BAR; PG8_MMA(1, 0, At, B0); PG8_MMA(1, 1, At, B1); PG8_BAR; PG8_SCHED;
.LBB0_667:
	s_add_u32 s68, s62, 0x100
	s_addc_u32 s69, s63, 0
	s_add_i32 s48, 0, 0x10000
	s_cmpk_eq_i32 s78, 0x54
	s_cselect_b32 s77, s11, s69
	s_cselect_b32 s76, s10, s68
	s_cselect_b32 s71, s61, s75
	s_cselect_b32 s70, s60, s73
	s_add_i32 s49, 0, 0x14000
	v_add_u32_e32 v136, s48, v233
	v_add_u32_e32 v160, s49, v233
	ds_read_b128 v[108:111], v136
	ds_read_b128 v[112:115], v136 offset:1024
	ds_read_b128 v[128:131], v136 offset:2048
	ds_read_b128 v[136:139], v136 offset:3072
	ds_read_b128 v[148:151], v160
	ds_read_b128 v[152:155], v160 offset:1024
	ds_read_b128 v[156:159], v160 offset:2048
	ds_read_b128 v[160:163], v160 offset:3072
	v_lshl_add_u64 v[198:199], s[62:63], 0, v[196:197]
	s_add_i32 m0, s6, 0xc000
	ds_read_b128 v[164:167], v234
	ds_read_b128 v[168:171], v234 offset:1024
	ds_read_b128 v[172:175], v234 offset:2048
	ds_read_b128 v[176:179], v234 offset:3072
	ds_read_b128 v[180:183], v234 offset:4096
	ds_read_b128 v[184:187], v234 offset:5120
	ds_read_b128 v[206:209], v234 offset:6144
	ds_read_b128 v[210:213], v234 offset:7168
	global_load_lds_dwordx4 v[198:199], off
	v_lshl_add_u64 v[198:199], s[62:63], 0, v[194:195]
	s_add_i32 m0, s6, 0xe000
	s_nop 0
	global_load_lds_dwordx4 v[198:199], off
	s_waitcnt vmcnt(8)
	s_waitcnt lgkmcnt(0)
	s_setprio 1
	s_barrier
	v_mfma_f32_16x16x32_bf16 v[144:147], v[108:111], v[164:167], v[144:147]
	v_mfma_f32_16x16x32_bf16 v[140:143], v[128:131], v[164:167], v[140:143]
	v_mfma_f32_16x16x32_bf16 v[120:123], v[108:111], v[172:175], v[120:123]
	v_mfma_f32_16x16x32_bf16 v[116:119], v[128:131], v[172:175], v[116:119]
	v_mfma_f32_16x16x32_bf16 v[96:99], v[108:111], v[180:183], v[96:99]
	v_mfma_f32_16x16x32_bf16 v[92:95], v[128:131], v[180:183], v[92:95]
	v_mfma_f32_16x16x32_bf16 v[80:83], v[108:111], v[206:209], v[80:83]
	v_mfma_f32_16x16x32_bf16 v[76:79], v[128:131], v[206:209], v[76:79]
	v_mfma_f32_16x16x32_bf16 v[144:147], v[112:115], v[168:171], v[144:147]
	v_mfma_f32_16x16x32_bf16 v[140:143], v[136:139], v[168:171], v[140:143]
	v_mfma_f32_16x16x32_bf16 v[120:123], v[112:115], v[176:179], v[120:123]
	v_mfma_f32_16x16x32_bf16 v[116:119], v[136:139], v[176:179], v[116:119]
	v_mfma_f32_16x16x32_bf16 v[96:99], v[112:115], v[184:187], v[96:99]
	v_mfma_f32_16x16x32_bf16 v[92:95], v[136:139], v[184:187], v[92:95]
	v_mfma_f32_16x16x32_bf16 v[80:83], v[112:115], v[210:213], v[80:83]
	v_mfma_f32_16x16x32_bf16 v[76:79], v[136:139], v[210:213], v[76:79]
	s_setprio 0
	s_setprio 1
	v_mfma_f32_16x16x32_bf16 v[132:135], v[148:151], v[164:167], v[132:135]
	v_mfma_f32_16x16x32_bf16 v[124:127], v[156:159], v[164:167], v[124:127]
	v_mfma_f32_16x16x32_bf16 v[104:107], v[148:151], v[172:175], v[104:107]
	v_mfma_f32_16x16x32_bf16 v[100:103], v[156:159], v[172:175], v[100:103]
	v_mfma_f32_16x16x32_bf16 v[88:91], v[148:151], v[180:183], v[88:91]
	v_mfma_f32_16x16x32_bf16 v[84:87], v[156:159], v[180:183], v[84:87]
	v_mfma_f32_16x16x32_bf16 v[72:75], v[148:151], v[206:209], v[72:75]
	v_mfma_f32_16x16x32_bf16 v[68:71], v[156:159], v[206:209], v[68:71]
	v_mfma_f32_16x16x32_bf16 v[132:135], v[152:155], v[168:171], v[132:135]
	v_mfma_f32_16x16x32_bf16 v[124:127], v[160:163], v[168:171], v[124:127]
	v_mfma_f32_16x16x32_bf16 v[104:107], v[152:155], v[176:179], v[104:107]
	v_mfma_f32_16x16x32_bf16 v[100:103], v[160:163], v[176:179], v[100:103]
	v_mfma_f32_16x16x32_bf16 v[88:91], v[152:155], v[184:187], v[88:91]
	v_mfma_f32_16x16x32_bf16 v[84:87], v[160:163], v[184:187], v[84:87]
	v_mfma_f32_16x16x32_bf16 v[72:75], v[152:155], v[210:213], v[72:75]
	v_mfma_f32_16x16x32_bf16 v[68:71], v[160:163], v[210:213], v[68:71]
	s_barrier
	s_setprio 0
	s_add_i32 s48, s48, s5
	v_lshl_add_u64 v[198:199], s[70:71], 0, v[200:201]
	s_mov_b32 m0, s48
	ds_read_b128 v[164:167], v234 offset:16384
	ds_read_b128 v[168:171], v234 offset:17408
	ds_read_b128 v[172:175], v234 offset:18432
	ds_read_b128 v[176:179], v234 offset:19456
	ds_read_b128 v[180:183], v234 offset:20480
	ds_read_b128 v[184:187], v234 offset:21504
	ds_read_b128 v[206:209], v234 offset:22528
	ds_read_b128 v[210:213], v234 offset:23552
	global_load_lds_dwordx4 v[198:199], off
	s_add_i32 m0, s48, 0x2000
	s_add_u32 s62, s70, 0x160000
	v_lshl_add_u64 v[214:215], s[70:71], 0, v[188:189]
	s_addc_u32 s63, s71, 0
	s_add_i32 s48, s49, s5
	global_load_lds_dwordx4 v[214:215], off
	v_lshl_add_u64 v[216:217], s[62:63], 0, v[200:201]
	s_mov_b32 m0, s48
	v_lshl_add_u64 v[218:219], s[76:77], 0, v[190:191]
	global_load_lds_dwordx4 v[216:217], off
	v_lshl_add_u64 v[216:217], s[62:63], 0, v[188:189]
	s_add_i32 m0, s48, 0x2000
	s_nop 0
	global_load_lds_dwordx4 v[216:217], off
	v_lshl_add_u64 v[216:217], s[76:77], 0, v[192:193]
	s_mov_b32 m0, s6
	s_nop 0
	global_load_lds_dwordx4 v[216:217], off
	s_mov_b32 m0, s7
	s_nop 0
	global_load_lds_dwordx4 v[218:219], off
	s_waitcnt vmcnt(8)
	s_waitcnt lgkmcnt(0)
	s_setprio 1
	s_barrier
; #define PG8_STAGE(bufoff, gbase, voff) do { _Pragma("unroll") for (int _i = 0; _i < 2; ++_i) \
;         __builtin_amdgcn_global_load_lds((const unsigned*)((const char*)(gbase) + (voff)[_i]), (PG8_LAS unsigned*)(lds + (bufoff) + ldsw + _i * 8192), 16, 0, 0); } while (0)
; #define PG8_LDA(dst, b, h) do { _Pragma("unroll") for (int m = 0; m < 4; ++m) _Pragma("unroll") for (int k = 0; k < 2; ++k) dst[m][k] = *(const PG8_LAS bf16x8*)(lds + PG8_SA(b, h) + aoff + m * 2048 + k * 1024); } while (0)
; #define PG8_LDB(dst, b, h) do { _Pragma("unroll") for (int n = 0; n < 2; ++n) _Pragma("unroll") for (int k = 0; k < 2; ++k) dst[n][k] = *(const PG8_LAS bf16x8*)(lds + PG8_SB(b, h) + boff + n * 2048 + k * 1024); } while (0)
; #define PG8_MMA(ai, bj, At, Bt) do { __builtin_amdgcn_s_setprio(1); _Pragma("unroll") for (int m = 0; m < 4; ++m) _Pragma("unroll") for (int n = 0; n < 2; ++n) _Pragma("unroll") for (int k = 0; k < 2; ++k) \
;         acc[ai][bj][m][n] = __builtin_amdgcn_mfma_f32_16x16x32_bf16(Bt[n][k], At[m][k], acc[ai][bj][m][n], 0, 0, 0); __builtin_amdgcn_s_setprio(0); } while (0)
; #define PG8_WAIT_V(n) asm volatile("s_waitcnt vmcnt(" #n ")" ::: "memory")
; #define PG8_WAIT_L(n) asm volatile("s_waitcnt lgkmcnt(" #n ")" ::: "memory")
; #define PG8_BAR __builtin_amdgcn_s_barrier()
; #define PG8_SCHED __builtin_amdgcn_sched_barrier(0)
;     ...
;             PG8_WAIT_V(8); PG8_WAIT_L(0); PG8_BAR; PG8_MMA(1, 0, At, B0); PG8_MMA(1, 1, At, B1); PG8_BAR; PG8_SCHED;
;             PG8_LDB(B0, 1, 0); PG8_LDB(B1, 1, 1); PG8_SCHED; PG8_LDA(At, 1, 0); PG8_STAGE(PG8_SA(0, 1), a2 + hstep, voffA);
;             PG8_WAIT_V(8); PG8_WAIT_L(0); PG8_BAR; PG8_MMA(0, 0, At, B0); PG8_MMA(0, 1, At, B1); PG8_BAR; PG8_SCHED;
	v_mfma_f32_16x16x32_bf16 v[64:67], v[108:111], v[164:167], v[64:67]
	v_mfma_f32_16x16x32_bf16 v[60:63], v[128:131], v[164:167], v[60:63]
	v_mfma_f32_16x16x32_bf16 v[48:51], v[108:111], v[172:175], v[48:51]
	v_mfma_f32_16x16x32_bf16 v[44:47], v[128:131], v[172:175], v[44:47]
	v_mfma_f32_16x16x32_bf16 v[32:35], v[108:111], v[180:183], v[32:35]
	v_mfma_f32_16x16x32_bf16 v[28:31], v[128:131], v[180:183], v[28:31]
	v_mfma_f32_16x16x32_bf16 v[16:19], v[108:111], v[206:209], v[16:19]
	v_mfma_f32_16x16x32_bf16 v[12:15], v[128:131], v[206:209], v[12:15]
	v_mfma_f32_16x16x32_bf16 v[64:67], v[112:115], v[168:171], v[64:67]
	v_mfma_f32_16x16x32_bf16 v[60:63], v[136:139], v[168:171], v[60:63]
	v_mfma_f32_16x16x32_bf16 v[48:51], v[112:115], v[176:179], v[48:51]
	v_mfma_f32_16x16x32_bf16 v[44:47], v[136:139], v[176:179], v[44:47]
	v_mfma_f32_16x16x32_bf16 v[32:35], v[112:115], v[184:187], v[32:35]
	v_mfma_f32_16x16x32_bf16 v[28:31], v[136:139], v[184:187], v[28:31]
	v_mfma_f32_16x16x32_bf16 v[16:19], v[112:115], v[210:213], v[16:19]
	v_mfma_f32_16x16x32_bf16 v[12:15], v[136:139], v[210:213], v[12:15]
	s_setprio 0
	s_setprio 1
	v_mfma_f32_16x16x32_bf16 v[56:59], v[148:151], v[164:167], v[56:59]
	v_mfma_f32_16x16x32_bf16 v[52:55], v[156:159], v[164:167], v[52:55]
	v_mfma_f32_16x16x32_bf16 v[40:43], v[148:151], v[172:175], v[40:43]
	v_mfma_f32_16x16x32_bf16 v[36:39], v[156:159], v[172:175], v[36:39]
	v_mfma_f32_16x16x32_bf16 v[24:27], v[148:151], v[180:183], v[24:27]
	v_mfma_f32_16x16x32_bf16 v[20:23], v[156:159], v[180:183], v[20:23]
	v_mfma_f32_16x16x32_bf16 v[8:11], v[148:151], v[206:209], v[8:11]
	v_mfma_f32_16x16x32_bf16 v[4:7], v[156:159], v[206:209], v[4:7]
	v_mfma_f32_16x16x32_bf16 v[56:59], v[152:155], v[168:171], v[56:59]
	v_mfma_f32_16x16x32_bf16 v[52:55], v[160:163], v[168:171], v[52:55]
	v_mfma_f32_16x16x32_bf16 v[40:43], v[152:155], v[176:179], v[40:43]
	v_mfma_f32_16x16x32_bf16 v[36:39], v[160:163], v[176:179], v[36:39]
	v_mfma_f32_16x16x32_bf16 v[24:27], v[152:155], v[184:187], v[24:27]
	v_mfma_f32_16x16x32_bf16 v[20:23], v[160:163], v[184:187], v[20:23]
	v_mfma_f32_16x16x32_bf16 v[8:11], v[152:155], v[210:213], v[8:11]
	v_mfma_f32_16x16x32_bf16 v[4:7], v[160:163], v[210:213], v[4:7]
	s_barrier
	s_setprio 0
	s_add_i32 s48, 0, 0x18000
	s_add_i32 s49, 0, 0x1c000
	v_add_u32_e32 v136, s48, v233
	v_add_u32_e32 v160, s49, v233
	ds_read_b128 v[108:111], v136
	ds_read_b128 v[112:115], v136 offset:1024
	ds_read_b128 v[128:131], v136 offset:2048
	ds_read_b128 v[136:139], v136 offset:3072
	ds_read_b128 v[148:151], v160
	ds_read_b128 v[152:155], v160 offset:1024
	ds_read_b128 v[156:159], v160 offset:2048
	ds_read_b128 v[160:163], v160 offset:3072
	s_add_u32 s62, s76, 0x160000
	s_addc_u32 s63, s77, 0
	s_mov_b32 m0, s20
	v_lshl_add_u64 v[220:221], s[62:63], 0, v[192:193]
	ds_read_b128 v[164:167], v234 offset:32768
	ds_read_b128 v[168:171], v234 offset:33792
	ds_read_b128 v[172:175], v234 offset:34816
	ds_read_b128 v[176:179], v234 offset:35840
	ds_read_b128 v[180:183], v234 offset:36864
	ds_read_b128 v[184:187], v234 offset:37888
	ds_read_b128 v[206:209], v234 offset:38912
	ds_read_b128 v[210:213], v234 offset:39936
	global_load_lds_dwordx4 v[220:221], off
	v_lshl_add_u64 v[220:221], s[62:63], 0, v[190:191]
	s_mov_b32 m0, s21
	s_nop 0
	global_load_lds_dwordx4 v[220:221], off
	s_waitcnt vmcnt(8)
	s_waitcnt lgkmcnt(0)
	s_setprio 1
	s_barrier
	v_mfma_f32_16x16x32_bf16 v[144:147], v[108:111], v[164:167], v[144:147]
	v_mfma_f32_16x16x32_bf16 v[140:143], v[128:131], v[164:167], v[140:143]
	v_mfma_f32_16x16x32_bf16 v[120:123], v[108:111], v[172:175], v[120:123]
	v_mfma_f32_16x16x32_bf16 v[116:119], v[128:131], v[172:175], v[116:119]
	v_mfma_f32_16x16x32_bf16 v[96:99], v[108:111], v[180:183], v[96:99]
	v_mfma_f32_16x16x32_bf16 v[92:95], v[128:131], v[180:183], v[92:95]
	v_mfma_f32_16x16x32_bf16 v[80:83], v[108:111], v[206:209], v[80:83]
	v_mfma_f32_16x16x32_bf16 v[76:79], v[128:131], v[206:209], v[76:79]
	v_mfma_f32_16x16x32_bf16 v[144:147], v[112:115], v[168:171], v[144:147]
	v_mfma_f32_16x16x32_bf16 v[140:143], v[136:139], v[168:171], v[140:143]
	v_mfma_f32_16x16x32_bf16 v[120:123], v[112:115], v[176:179], v[120:123]
	v_mfma_f32_16x16x32_bf16 v[116:119], v[136:139], v[176:179], v[116:119]
	v_mfma_f32_16x16x32_bf16 v[96:99], v[112:115], v[184:187], v[96:99]
	v_mfma_f32_16x16x32_bf16 v[92:95], v[136:139], v[184:187], v[92:95]
	v_mfma_f32_16x16x32_bf16 v[80:83], v[112:115], v[210:213], v[80:83]
	v_mfma_f32_16x16x32_bf16 v[76:79], v[136:139], v[210:213], v[76:79]
	s_setprio 0
	s_setprio 1
	v_mfma_f32_16x16x32_bf16 v[132:135], v[148:151], v[164:167], v[132:135]
	v_mfma_f32_16x16x32_bf16 v[124:127], v[156:159], v[164:167], v[124:127]
	v_mfma_f32_16x16x32_bf16 v[104:107], v[148:151], v[172:175], v[104:107]
	v_mfma_f32_16x16x32_bf16 v[100:103], v[156:159], v[172:175], v[100:103]
	v_mfma_f32_16x16x32_bf16 v[88:91], v[148:151], v[180:183], v[88:91]
	v_mfma_f32_16x16x32_bf16 v[84:87], v[156:159], v[180:183], v[84:87]
	v_mfma_f32_16x16x32_bf16 v[72:75], v[148:151], v[206:209], v[72:75]
	v_mfma_f32_16x16x32_bf16 v[68:71], v[156:159], v[206:209], v[68:71]
	v_mfma_f32_16x16x32_bf16 v[132:135], v[152:155], v[168:171], v[132:135]
	v_mfma_f32_16x16x32_bf16 v[124:127], v[160:163], v[168:171], v[124:127]
	v_mfma_f32_16x16x32_bf16 v[104:107], v[152:155], v[176:179], v[104:107]
	v_mfma_f32_16x16x32_bf16 v[100:103], v[160:163], v[176:179], v[100:103]
	v_mfma_f32_16x16x32_bf16 v[88:91], v[152:155], v[184:187], v[88:91]
	v_mfma_f32_16x16x32_bf16 v[84:87], v[160:163], v[184:187], v[84:87]
	v_mfma_f32_16x16x32_bf16 v[72:75], v[152:155], v[210:213], v[72:75]
	v_mfma_f32_16x16x32_bf16 v[68:71], v[160:163], v[210:213], v[68:71]
	s_barrier
; #define PG8_STAGE(bufoff, gbase, voff) do { _Pragma("unroll") for (int _i = 0; _i < 2; ++_i) \
;         __builtin_amdgcn_global_load_lds((const unsigned*)((const char*)(gbase) + (voff)[_i]), (PG8_LAS unsigned*)(lds + (bufoff) + ldsw + _i * 8192), 16, 0, 0); } while (0)
; #define PG8_LDA(dst, b, h) do { _Pragma("unroll") for (int m = 0; m < 4; ++m) _Pragma("unroll") for (int k = 0; k < 2; ++k) dst[m][k] = *(const PG8_LAS bf16x8*)(lds + PG8_SA(b, h) + aoff + m * 2048 + k * 1024); } while (0)
; #define PG8_MMA(ai, bj, At, Bt) do { __builtin_amdgcn_s_setprio(1); _Pragma("unroll") for (int m = 0; m < 4; ++m) _Pragma("unroll") for (int n = 0; n < 2; ++n) _Pragma("unroll") for (int k = 0; k < 2; ++k) \
;         acc[ai][bj][m][n] = __builtin_amdgcn_mfma_f32_16x16x32_bf16(Bt[n][k], At[m][k], acc[ai][bj][m][n], 0, 0, 0); __builtin_amdgcn_s_setprio(0); } while (0)
; #define PG8_WAIT_V(n) asm volatile("s_waitcnt vmcnt(" #n ")" ::: "memory")
; #define PG8_WAIT_L(n) asm volatile("s_waitcnt lgkmcnt(" #n ")" ::: "memory")
; #define PG8_BAR __builtin_amdgcn_s_barrier()
; #define PG8_SCHED __builtin_amdgcn_sched_barrier(0)
;     ...
;             PG8_WAIT_V(8); PG8_WAIT_L(0); PG8_BAR; PG8_MMA(0, 0, At, B0); PG8_MMA(0, 1, At, B1); PG8_BAR; PG8_SCHED;
;             PG8_LDA(At, 1, 1); PG8_STAGE(PG8_SB(1, 0), b3, voffB); PG8_STAGE(PG8_SB(1, 1), b3 + hstep, voffB); PG8_STAGE(PG8_SA(1, 0), a3, voffA);
;             PG8_WAIT_V(8); PG8_WAIT_L(0); PG8_BAR; PG8_MMA(1, 0, At, B0); PG8_MMA(1, 1, At, B1); PG8_BAR; PG8_SCHED;
;     ...
;         if constexpr (ALIGN_EPI) { if (wr == 0) PG8_BAR; }
	s_setprio 0
	s_add_i32 s48, s48, s5
	v_lshl_add_u64 v[198:199], v[198:199], 0, s[66:67]
	s_mov_b32 m0, s48
	ds_read_b128 v[164:167], v234 offset:49152
	ds_read_b128 v[168:171], v234 offset:50176
	ds_read_b128 v[172:175], v234 offset:51200
	ds_read_b128 v[176:179], v234 offset:52224
	ds_read_b128 v[180:183], v234 offset:53248
	ds_read_b128 v[184:187], v234 offset:54272
	ds_read_b128 v[206:209], v234 offset:55296
	ds_read_b128 v[210:213], v234 offset:56320
	global_load_lds_dwordx4 v[198:199], off
	s_add_i32 m0, s48, 0x2000
	s_add_u32 s62, s70, 0x160080
	v_lshl_add_u64 v[198:199], v[214:215], 0, s[66:67]
	s_addc_u32 s63, s71, 0
	s_add_i32 s48, s49, s5
	global_load_lds_dwordx4 v[198:199], off
	v_lshl_add_u64 v[198:199], s[62:63], 0, v[200:201]
	s_mov_b32 m0, s48
	s_nop 0
	global_load_lds_dwordx4 v[198:199], off
	v_lshl_add_u64 v[198:199], s[62:63], 0, v[188:189]
	s_add_i32 m0, s48, 0x2000
	s_nop 0
	global_load_lds_dwordx4 v[198:199], off
	v_lshl_add_u64 v[198:199], v[216:217], 0, s[66:67]
	s_mov_b32 m0, s53
	s_nop 0
	global_load_lds_dwordx4 v[198:199], off
	v_lshl_add_u64 v[198:199], v[218:219], 0, s[66:67]
	s_mov_b32 m0, s54
	s_nop 0
	global_load_lds_dwordx4 v[198:199], off
	s_waitcnt vmcnt(8)
	s_waitcnt lgkmcnt(0)
	s_setprio 1
	s_barrier
	v_mfma_f32_16x16x32_bf16 v[64:67], v[108:111], v[164:167], v[64:67]
	v_mfma_f32_16x16x32_bf16 v[60:63], v[128:131], v[164:167], v[60:63]
	v_mfma_f32_16x16x32_bf16 v[48:51], v[108:111], v[172:175], v[48:51]
	v_mfma_f32_16x16x32_bf16 v[44:47], v[128:131], v[172:175], v[44:47]
	v_mfma_f32_16x16x32_bf16 v[32:35], v[108:111], v[180:183], v[32:35]
	v_mfma_f32_16x16x32_bf16 v[28:31], v[128:131], v[180:183], v[28:31]
	v_mfma_f32_16x16x32_bf16 v[16:19], v[108:111], v[206:209], v[16:19]
	v_mfma_f32_16x16x32_bf16 v[12:15], v[128:131], v[206:209], v[12:15]
	v_mfma_f32_16x16x32_bf16 v[64:67], v[112:115], v[168:171], v[64:67]
	v_mfma_f32_16x16x32_bf16 v[60:63], v[136:139], v[168:171], v[60:63]
	v_mfma_f32_16x16x32_bf16 v[48:51], v[112:115], v[176:179], v[48:51]
	v_mfma_f32_16x16x32_bf16 v[44:47], v[136:139], v[176:179], v[44:47]
	v_mfma_f32_16x16x32_bf16 v[32:35], v[112:115], v[184:187], v[32:35]
	v_mfma_f32_16x16x32_bf16 v[28:31], v[136:139], v[184:187], v[28:31]
	v_mfma_f32_16x16x32_bf16 v[16:19], v[112:115], v[210:213], v[16:19]
	v_mfma_f32_16x16x32_bf16 v[12:15], v[136:139], v[210:213], v[12:15]
	s_setprio 0
	s_setprio 1
	v_mfma_f32_16x16x32_bf16 v[56:59], v[148:151], v[164:167], v[56:59]
	v_mfma_f32_16x16x32_bf16 v[52:55], v[156:159], v[164:167], v[52:55]
	v_mfma_f32_16x16x32_bf16 v[40:43], v[148:151], v[172:175], v[40:43]
	v_mfma_f32_16x16x32_bf16 v[36:39], v[156:159], v[172:175], v[36:39]
	v_mfma_f32_16x16x32_bf16 v[24:27], v[148:151], v[180:183], v[24:27]
	v_mfma_f32_16x16x32_bf16 v[20:23], v[156:159], v[180:183], v[20:23]
	v_mfma_f32_16x16x32_bf16 v[8:11], v[148:151], v[206:209], v[8:11]
	v_mfma_f32_16x16x32_bf16 v[4:7], v[156:159], v[206:209], v[4:7]
	v_mfma_f32_16x16x32_bf16 v[56:59], v[152:155], v[168:171], v[56:59]
	v_mfma_f32_16x16x32_bf16 v[52:55], v[160:163], v[168:171], v[52:55]
	v_mfma_f32_16x16x32_bf16 v[40:43], v[152:155], v[176:179], v[40:43]
	v_mfma_f32_16x16x32_bf16 v[36:39], v[160:163], v[176:179], v[36:39]
	v_mfma_f32_16x16x32_bf16 v[24:27], v[152:155], v[184:187], v[24:27]
	v_mfma_f32_16x16x32_bf16 v[20:23], v[160:163], v[184:187], v[20:23]
	v_mfma_f32_16x16x32_bf16 v[8:11], v[152:155], v[210:213], v[8:11]
	v_mfma_f32_16x16x32_bf16 v[4:7], v[160:163], v[210:213], v[4:7]
	s_barrier
	s_setprio 0
	s_add_i32 s78, s78, 2
	s_add_u32 s73, s73, 0x100
	s_addc_u32 s75, s75, 0
	s_cmpk_gt_u32 s78, 0x55
	s_mov_b64 s[62:63], s[68:69]
	s_cbranch_scc0 .LBB0_667
	s_and_b64 vcc, exec, s[24:25]
	s_cbranch_vccz .LBB0_670
	s_barrier

;     __device__ __forceinline__ bool next(int i, Unit& u) const { if (i >= n) return false; u.pm = pm; u.pn = pn0 + i; return true; }
;     __device__ __forceinline__ bool next(int i, Unit& u) const { if (i) return false; u.pm = pm; u.pn = pn; return true; }
; #define PG8_STAGE(bufoff, gbase, voff) do { _Pragma("unroll") for (int _i = 0; _i < 2; ++_i) \
;         __builtin_amdgcn_global_load_lds((const unsigned*)((const char*)(gbase) + (voff)[_i]), (PG8_LAS unsigned*)(lds + (bufoff) + ldsw + _i * 8192), 16, 0, 0); } while (0)
; #define PG8_LDA(dst, b, h) do { _Pragma("unroll") for (int m = 0; m < 4; ++m) _Pragma("unroll") for (int k = 0; k < 2; ++k) dst[m][k] = *(const PG8_LAS bf16x8*)(lds + PG8_SA(b, h) + aoff + m * 2048 + k * 1024); } while (0)
; #define PG8_LDB(dst, b, h) do { _Pragma("unroll") for (int n = 0; n < 2; ++n) _Pragma("unroll") for (int k = 0; k < 2; ++k) dst[n][k] = *(const PG8_LAS bf16x8*)(lds + PG8_SB(b, h) + boff + n * 2048 + k * 1024); } while (0)
; #define PG8_WAIT_V(n) asm volatile("s_waitcnt vmcnt(" #n ")" ::: "memory")
;     ...
;         const bool has_next = S.next(ui + 1, nxt);
;         const char* nA = has_next ? (const char*)g.A + (size_t)nxt.pm * tstep : cA; const char* nB = has_next ? (const char*)g.Bt + (size_t)nxt.pn * tstep : cB;
;         for (int t = 0; t < nt; t += 2) {
;             const bool last = (t == nt - 2);
;             const char* a1 = cA + (size_t)(t + 1) * kstep;
;             const char* a2 = last ? nA : cA + (size_t)(t + 2) * kstep; const char* b2 = last ? nB : cB + (size_t)(t + 2) * kstep;
;             const char* a3 = a2 + kstep; const char* b3 = b2 + kstep;
;             if (last && has_next) S.a_ready(nxt);
;             if (t == 0) E.pre_issue(pre, cur, tid, ui); else if (t == 2) E.pre_finish(pre, tid, ui);
;             if constexpr (SP2) {
;             PG8_LDB(B0, 0, 0); PG8_LDB(B1, 0, 1); PG8_SCHED; PG8_LDA(At, 0, 0); PG8_STAGE(PG8_SA(1, 1), a1 + hstep, voffA);
;             PG8_WAIT_V(8); PG8_WAIT_L(0); PG8_BAR; PG8_MMA(0, 0, At, B0); PG8_MMA(0, 1, At, B1); PG8_BAR; PG8_SCHED;
;     ...
; #pragma unroll
;         for (int a = 0; a < 2; ++a)
; #pragma unroll
;             for (int b = 0; b < 2; ++b)
; #pragma unroll
;                 for (int m = 0; m < 4; ++m)
; #pragma unroll
;                     for (int n = 0; n < 2; ++n) acc[a][b][m][n] = (f32x4){0.f, 0.f, 0.f, 0.f};
.LBB0_752:
	s_ashr_i32 s61, s60, 31
	s_lshl_b64 s[54:55], s[60:61], 20
	s_add_u32 s62, s36, s54
	s_addc_u32 s63, s37, s55
	s_and_b64 s[54:55], s[8:9], exec
	s_cselect_b32 s53, s63, s69
	s_cselect_b32 s54, s62, s68
	s_ashr_i32 s25, s24, 31
	s_lshl_b64 s[58:59], s[24:25], 20
	s_add_u32 s70, s81, s58
	s_addc_u32 s71, s6, s59
	s_and_b64 s[58:59], s[8:9], exec
	s_cselect_b32 s25, s71, s77
	s_cselect_b32 s55, s70, s76
	s_add_u32 s68, s68, 0x80080
	s_addc_u32 s69, s69, 0
	s_add_u32 s56, s76, 0x100
	v_mov_b32_e32 v4, 0
	s_addc_u32 s58, s77, 0
	s_mov_b32 s59, -2
	v_mov_b32_e32 v5, v4
	v_mov_b32_e32 v6, v4
	v_mov_b32_e32 v7, v4
	v_mov_b32_e32 v8, v4
	v_mov_b32_e32 v9, v4
	v_mov_b32_e32 v10, v4
	v_mov_b32_e32 v11, v4
	v_mov_b32_e32 v16, v4
	v_mov_b32_e32 v17, v4
	v_mov_b32_e32 v18, v4
	v_mov_b32_e32 v19, v4
	s_waitcnt vmcnt(0)
	v_mov_b32_e32 v24, v4
	v_mov_b32_e32 v25, v4
	v_mov_b32_e32 v26, v4
	v_mov_b32_e32 v27, v4
	v_mov_b32_e32 v32, v4
	v_mov_b32_e32 v33, v4
	v_mov_b32_e32 v34, v4
	v_mov_b32_e32 v35, v4
	v_mov_b32_e32 v40, v4
	v_mov_b32_e32 v41, v4
	v_mov_b32_e32 v42, v4
	v_mov_b32_e32 v43, v4
	v_mov_b32_e32 v48, v4
	v_mov_b32_e32 v49, v4
	v_mov_b32_e32 v50, v4
	v_mov_b32_e32 v51, v4
	v_mov_b32_e32 v56, v4
	v_mov_b32_e32 v57, v4
	v_mov_b32_e32 v58, v4
	v_mov_b32_e32 v59, v4
	v_mov_b32_e32 v12, v4
	v_mov_b32_e32 v13, v4
	v_mov_b32_e32 v14, v4
	v_mov_b32_e32 v15, v4
	v_mov_b32_e32 v20, v4
	v_mov_b32_e32 v21, v4
	v_mov_b32_e32 v22, v4
	v_mov_b32_e32 v23, v4
	v_mov_b32_e32 v28, v4
	v_mov_b32_e32 v29, v4
	v_mov_b32_e32 v30, v4
	v_mov_b32_e32 v31, v4
	v_mov_b32_e32 v36, v4
	v_mov_b32_e32 v37, v4
	v_mov_b32_e32 v38, v4
	v_mov_b32_e32 v39, v4
	v_mov_b32_e32 v44, v4
	v_mov_b32_e32 v45, v4
	v_mov_b32_e32 v46, v4
	v_mov_b32_e32 v47, v4
	v_mov_b32_e32 v52, v4
	v_mov_b32_e32 v53, v4
	v_mov_b32_e32 v54, v4
	v_mov_b32_e32 v55, v4
	v_mov_b32_e32 v60, v4
	v_mov_b32_e32 v61, v4
	v_mov_b32_e32 v62, v4
	v_mov_b32_e32 v63, v4
	v_mov_b32_e32 v64, v4
	v_mov_b32_e32 v65, v4
	v_mov_b32_e32 v66, v4
	v_mov_b32_e32 v67, v4
	v_mov_b32_e32 v68, v4
	v_mov_b32_e32 v69, v4
	v_mov_b32_e32 v70, v4
	v_mov_b32_e32 v71, v4
	v_mov_b32_e32 v72, v4
	v_mov_b32_e32 v73, v4
	v_mov_b32_e32 v74, v4
	v_mov_b32_e32 v75, v4
	v_mov_b32_e32 v80, v4
	v_mov_b32_e32 v81, v4
	v_mov_b32_e32 v82, v4
	v_mov_b32_e32 v83, v4
	v_mov_b32_e32 v88, v4
	v_mov_b32_e32 v89, v4
	v_mov_b32_e32 v90, v4
	v_mov_b32_e32 v91, v4
	v_mov_b32_e32 v96, v4
	v_mov_b32_e32 v97, v4
	v_mov_b32_e32 v98, v4
	v_mov_b32_e32 v99, v4
	v_mov_b32_e32 v104, v4
	v_mov_b32_e32 v105, v4
	v_mov_b32_e32 v106, v4
	v_mov_b32_e32 v107, v4
	v_mov_b32_e32 v112, v4
	v_mov_b32_e32 v113, v4
	v_mov_b32_e32 v114, v4
	v_mov_b32_e32 v115, v4
	v_mov_b32_e32 v120, v4
	v_mov_b32_e32 v121, v4
	v_mov_b32_e32 v122, v4
	v_mov_b32_e32 v123, v4
	v_mov_b32_e32 v76, v4
	v_mov_b32_e32 v77, v4
	v_mov_b32_e32 v78, v4
	v_mov_b32_e32 v79, v4
	v_mov_b32_e32 v84, v4
	v_mov_b32_e32 v85, v4
	v_mov_b32_e32 v86, v4
	v_mov_b32_e32 v87, v4
	v_mov_b32_e32 v92, v4
	v_mov_b32_e32 v93, v4
	v_mov_b32_e32 v94, v4
	v_mov_b32_e32 v95, v4
	v_mov_b32_e32 v100, v4
	v_mov_b32_e32 v101, v4
	v_mov_b32_e32 v102, v4
	v_mov_b32_e32 v103, v4
	v_mov_b32_e32 v108, v4
	v_mov_b32_e32 v109, v4
	v_mov_b32_e32 v110, v4
	v_mov_b32_e32 v111, v4
	v_mov_b32_e32 v116, v4
	v_mov_b32_e32 v117, v4
	v_mov_b32_e32 v118, v4
	v_mov_b32_e32 v119, v4
	v_mov_b32_e32 v124, v4
	v_mov_b32_e32 v125, v4
	v_mov_b32_e32 v126, v4
	v_mov_b32_e32 v127, v4
	v_mov_b32_e32 v128, v4
	v_mov_b32_e32 v129, v4
	v_mov_b32_e32 v130, v4
	v_mov_b32_e32 v131, v4
	s_waitcnt lgkmcnt(0)
.LBB0_753:
	s_add_u32 s48, s68, 0xfff80080
	s_addc_u32 s49, s69, -1
	s_add_i32 s61, 0, 0x10000
	s_cmp_eq_u32 s59, 28
	s_cselect_b32 s79, s53, s49
	s_cselect_b32 s78, s54, s48
	v_add_u32_e32 v155, s61, v145
	s_cselect_b32 s77, s25, s58
	s_cselect_b32 s76, s55, s56
	s_add_i32 s48, 0, 0x14000
	ds_read_b128 v[132:135], v155
	ds_read_b128 v[158:161], v155 offset:1024
	ds_read_b128 v[162:165], v155 offset:2048
	ds_read_b128 v[166:169], v155 offset:3072
	v_add_u32_e32 v155, s48, v145
	ds_read_b128 v[170:173], v155
	ds_read_b128 v[176:179], v155 offset:1024
	ds_read_b128 v[180:183], v155 offset:2048
	ds_read_b128 v[184:187], v155 offset:3072
	v_lshl_add_u64 v[232:233], s[68:69], 0, v[150:151]
	s_add_i32 m0, s1, 0xc000
	ds_read_b128 v[188:191], v175
	ds_read_b128 v[192:195], v175 offset:1024
	ds_read_b128 v[196:199], v175 offset:2048
	ds_read_b128 v[206:209], v175 offset:3072
	ds_read_b128 v[210:213], v175 offset:4096
	ds_read_b128 v[214:217], v175 offset:5120
	ds_read_b128 v[218:221], v175 offset:6144
	ds_read_b128 v[222:225], v175 offset:7168
	global_load_lds_dwordx4 v[232:233], off
	v_lshl_add_u64 v[232:233], s[68:69], 0, v[152:153]
	s_add_i32 m0, s1, 0xe000
	s_nop 0
	global_load_lds_dwordx4 v[232:233], off
	s_waitcnt vmcnt(8)
	s_waitcnt lgkmcnt(0)
	s_setprio 1
	s_barrier
; #define PG8_STAGE(bufoff, gbase, voff) do { _Pragma("unroll") for (int _i = 0; _i < 2; ++_i) \
;         __builtin_amdgcn_global_load_lds((const unsigned*)((const char*)(gbase) + (voff)[_i]), (PG8_LAS unsigned*)(lds + (bufoff) + ldsw + _i * 8192), 16, 0, 0); } while (0)
; #define PG8_LDA(dst, b, h) do { _Pragma("unroll") for (int m = 0; m < 4; ++m) _Pragma("unroll") for (int k = 0; k < 2; ++k) dst[m][k] = *(const PG8_LAS bf16x8*)(lds + PG8_SA(b, h) + aoff + m * 2048 + k * 1024); } while (0)
; #define PG8_MMA(ai, bj, At, Bt) do { __builtin_amdgcn_s_setprio(1); _Pragma("unroll") for (int m = 0; m < 4; ++m) _Pragma("unroll") for (int n = 0; n < 2; ++n) _Pragma("unroll") for (int k = 0; k < 2; ++k) \
;         acc[ai][bj][m][n] = __builtin_amdgcn_mfma_f32_16x16x32_bf16(Bt[n][k], At[m][k], acc[ai][bj][m][n], 0, 0, 0); __builtin_amdgcn_s_setprio(0); } while (0)
; #define PG8_WAIT_V(n) asm volatile("s_waitcnt vmcnt(" #n ")" ::: "memory")
; #define PG8_WAIT_L(n) asm volatile("s_waitcnt lgkmcnt(" #n ")" ::: "memory")
; #define PG8_BAR __builtin_amdgcn_s_barrier()
; #define PG8_SCHED __builtin_amdgcn_sched_barrier(0)
;     ...
;             PG8_WAIT_V(8); PG8_WAIT_L(0); PG8_BAR; PG8_MMA(0, 0, At, B0); PG8_MMA(0, 1, At, B1); PG8_BAR; PG8_SCHED;
;             PG8_LDA(At, 0, 1); PG8_STAGE(PG8_SB(0, 0), b2, voffB); PG8_STAGE(PG8_SB(0, 1), b2 + hstep, voffB); PG8_STAGE(PG8_SA(0, 0), a2, voffA);
;             PG8_WAIT_V(8); PG8_WAIT_L(0); PG8_BAR; PG8_MMA(1, 0, At, B0); PG8_MMA(1, 1, At, B1); PG8_BAR; PG8_SCHED;
	v_mfma_f32_16x16x32_bf16 v[128:131], v[132:135], v[188:191], v[128:131]
	v_mfma_f32_16x16x32_bf16 v[124:127], v[162:165], v[188:191], v[124:127]
	v_mfma_f32_16x16x32_bf16 v[116:119], v[132:135], v[196:199], v[116:119]
	v_mfma_f32_16x16x32_bf16 v[108:111], v[162:165], v[196:199], v[108:111]
	v_mfma_f32_16x16x32_bf16 v[100:103], v[132:135], v[210:213], v[100:103]
	v_mfma_f32_16x16x32_bf16 v[92:95], v[162:165], v[210:213], v[92:95]
	v_mfma_f32_16x16x32_bf16 v[84:87], v[132:135], v[218:221], v[84:87]
	v_mfma_f32_16x16x32_bf16 v[76:79], v[162:165], v[218:221], v[76:79]
	v_mfma_f32_16x16x32_bf16 v[128:131], v[158:161], v[192:195], v[128:131]
	v_mfma_f32_16x16x32_bf16 v[124:127], v[166:169], v[192:195], v[124:127]
	v_mfma_f32_16x16x32_bf16 v[116:119], v[158:161], v[206:209], v[116:119]
	v_mfma_f32_16x16x32_bf16 v[108:111], v[166:169], v[206:209], v[108:111]
	v_mfma_f32_16x16x32_bf16 v[100:103], v[158:161], v[214:217], v[100:103]
	v_mfma_f32_16x16x32_bf16 v[92:95], v[166:169], v[214:217], v[92:95]
	v_mfma_f32_16x16x32_bf16 v[84:87], v[158:161], v[222:225], v[84:87]
	v_mfma_f32_16x16x32_bf16 v[76:79], v[166:169], v[222:225], v[76:79]
	s_setprio 0
	s_setprio 1
	v_mfma_f32_16x16x32_bf16 v[120:123], v[170:173], v[188:191], v[120:123]
	v_mfma_f32_16x16x32_bf16 v[112:115], v[180:183], v[188:191], v[112:115]
	v_mfma_f32_16x16x32_bf16 v[104:107], v[170:173], v[196:199], v[104:107]
	v_mfma_f32_16x16x32_bf16 v[96:99], v[180:183], v[196:199], v[96:99]
	v_mfma_f32_16x16x32_bf16 v[88:91], v[170:173], v[210:213], v[88:91]
	v_mfma_f32_16x16x32_bf16 v[80:83], v[180:183], v[210:213], v[80:83]
	v_mfma_f32_16x16x32_bf16 v[72:75], v[170:173], v[218:221], v[72:75]
	v_mfma_f32_16x16x32_bf16 v[68:71], v[180:183], v[218:221], v[68:71]
	v_mfma_f32_16x16x32_bf16 v[120:123], v[176:179], v[192:195], v[120:123]
	v_mfma_f32_16x16x32_bf16 v[112:115], v[184:187], v[192:195], v[112:115]
	v_mfma_f32_16x16x32_bf16 v[104:107], v[176:179], v[206:209], v[104:107]
	v_mfma_f32_16x16x32_bf16 v[96:99], v[184:187], v[206:209], v[96:99]
	v_mfma_f32_16x16x32_bf16 v[88:91], v[176:179], v[214:217], v[88:91]
	v_mfma_f32_16x16x32_bf16 v[80:83], v[184:187], v[214:217], v[80:83]
	v_mfma_f32_16x16x32_bf16 v[72:75], v[176:179], v[222:225], v[72:75]
	v_mfma_f32_16x16x32_bf16 v[68:71], v[184:187], v[222:225], v[68:71]
	s_barrier
	s_setprio 0
	s_add_i32 s49, s61, s0
	v_lshl_add_u64 v[232:233], s[76:77], 0, v[140:141]
	s_mov_b32 m0, s49
	ds_read_b128 v[188:191], v175 offset:16384
	ds_read_b128 v[192:195], v175 offset:17408
	ds_read_b128 v[196:199], v175 offset:18432
	ds_read_b128 v[206:209], v175 offset:19456
	ds_read_b128 v[210:213], v175 offset:20480
	ds_read_b128 v[214:217], v175 offset:21504
	ds_read_b128 v[218:221], v175 offset:22528
	ds_read_b128 v[222:225], v175 offset:23552
	global_load_lds_dwordx4 v[232:233], off
	s_add_i32 m0, s49, 0x2000
	s_add_u32 s82, s76, 0x80000
	v_lshl_add_u64 v[234:235], s[76:77], 0, v[136:137]
	s_addc_u32 s83, s77, 0
	s_add_i32 s48, s48, s0
	global_load_lds_dwordx4 v[234:235], off
	v_lshl_add_u64 v[236:237], s[82:83], 0, v[140:141]
	s_mov_b32 m0, s48
	v_lshl_add_u64 v[238:239], s[78:79], 0, v[138:139]
	global_load_lds_dwordx4 v[236:237], off
	v_lshl_add_u64 v[236:237], s[82:83], 0, v[136:137]
	s_add_i32 m0, s48, 0x2000
	s_nop 0
	global_load_lds_dwordx4 v[236:237], off
	v_lshl_add_u64 v[236:237], s[78:79], 0, v[142:143]
	s_mov_b32 m0, s1
	s_nop 0
	global_load_lds_dwordx4 v[236:237], off
	s_mov_b32 m0, s4
	s_nop 0
	global_load_lds_dwordx4 v[238:239], off
	s_waitcnt vmcnt(8)
	s_waitcnt lgkmcnt(0)
	s_setprio 1
	s_barrier
	v_mfma_f32_16x16x32_bf16 v[64:67], v[132:135], v[188:191], v[64:67]
	v_mfma_f32_16x16x32_bf16 v[60:63], v[162:165], v[188:191], v[60:63]
	v_mfma_f32_16x16x32_bf16 v[52:55], v[132:135], v[196:199], v[52:55]
	v_mfma_f32_16x16x32_bf16 v[44:47], v[162:165], v[196:199], v[44:47]
	v_mfma_f32_16x16x32_bf16 v[36:39], v[132:135], v[210:213], v[36:39]
	v_mfma_f32_16x16x32_bf16 v[28:31], v[162:165], v[210:213], v[28:31]
	v_mfma_f32_16x16x32_bf16 v[20:23], v[132:135], v[218:221], v[20:23]
	v_mfma_f32_16x16x32_bf16 v[12:15], v[162:165], v[218:221], v[12:15]
	v_mfma_f32_16x16x32_bf16 v[64:67], v[158:161], v[192:195], v[64:67]
	v_mfma_f32_16x16x32_bf16 v[60:63], v[166:169], v[192:195], v[60:63]
	v_mfma_f32_16x16x32_bf16 v[52:55], v[158:161], v[206:209], v[52:55]
	v_mfma_f32_16x16x32_bf16 v[44:47], v[166:169], v[206:209], v[44:47]
	v_mfma_f32_16x16x32_bf16 v[36:39], v[158:161], v[214:217], v[36:39]
	v_mfma_f32_16x16x32_bf16 v[28:31], v[166:169], v[214:217], v[28:31]
	v_mfma_f32_16x16x32_bf16 v[20:23], v[158:161], v[222:225], v[20:23]
	v_mfma_f32_16x16x32_bf16 v[12:15], v[166:169], v[222:225], v[12:15]
	s_setprio 0
	s_setprio 1
	v_mfma_f32_16x16x32_bf16 v[56:59], v[170:173], v[188:191], v[56:59]
	v_mfma_f32_16x16x32_bf16 v[48:51], v[180:183], v[188:191], v[48:51]
	v_mfma_f32_16x16x32_bf16 v[40:43], v[170:173], v[196:199], v[40:43]
	v_mfma_f32_16x16x32_bf16 v[32:35], v[180:183], v[196:199], v[32:35]
	v_mfma_f32_16x16x32_bf16 v[24:27], v[170:173], v[210:213], v[24:27]
	v_mfma_f32_16x16x32_bf16 v[16:19], v[180:183], v[210:213], v[16:19]
	v_mfma_f32_16x16x32_bf16 v[8:11], v[170:173], v[218:221], v[8:11]
	v_mfma_f32_16x16x32_bf16 v[4:7], v[180:183], v[218:221], v[4:7]
	v_mfma_f32_16x16x32_bf16 v[56:59], v[176:179], v[192:195], v[56:59]
	v_mfma_f32_16x16x32_bf16 v[48:51], v[184:187], v[192:195], v[48:51]
	v_mfma_f32_16x16x32_bf16 v[40:43], v[176:179], v[206:209], v[40:43]
	v_mfma_f32_16x16x32_bf16 v[32:35], v[184:187], v[206:209], v[32:35]
	v_mfma_f32_16x16x32_bf16 v[24:27], v[176:179], v[214:217], v[24:27]
	v_mfma_f32_16x16x32_bf16 v[16:19], v[184:187], v[214:217], v[16:19]
	v_mfma_f32_16x16x32_bf16 v[8:11], v[176:179], v[222:225], v[8:11]
	v_mfma_f32_16x16x32_bf16 v[4:7], v[184:187], v[222:225], v[4:7]
	s_barrier
; #define PG8_STAGE(bufoff, gbase, voff) do { _Pragma("unroll") for (int _i = 0; _i < 2; ++_i) \
;         __builtin_amdgcn_global_load_lds((const unsigned*)((const char*)(gbase) + (voff)[_i]), (PG8_LAS unsigned*)(lds + (bufoff) + ldsw + _i * 8192), 16, 0, 0); } while (0)
; #define PG8_LDA(dst, b, h) do { _Pragma("unroll") for (int m = 0; m < 4; ++m) _Pragma("unroll") for (int k = 0; k < 2; ++k) dst[m][k] = *(const PG8_LAS bf16x8*)(lds + PG8_SA(b, h) + aoff + m * 2048 + k * 1024); } while (0)
; #define PG8_LDB(dst, b, h) do { _Pragma("unroll") for (int n = 0; n < 2; ++n) _Pragma("unroll") for (int k = 0; k < 2; ++k) dst[n][k] = *(const PG8_LAS bf16x8*)(lds + PG8_SB(b, h) + boff + n * 2048 + k * 1024); } while (0)
; #define PG8_MMA(ai, bj, At, Bt) do { __builtin_amdgcn_s_setprio(1); _Pragma("unroll") for (int m = 0; m < 4; ++m) _Pragma("unroll") for (int n = 0; n < 2; ++n) _Pragma("unroll") for (int k = 0; k < 2; ++k) \
;         acc[ai][bj][m][n] = __builtin_amdgcn_mfma_f32_16x16x32_bf16(Bt[n][k], At[m][k], acc[ai][bj][m][n], 0, 0, 0); __builtin_amdgcn_s_setprio(0); } while (0)
; #define PG8_WAIT_V(n) asm volatile("s_waitcnt vmcnt(" #n ")" ::: "memory")
; #define PG8_WAIT_L(n) asm volatile("s_waitcnt lgkmcnt(" #n ")" ::: "memory")
; #define PG8_BAR __builtin_amdgcn_s_barrier()
; #define PG8_SCHED __builtin_amdgcn_sched_barrier(0)
;     ...
;             PG8_WAIT_V(8); PG8_WAIT_L(0); PG8_BAR; PG8_MMA(1, 0, At, B0); PG8_MMA(1, 1, At, B1); PG8_BAR; PG8_SCHED;
;             PG8_LDB(B0, 1, 0); PG8_LDB(B1, 1, 1); PG8_SCHED; PG8_LDA(At, 1, 0); PG8_STAGE(PG8_SA(0, 1), a2 + hstep, voffA);
;             PG8_WAIT_V(8); PG8_WAIT_L(0); PG8_BAR; PG8_MMA(0, 0, At, B0); PG8_MMA(0, 1, At, B1); PG8_BAR; PG8_SCHED;
	s_setprio 0
	s_add_i32 s48, 0, 0x18000
	v_add_u32_e32 v155, s48, v145
	s_add_i32 s49, 0, 0x1c000
	ds_read_b128 v[132:135], v155
	ds_read_b128 v[158:161], v155 offset:1024
	ds_read_b128 v[162:165], v155 offset:2048
	ds_read_b128 v[166:169], v155 offset:3072
	v_add_u32_e32 v155, s49, v145
	ds_read_b128 v[170:173], v155
	ds_read_b128 v[176:179], v155 offset:1024
	ds_read_b128 v[180:183], v155 offset:2048
	ds_read_b128 v[184:187], v155 offset:3072
	s_add_u32 s78, s78, 0x80000
	s_addc_u32 s79, s79, 0
	s_mov_b32 m0, s5
	v_lshl_add_u64 v[240:241], s[78:79], 0, v[142:143]
	ds_read_b128 v[188:191], v175 offset:32768
	ds_read_b128 v[192:195], v175 offset:33792
	ds_read_b128 v[196:199], v175 offset:34816
	ds_read_b128 v[206:209], v175 offset:35840
	ds_read_b128 v[210:213], v175 offset:36864
	ds_read_b128 v[214:217], v175 offset:37888
	ds_read_b128 v[218:221], v175 offset:38912
	ds_read_b128 v[222:225], v175 offset:39936
	global_load_lds_dwordx4 v[240:241], off
	v_lshl_add_u64 v[240:241], s[78:79], 0, v[138:139]
	s_mov_b32 m0, s7
	s_nop 0
	global_load_lds_dwordx4 v[240:241], off
	s_waitcnt vmcnt(8)
	s_waitcnt lgkmcnt(0)
	s_setprio 1
	s_barrier
	v_mfma_f32_16x16x32_bf16 v[128:131], v[132:135], v[188:191], v[128:131]
	v_mfma_f32_16x16x32_bf16 v[124:127], v[162:165], v[188:191], v[124:127]
	v_mfma_f32_16x16x32_bf16 v[116:119], v[132:135], v[196:199], v[116:119]
	v_mfma_f32_16x16x32_bf16 v[108:111], v[162:165], v[196:199], v[108:111]
	v_mfma_f32_16x16x32_bf16 v[100:103], v[132:135], v[210:213], v[100:103]
	v_mfma_f32_16x16x32_bf16 v[92:95], v[162:165], v[210:213], v[92:95]
	v_mfma_f32_16x16x32_bf16 v[84:87], v[132:135], v[218:221], v[84:87]
	v_mfma_f32_16x16x32_bf16 v[76:79], v[162:165], v[218:221], v[76:79]
	v_mfma_f32_16x16x32_bf16 v[128:131], v[158:161], v[192:195], v[128:131]
	v_mfma_f32_16x16x32_bf16 v[124:127], v[166:169], v[192:195], v[124:127]
	v_mfma_f32_16x16x32_bf16 v[116:119], v[158:161], v[206:209], v[116:119]
	v_mfma_f32_16x16x32_bf16 v[108:111], v[166:169], v[206:209], v[108:111]
	v_mfma_f32_16x16x32_bf16 v[100:103], v[158:161], v[214:217], v[100:103]
	v_mfma_f32_16x16x32_bf16 v[92:95], v[166:169], v[214:217], v[92:95]
	v_mfma_f32_16x16x32_bf16 v[84:87], v[158:161], v[222:225], v[84:87]
	v_mfma_f32_16x16x32_bf16 v[76:79], v[166:169], v[222:225], v[76:79]
	s_setprio 0
	s_setprio 1
	v_mfma_f32_16x16x32_bf16 v[120:123], v[170:173], v[188:191], v[120:123]
	v_mfma_f32_16x16x32_bf16 v[112:115], v[180:183], v[188:191], v[112:115]
	v_mfma_f32_16x16x32_bf16 v[104:107], v[170:173], v[196:199], v[104:107]
	v_mfma_f32_16x16x32_bf16 v[96:99], v[180:183], v[196:199], v[96:99]
	v_mfma_f32_16x16x32_bf16 v[88:91], v[170:173], v[210:213], v[88:91]
	v_mfma_f32_16x16x32_bf16 v[80:83], v[180:183], v[210:213], v[80:83]
	v_mfma_f32_16x16x32_bf16 v[72:75], v[170:173], v[218:221], v[72:75]
	v_mfma_f32_16x16x32_bf16 v[68:71], v[180:183], v[218:221], v[68:71]
	v_mfma_f32_16x16x32_bf16 v[120:123], v[176:179], v[192:195], v[120:123]
	v_mfma_f32_16x16x32_bf16 v[112:115], v[184:187], v[192:195], v[112:115]
	v_mfma_f32_16x16x32_bf16 v[104:107], v[176:179], v[206:209], v[104:107]
	v_mfma_f32_16x16x32_bf16 v[96:99], v[184:187], v[206:209], v[96:99]
	v_mfma_f32_16x16x32_bf16 v[88:91], v[176:179], v[214:217], v[88:91]
	v_mfma_f32_16x16x32_bf16 v[80:83], v[184:187], v[214:217], v[80:83]
	v_mfma_f32_16x16x32_bf16 v[72:75], v[176:179], v[222:225], v[72:75]
	v_mfma_f32_16x16x32_bf16 v[68:71], v[184:187], v[222:225], v[68:71]
	s_barrier
; #define PG8_STAGE(bufoff, gbase, voff) do { _Pragma("unroll") for (int _i = 0; _i < 2; ++_i) \
;         __builtin_amdgcn_global_load_lds((const unsigned*)((const char*)(gbase) + (voff)[_i]), (PG8_LAS unsigned*)(lds + (bufoff) + ldsw + _i * 8192), 16, 0, 0); } while (0)
; #define PG8_LDA(dst, b, h) do { _Pragma("unroll") for (int m = 0; m < 4; ++m) _Pragma("unroll") for (int k = 0; k < 2; ++k) dst[m][k] = *(const PG8_LAS bf16x8*)(lds + PG8_SA(b, h) + aoff + m * 2048 + k * 1024); } while (0)
; #define PG8_MMA(ai, bj, At, Bt) do { __builtin_amdgcn_s_setprio(1); _Pragma("unroll") for (int m = 0; m < 4; ++m) _Pragma("unroll") for (int n = 0; n < 2; ++n) _Pragma("unroll") for (int k = 0; k < 2; ++k) \
;         acc[ai][bj][m][n] = __builtin_amdgcn_mfma_f32_16x16x32_bf16(Bt[n][k], At[m][k], acc[ai][bj][m][n], 0, 0, 0); __builtin_amdgcn_s_setprio(0); } while (0)
; #define PG8_WAIT_V(n) asm volatile("s_waitcnt vmcnt(" #n ")" ::: "memory")
; #define PG8_WAIT_L(n) asm volatile("s_waitcnt lgkmcnt(" #n ")" ::: "memory")
; #define PG8_BAR __builtin_amdgcn_s_barrier()
; #define PG8_SCHED __builtin_amdgcn_sched_barrier(0)
;     ...
;             PG8_WAIT_V(8); PG8_WAIT_L(0); PG8_BAR; PG8_MMA(0, 0, At, B0); PG8_MMA(0, 1, At, B1); PG8_BAR; PG8_SCHED;
;             PG8_LDA(At, 1, 1); PG8_STAGE(PG8_SB(1, 0), b3, voffB); PG8_STAGE(PG8_SB(1, 1), b3 + hstep, voffB); PG8_STAGE(PG8_SA(1, 0), a3, voffA);
;             PG8_WAIT_V(8); PG8_WAIT_L(0); PG8_BAR; PG8_MMA(1, 0, At, B0); PG8_MMA(1, 1, At, B1); PG8_BAR; PG8_SCHED;
;     ...
;         if constexpr (ALIGN_EPI) { if (wr == 0) PG8_BAR; }
	s_setprio 0
	s_add_i32 s48, s48, s0
	v_lshl_add_u64 v[232:233], v[232:233], 0, s[66:67]
	s_mov_b32 m0, s48
	ds_read_b128 v[188:191], v175 offset:49152
	ds_read_b128 v[192:195], v175 offset:50176
	ds_read_b128 v[196:199], v175 offset:51200
	ds_read_b128 v[206:209], v175 offset:52224
	ds_read_b128 v[210:213], v175 offset:53248
	ds_read_b128 v[214:217], v175 offset:54272
	ds_read_b128 v[218:221], v175 offset:55296
	ds_read_b128 v[222:225], v175 offset:56320
	global_load_lds_dwordx4 v[232:233], off
	s_add_i32 m0, s48, 0x2000
	s_add_u32 s76, s76, 0x80080
	v_lshl_add_u64 v[232:233], v[234:235], 0, s[66:67]
	s_addc_u32 s77, s77, 0
	s_add_i32 s48, s49, s0
	global_load_lds_dwordx4 v[232:233], off
	v_lshl_add_u64 v[232:233], s[76:77], 0, v[140:141]
	s_mov_b32 m0, s48
	s_nop 0
	global_load_lds_dwordx4 v[232:233], off
	v_lshl_add_u64 v[232:233], s[76:77], 0, v[136:137]
	s_add_i32 m0, s48, 0x2000
	s_nop 0
	global_load_lds_dwordx4 v[232:233], off
	v_lshl_add_u64 v[232:233], v[236:237], 0, s[66:67]
	s_mov_b32 m0, s21
	s_nop 0
	global_load_lds_dwordx4 v[232:233], off
	v_lshl_add_u64 v[232:233], v[238:239], 0, s[66:67]
	s_mov_b32 m0, s23
	s_nop 0
	global_load_lds_dwordx4 v[232:233], off
	s_waitcnt vmcnt(8)
	s_waitcnt lgkmcnt(0)
	s_setprio 1
	s_barrier
	v_mfma_f32_16x16x32_bf16 v[64:67], v[132:135], v[188:191], v[64:67]
	v_mfma_f32_16x16x32_bf16 v[60:63], v[162:165], v[188:191], v[60:63]
	v_mfma_f32_16x16x32_bf16 v[52:55], v[132:135], v[196:199], v[52:55]
	v_mfma_f32_16x16x32_bf16 v[44:47], v[162:165], v[196:199], v[44:47]
	v_mfma_f32_16x16x32_bf16 v[36:39], v[132:135], v[210:213], v[36:39]
	v_mfma_f32_16x16x32_bf16 v[28:31], v[162:165], v[210:213], v[28:31]
	v_mfma_f32_16x16x32_bf16 v[20:23], v[132:135], v[218:221], v[20:23]
	v_mfma_f32_16x16x32_bf16 v[12:15], v[162:165], v[218:221], v[12:15]
	v_mfma_f32_16x16x32_bf16 v[64:67], v[158:161], v[192:195], v[64:67]
	v_mfma_f32_16x16x32_bf16 v[60:63], v[166:169], v[192:195], v[60:63]
	v_mfma_f32_16x16x32_bf16 v[52:55], v[158:161], v[206:209], v[52:55]
	v_mfma_f32_16x16x32_bf16 v[44:47], v[166:169], v[206:209], v[44:47]
	v_mfma_f32_16x16x32_bf16 v[36:39], v[158:161], v[214:217], v[36:39]
	v_mfma_f32_16x16x32_bf16 v[28:31], v[166:169], v[214:217], v[28:31]
	v_mfma_f32_16x16x32_bf16 v[20:23], v[158:161], v[222:225], v[20:23]
	v_mfma_f32_16x16x32_bf16 v[12:15], v[166:169], v[222:225], v[12:15]
	s_setprio 0
	s_setprio 1
	v_mfma_f32_16x16x32_bf16 v[56:59], v[170:173], v[188:191], v[56:59]
	v_mfma_f32_16x16x32_bf16 v[48:51], v[180:183], v[188:191], v[48:51]
	v_mfma_f32_16x16x32_bf16 v[40:43], v[170:173], v[196:199], v[40:43]
	v_mfma_f32_16x16x32_bf16 v[32:35], v[180:183], v[196:199], v[32:35]
	v_mfma_f32_16x16x32_bf16 v[24:27], v[170:173], v[210:213], v[24:27]
	v_mfma_f32_16x16x32_bf16 v[16:19], v[180:183], v[210:213], v[16:19]
	v_mfma_f32_16x16x32_bf16 v[8:11], v[170:173], v[218:221], v[8:11]
	v_mfma_f32_16x16x32_bf16 v[4:7], v[180:183], v[218:221], v[4:7]
	v_mfma_f32_16x16x32_bf16 v[56:59], v[176:179], v[192:195], v[56:59]
	v_mfma_f32_16x16x32_bf16 v[48:51], v[184:187], v[192:195], v[48:51]
	v_mfma_f32_16x16x32_bf16 v[40:43], v[176:179], v[206:209], v[40:43]
	v_mfma_f32_16x16x32_bf16 v[32:35], v[184:187], v[206:209], v[32:35]
	v_mfma_f32_16x16x32_bf16 v[24:27], v[176:179], v[214:217], v[24:27]
	v_mfma_f32_16x16x32_bf16 v[16:19], v[184:187], v[214:217], v[16:19]
	v_mfma_f32_16x16x32_bf16 v[8:11], v[176:179], v[222:225], v[8:11]
	v_mfma_f32_16x16x32_bf16 v[4:7], v[184:187], v[222:225], v[4:7]
	s_barrier
	s_setprio 0
	s_add_i32 s59, s59, 2
	s_add_u32 s68, s68, 0x100
	s_addc_u32 s69, s69, 0
	s_add_u32 s56, s56, 0x100
	s_addc_u32 s58, s58, 0
	s_cmp_gt_u32 s59, 29
	s_cbranch_scc0 .LBB0_753
	s_and_b64 vcc, exec, s[12:13]
	s_cbranch_vccz .LBB0_756
	s_barrier

; #define PG8_STAGE(bufoff, gbase, voff) do { _Pragma("unroll") for (int _i = 0; _i < 2; ++_i) \
;         __builtin_amdgcn_global_load_lds((const unsigned*)((const char*)(gbase) + (voff)[_i]), (PG8_LAS unsigned*)(lds + (bufoff) + ldsw + _i * 8192), 16, 0, 0); } while (0)
; #define PG8_LDA(dst, b, h) do { _Pragma("unroll") for (int m = 0; m < 4; ++m) _Pragma("unroll") for (int k = 0; k < 2; ++k) dst[m][k] = *(const PG8_LAS bf16x8*)(lds + PG8_SA(b, h) + aoff + m * 2048 + k * 1024); } while (0)
; #define PG8_LDB(dst, b, h) do { _Pragma("unroll") for (int n = 0; n < 2; ++n) _Pragma("unroll") for (int k = 0; k < 2; ++k) dst[n][k] = *(const PG8_LAS bf16x8*)(lds + PG8_SB(b, h) + boff + n * 2048 + k * 1024); } while (0)
; #define PG8_MMA(ai, bj, At, Bt) do { __builtin_amdgcn_s_setprio(1); _Pragma("unroll") for (int m = 0; m < 4; ++m) _Pragma("unroll") for (int n = 0; n < 2; ++n) _Pragma("unroll") for (int k = 0; k < 2; ++k) \
;         acc[ai][bj][m][n] = __builtin_amdgcn_mfma_f32_16x16x32_bf16(Bt[n][k], At[m][k], acc[ai][bj][m][n], 0, 0, 0); __builtin_amdgcn_s_setprio(0); } while (0)
; #define PG8_WAIT_V(n) asm volatile("s_waitcnt vmcnt(" #n ")" ::: "memory")
; #define PG8_WAIT_L(n) asm volatile("s_waitcnt lgkmcnt(" #n ")" ::: "memory")
; #define PG8_BAR __builtin_amdgcn_s_barrier()
;     ...
;         for (int t = 0; t < nt; t += 2) {
;             const bool last = (t == nt - 2);
;             const char* a1 = cA + (size_t)(t + 1) * kstep;
;             const char* a2 = last ? nA : cA + (size_t)(t + 2) * kstep; const char* b2 = last ? nB : cB + (size_t)(t + 2) * kstep;
;             const char* a3 = a2 + kstep; const char* b3 = b2 + kstep;
;             if (last && has_next) S.a_ready(nxt);
;             if (t == 0) E.pre_issue(pre, cur, tid, ui); else if (t == 2) E.pre_finish(pre, tid, ui);
;             if constexpr (SP2) {
;             PG8_LDB(B0, 0, 0); PG8_LDB(B1, 0, 1); PG8_SCHED; PG8_LDA(At, 0, 0); PG8_STAGE(PG8_SA(1, 1), a1 + hstep, voffA);
;             PG8_WAIT_V(8); PG8_WAIT_L(0); PG8_BAR; PG8_MMA(0, 0, At, B0); PG8_MMA(0, 1, At, B1); PG8_BAR; PG8_SCHED;
;             PG8_LDA(At, 0, 1); PG8_STAGE(PG8_SB(0, 0), b2, voffB); PG8_STAGE(PG8_SB(0, 1), b2 + hstep, voffB); PG8_STAGE(PG8_SA(0, 0), a2, voffA);
;             PG8_WAIT_V(8); PG8_WAIT_L(0); PG8_BAR; PG8_MMA(1, 0, At, B0); PG8_MMA(1, 1, At, B1); PG8_BAR; PG8_SCHED;
.LBB0_998:
	s_add_u32 s48, s68, 0xfff80080
	s_addc_u32 s49, s69, -1
	s_add_i32 s81, 0, 0x10000
	s_cmp_eq_u32 s79, 28
	s_cselect_b32 s77, s51, s49
	s_cselect_b32 s76, s59, s48
	s_cselect_b32 s71, s25, s78
	s_cselect_b32 s70, s73, s75
	s_add_i32 s48, 0, 0x14000
	v_add_u32_e32 v136, s81, v233
	v_add_u32_e32 v160, s48, v233
	ds_read_b128 v[108:111], v136
	ds_read_b128 v[112:115], v136 offset:1024
	ds_read_b128 v[128:131], v136 offset:2048
	ds_read_b128 v[136:139], v136 offset:3072
	ds_read_b128 v[148:151], v160
	ds_read_b128 v[152:155], v160 offset:1024
	ds_read_b128 v[156:159], v160 offset:2048
	ds_read_b128 v[160:163], v160 offset:3072
	v_lshl_add_u64 v[198:199], s[68:69], 0, v[196:197]
	s_add_i32 m0, s6, 0xc000
	ds_read_b128 v[164:167], v234
	ds_read_b128 v[168:171], v234 offset:1024
	ds_read_b128 v[172:175], v234 offset:2048
	ds_read_b128 v[176:179], v234 offset:3072
	ds_read_b128 v[180:183], v234 offset:4096
	ds_read_b128 v[184:187], v234 offset:5120
	ds_read_b128 v[206:209], v234 offset:6144
	ds_read_b128 v[210:213], v234 offset:7168
	global_load_lds_dwordx4 v[198:199], off
	v_lshl_add_u64 v[198:199], s[68:69], 0, v[194:195]
	s_add_i32 m0, s6, 0xe000
	s_nop 0
	global_load_lds_dwordx4 v[198:199], off
	s_waitcnt vmcnt(8)
	s_waitcnt lgkmcnt(0)
	s_setprio 1
	s_barrier
	v_mfma_f32_16x16x32_bf16 v[144:147], v[108:111], v[164:167], v[144:147]
	v_mfma_f32_16x16x32_bf16 v[140:143], v[128:131], v[164:167], v[140:143]
	v_mfma_f32_16x16x32_bf16 v[120:123], v[108:111], v[172:175], v[120:123]
	v_mfma_f32_16x16x32_bf16 v[116:119], v[128:131], v[172:175], v[116:119]
	v_mfma_f32_16x16x32_bf16 v[96:99], v[108:111], v[180:183], v[96:99]
	v_mfma_f32_16x16x32_bf16 v[92:95], v[128:131], v[180:183], v[92:95]
	v_mfma_f32_16x16x32_bf16 v[80:83], v[108:111], v[206:209], v[80:83]
	v_mfma_f32_16x16x32_bf16 v[76:79], v[128:131], v[206:209], v[76:79]
	v_mfma_f32_16x16x32_bf16 v[144:147], v[112:115], v[168:171], v[144:147]
	v_mfma_f32_16x16x32_bf16 v[140:143], v[136:139], v[168:171], v[140:143]
	v_mfma_f32_16x16x32_bf16 v[120:123], v[112:115], v[176:179], v[120:123]
	v_mfma_f32_16x16x32_bf16 v[116:119], v[136:139], v[176:179], v[116:119]
	v_mfma_f32_16x16x32_bf16 v[96:99], v[112:115], v[184:187], v[96:99]
	v_mfma_f32_16x16x32_bf16 v[92:95], v[136:139], v[184:187], v[92:95]
	v_mfma_f32_16x16x32_bf16 v[80:83], v[112:115], v[210:213], v[80:83]
	v_mfma_f32_16x16x32_bf16 v[76:79], v[136:139], v[210:213], v[76:79]
	s_setprio 0
	s_setprio 1
	v_mfma_f32_16x16x32_bf16 v[132:135], v[148:151], v[164:167], v[132:135]
	v_mfma_f32_16x16x32_bf16 v[124:127], v[156:159], v[164:167], v[124:127]
	v_mfma_f32_16x16x32_bf16 v[104:107], v[148:151], v[172:175], v[104:107]
	v_mfma_f32_16x16x32_bf16 v[100:103], v[156:159], v[172:175], v[100:103]
	v_mfma_f32_16x16x32_bf16 v[88:91], v[148:151], v[180:183], v[88:91]
	v_mfma_f32_16x16x32_bf16 v[84:87], v[156:159], v[180:183], v[84:87]
	v_mfma_f32_16x16x32_bf16 v[72:75], v[148:151], v[206:209], v[72:75]
	v_mfma_f32_16x16x32_bf16 v[68:71], v[156:159], v[206:209], v[68:71]
	v_mfma_f32_16x16x32_bf16 v[132:135], v[152:155], v[168:171], v[132:135]
	v_mfma_f32_16x16x32_bf16 v[124:127], v[160:163], v[168:171], v[124:127]
	v_mfma_f32_16x16x32_bf16 v[104:107], v[152:155], v[176:179], v[104:107]
	v_mfma_f32_16x16x32_bf16 v[100:103], v[160:163], v[176:179], v[100:103]
	v_mfma_f32_16x16x32_bf16 v[88:91], v[152:155], v[184:187], v[88:91]
	v_mfma_f32_16x16x32_bf16 v[84:87], v[160:163], v[184:187], v[84:87]
	v_mfma_f32_16x16x32_bf16 v[72:75], v[152:155], v[210:213], v[72:75]
	v_mfma_f32_16x16x32_bf16 v[68:71], v[160:163], v[210:213], v[68:71]
	s_barrier
	s_setprio 0
	s_add_i32 s49, s81, s5
	v_lshl_add_u64 v[198:199], s[70:71], 0, v[200:201]
	s_mov_b32 m0, s49
	ds_read_b128 v[164:167], v234 offset:16384
	ds_read_b128 v[168:171], v234 offset:17408
	ds_read_b128 v[172:175], v234 offset:18432
	ds_read_b128 v[176:179], v234 offset:19456
	ds_read_b128 v[180:183], v234 offset:20480
	ds_read_b128 v[184:187], v234 offset:21504
	ds_read_b128 v[206:209], v234 offset:22528
	ds_read_b128 v[210:213], v234 offset:23552
	global_load_lds_dwordx4 v[198:199], off
	s_add_i32 m0, s49, 0x2000
	s_add_u32 s84, s70, 0x80000
	v_lshl_add_u64 v[214:215], s[70:71], 0, v[188:189]
	s_addc_u32 s85, s71, 0
	s_add_i32 s48, s48, s5
	global_load_lds_dwordx4 v[214:215], off
	v_lshl_add_u64 v[216:217], s[84:85], 0, v[200:201]
	s_mov_b32 m0, s48
	v_lshl_add_u64 v[218:219], s[76:77], 0, v[190:191]
	global_load_lds_dwordx4 v[216:217], off
	v_lshl_add_u64 v[216:217], s[84:85], 0, v[188:189]
	s_add_i32 m0, s48, 0x2000
	s_nop 0
	global_load_lds_dwordx4 v[216:217], off
	v_lshl_add_u64 v[216:217], s[76:77], 0, v[192:193]
	s_mov_b32 m0, s6
	s_nop 0
	global_load_lds_dwordx4 v[216:217], off
	s_mov_b32 m0, s20
	s_nop 0
	global_load_lds_dwordx4 v[218:219], off
	s_waitcnt vmcnt(8)
	s_waitcnt lgkmcnt(0)
	s_setprio 1
	s_barrier
; #define PG8_STAGE(bufoff, gbase, voff) do { _Pragma("unroll") for (int _i = 0; _i < 2; ++_i) \
;         __builtin_amdgcn_global_load_lds((const unsigned*)((const char*)(gbase) + (voff)[_i]), (PG8_LAS unsigned*)(lds + (bufoff) + ldsw + _i * 8192), 16, 0, 0); } while (0)
; #define PG8_LDA(dst, b, h) do { _Pragma("unroll") for (int m = 0; m < 4; ++m) _Pragma("unroll") for (int k = 0; k < 2; ++k) dst[m][k] = *(const PG8_LAS bf16x8*)(lds + PG8_SA(b, h) + aoff + m * 2048 + k * 1024); } while (0)
; #define PG8_LDB(dst, b, h) do { _Pragma("unroll") for (int n = 0; n < 2; ++n) _Pragma("unroll") for (int k = 0; k < 2; ++k) dst[n][k] = *(const PG8_LAS bf16x8*)(lds + PG8_SB(b, h) + boff + n * 2048 + k * 1024); } while (0)
; #define PG8_MMA(ai, bj, At, Bt) do { __builtin_amdgcn_s_setprio(1); _Pragma("unroll") for (int m = 0; m < 4; ++m) _Pragma("unroll") for (int n = 0; n < 2; ++n) _Pragma("unroll") for (int k = 0; k < 2; ++k) \
;         acc[ai][bj][m][n] = __builtin_amdgcn_mfma_f32_16x16x32_bf16(Bt[n][k], At[m][k], acc[ai][bj][m][n], 0, 0, 0); __builtin_amdgcn_s_setprio(0); } while (0)
; #define PG8_WAIT_V(n) asm volatile("s_waitcnt vmcnt(" #n ")" ::: "memory")
; #define PG8_WAIT_L(n) asm volatile("s_waitcnt lgkmcnt(" #n ")" ::: "memory")
; #define PG8_BAR __builtin_amdgcn_s_barrier()
; #define PG8_SCHED __builtin_amdgcn_sched_barrier(0)
;     ...
;             PG8_WAIT_V(8); PG8_WAIT_L(0); PG8_BAR; PG8_MMA(1, 0, At, B0); PG8_MMA(1, 1, At, B1); PG8_BAR; PG8_SCHED;
;             PG8_LDB(B0, 1, 0); PG8_LDB(B1, 1, 1); PG8_SCHED; PG8_LDA(At, 1, 0); PG8_STAGE(PG8_SA(0, 1), a2 + hstep, voffA);
;             PG8_WAIT_V(8); PG8_WAIT_L(0); PG8_BAR; PG8_MMA(0, 0, At, B0); PG8_MMA(0, 1, At, B1); PG8_BAR; PG8_SCHED;
	v_mfma_f32_16x16x32_bf16 v[64:67], v[108:111], v[164:167], v[64:67]
	v_mfma_f32_16x16x32_bf16 v[60:63], v[128:131], v[164:167], v[60:63]
	v_mfma_f32_16x16x32_bf16 v[48:51], v[108:111], v[172:175], v[48:51]
	v_mfma_f32_16x16x32_bf16 v[44:47], v[128:131], v[172:175], v[44:47]
	v_mfma_f32_16x16x32_bf16 v[32:35], v[108:111], v[180:183], v[32:35]
	v_mfma_f32_16x16x32_bf16 v[28:31], v[128:131], v[180:183], v[28:31]
	v_mfma_f32_16x16x32_bf16 v[16:19], v[108:111], v[206:209], v[16:19]
	v_mfma_f32_16x16x32_bf16 v[12:15], v[128:131], v[206:209], v[12:15]
	v_mfma_f32_16x16x32_bf16 v[64:67], v[112:115], v[168:171], v[64:67]
	v_mfma_f32_16x16x32_bf16 v[60:63], v[136:139], v[168:171], v[60:63]
	v_mfma_f32_16x16x32_bf16 v[48:51], v[112:115], v[176:179], v[48:51]
	v_mfma_f32_16x16x32_bf16 v[44:47], v[136:139], v[176:179], v[44:47]
	v_mfma_f32_16x16x32_bf16 v[32:35], v[112:115], v[184:187], v[32:35]
	v_mfma_f32_16x16x32_bf16 v[28:31], v[136:139], v[184:187], v[28:31]
	v_mfma_f32_16x16x32_bf16 v[16:19], v[112:115], v[210:213], v[16:19]
	v_mfma_f32_16x16x32_bf16 v[12:15], v[136:139], v[210:213], v[12:15]
	s_setprio 0
	s_setprio 1
	v_mfma_f32_16x16x32_bf16 v[56:59], v[148:151], v[164:167], v[56:59]
	v_mfma_f32_16x16x32_bf16 v[52:55], v[156:159], v[164:167], v[52:55]
	v_mfma_f32_16x16x32_bf16 v[40:43], v[148:151], v[172:175], v[40:43]
	v_mfma_f32_16x16x32_bf16 v[36:39], v[156:159], v[172:175], v[36:39]
	v_mfma_f32_16x16x32_bf16 v[24:27], v[148:151], v[180:183], v[24:27]
	v_mfma_f32_16x16x32_bf16 v[20:23], v[156:159], v[180:183], v[20:23]
	v_mfma_f32_16x16x32_bf16 v[8:11], v[148:151], v[206:209], v[8:11]
	v_mfma_f32_16x16x32_bf16 v[4:7], v[156:159], v[206:209], v[4:7]
	v_mfma_f32_16x16x32_bf16 v[56:59], v[152:155], v[168:171], v[56:59]
	v_mfma_f32_16x16x32_bf16 v[52:55], v[160:163], v[168:171], v[52:55]
	v_mfma_f32_16x16x32_bf16 v[40:43], v[152:155], v[176:179], v[40:43]
	v_mfma_f32_16x16x32_bf16 v[36:39], v[160:163], v[176:179], v[36:39]
	v_mfma_f32_16x16x32_bf16 v[24:27], v[152:155], v[184:187], v[24:27]
	v_mfma_f32_16x16x32_bf16 v[20:23], v[160:163], v[184:187], v[20:23]
	v_mfma_f32_16x16x32_bf16 v[8:11], v[152:155], v[210:213], v[8:11]
	v_mfma_f32_16x16x32_bf16 v[4:7], v[160:163], v[210:213], v[4:7]
	s_barrier
	s_setprio 0
	s_add_i32 s48, 0, 0x18000
	s_add_i32 s49, 0, 0x1c000
	v_add_u32_e32 v136, s48, v233
	v_add_u32_e32 v160, s49, v233
	ds_read_b128 v[108:111], v136
	ds_read_b128 v[112:115], v136 offset:1024
	ds_read_b128 v[128:131], v136 offset:2048
	ds_read_b128 v[136:139], v136 offset:3072
	ds_read_b128 v[148:151], v160
	ds_read_b128 v[152:155], v160 offset:1024
	ds_read_b128 v[156:159], v160 offset:2048
	ds_read_b128 v[160:163], v160 offset:3072
	s_add_u32 s76, s76, 0x80000
	s_addc_u32 s77, s77, 0
	s_mov_b32 m0, s21
	v_lshl_add_u64 v[220:221], s[76:77], 0, v[192:193]
	ds_read_b128 v[164:167], v234 offset:32768
	ds_read_b128 v[168:171], v234 offset:33792
	ds_read_b128 v[172:175], v234 offset:34816
	ds_read_b128 v[176:179], v234 offset:35840
	ds_read_b128 v[180:183], v234 offset:36864
	ds_read_b128 v[184:187], v234 offset:37888
	ds_read_b128 v[206:209], v234 offset:38912
	ds_read_b128 v[210:213], v234 offset:39936
	global_load_lds_dwordx4 v[220:221], off
	v_lshl_add_u64 v[220:221], s[76:77], 0, v[190:191]
	s_mov_b32 m0, s23
	s_nop 0
	global_load_lds_dwordx4 v[220:221], off
	s_waitcnt vmcnt(8)
	s_waitcnt lgkmcnt(0)
	s_setprio 1
	s_barrier
	v_mfma_f32_16x16x32_bf16 v[144:147], v[108:111], v[164:167], v[144:147]
	v_mfma_f32_16x16x32_bf16 v[140:143], v[128:131], v[164:167], v[140:143]
	v_mfma_f32_16x16x32_bf16 v[120:123], v[108:111], v[172:175], v[120:123]
	v_mfma_f32_16x16x32_bf16 v[116:119], v[128:131], v[172:175], v[116:119]
	v_mfma_f32_16x16x32_bf16 v[96:99], v[108:111], v[180:183], v[96:99]
	v_mfma_f32_16x16x32_bf16 v[92:95], v[128:131], v[180:183], v[92:95]
	v_mfma_f32_16x16x32_bf16 v[80:83], v[108:111], v[206:209], v[80:83]
	v_mfma_f32_16x16x32_bf16 v[76:79], v[128:131], v[206:209], v[76:79]
	v_mfma_f32_16x16x32_bf16 v[144:147], v[112:115], v[168:171], v[144:147]
	v_mfma_f32_16x16x32_bf16 v[140:143], v[136:139], v[168:171], v[140:143]
	v_mfma_f32_16x16x32_bf16 v[120:123], v[112:115], v[176:179], v[120:123]
	v_mfma_f32_16x16x32_bf16 v[116:119], v[136:139], v[176:179], v[116:119]
	v_mfma_f32_16x16x32_bf16 v[96:99], v[112:115], v[184:187], v[96:99]
	v_mfma_f32_16x16x32_bf16 v[92:95], v[136:139], v[184:187], v[92:95]
	v_mfma_f32_16x16x32_bf16 v[80:83], v[112:115], v[210:213], v[80:83]
	v_mfma_f32_16x16x32_bf16 v[76:79], v[136:139], v[210:213], v[76:79]
	s_setprio 0
	s_setprio 1
	v_mfma_f32_16x16x32_bf16 v[132:135], v[148:151], v[164:167], v[132:135]
	v_mfma_f32_16x16x32_bf16 v[124:127], v[156:159], v[164:167], v[124:127]
	v_mfma_f32_16x16x32_bf16 v[104:107], v[148:151], v[172:175], v[104:107]
	v_mfma_f32_16x16x32_bf16 v[100:103], v[156:159], v[172:175], v[100:103]
	v_mfma_f32_16x16x32_bf16 v[88:91], v[148:151], v[180:183], v[88:91]
	v_mfma_f32_16x16x32_bf16 v[84:87], v[156:159], v[180:183], v[84:87]
	v_mfma_f32_16x16x32_bf16 v[72:75], v[148:151], v[206:209], v[72:75]
	v_mfma_f32_16x16x32_bf16 v[68:71], v[156:159], v[206:209], v[68:71]
	v_mfma_f32_16x16x32_bf16 v[132:135], v[152:155], v[168:171], v[132:135]
	v_mfma_f32_16x16x32_bf16 v[124:127], v[160:163], v[168:171], v[124:127]
	v_mfma_f32_16x16x32_bf16 v[104:107], v[152:155], v[176:179], v[104:107]
	v_mfma_f32_16x16x32_bf16 v[100:103], v[160:163], v[176:179], v[100:103]
	v_mfma_f32_16x16x32_bf16 v[88:91], v[152:155], v[184:187], v[88:91]
	v_mfma_f32_16x16x32_bf16 v[84:87], v[160:163], v[184:187], v[84:87]
	v_mfma_f32_16x16x32_bf16 v[72:75], v[152:155], v[210:213], v[72:75]
	v_mfma_f32_16x16x32_bf16 v[68:71], v[160:163], v[210:213], v[68:71]
	s_barrier
; #define PG8_STAGE(bufoff, gbase, voff) do { _Pragma("unroll") for (int _i = 0; _i < 2; ++_i) \
;         __builtin_amdgcn_global_load_lds((const unsigned*)((const char*)(gbase) + (voff)[_i]), (PG8_LAS unsigned*)(lds + (bufoff) + ldsw + _i * 8192), 16, 0, 0); } while (0)
; #define PG8_LDA(dst, b, h) do { _Pragma("unroll") for (int m = 0; m < 4; ++m) _Pragma("unroll") for (int k = 0; k < 2; ++k) dst[m][k] = *(const PG8_LAS bf16x8*)(lds + PG8_SA(b, h) + aoff + m * 2048 + k * 1024); } while (0)
; #define PG8_MMA(ai, bj, At, Bt) do { __builtin_amdgcn_s_setprio(1); _Pragma("unroll") for (int m = 0; m < 4; ++m) _Pragma("unroll") for (int n = 0; n < 2; ++n) _Pragma("unroll") for (int k = 0; k < 2; ++k) \
;         acc[ai][bj][m][n] = __builtin_amdgcn_mfma_f32_16x16x32_bf16(Bt[n][k], At[m][k], acc[ai][bj][m][n], 0, 0, 0); __builtin_amdgcn_s_setprio(0); } while (0)
; #define PG8_WAIT_V(n) asm volatile("s_waitcnt vmcnt(" #n ")" ::: "memory")
; #define PG8_WAIT_L(n) asm volatile("s_waitcnt lgkmcnt(" #n ")" ::: "memory")
; #define PG8_BAR __builtin_amdgcn_s_barrier()
; #define PG8_SCHED __builtin_amdgcn_sched_barrier(0)
;     ...
;             PG8_WAIT_V(8); PG8_WAIT_L(0); PG8_BAR; PG8_MMA(0, 0, At, B0); PG8_MMA(0, 1, At, B1); PG8_BAR; PG8_SCHED;
;             PG8_LDA(At, 1, 1); PG8_STAGE(PG8_SB(1, 0), b3, voffB); PG8_STAGE(PG8_SB(1, 1), b3 + hstep, voffB); PG8_STAGE(PG8_SA(1, 0), a3, voffA);
;             PG8_WAIT_V(8); PG8_WAIT_L(0); PG8_BAR; PG8_MMA(1, 0, At, B0); PG8_MMA(1, 1, At, B1); PG8_BAR; PG8_SCHED;
;     ...
;         if constexpr (ALIGN_EPI) { if (wr == 0) PG8_BAR; }
	s_setprio 0
	s_add_i32 s48, s48, s5
	v_lshl_add_u64 v[198:199], v[198:199], 0, s[66:67]
	s_mov_b32 m0, s48
	ds_read_b128 v[164:167], v234 offset:49152
	ds_read_b128 v[168:171], v234 offset:50176
	ds_read_b128 v[172:175], v234 offset:51200
	ds_read_b128 v[176:179], v234 offset:52224
	ds_read_b128 v[180:183], v234 offset:53248
	ds_read_b128 v[184:187], v234 offset:54272
	ds_read_b128 v[206:209], v234 offset:55296
	ds_read_b128 v[210:213], v234 offset:56320
	global_load_lds_dwordx4 v[198:199], off
	s_add_i32 m0, s48, 0x2000
	s_add_u32 s70, s70, 0x80080
	v_lshl_add_u64 v[198:199], v[214:215], 0, s[66:67]
	s_addc_u32 s71, s71, 0
	s_add_i32 s48, s49, s5
	global_load_lds_dwordx4 v[198:199], off
	v_lshl_add_u64 v[198:199], s[70:71], 0, v[200:201]
	s_mov_b32 m0, s48
	s_nop 0
	global_load_lds_dwordx4 v[198:199], off
	v_lshl_add_u64 v[198:199], s[70:71], 0, v[188:189]
	s_add_i32 m0, s48, 0x2000
	s_nop 0
	global_load_lds_dwordx4 v[198:199], off
	v_lshl_add_u64 v[198:199], v[216:217], 0, s[66:67]
	s_mov_b32 m0, s54
	s_nop 0
	global_load_lds_dwordx4 v[198:199], off
	v_lshl_add_u64 v[198:199], v[218:219], 0, s[66:67]
	s_mov_b32 m0, s55
	s_nop 0
	global_load_lds_dwordx4 v[198:199], off
	s_waitcnt vmcnt(8)
	s_waitcnt lgkmcnt(0)
	s_setprio 1
	s_barrier
	v_mfma_f32_16x16x32_bf16 v[64:67], v[108:111], v[164:167], v[64:67]
	v_mfma_f32_16x16x32_bf16 v[60:63], v[128:131], v[164:167], v[60:63]
	v_mfma_f32_16x16x32_bf16 v[48:51], v[108:111], v[172:175], v[48:51]
	v_mfma_f32_16x16x32_bf16 v[44:47], v[128:131], v[172:175], v[44:47]
	v_mfma_f32_16x16x32_bf16 v[32:35], v[108:111], v[180:183], v[32:35]
	v_mfma_f32_16x16x32_bf16 v[28:31], v[128:131], v[180:183], v[28:31]
	v_mfma_f32_16x16x32_bf16 v[16:19], v[108:111], v[206:209], v[16:19]
	v_mfma_f32_16x16x32_bf16 v[12:15], v[128:131], v[206:209], v[12:15]
	v_mfma_f32_16x16x32_bf16 v[64:67], v[112:115], v[168:171], v[64:67]
	v_mfma_f32_16x16x32_bf16 v[60:63], v[136:139], v[168:171], v[60:63]
	v_mfma_f32_16x16x32_bf16 v[48:51], v[112:115], v[176:179], v[48:51]
	v_mfma_f32_16x16x32_bf16 v[44:47], v[136:139], v[176:179], v[44:47]
	v_mfma_f32_16x16x32_bf16 v[32:35], v[112:115], v[184:187], v[32:35]
	v_mfma_f32_16x16x32_bf16 v[28:31], v[136:139], v[184:187], v[28:31]
	v_mfma_f32_16x16x32_bf16 v[16:19], v[112:115], v[210:213], v[16:19]
	v_mfma_f32_16x16x32_bf16 v[12:15], v[136:139], v[210:213], v[12:15]
	s_setprio 0
	s_setprio 1
	v_mfma_f32_16x16x32_bf16 v[56:59], v[148:151], v[164:167], v[56:59]
	v_mfma_f32_16x16x32_bf16 v[52:55], v[156:159], v[164:167], v[52:55]
	v_mfma_f32_16x16x32_bf16 v[40:43], v[148:151], v[172:175], v[40:43]
	v_mfma_f32_16x16x32_bf16 v[36:39], v[156:159], v[172:175], v[36:39]
	v_mfma_f32_16x16x32_bf16 v[24:27], v[148:151], v[180:183], v[24:27]
	v_mfma_f32_16x16x32_bf16 v[20:23], v[156:159], v[180:183], v[20:23]
	v_mfma_f32_16x16x32_bf16 v[8:11], v[148:151], v[206:209], v[8:11]
	v_mfma_f32_16x16x32_bf16 v[4:7], v[156:159], v[206:209], v[4:7]
	v_mfma_f32_16x16x32_bf16 v[56:59], v[152:155], v[168:171], v[56:59]
	v_mfma_f32_16x16x32_bf16 v[52:55], v[160:163], v[168:171], v[52:55]
	v_mfma_f32_16x16x32_bf16 v[40:43], v[152:155], v[176:179], v[40:43]
	v_mfma_f32_16x16x32_bf16 v[36:39], v[160:163], v[176:179], v[36:39]
	v_mfma_f32_16x16x32_bf16 v[24:27], v[152:155], v[184:187], v[24:27]
	v_mfma_f32_16x16x32_bf16 v[20:23], v[160:163], v[184:187], v[20:23]
	v_mfma_f32_16x16x32_bf16 v[8:11], v[152:155], v[210:213], v[8:11]
	v_mfma_f32_16x16x32_bf16 v[4:7], v[160:163], v[210:213], v[4:7]
	s_barrier
	s_setprio 0
	s_add_i32 s79, s79, 2
	s_add_u32 s75, s75, 0x100
	s_addc_u32 s78, s78, 0
	s_add_u32 s68, s68, 0x100
	s_addc_u32 s69, s69, 0
	s_cmp_gt_u32 s79, 29
	s_cbranch_scc0 .LBB0_998
	s_and_b64 vcc, exec, s[14:15]
	s_cbranch_vccz .LBB0_1001
	s_barrier

; #define PG8_STAGE(bufoff, gbase, voff) do { _Pragma("unroll") for (int _i = 0; _i < 2; ++_i) \
;         __builtin_amdgcn_global_load_lds((const unsigned*)((const char*)(gbase) + (voff)[_i]), (PG8_LAS unsigned*)(lds + (bufoff) + ldsw + _i * 8192), 16, 0, 0); } while (0)
; #define PG8_LDA(dst, b, h) do { _Pragma("unroll") for (int m = 0; m < 4; ++m) _Pragma("unroll") for (int k = 0; k < 2; ++k) dst[m][k] = *(const PG8_LAS bf16x8*)(lds + PG8_SA(b, h) + aoff + m * 2048 + k * 1024); } while (0)
; #define PG8_LDB(dst, b, h) do { _Pragma("unroll") for (int n = 0; n < 2; ++n) _Pragma("unroll") for (int k = 0; k < 2; ++k) dst[n][k] = *(const PG8_LAS bf16x8*)(lds + PG8_SB(b, h) + boff + n * 2048 + k * 1024); } while (0)
; #define PG8_MMA(ai, bj, At, Bt) do { __builtin_amdgcn_s_setprio(1); _Pragma("unroll") for (int m = 0; m < 4; ++m) _Pragma("unroll") for (int n = 0; n < 2; ++n) _Pragma("unroll") for (int k = 0; k < 2; ++k) \
;         acc[ai][bj][m][n] = __builtin_amdgcn_mfma_f32_16x16x32_bf16(Bt[n][k], At[m][k], acc[ai][bj][m][n], 0, 0, 0); __builtin_amdgcn_s_setprio(0); } while (0)
; #define PG8_WAIT_V(n) asm volatile("s_waitcnt vmcnt(" #n ")" ::: "memory")
; #define PG8_WAIT_L(n) asm volatile("s_waitcnt lgkmcnt(" #n ")" ::: "memory")
; #define PG8_BAR __builtin_amdgcn_s_barrier()
;     ...
;         for (int t = 0; t < nt; t += 2) {
;             const bool last = (t == nt - 2);
;             const char* a1 = cA + (size_t)(t + 1) * kstep;
;             const char* a2 = last ? nA : cA + (size_t)(t + 2) * kstep; const char* b2 = last ? nB : cB + (size_t)(t + 2) * kstep;
;             const char* a3 = a2 + kstep; const char* b3 = b2 + kstep;
;             if (last && has_next) S.a_ready(nxt);
;             if (t == 0) E.pre_issue(pre, cur, tid, ui); else if (t == 2) E.pre_finish(pre, tid, ui);
;             if constexpr (SP2) {
;             PG8_LDB(B0, 0, 0); PG8_LDB(B1, 0, 1); PG8_SCHED; PG8_LDA(At, 0, 0); PG8_STAGE(PG8_SA(1, 1), a1 + hstep, voffA);
;             PG8_WAIT_V(8); PG8_WAIT_L(0); PG8_BAR; PG8_MMA(0, 0, At, B0); PG8_MMA(0, 1, At, B1); PG8_BAR; PG8_SCHED;
;             PG8_LDA(At, 0, 1); PG8_STAGE(PG8_SB(0, 0), b2, voffB); PG8_STAGE(PG8_SB(0, 1), b2 + hstep, voffB); PG8_STAGE(PG8_SA(0, 0), a2, voffA);
;             PG8_WAIT_V(8); PG8_WAIT_L(0); PG8_BAR; PG8_MMA(1, 0, At, B0); PG8_MMA(1, 1, At, B1); PG8_BAR; PG8_SCHED;
.LBB0_1086:
	s_add_u32 s10, s8, 0xfff80080
	s_addc_u32 s11, s9, -1
	s_add_i32 s48, 0, 0x10000
	s_cmp_eq_u32 s97, 28
	s_cselect_b32 s13, s69, s11
	s_cselect_b32 s12, s76, s10
	v_add_u32_e32 v100, s48, v221
	s_cselect_b32 s11, s77, s89
	s_cselect_b32 s10, s82, s83
	s_add_i32 vcc_lo, 0, 0x14000
	ds_read_b128 v[106:109], v100
	ds_read_b128 v[110:113], v100 offset:1024
	ds_read_b128 v[114:117], v100 offset:2048
	ds_read_b128 v[118:121], v100 offset:3072
	v_add_u32_e32 v100, vcc_lo, v221
	ds_read_b128 v[122:125], v100
	ds_read_b128 v[126:129], v100 offset:1024
	ds_read_b128 v[130:133], v100 offset:2048
	ds_read_b128 v[134:137], v100 offset:3072
	v_lshl_add_u64 v[100:101], s[8:9], 0, v[190:191]
	s_add_i32 m0, s1, 0xc000
	ds_read_b128 v[166:169], v222
	ds_read_b128 v[170:173], v222 offset:1024
	ds_read_b128 v[174:177], v222 offset:2048
	ds_read_b128 v[178:181], v222 offset:3072
	ds_read_b128 v[194:197], v222 offset:4096
	ds_read_b128 v[206:209], v222 offset:5120
	ds_read_b128 v[210:213], v222 offset:6144
	ds_read_b128 v[214:217], v222 offset:7168
	global_load_lds_dwordx4 v[100:101], off
	v_lshl_add_u64 v[100:101], s[8:9], 0, v[192:193]
	s_add_i32 m0, s1, 0xe000
	s_nop 0
	global_load_lds_dwordx4 v[100:101], off
	s_waitcnt vmcnt(8)
	s_waitcnt lgkmcnt(0)
	s_setprio 1
	s_barrier
	v_mfma_f32_16x16x32_bf16 v[4:7], v[106:109], v[166:169], v[4:7]
	v_mfma_f32_16x16x32_bf16 v[72:75], v[114:117], v[166:169], v[72:75]
	v_mfma_f32_16x16x32_bf16 v[162:165], v[106:109], v[174:177], v[162:165]
	v_mfma_f32_16x16x32_bf16 v[60:63], v[114:117], v[174:177], v[60:63]
	v_mfma_f32_16x16x32_bf16 v[158:161], v[106:109], v[194:197], v[158:161]
	v_mfma_f32_16x16x32_bf16 v[56:59], v[114:117], v[194:197], v[56:59]
	v_mfma_f32_16x16x32_bf16 v[96:99], v[106:109], v[210:213], v[96:99]
	v_mfma_f32_16x16x32_bf16 v[76:79], v[114:117], v[210:213], v[76:79]
	v_mfma_f32_16x16x32_bf16 v[4:7], v[110:113], v[170:173], v[4:7]
	v_mfma_f32_16x16x32_bf16 v[72:75], v[118:121], v[170:173], v[72:75]
	v_mfma_f32_16x16x32_bf16 v[162:165], v[110:113], v[178:181], v[162:165]
	v_mfma_f32_16x16x32_bf16 v[60:63], v[118:121], v[178:181], v[60:63]
	v_mfma_f32_16x16x32_bf16 v[158:161], v[110:113], v[206:209], v[158:161]
	v_mfma_f32_16x16x32_bf16 v[56:59], v[118:121], v[206:209], v[56:59]
	v_mfma_f32_16x16x32_bf16 v[96:99], v[110:113], v[214:217], v[96:99]
	v_mfma_f32_16x16x32_bf16 v[76:79], v[118:121], v[214:217], v[76:79]
	s_setprio 0
	s_setprio 1
	v_mfma_f32_16x16x32_bf16 v[8:11], v[122:125], v[166:169], v[8:11]
	v_mfma_f32_16x16x32_bf16 v[64:67], v[130:133], v[166:169], v[64:67]
	v_mfma_f32_16x16x32_bf16 v[154:157], v[122:125], v[174:177], v[154:157]
	v_mfma_f32_16x16x32_bf16 v[52:55], v[130:133], v[174:177], v[52:55]
	v_mfma_f32_16x16x32_bf16 v[150:153], v[122:125], v[194:197], v[150:153]
	v_mfma_f32_16x16x32_bf16 v[48:51], v[130:133], v[194:197], v[48:51]
	v_mfma_f32_16x16x32_bf16 v[92:95], v[122:125], v[210:213], v[92:95]
	v_mfma_f32_16x16x32_bf16 v[68:71], v[130:133], v[210:213], v[68:71]
	v_mfma_f32_16x16x32_bf16 v[8:11], v[126:129], v[170:173], v[8:11]
	v_mfma_f32_16x16x32_bf16 v[64:67], v[134:137], v[170:173], v[64:67]
	v_mfma_f32_16x16x32_bf16 v[154:157], v[126:129], v[178:181], v[154:157]
	v_mfma_f32_16x16x32_bf16 v[52:55], v[134:137], v[178:181], v[52:55]
	v_mfma_f32_16x16x32_bf16 v[150:153], v[126:129], v[206:209], v[150:153]
	v_mfma_f32_16x16x32_bf16 v[48:51], v[134:137], v[206:209], v[48:51]
	v_mfma_f32_16x16x32_bf16 v[92:95], v[126:129], v[214:217], v[92:95]
	v_mfma_f32_16x16x32_bf16 v[68:71], v[134:137], v[214:217], v[68:71]
	s_barrier
	s_setprio 0
	s_add_i32 s48, s48, s0
	v_lshl_add_u64 v[198:199], s[10:11], 0, v[186:187]
	s_mov_b32 m0, s48
	ds_read_b128 v[166:169], v222 offset:16384
	ds_read_b128 v[170:173], v222 offset:17408
	ds_read_b128 v[174:177], v222 offset:18432
	ds_read_b128 v[178:181], v222 offset:19456
	ds_read_b128 v[194:197], v222 offset:20480
	ds_read_b128 v[206:209], v222 offset:21504
	ds_read_b128 v[210:213], v222 offset:22528
	ds_read_b128 v[214:217], v222 offset:23552
	global_load_lds_dwordx4 v[198:199], off
	s_add_i32 m0, s48, 0x2000
	s_add_u32 s48, s10, 0x80000
	v_lshl_add_u64 v[218:219], s[10:11], 0, v[182:183]
	s_addc_u32 s49, s11, 0
	s_add_i32 vcc_lo, vcc_lo, s0
	global_load_lds_dwordx4 v[218:219], off
	v_lshl_add_u64 v[100:101], s[48:49], 0, v[186:187]
	s_mov_b32 m0, vcc_lo
	v_lshl_add_u64 v[224:225], s[12:13], 0, v[188:189]
	global_load_lds_dwordx4 v[100:101], off
	v_lshl_add_u64 v[100:101], s[48:49], 0, v[182:183]
	s_add_i32 m0, vcc_lo, 0x2000
	v_lshl_add_u64 v[232:233], s[12:13], 0, v[184:185]
	global_load_lds_dwordx4 v[100:101], off
	s_mov_b32 m0, s1
	s_nop 0
	global_load_lds_dwordx4 v[224:225], off
	s_mov_b32 m0, s4
	s_nop 0
	global_load_lds_dwordx4 v[232:233], off
	s_waitcnt vmcnt(8)
	s_waitcnt lgkmcnt(0)
	s_setprio 1
	s_barrier
; #define PG8_STAGE(bufoff, gbase, voff) do { _Pragma("unroll") for (int _i = 0; _i < 2; ++_i) \
;         __builtin_amdgcn_global_load_lds((const unsigned*)((const char*)(gbase) + (voff)[_i]), (PG8_LAS unsigned*)(lds + (bufoff) + ldsw + _i * 8192), 16, 0, 0); } while (0)
; #define PG8_LDA(dst, b, h) do { _Pragma("unroll") for (int m = 0; m < 4; ++m) _Pragma("unroll") for (int k = 0; k < 2; ++k) dst[m][k] = *(const PG8_LAS bf16x8*)(lds + PG8_SA(b, h) + aoff + m * 2048 + k * 1024); } while (0)
; #define PG8_LDB(dst, b, h) do { _Pragma("unroll") for (int n = 0; n < 2; ++n) _Pragma("unroll") for (int k = 0; k < 2; ++k) dst[n][k] = *(const PG8_LAS bf16x8*)(lds + PG8_SB(b, h) + boff + n * 2048 + k * 1024); } while (0)
; #define PG8_MMA(ai, bj, At, Bt) do { __builtin_amdgcn_s_setprio(1); _Pragma("unroll") for (int m = 0; m < 4; ++m) _Pragma("unroll") for (int n = 0; n < 2; ++n) _Pragma("unroll") for (int k = 0; k < 2; ++k) \
;         acc[ai][bj][m][n] = __builtin_amdgcn_mfma_f32_16x16x32_bf16(Bt[n][k], At[m][k], acc[ai][bj][m][n], 0, 0, 0); __builtin_amdgcn_s_setprio(0); } while (0)
; #define PG8_WAIT_V(n) asm volatile("s_waitcnt vmcnt(" #n ")" ::: "memory")
; #define PG8_WAIT_L(n) asm volatile("s_waitcnt lgkmcnt(" #n ")" ::: "memory")
; #define PG8_BAR __builtin_amdgcn_s_barrier()
; #define PG8_SCHED __builtin_amdgcn_sched_barrier(0)
;     ...
;             PG8_WAIT_V(8); PG8_WAIT_L(0); PG8_BAR; PG8_MMA(1, 0, At, B0); PG8_MMA(1, 1, At, B1); PG8_BAR; PG8_SCHED;
;             PG8_LDB(B0, 1, 0); PG8_LDB(B1, 1, 1); PG8_SCHED; PG8_LDA(At, 1, 0); PG8_STAGE(PG8_SA(0, 1), a2 + hstep, voffA);
;             PG8_WAIT_V(8); PG8_WAIT_L(0); PG8_BAR; PG8_MMA(0, 0, At, B0); PG8_MMA(0, 1, At, B1); PG8_BAR; PG8_SCHED;
	v_mfma_f32_16x16x32_bf16 v[146:149], v[106:109], v[166:169], v[146:149]
	v_mfma_f32_16x16x32_bf16 v[44:47], v[114:117], v[166:169], v[44:47]
	v_mfma_f32_16x16x32_bf16 v[142:145], v[106:109], v[174:177], v[142:145]
	v_mfma_f32_16x16x32_bf16 v[40:43], v[114:117], v[174:177], v[40:43]
	v_mfma_f32_16x16x32_bf16 v[138:141], v[106:109], v[194:197], v[138:141]
	v_mfma_f32_16x16x32_bf16 v[36:39], v[114:117], v[194:197], v[36:39]
	v_mfma_f32_16x16x32_bf16 v[80:83], v[106:109], v[210:213], v[80:83]
	v_mfma_f32_16x16x32_bf16 v[20:23], v[114:117], v[210:213], v[20:23]
	v_mfma_f32_16x16x32_bf16 v[146:149], v[110:113], v[170:173], v[146:149]
	v_mfma_f32_16x16x32_bf16 v[44:47], v[118:121], v[170:173], v[44:47]
	v_mfma_f32_16x16x32_bf16 v[142:145], v[110:113], v[178:181], v[142:145]
	v_mfma_f32_16x16x32_bf16 v[40:43], v[118:121], v[178:181], v[40:43]
	v_mfma_f32_16x16x32_bf16 v[138:141], v[110:113], v[206:209], v[138:141]
	v_mfma_f32_16x16x32_bf16 v[36:39], v[118:121], v[206:209], v[36:39]
	v_mfma_f32_16x16x32_bf16 v[80:83], v[110:113], v[214:217], v[80:83]
	v_mfma_f32_16x16x32_bf16 v[20:23], v[118:121], v[214:217], v[20:23]
	s_setprio 0
	s_setprio 1
	v_mfma_f32_16x16x32_bf16 v[100:103], v[122:125], v[166:169], v[102:105]
	v_mfma_f32_16x16x32_bf16 v[32:35], v[130:133], v[166:169], v[32:35]
	v_mfma_f32_16x16x32_bf16 v[88:91], v[122:125], v[174:177], v[88:91]
	v_mfma_f32_16x16x32_bf16 v[28:31], v[130:133], v[174:177], v[28:31]
	v_mfma_f32_16x16x32_bf16 v[84:87], v[122:125], v[194:197], v[84:87]
	v_mfma_f32_16x16x32_bf16 v[24:27], v[130:133], v[194:197], v[24:27]
	v_mfma_f32_16x16x32_bf16 v[16:19], v[122:125], v[210:213], v[16:19]
	v_mfma_f32_16x16x32_bf16 v[12:15], v[130:133], v[210:213], v[12:15]
	v_mfma_f32_16x16x32_bf16 v[100:103], v[126:129], v[170:173], v[100:103]
	v_mfma_f32_16x16x32_bf16 v[32:35], v[134:137], v[170:173], v[32:35]
	v_mfma_f32_16x16x32_bf16 v[88:91], v[126:129], v[178:181], v[88:91]
	v_mfma_f32_16x16x32_bf16 v[28:31], v[134:137], v[178:181], v[28:31]
	v_mfma_f32_16x16x32_bf16 v[84:87], v[126:129], v[206:209], v[84:87]
	v_mfma_f32_16x16x32_bf16 v[24:27], v[134:137], v[206:209], v[24:27]
	v_mfma_f32_16x16x32_bf16 v[16:19], v[126:129], v[214:217], v[16:19]
	v_mfma_f32_16x16x32_bf16 v[12:15], v[134:137], v[214:217], v[12:15]
	s_barrier
	s_setprio 0
	s_add_i32 s48, 0, 0x18000
	s_add_i32 s49, 0, 0x1c000
	v_add_u32_e32 v116, s48, v221
	v_add_u32_e32 v132, s49, v221
	ds_read_b128 v[104:107], v116
	ds_read_b128 v[108:111], v116 offset:1024
	ds_read_b128 v[112:115], v116 offset:2048
	ds_read_b128 v[116:119], v116 offset:3072
	ds_read_b128 v[120:123], v132
	ds_read_b128 v[124:127], v132 offset:1024
	ds_read_b128 v[128:131], v132 offset:2048
	ds_read_b128 v[132:135], v132 offset:3072
	s_add_u32 s12, s12, 0x80000
	s_addc_u32 s13, s13, 0
	s_mov_b32 m0, s5
	v_lshl_add_u64 v[136:137], s[12:13], 0, v[188:189]
	ds_read_b128 v[166:169], v222 offset:32768
	ds_read_b128 v[170:173], v222 offset:33792
	ds_read_b128 v[174:177], v222 offset:34816
	ds_read_b128 v[178:181], v222 offset:35840
	ds_read_b128 v[194:197], v222 offset:36864
	ds_read_b128 v[206:209], v222 offset:37888
	ds_read_b128 v[210:213], v222 offset:38912
	ds_read_b128 v[214:217], v222 offset:39936
	global_load_lds_dwordx4 v[136:137], off
	v_lshl_add_u64 v[136:137], s[12:13], 0, v[184:185]
	s_mov_b32 m0, s44
	s_nop 0
	global_load_lds_dwordx4 v[136:137], off
	s_waitcnt vmcnt(8)
	s_waitcnt lgkmcnt(0)
	s_setprio 1
	s_barrier
	v_mfma_f32_16x16x32_bf16 v[4:7], v[104:107], v[166:169], v[4:7]
	v_mfma_f32_16x16x32_bf16 v[72:75], v[112:115], v[166:169], v[72:75]
	v_mfma_f32_16x16x32_bf16 v[162:165], v[104:107], v[174:177], v[162:165]
	v_mfma_f32_16x16x32_bf16 v[60:63], v[112:115], v[174:177], v[60:63]
	v_mfma_f32_16x16x32_bf16 v[158:161], v[104:107], v[194:197], v[158:161]
	v_mfma_f32_16x16x32_bf16 v[56:59], v[112:115], v[194:197], v[56:59]
	v_mfma_f32_16x16x32_bf16 v[96:99], v[104:107], v[210:213], v[96:99]
	v_mfma_f32_16x16x32_bf16 v[76:79], v[112:115], v[210:213], v[76:79]
	v_mfma_f32_16x16x32_bf16 v[4:7], v[108:111], v[170:173], v[4:7]
	v_mfma_f32_16x16x32_bf16 v[72:75], v[116:119], v[170:173], v[72:75]
	v_mfma_f32_16x16x32_bf16 v[162:165], v[108:111], v[178:181], v[162:165]
	v_mfma_f32_16x16x32_bf16 v[60:63], v[116:119], v[178:181], v[60:63]
	v_mfma_f32_16x16x32_bf16 v[158:161], v[108:111], v[206:209], v[158:161]
	v_mfma_f32_16x16x32_bf16 v[56:59], v[116:119], v[206:209], v[56:59]
	v_mfma_f32_16x16x32_bf16 v[96:99], v[108:111], v[214:217], v[96:99]
	v_mfma_f32_16x16x32_bf16 v[76:79], v[116:119], v[214:217], v[76:79]
	s_setprio 0
	s_setprio 1
	v_mfma_f32_16x16x32_bf16 v[8:11], v[120:123], v[166:169], v[8:11]
	v_mfma_f32_16x16x32_bf16 v[64:67], v[128:131], v[166:169], v[64:67]
	v_mfma_f32_16x16x32_bf16 v[154:157], v[120:123], v[174:177], v[154:157]
	v_mfma_f32_16x16x32_bf16 v[52:55], v[128:131], v[174:177], v[52:55]
	v_mfma_f32_16x16x32_bf16 v[150:153], v[120:123], v[194:197], v[150:153]
	v_mfma_f32_16x16x32_bf16 v[48:51], v[128:131], v[194:197], v[48:51]
	v_mfma_f32_16x16x32_bf16 v[92:95], v[120:123], v[210:213], v[92:95]
	v_mfma_f32_16x16x32_bf16 v[68:71], v[128:131], v[210:213], v[68:71]
	v_mfma_f32_16x16x32_bf16 v[8:11], v[124:127], v[170:173], v[8:11]
	v_mfma_f32_16x16x32_bf16 v[64:67], v[132:135], v[170:173], v[64:67]
	v_mfma_f32_16x16x32_bf16 v[154:157], v[124:127], v[178:181], v[154:157]
	v_mfma_f32_16x16x32_bf16 v[52:55], v[132:135], v[178:181], v[52:55]
	v_mfma_f32_16x16x32_bf16 v[150:153], v[124:127], v[206:209], v[150:153]
	v_mfma_f32_16x16x32_bf16 v[48:51], v[132:135], v[206:209], v[48:51]
	v_mfma_f32_16x16x32_bf16 v[92:95], v[124:127], v[214:217], v[92:95]
	v_mfma_f32_16x16x32_bf16 v[68:71], v[132:135], v[214:217], v[68:71]
	s_barrier
; #define PG8_STAGE(bufoff, gbase, voff) do { _Pragma("unroll") for (int _i = 0; _i < 2; ++_i) \
;         __builtin_amdgcn_global_load_lds((const unsigned*)((const char*)(gbase) + (voff)[_i]), (PG8_LAS unsigned*)(lds + (bufoff) + ldsw + _i * 8192), 16, 0, 0); } while (0)
; #define PG8_LDA(dst, b, h) do { _Pragma("unroll") for (int m = 0; m < 4; ++m) _Pragma("unroll") for (int k = 0; k < 2; ++k) dst[m][k] = *(const PG8_LAS bf16x8*)(lds + PG8_SA(b, h) + aoff + m * 2048 + k * 1024); } while (0)
; #define PG8_MMA(ai, bj, At, Bt) do { __builtin_amdgcn_s_setprio(1); _Pragma("unroll") for (int m = 0; m < 4; ++m) _Pragma("unroll") for (int n = 0; n < 2; ++n) _Pragma("unroll") for (int k = 0; k < 2; ++k) \
;         acc[ai][bj][m][n] = __builtin_amdgcn_mfma_f32_16x16x32_bf16(Bt[n][k], At[m][k], acc[ai][bj][m][n], 0, 0, 0); __builtin_amdgcn_s_setprio(0); } while (0)
; #define PG8_WAIT_V(n) asm volatile("s_waitcnt vmcnt(" #n ")" ::: "memory")
; #define PG8_WAIT_L(n) asm volatile("s_waitcnt lgkmcnt(" #n ")" ::: "memory")
; #define PG8_BAR __builtin_amdgcn_s_barrier()
; #define PG8_SCHED __builtin_amdgcn_sched_barrier(0)
;     ...
;             PG8_WAIT_V(8); PG8_WAIT_L(0); PG8_BAR; PG8_MMA(0, 0, At, B0); PG8_MMA(0, 1, At, B1); PG8_BAR; PG8_SCHED;
;             PG8_LDA(At, 1, 1); PG8_STAGE(PG8_SB(1, 0), b3, voffB); PG8_STAGE(PG8_SB(1, 1), b3 + hstep, voffB); PG8_STAGE(PG8_SA(1, 0), a3, voffA);
;             PG8_WAIT_V(8); PG8_WAIT_L(0); PG8_BAR; PG8_MMA(1, 0, At, B0); PG8_MMA(1, 1, At, B1); PG8_BAR; PG8_SCHED;
;     ...
;         if constexpr (ALIGN_EPI) { if (wr == 0) PG8_BAR; }
	s_setprio 0
	s_add_i32 s12, s48, s0
	v_lshl_add_u64 v[136:137], v[198:199], 0, s[66:67]
	s_mov_b32 m0, s12
	ds_read_b128 v[166:169], v222 offset:49152
	ds_read_b128 v[170:173], v222 offset:50176
	ds_read_b128 v[174:177], v222 offset:51200
	ds_read_b128 v[178:181], v222 offset:52224
	ds_read_b128 v[194:197], v222 offset:53248
	ds_read_b128 v[206:209], v222 offset:54272
	ds_read_b128 v[210:213], v222 offset:55296
	ds_read_b128 v[214:217], v222 offset:56320
	global_load_lds_dwordx4 v[136:137], off
	s_add_i32 m0, s12, 0x2000
	s_add_u32 s10, s10, 0x80080
	v_lshl_add_u64 v[136:137], v[218:219], 0, s[66:67]
	s_addc_u32 s11, s11, 0
	s_add_i32 s12, s49, s0
	global_load_lds_dwordx4 v[136:137], off
	v_lshl_add_u64 v[136:137], s[10:11], 0, v[186:187]
	s_mov_b32 m0, s12
	s_nop 0
	global_load_lds_dwordx4 v[136:137], off
	v_lshl_add_u64 v[136:137], s[10:11], 0, v[182:183]
	s_add_i32 m0, s12, 0x2000
	s_nop 0
	global_load_lds_dwordx4 v[136:137], off
	v_lshl_add_u64 v[136:137], v[224:225], 0, s[66:67]
	s_mov_b32 m0, s42
	s_nop 0
	global_load_lds_dwordx4 v[136:137], off
	v_lshl_add_u64 v[136:137], v[232:233], 0, s[66:67]
	s_mov_b32 m0, s55
	s_nop 0
	global_load_lds_dwordx4 v[136:137], off
	s_waitcnt vmcnt(8)
	s_waitcnt lgkmcnt(0)
	s_setprio 1
	s_barrier
	v_mfma_f32_16x16x32_bf16 v[146:149], v[104:107], v[166:169], v[146:149]
	v_mfma_f32_16x16x32_bf16 v[44:47], v[112:115], v[166:169], v[44:47]
	v_mfma_f32_16x16x32_bf16 v[142:145], v[104:107], v[174:177], v[142:145]
	v_mfma_f32_16x16x32_bf16 v[40:43], v[112:115], v[174:177], v[40:43]
	v_mfma_f32_16x16x32_bf16 v[136:139], v[104:107], v[194:197], v[138:141]
	v_mfma_f32_16x16x32_bf16 v[36:39], v[112:115], v[194:197], v[36:39]
	v_mfma_f32_16x16x32_bf16 v[80:83], v[104:107], v[210:213], v[80:83]
	v_mfma_f32_16x16x32_bf16 v[20:23], v[112:115], v[210:213], v[20:23]
	v_mfma_f32_16x16x32_bf16 v[146:149], v[108:111], v[170:173], v[146:149]
	v_mfma_f32_16x16x32_bf16 v[44:47], v[116:119], v[170:173], v[44:47]
	v_mfma_f32_16x16x32_bf16 v[142:145], v[108:111], v[178:181], v[142:145]
	v_mfma_f32_16x16x32_bf16 v[40:43], v[116:119], v[178:181], v[40:43]
	v_mfma_f32_16x16x32_bf16 v[138:141], v[108:111], v[206:209], v[136:139]
	v_mfma_f32_16x16x32_bf16 v[36:39], v[116:119], v[206:209], v[36:39]
	v_mfma_f32_16x16x32_bf16 v[80:83], v[108:111], v[214:217], v[80:83]
	v_mfma_f32_16x16x32_bf16 v[20:23], v[116:119], v[214:217], v[20:23]
	s_setprio 0
	s_setprio 1
	v_mfma_f32_16x16x32_bf16 v[100:103], v[120:123], v[166:169], v[100:103]
	v_mfma_f32_16x16x32_bf16 v[32:35], v[128:131], v[166:169], v[32:35]
	v_mfma_f32_16x16x32_bf16 v[88:91], v[120:123], v[174:177], v[88:91]
	v_mfma_f32_16x16x32_bf16 v[28:31], v[128:131], v[174:177], v[28:31]
	v_mfma_f32_16x16x32_bf16 v[84:87], v[120:123], v[194:197], v[84:87]
	v_mfma_f32_16x16x32_bf16 v[24:27], v[128:131], v[194:197], v[24:27]
	v_mfma_f32_16x16x32_bf16 v[16:19], v[120:123], v[210:213], v[16:19]
	v_mfma_f32_16x16x32_bf16 v[12:15], v[128:131], v[210:213], v[12:15]
	v_mfma_f32_16x16x32_bf16 v[102:105], v[124:127], v[170:173], v[100:103]
	v_mfma_f32_16x16x32_bf16 v[32:35], v[132:135], v[170:173], v[32:35]
	v_mfma_f32_16x16x32_bf16 v[88:91], v[124:127], v[178:181], v[88:91]
	v_mfma_f32_16x16x32_bf16 v[28:31], v[132:135], v[178:181], v[28:31]
	v_mfma_f32_16x16x32_bf16 v[84:87], v[124:127], v[206:209], v[84:87]
	v_mfma_f32_16x16x32_bf16 v[24:27], v[132:135], v[206:209], v[24:27]
	v_mfma_f32_16x16x32_bf16 v[16:19], v[124:127], v[214:217], v[16:19]
	v_mfma_f32_16x16x32_bf16 v[12:15], v[132:135], v[214:217], v[12:15]
	s_barrier
	s_setprio 0
	s_add_i32 s97, s97, 2
	s_add_u32 s8, s8, 0x100
	s_addc_u32 s9, s9, 0
	s_add_u32 s83, s83, 0x100
	s_addc_u32 s89, s89, 0
	s_cmp_gt_u32 s97, 29
	s_cbranch_scc0 .LBB0_1086
	s_and_b64 vcc, exec, s[70:71]
	s_cbranch_vccz .LBB0_1089
	s_barrier

; #define PG8_STAGE(bufoff, gbase, voff) do { _Pragma("unroll") for (int _i = 0; _i < 2; ++_i) \
;         __builtin_amdgcn_global_load_lds((const unsigned*)((const char*)(gbase) + (voff)[_i]), (PG8_LAS unsigned*)(lds + (bufoff) + ldsw + _i * 8192), 16, 0, 0); } while (0)
; #define PG8_LDA(dst, b, h) do { _Pragma("unroll") for (int m = 0; m < 4; ++m) _Pragma("unroll") for (int k = 0; k < 2; ++k) dst[m][k] = *(const PG8_LAS bf16x8*)(lds + PG8_SA(b, h) + aoff + m * 2048 + k * 1024); } while (0)
; #define PG8_LDB(dst, b, h) do { _Pragma("unroll") for (int n = 0; n < 2; ++n) _Pragma("unroll") for (int k = 0; k < 2; ++k) dst[n][k] = *(const PG8_LAS bf16x8*)(lds + PG8_SB(b, h) + boff + n * 2048 + k * 1024); } while (0)
; #define PG8_MMA(ai, bj, At, Bt) do { __builtin_amdgcn_s_setprio(1); _Pragma("unroll") for (int m = 0; m < 4; ++m) _Pragma("unroll") for (int n = 0; n < 2; ++n) _Pragma("unroll") for (int k = 0; k < 2; ++k) \
;         acc[ai][bj][m][n] = __builtin_amdgcn_mfma_f32_16x16x32_bf16(Bt[n][k], At[m][k], acc[ai][bj][m][n], 0, 0, 0); __builtin_amdgcn_s_setprio(0); } while (0)
; #define PG8_WAIT_V(n) asm volatile("s_waitcnt vmcnt(" #n ")" ::: "memory")
; #define PG8_WAIT_L(n) asm volatile("s_waitcnt lgkmcnt(" #n ")" ::: "memory")
; #define PG8_BAR __builtin_amdgcn_s_barrier()
;     ...
;         for (int t = 0; t < nt; t += 2) {
;             const bool last = (t == nt - 2);
;             const char* a1 = cA + (size_t)(t + 1) * kstep;
;             const char* a2 = last ? nA : cA + (size_t)(t + 2) * kstep; const char* b2 = last ? nB : cB + (size_t)(t + 2) * kstep;
;             const char* a3 = a2 + kstep; const char* b3 = b2 + kstep;
;             if (last && has_next) S.a_ready(nxt);
;             if (t == 0) E.pre_issue(pre, cur, tid, ui); else if (t == 2) E.pre_finish(pre, tid, ui);
;             if constexpr (SP2) {
;             PG8_LDB(B0, 0, 0); PG8_LDB(B1, 0, 1); PG8_SCHED; PG8_LDA(At, 0, 0); PG8_STAGE(PG8_SA(1, 1), a1 + hstep, voffA);
;             PG8_WAIT_V(8); PG8_WAIT_L(0); PG8_BAR; PG8_MMA(0, 0, At, B0); PG8_MMA(0, 1, At, B1); PG8_BAR; PG8_SCHED;
;             PG8_LDA(At, 0, 1); PG8_STAGE(PG8_SB(0, 0), b2, voffB); PG8_STAGE(PG8_SB(0, 1), b2 + hstep, voffB); PG8_STAGE(PG8_SA(0, 0), a2, voffA);
;             PG8_WAIT_V(8); PG8_WAIT_L(0); PG8_BAR; PG8_MMA(1, 0, At, B0); PG8_MMA(1, 1, At, B1); PG8_BAR; PG8_SCHED;
.LBB0_1212:
	s_add_u32 s62, s60, 0x100
	s_addc_u32 s63, s61, 0
	s_add_i32 s48, 0, 0x10000
	s_cmpk_eq_i32 s79, 0x54
	s_cselect_b32 s71, s9, s63
	s_cselect_b32 s70, s8, s62
	s_cselect_b32 s69, s25, s78
	s_cselect_b32 s68, s24, s77
	s_add_i32 s81, 0, 0x14000
	v_add_u32_e32 v136, s48, v233
	v_add_u32_e32 v160, s81, v233
	ds_read_b128 v[108:111], v136
	ds_read_b128 v[112:115], v136 offset:1024
	ds_read_b128 v[128:131], v136 offset:2048
	ds_read_b128 v[136:139], v136 offset:3072
	ds_read_b128 v[148:151], v160
	ds_read_b128 v[152:155], v160 offset:1024
	ds_read_b128 v[156:159], v160 offset:2048
	ds_read_b128 v[160:163], v160 offset:3072
	v_lshl_add_u64 v[198:199], s[60:61], 0, v[196:197]
	s_add_i32 m0, s5, 0xc000
	ds_read_b128 v[164:167], v234
	ds_read_b128 v[168:171], v234 offset:1024
	ds_read_b128 v[172:175], v234 offset:2048
	ds_read_b128 v[176:179], v234 offset:3072
	ds_read_b128 v[180:183], v234 offset:4096
	ds_read_b128 v[184:187], v234 offset:5120
	ds_read_b128 v[206:209], v234 offset:6144
	ds_read_b128 v[210:213], v234 offset:7168
	global_load_lds_dwordx4 v[198:199], off
	v_lshl_add_u64 v[198:199], s[60:61], 0, v[194:195]
	s_add_i32 m0, s5, 0xe000
	s_nop 0
	global_load_lds_dwordx4 v[198:199], off
	s_waitcnt vmcnt(8)
	s_waitcnt lgkmcnt(0)
	s_setprio 1
	s_barrier
	v_mfma_f32_16x16x32_bf16 v[144:147], v[108:111], v[164:167], v[144:147]
	v_mfma_f32_16x16x32_bf16 v[140:143], v[128:131], v[164:167], v[140:143]
	v_mfma_f32_16x16x32_bf16 v[120:123], v[108:111], v[172:175], v[120:123]
	v_mfma_f32_16x16x32_bf16 v[116:119], v[128:131], v[172:175], v[116:119]
	v_mfma_f32_16x16x32_bf16 v[96:99], v[108:111], v[180:183], v[96:99]
	v_mfma_f32_16x16x32_bf16 v[92:95], v[128:131], v[180:183], v[92:95]
	v_mfma_f32_16x16x32_bf16 v[80:83], v[108:111], v[206:209], v[80:83]
	v_mfma_f32_16x16x32_bf16 v[76:79], v[128:131], v[206:209], v[76:79]
	v_mfma_f32_16x16x32_bf16 v[144:147], v[112:115], v[168:171], v[144:147]
	v_mfma_f32_16x16x32_bf16 v[140:143], v[136:139], v[168:171], v[140:143]
	v_mfma_f32_16x16x32_bf16 v[120:123], v[112:115], v[176:179], v[120:123]
	v_mfma_f32_16x16x32_bf16 v[116:119], v[136:139], v[176:179], v[116:119]
	v_mfma_f32_16x16x32_bf16 v[96:99], v[112:115], v[184:187], v[96:99]
	v_mfma_f32_16x16x32_bf16 v[92:95], v[136:139], v[184:187], v[92:95]
	v_mfma_f32_16x16x32_bf16 v[80:83], v[112:115], v[210:213], v[80:83]
	v_mfma_f32_16x16x32_bf16 v[76:79], v[136:139], v[210:213], v[76:79]
	s_setprio 0
	s_setprio 1
	v_mfma_f32_16x16x32_bf16 v[132:135], v[148:151], v[164:167], v[132:135]
	v_mfma_f32_16x16x32_bf16 v[124:127], v[156:159], v[164:167], v[124:127]
	v_mfma_f32_16x16x32_bf16 v[104:107], v[148:151], v[172:175], v[104:107]
	v_mfma_f32_16x16x32_bf16 v[100:103], v[156:159], v[172:175], v[100:103]
	v_mfma_f32_16x16x32_bf16 v[88:91], v[148:151], v[180:183], v[88:91]
	v_mfma_f32_16x16x32_bf16 v[84:87], v[156:159], v[180:183], v[84:87]
	v_mfma_f32_16x16x32_bf16 v[72:75], v[148:151], v[206:209], v[72:75]
	v_mfma_f32_16x16x32_bf16 v[68:71], v[156:159], v[206:209], v[68:71]
	v_mfma_f32_16x16x32_bf16 v[132:135], v[152:155], v[168:171], v[132:135]
	v_mfma_f32_16x16x32_bf16 v[124:127], v[160:163], v[168:171], v[124:127]
	v_mfma_f32_16x16x32_bf16 v[104:107], v[152:155], v[176:179], v[104:107]
	v_mfma_f32_16x16x32_bf16 v[100:103], v[160:163], v[176:179], v[100:103]
	v_mfma_f32_16x16x32_bf16 v[88:91], v[152:155], v[184:187], v[88:91]
	v_mfma_f32_16x16x32_bf16 v[84:87], v[160:163], v[184:187], v[84:87]
	v_mfma_f32_16x16x32_bf16 v[72:75], v[152:155], v[210:213], v[72:75]
	v_mfma_f32_16x16x32_bf16 v[68:71], v[160:163], v[210:213], v[68:71]
	s_barrier
	s_setprio 0
	s_add_i32 s48, s48, s4
	v_lshl_add_u64 v[198:199], s[68:69], 0, v[200:201]
	s_mov_b32 m0, s48
	ds_read_b128 v[164:167], v234 offset:16384
	ds_read_b128 v[168:171], v234 offset:17408
	ds_read_b128 v[172:175], v234 offset:18432
	ds_read_b128 v[176:179], v234 offset:19456
	ds_read_b128 v[180:183], v234 offset:20480
	ds_read_b128 v[184:187], v234 offset:21504
	ds_read_b128 v[206:209], v234 offset:22528
	ds_read_b128 v[210:213], v234 offset:23552
	global_load_lds_dwordx4 v[198:199], off
	s_add_i32 m0, s48, 0x2000
	s_add_u32 s48, s68, 0x160000
	v_lshl_add_u64 v[214:215], s[68:69], 0, v[188:189]
	s_addc_u32 s49, s69, 0
	s_add_i32 s60, s81, s4
	global_load_lds_dwordx4 v[214:215], off
	v_lshl_add_u64 v[216:217], s[48:49], 0, v[200:201]
	s_mov_b32 m0, s60
	v_lshl_add_u64 v[218:219], s[70:71], 0, v[190:191]
	global_load_lds_dwordx4 v[216:217], off
	v_lshl_add_u64 v[216:217], s[48:49], 0, v[188:189]
	s_add_i32 m0, s60, 0x2000
	s_nop 0
	global_load_lds_dwordx4 v[216:217], off
	v_lshl_add_u64 v[216:217], s[70:71], 0, v[192:193]
	s_mov_b32 m0, s5
	s_nop 0
	global_load_lds_dwordx4 v[216:217], off
	s_mov_b32 m0, s20
	s_nop 0
	global_load_lds_dwordx4 v[218:219], off
	s_waitcnt vmcnt(8)
	s_waitcnt lgkmcnt(0)
	s_setprio 1
	s_barrier
; #define PG8_STAGE(bufoff, gbase, voff) do { _Pragma("unroll") for (int _i = 0; _i < 2; ++_i) \
;         __builtin_amdgcn_global_load_lds((const unsigned*)((const char*)(gbase) + (voff)[_i]), (PG8_LAS unsigned*)(lds + (bufoff) + ldsw + _i * 8192), 16, 0, 0); } while (0)
; #define PG8_LDA(dst, b, h) do { _Pragma("unroll") for (int m = 0; m < 4; ++m) _Pragma("unroll") for (int k = 0; k < 2; ++k) dst[m][k] = *(const PG8_LAS bf16x8*)(lds + PG8_SA(b, h) + aoff + m * 2048 + k * 1024); } while (0)
; #define PG8_LDB(dst, b, h) do { _Pragma("unroll") for (int n = 0; n < 2; ++n) _Pragma("unroll") for (int k = 0; k < 2; ++k) dst[n][k] = *(const PG8_LAS bf16x8*)(lds + PG8_SB(b, h) + boff + n * 2048 + k * 1024); } while (0)
; #define PG8_MMA(ai, bj, At, Bt) do { __builtin_amdgcn_s_setprio(1); _Pragma("unroll") for (int m = 0; m < 4; ++m) _Pragma("unroll") for (int n = 0; n < 2; ++n) _Pragma("unroll") for (int k = 0; k < 2; ++k) \
;         acc[ai][bj][m][n] = __builtin_amdgcn_mfma_f32_16x16x32_bf16(Bt[n][k], At[m][k], acc[ai][bj][m][n], 0, 0, 0); __builtin_amdgcn_s_setprio(0); } while (0)
; #define PG8_WAIT_V(n) asm volatile("s_waitcnt vmcnt(" #n ")" ::: "memory")
; #define PG8_WAIT_L(n) asm volatile("s_waitcnt lgkmcnt(" #n ")" ::: "memory")
; #define PG8_BAR __builtin_amdgcn_s_barrier()
; #define PG8_SCHED __builtin_amdgcn_sched_barrier(0)
;     ...
;             PG8_WAIT_V(8); PG8_WAIT_L(0); PG8_BAR; PG8_MMA(1, 0, At, B0); PG8_MMA(1, 1, At, B1); PG8_BAR; PG8_SCHED;
;             PG8_LDB(B0, 1, 0); PG8_LDB(B1, 1, 1); PG8_SCHED; PG8_LDA(At, 1, 0); PG8_STAGE(PG8_SA(0, 1), a2 + hstep, voffA);
;             PG8_WAIT_V(8); PG8_WAIT_L(0); PG8_BAR; PG8_MMA(0, 0, At, B0); PG8_MMA(0, 1, At, B1); PG8_BAR; PG8_SCHED;
	v_mfma_f32_16x16x32_bf16 v[64:67], v[108:111], v[164:167], v[64:67]
	v_mfma_f32_16x16x32_bf16 v[60:63], v[128:131], v[164:167], v[60:63]
	v_mfma_f32_16x16x32_bf16 v[48:51], v[108:111], v[172:175], v[48:51]
	v_mfma_f32_16x16x32_bf16 v[44:47], v[128:131], v[172:175], v[44:47]
	v_mfma_f32_16x16x32_bf16 v[32:35], v[108:111], v[180:183], v[32:35]
	v_mfma_f32_16x16x32_bf16 v[28:31], v[128:131], v[180:183], v[28:31]
	v_mfma_f32_16x16x32_bf16 v[16:19], v[108:111], v[206:209], v[16:19]
	v_mfma_f32_16x16x32_bf16 v[12:15], v[128:131], v[206:209], v[12:15]
	v_mfma_f32_16x16x32_bf16 v[64:67], v[112:115], v[168:171], v[64:67]
	v_mfma_f32_16x16x32_bf16 v[60:63], v[136:139], v[168:171], v[60:63]
	v_mfma_f32_16x16x32_bf16 v[48:51], v[112:115], v[176:179], v[48:51]
	v_mfma_f32_16x16x32_bf16 v[44:47], v[136:139], v[176:179], v[44:47]
	v_mfma_f32_16x16x32_bf16 v[32:35], v[112:115], v[184:187], v[32:35]
	v_mfma_f32_16x16x32_bf16 v[28:31], v[136:139], v[184:187], v[28:31]
	v_mfma_f32_16x16x32_bf16 v[16:19], v[112:115], v[210:213], v[16:19]
	v_mfma_f32_16x16x32_bf16 v[12:15], v[136:139], v[210:213], v[12:15]
	s_setprio 0
	s_setprio 1
	v_mfma_f32_16x16x32_bf16 v[56:59], v[148:151], v[164:167], v[56:59]
	v_mfma_f32_16x16x32_bf16 v[52:55], v[156:159], v[164:167], v[52:55]
	v_mfma_f32_16x16x32_bf16 v[40:43], v[148:151], v[172:175], v[40:43]
	v_mfma_f32_16x16x32_bf16 v[36:39], v[156:159], v[172:175], v[36:39]
	v_mfma_f32_16x16x32_bf16 v[24:27], v[148:151], v[180:183], v[24:27]
	v_mfma_f32_16x16x32_bf16 v[20:23], v[156:159], v[180:183], v[20:23]
	v_mfma_f32_16x16x32_bf16 v[8:11], v[148:151], v[206:209], v[8:11]
	v_mfma_f32_16x16x32_bf16 v[4:7], v[156:159], v[206:209], v[4:7]
	v_mfma_f32_16x16x32_bf16 v[56:59], v[152:155], v[168:171], v[56:59]
	v_mfma_f32_16x16x32_bf16 v[52:55], v[160:163], v[168:171], v[52:55]
	v_mfma_f32_16x16x32_bf16 v[40:43], v[152:155], v[176:179], v[40:43]
	v_mfma_f32_16x16x32_bf16 v[36:39], v[160:163], v[176:179], v[36:39]
	v_mfma_f32_16x16x32_bf16 v[24:27], v[152:155], v[184:187], v[24:27]
	v_mfma_f32_16x16x32_bf16 v[20:23], v[160:163], v[184:187], v[20:23]
	v_mfma_f32_16x16x32_bf16 v[8:11], v[152:155], v[210:213], v[8:11]
	v_mfma_f32_16x16x32_bf16 v[4:7], v[160:163], v[210:213], v[4:7]
	s_barrier
	s_setprio 0
	s_add_i32 s60, 0, 0x18000
	s_add_i32 s61, 0, 0x1c000
	v_add_u32_e32 v136, s60, v233
	v_add_u32_e32 v160, s61, v233
	ds_read_b128 v[108:111], v136
	ds_read_b128 v[112:115], v136 offset:1024
	ds_read_b128 v[128:131], v136 offset:2048
	ds_read_b128 v[136:139], v136 offset:3072
	ds_read_b128 v[148:151], v160
	ds_read_b128 v[152:155], v160 offset:1024
	ds_read_b128 v[156:159], v160 offset:2048
	ds_read_b128 v[160:163], v160 offset:3072
	s_add_u32 s48, s70, 0x160000
	s_addc_u32 s49, s71, 0
	s_mov_b32 m0, s21
	v_lshl_add_u64 v[220:221], s[48:49], 0, v[192:193]
	ds_read_b128 v[164:167], v234 offset:32768
	ds_read_b128 v[168:171], v234 offset:33792
	ds_read_b128 v[172:175], v234 offset:34816
	ds_read_b128 v[176:179], v234 offset:35840
	ds_read_b128 v[180:183], v234 offset:36864
	ds_read_b128 v[184:187], v234 offset:37888
	ds_read_b128 v[206:209], v234 offset:38912
	ds_read_b128 v[210:213], v234 offset:39936
	global_load_lds_dwordx4 v[220:221], off
	v_lshl_add_u64 v[220:221], s[48:49], 0, v[190:191]
	s_mov_b32 m0, s23
	s_nop 0
	global_load_lds_dwordx4 v[220:221], off
	s_waitcnt vmcnt(8)
	s_waitcnt lgkmcnt(0)
	s_setprio 1
	s_barrier
	v_mfma_f32_16x16x32_bf16 v[144:147], v[108:111], v[164:167], v[144:147]
	v_mfma_f32_16x16x32_bf16 v[140:143], v[128:131], v[164:167], v[140:143]
	v_mfma_f32_16x16x32_bf16 v[120:123], v[108:111], v[172:175], v[120:123]
	v_mfma_f32_16x16x32_bf16 v[116:119], v[128:131], v[172:175], v[116:119]
	v_mfma_f32_16x16x32_bf16 v[96:99], v[108:111], v[180:183], v[96:99]
	v_mfma_f32_16x16x32_bf16 v[92:95], v[128:131], v[180:183], v[92:95]
	v_mfma_f32_16x16x32_bf16 v[80:83], v[108:111], v[206:209], v[80:83]
	v_mfma_f32_16x16x32_bf16 v[76:79], v[128:131], v[206:209], v[76:79]
	v_mfma_f32_16x16x32_bf16 v[144:147], v[112:115], v[168:171], v[144:147]
	v_mfma_f32_16x16x32_bf16 v[140:143], v[136:139], v[168:171], v[140:143]
	v_mfma_f32_16x16x32_bf16 v[120:123], v[112:115], v[176:179], v[120:123]
	v_mfma_f32_16x16x32_bf16 v[116:119], v[136:139], v[176:179], v[116:119]
	v_mfma_f32_16x16x32_bf16 v[96:99], v[112:115], v[184:187], v[96:99]
	v_mfma_f32_16x16x32_bf16 v[92:95], v[136:139], v[184:187], v[92:95]
	v_mfma_f32_16x16x32_bf16 v[80:83], v[112:115], v[210:213], v[80:83]
	v_mfma_f32_16x16x32_bf16 v[76:79], v[136:139], v[210:213], v[76:79]
	s_setprio 0
	s_setprio 1
	v_mfma_f32_16x16x32_bf16 v[132:135], v[148:151], v[164:167], v[132:135]
	v_mfma_f32_16x16x32_bf16 v[124:127], v[156:159], v[164:167], v[124:127]
	v_mfma_f32_16x16x32_bf16 v[104:107], v[148:151], v[172:175], v[104:107]
	v_mfma_f32_16x16x32_bf16 v[100:103], v[156:159], v[172:175], v[100:103]
	v_mfma_f32_16x16x32_bf16 v[88:91], v[148:151], v[180:183], v[88:91]
	v_mfma_f32_16x16x32_bf16 v[84:87], v[156:159], v[180:183], v[84:87]
	v_mfma_f32_16x16x32_bf16 v[72:75], v[148:151], v[206:209], v[72:75]
	v_mfma_f32_16x16x32_bf16 v[68:71], v[156:159], v[206:209], v[68:71]
	v_mfma_f32_16x16x32_bf16 v[132:135], v[152:155], v[168:171], v[132:135]
	v_mfma_f32_16x16x32_bf16 v[124:127], v[160:163], v[168:171], v[124:127]
	v_mfma_f32_16x16x32_bf16 v[104:107], v[152:155], v[176:179], v[104:107]
	v_mfma_f32_16x16x32_bf16 v[100:103], v[160:163], v[176:179], v[100:103]
	v_mfma_f32_16x16x32_bf16 v[88:91], v[152:155], v[184:187], v[88:91]
	v_mfma_f32_16x16x32_bf16 v[84:87], v[160:163], v[184:187], v[84:87]
	v_mfma_f32_16x16x32_bf16 v[72:75], v[152:155], v[210:213], v[72:75]
	v_mfma_f32_16x16x32_bf16 v[68:71], v[160:163], v[210:213], v[68:71]
	s_barrier
; #define PG8_STAGE(bufoff, gbase, voff) do { _Pragma("unroll") for (int _i = 0; _i < 2; ++_i) \
;         __builtin_amdgcn_global_load_lds((const unsigned*)((const char*)(gbase) + (voff)[_i]), (PG8_LAS unsigned*)(lds + (bufoff) + ldsw + _i * 8192), 16, 0, 0); } while (0)
; #define PG8_LDA(dst, b, h) do { _Pragma("unroll") for (int m = 0; m < 4; ++m) _Pragma("unroll") for (int k = 0; k < 2; ++k) dst[m][k] = *(const PG8_LAS bf16x8*)(lds + PG8_SA(b, h) + aoff + m * 2048 + k * 1024); } while (0)
; #define PG8_MMA(ai, bj, At, Bt) do { __builtin_amdgcn_s_setprio(1); _Pragma("unroll") for (int m = 0; m < 4; ++m) _Pragma("unroll") for (int n = 0; n < 2; ++n) _Pragma("unroll") for (int k = 0; k < 2; ++k) \
;         acc[ai][bj][m][n] = __builtin_amdgcn_mfma_f32_16x16x32_bf16(Bt[n][k], At[m][k], acc[ai][bj][m][n], 0, 0, 0); __builtin_amdgcn_s_setprio(0); } while (0)
; #define PG8_WAIT_V(n) asm volatile("s_waitcnt vmcnt(" #n ")" ::: "memory")
; #define PG8_WAIT_L(n) asm volatile("s_waitcnt lgkmcnt(" #n ")" ::: "memory")
; #define PG8_BAR __builtin_amdgcn_s_barrier()
; #define PG8_SCHED __builtin_amdgcn_sched_barrier(0)
;     ...
;             PG8_WAIT_V(8); PG8_WAIT_L(0); PG8_BAR; PG8_MMA(0, 0, At, B0); PG8_MMA(0, 1, At, B1); PG8_BAR; PG8_SCHED;
;             PG8_LDA(At, 1, 1); PG8_STAGE(PG8_SB(1, 0), b3, voffB); PG8_STAGE(PG8_SB(1, 1), b3 + hstep, voffB); PG8_STAGE(PG8_SA(1, 0), a3, voffA);
;             PG8_WAIT_V(8); PG8_WAIT_L(0); PG8_BAR; PG8_MMA(1, 0, At, B0); PG8_MMA(1, 1, At, B1); PG8_BAR; PG8_SCHED;
;     ...
;         if constexpr (ALIGN_EPI) { if (wr == 0) PG8_BAR; }
	s_setprio 0
	s_add_i32 s48, s60, s4
	v_lshl_add_u64 v[198:199], v[198:199], 0, s[66:67]
	s_mov_b32 m0, s48
	ds_read_b128 v[164:167], v234 offset:49152
	ds_read_b128 v[168:171], v234 offset:50176
	ds_read_b128 v[172:175], v234 offset:51200
	ds_read_b128 v[176:179], v234 offset:52224
	ds_read_b128 v[180:183], v234 offset:53248
	ds_read_b128 v[184:187], v234 offset:54272
	ds_read_b128 v[206:209], v234 offset:55296
	ds_read_b128 v[210:213], v234 offset:56320
	global_load_lds_dwordx4 v[198:199], off
	s_add_i32 m0, s48, 0x2000
	s_add_u32 s48, s68, 0x160080
	v_lshl_add_u64 v[198:199], v[214:215], 0, s[66:67]
	s_addc_u32 s49, s69, 0
	s_add_i32 s60, s61, s4
	global_load_lds_dwordx4 v[198:199], off
	v_lshl_add_u64 v[198:199], s[48:49], 0, v[200:201]
	s_mov_b32 m0, s60
	s_nop 0
	global_load_lds_dwordx4 v[198:199], off
	v_lshl_add_u64 v[198:199], s[48:49], 0, v[188:189]
	s_add_i32 m0, s60, 0x2000
	s_nop 0
	global_load_lds_dwordx4 v[198:199], off
	v_lshl_add_u64 v[198:199], v[216:217], 0, s[66:67]
	s_mov_b32 m0, s54
	s_nop 0
	global_load_lds_dwordx4 v[198:199], off
	v_lshl_add_u64 v[198:199], v[218:219], 0, s[66:67]
	s_mov_b32 m0, s55
	s_nop 0
	global_load_lds_dwordx4 v[198:199], off
	s_waitcnt vmcnt(8)
	s_waitcnt lgkmcnt(0)
	s_setprio 1
	s_barrier
	v_mfma_f32_16x16x32_bf16 v[64:67], v[108:111], v[164:167], v[64:67]
	v_mfma_f32_16x16x32_bf16 v[60:63], v[128:131], v[164:167], v[60:63]
	v_mfma_f32_16x16x32_bf16 v[48:51], v[108:111], v[172:175], v[48:51]
	v_mfma_f32_16x16x32_bf16 v[44:47], v[128:131], v[172:175], v[44:47]
	v_mfma_f32_16x16x32_bf16 v[32:35], v[108:111], v[180:183], v[32:35]
	v_mfma_f32_16x16x32_bf16 v[28:31], v[128:131], v[180:183], v[28:31]
	v_mfma_f32_16x16x32_bf16 v[16:19], v[108:111], v[206:209], v[16:19]
	v_mfma_f32_16x16x32_bf16 v[12:15], v[128:131], v[206:209], v[12:15]
	v_mfma_f32_16x16x32_bf16 v[64:67], v[112:115], v[168:171], v[64:67]
	v_mfma_f32_16x16x32_bf16 v[60:63], v[136:139], v[168:171], v[60:63]
	v_mfma_f32_16x16x32_bf16 v[48:51], v[112:115], v[176:179], v[48:51]
	v_mfma_f32_16x16x32_bf16 v[44:47], v[136:139], v[176:179], v[44:47]
	v_mfma_f32_16x16x32_bf16 v[32:35], v[112:115], v[184:187], v[32:35]
	v_mfma_f32_16x16x32_bf16 v[28:31], v[136:139], v[184:187], v[28:31]
	v_mfma_f32_16x16x32_bf16 v[16:19], v[112:115], v[210:213], v[16:19]
	v_mfma_f32_16x16x32_bf16 v[12:15], v[136:139], v[210:213], v[12:15]
	s_setprio 0
	s_setprio 1
	v_mfma_f32_16x16x32_bf16 v[56:59], v[148:151], v[164:167], v[56:59]
	v_mfma_f32_16x16x32_bf16 v[52:55], v[156:159], v[164:167], v[52:55]
	v_mfma_f32_16x16x32_bf16 v[40:43], v[148:151], v[172:175], v[40:43]
	v_mfma_f32_16x16x32_bf16 v[36:39], v[156:159], v[172:175], v[36:39]
	v_mfma_f32_16x16x32_bf16 v[24:27], v[148:151], v[180:183], v[24:27]
	v_mfma_f32_16x16x32_bf16 v[20:23], v[156:159], v[180:183], v[20:23]
	v_mfma_f32_16x16x32_bf16 v[8:11], v[148:151], v[206:209], v[8:11]
	v_mfma_f32_16x16x32_bf16 v[4:7], v[156:159], v[206:209], v[4:7]
	v_mfma_f32_16x16x32_bf16 v[56:59], v[152:155], v[168:171], v[56:59]
	v_mfma_f32_16x16x32_bf16 v[52:55], v[160:163], v[168:171], v[52:55]
	v_mfma_f32_16x16x32_bf16 v[40:43], v[152:155], v[176:179], v[40:43]
	v_mfma_f32_16x16x32_bf16 v[36:39], v[160:163], v[176:179], v[36:39]
	v_mfma_f32_16x16x32_bf16 v[24:27], v[152:155], v[184:187], v[24:27]
	v_mfma_f32_16x16x32_bf16 v[20:23], v[160:163], v[184:187], v[20:23]
	v_mfma_f32_16x16x32_bf16 v[8:11], v[152:155], v[210:213], v[8:11]
	v_mfma_f32_16x16x32_bf16 v[4:7], v[160:163], v[210:213], v[4:7]
	s_barrier
	s_setprio 0
	s_add_i32 s79, s79, 2
	s_add_u32 s77, s77, 0x100
	s_addc_u32 s78, s78, 0
	s_cmpk_gt_u32 s79, 0x55
	s_mov_b64 s[60:61], s[62:63]
	s_cbranch_scc0 .LBB0_1212
	s_and_b64 vcc, exec, s[12:13]
	s_cbranch_vccz .LBB0_1215
	s_barrier

; #define PG8_STAGE(bufoff, gbase, voff) do { _Pragma("unroll") for (int _i = 0; _i < 2; ++_i) \
;         __builtin_amdgcn_global_load_lds((const unsigned*)((const char*)(gbase) + (voff)[_i]), (PG8_LAS unsigned*)(lds + (bufoff) + ldsw + _i * 8192), 16, 0, 0); } while (0)
; #define PG8_LDA(dst, b, h) do { _Pragma("unroll") for (int m = 0; m < 4; ++m) _Pragma("unroll") for (int k = 0; k < 2; ++k) dst[m][k] = *(const PG8_LAS bf16x8*)(lds + PG8_SA(b, h) + aoff + m * 2048 + k * 1024); } while (0)
; #define PG8_LDB(dst, b, h) do { _Pragma("unroll") for (int n = 0; n < 2; ++n) _Pragma("unroll") for (int k = 0; k < 2; ++k) dst[n][k] = *(const PG8_LAS bf16x8*)(lds + PG8_SB(b, h) + boff + n * 2048 + k * 1024); } while (0)
; #define PG8_MMA(ai, bj, At, Bt) do { __builtin_amdgcn_s_setprio(1); _Pragma("unroll") for (int m = 0; m < 4; ++m) _Pragma("unroll") for (int n = 0; n < 2; ++n) _Pragma("unroll") for (int k = 0; k < 2; ++k) \
;         acc[ai][bj][m][n] = __builtin_amdgcn_mfma_f32_16x16x32_bf16(Bt[n][k], At[m][k], acc[ai][bj][m][n], 0, 0, 0); __builtin_amdgcn_s_setprio(0); } while (0)
; #define PG8_WAIT_V(n) asm volatile("s_waitcnt vmcnt(" #n ")" ::: "memory")
; #define PG8_WAIT_L(n) asm volatile("s_waitcnt lgkmcnt(" #n ")" ::: "memory")
; #define PG8_BAR __builtin_amdgcn_s_barrier()
;     ...
;         for (int t = 0; t < nt; t += 2) {
;             const bool last = (t == nt - 2);
;             const char* a1 = cA + (size_t)(t + 1) * kstep;
;             const char* a2 = last ? nA : cA + (size_t)(t + 2) * kstep; const char* b2 = last ? nB : cB + (size_t)(t + 2) * kstep;
;             const char* a3 = a2 + kstep; const char* b3 = b2 + kstep;
;             if (last && has_next) S.a_ready(nxt);
;             if (t == 0) E.pre_issue(pre, cur, tid, ui); else if (t == 2) E.pre_finish(pre, tid, ui);
;             if constexpr (SP2) {
;             PG8_LDB(B0, 0, 0); PG8_LDB(B1, 0, 1); PG8_SCHED; PG8_LDA(At, 0, 0); PG8_STAGE(PG8_SA(1, 1), a1 + hstep, voffA);
;             PG8_WAIT_V(8); PG8_WAIT_L(0); PG8_BAR; PG8_MMA(0, 0, At, B0); PG8_MMA(0, 1, At, B1); PG8_BAR; PG8_SCHED;
;             PG8_LDA(At, 0, 1); PG8_STAGE(PG8_SB(0, 0), b2, voffB); PG8_STAGE(PG8_SB(0, 1), b2 + hstep, voffB); PG8_STAGE(PG8_SA(0, 0), a2, voffA);
;             PG8_WAIT_V(8); PG8_WAIT_L(0); PG8_BAR; PG8_MMA(1, 0, At, B0); PG8_MMA(1, 1, At, B1); PG8_BAR; PG8_SCHED;
.LBB0_1254:
	s_add_u32 s60, s50, 0x100
	s_addc_u32 s61, s51, 0
	s_add_i32 s48, 0, 0x10000
	s_cmpk_eq_i32 s77, 0x54
	s_cselect_b32 s69, s7, s61
	s_cselect_b32 s68, s6, s60
	s_cselect_b32 s63, s25, s76
	s_cselect_b32 s62, s24, s75
	s_add_i32 s78, 0, 0x14000
	v_add_u32_e32 v136, s48, v233
	v_add_u32_e32 v160, s78, v233
	ds_read_b128 v[108:111], v136
	ds_read_b128 v[112:115], v136 offset:1024
	ds_read_b128 v[128:131], v136 offset:2048
	ds_read_b128 v[136:139], v136 offset:3072
	ds_read_b128 v[148:151], v160
	ds_read_b128 v[152:155], v160 offset:1024
	ds_read_b128 v[156:159], v160 offset:2048
	ds_read_b128 v[160:163], v160 offset:3072
	v_lshl_add_u64 v[198:199], s[50:51], 0, v[196:197]
	s_add_i32 m0, s21, 0xc000
	ds_read_b128 v[164:167], v234
	ds_read_b128 v[168:171], v234 offset:1024
	ds_read_b128 v[172:175], v234 offset:2048
	ds_read_b128 v[176:179], v234 offset:3072
	ds_read_b128 v[180:183], v234 offset:4096
	ds_read_b128 v[184:187], v234 offset:5120
	ds_read_b128 v[206:209], v234 offset:6144
	ds_read_b128 v[210:213], v234 offset:7168
	global_load_lds_dwordx4 v[198:199], off
	v_lshl_add_u64 v[198:199], s[50:51], 0, v[194:195]
	s_add_i32 m0, s21, 0xe000
	s_nop 0
	global_load_lds_dwordx4 v[198:199], off
	s_waitcnt vmcnt(8)
	s_waitcnt lgkmcnt(0)
	s_setprio 1
	s_barrier
	v_mfma_f32_16x16x32_bf16 v[144:147], v[108:111], v[164:167], v[144:147]
	v_mfma_f32_16x16x32_bf16 v[140:143], v[128:131], v[164:167], v[140:143]
	v_mfma_f32_16x16x32_bf16 v[120:123], v[108:111], v[172:175], v[120:123]
	v_mfma_f32_16x16x32_bf16 v[116:119], v[128:131], v[172:175], v[116:119]
	v_mfma_f32_16x16x32_bf16 v[96:99], v[108:111], v[180:183], v[96:99]
	v_mfma_f32_16x16x32_bf16 v[92:95], v[128:131], v[180:183], v[92:95]
	v_mfma_f32_16x16x32_bf16 v[80:83], v[108:111], v[206:209], v[80:83]
	v_mfma_f32_16x16x32_bf16 v[76:79], v[128:131], v[206:209], v[76:79]
	v_mfma_f32_16x16x32_bf16 v[144:147], v[112:115], v[168:171], v[144:147]
	v_mfma_f32_16x16x32_bf16 v[140:143], v[136:139], v[168:171], v[140:143]
	v_mfma_f32_16x16x32_bf16 v[120:123], v[112:115], v[176:179], v[120:123]
	v_mfma_f32_16x16x32_bf16 v[116:119], v[136:139], v[176:179], v[116:119]
	v_mfma_f32_16x16x32_bf16 v[96:99], v[112:115], v[184:187], v[96:99]
	v_mfma_f32_16x16x32_bf16 v[92:95], v[136:139], v[184:187], v[92:95]
	v_mfma_f32_16x16x32_bf16 v[80:83], v[112:115], v[210:213], v[80:83]
	v_mfma_f32_16x16x32_bf16 v[76:79], v[136:139], v[210:213], v[76:79]
	s_setprio 0
	s_setprio 1
	v_mfma_f32_16x16x32_bf16 v[132:135], v[148:151], v[164:167], v[132:135]
	v_mfma_f32_16x16x32_bf16 v[124:127], v[156:159], v[164:167], v[124:127]
	v_mfma_f32_16x16x32_bf16 v[104:107], v[148:151], v[172:175], v[104:107]
	v_mfma_f32_16x16x32_bf16 v[100:103], v[156:159], v[172:175], v[100:103]
	v_mfma_f32_16x16x32_bf16 v[88:91], v[148:151], v[180:183], v[88:91]
	v_mfma_f32_16x16x32_bf16 v[84:87], v[156:159], v[180:183], v[84:87]
	v_mfma_f32_16x16x32_bf16 v[72:75], v[148:151], v[206:209], v[72:75]
	v_mfma_f32_16x16x32_bf16 v[68:71], v[156:159], v[206:209], v[68:71]
	v_mfma_f32_16x16x32_bf16 v[132:135], v[152:155], v[168:171], v[132:135]
	v_mfma_f32_16x16x32_bf16 v[124:127], v[160:163], v[168:171], v[124:127]
	v_mfma_f32_16x16x32_bf16 v[104:107], v[152:155], v[176:179], v[104:107]
	v_mfma_f32_16x16x32_bf16 v[100:103], v[160:163], v[176:179], v[100:103]
	v_mfma_f32_16x16x32_bf16 v[88:91], v[152:155], v[184:187], v[88:91]
	v_mfma_f32_16x16x32_bf16 v[84:87], v[160:163], v[184:187], v[84:87]
	v_mfma_f32_16x16x32_bf16 v[72:75], v[152:155], v[210:213], v[72:75]
	v_mfma_f32_16x16x32_bf16 v[68:71], v[160:163], v[210:213], v[68:71]
	s_barrier
	s_setprio 0
	s_add_i32 s48, s48, s20
	v_lshl_add_u64 v[198:199], s[62:63], 0, v[200:201]
	s_mov_b32 m0, s48
	ds_read_b128 v[164:167], v234 offset:16384
	ds_read_b128 v[168:171], v234 offset:17408
	ds_read_b128 v[172:175], v234 offset:18432
	ds_read_b128 v[176:179], v234 offset:19456
	ds_read_b128 v[180:183], v234 offset:20480
	ds_read_b128 v[184:187], v234 offset:21504
	ds_read_b128 v[206:209], v234 offset:22528
	ds_read_b128 v[210:213], v234 offset:23552
	global_load_lds_dwordx4 v[198:199], off
	s_add_i32 m0, s48, 0x2000
	s_add_u32 s48, s62, 0x160000
	v_lshl_add_u64 v[214:215], s[62:63], 0, v[188:189]
	s_addc_u32 s49, s63, 0
	s_add_i32 s50, s78, s20
	global_load_lds_dwordx4 v[214:215], off
	v_lshl_add_u64 v[216:217], s[48:49], 0, v[200:201]
	s_mov_b32 m0, s50
	v_lshl_add_u64 v[218:219], s[68:69], 0, v[190:191]
	global_load_lds_dwordx4 v[216:217], off
	v_lshl_add_u64 v[216:217], s[48:49], 0, v[188:189]
	s_add_i32 m0, s50, 0x2000
	s_nop 0
	global_load_lds_dwordx4 v[216:217], off
	v_lshl_add_u64 v[216:217], s[68:69], 0, v[192:193]
	s_mov_b32 m0, s21
	s_nop 0
	global_load_lds_dwordx4 v[216:217], off
	s_mov_b32 m0, s23
	s_nop 0
	global_load_lds_dwordx4 v[218:219], off
	s_waitcnt vmcnt(8)
	s_waitcnt lgkmcnt(0)
	s_setprio 1
	s_barrier
; #define PG8_STAGE(bufoff, gbase, voff) do { _Pragma("unroll") for (int _i = 0; _i < 2; ++_i) \
;         __builtin_amdgcn_global_load_lds((const unsigned*)((const char*)(gbase) + (voff)[_i]), (PG8_LAS unsigned*)(lds + (bufoff) + ldsw + _i * 8192), 16, 0, 0); } while (0)
; #define PG8_LDA(dst, b, h) do { _Pragma("unroll") for (int m = 0; m < 4; ++m) _Pragma("unroll") for (int k = 0; k < 2; ++k) dst[m][k] = *(const PG8_LAS bf16x8*)(lds + PG8_SA(b, h) + aoff + m * 2048 + k * 1024); } while (0)
; #define PG8_LDB(dst, b, h) do { _Pragma("unroll") for (int n = 0; n < 2; ++n) _Pragma("unroll") for (int k = 0; k < 2; ++k) dst[n][k] = *(const PG8_LAS bf16x8*)(lds + PG8_SB(b, h) + boff + n * 2048 + k * 1024); } while (0)
; #define PG8_MMA(ai, bj, At, Bt) do { __builtin_amdgcn_s_setprio(1); _Pragma("unroll") for (int m = 0; m < 4; ++m) _Pragma("unroll") for (int n = 0; n < 2; ++n) _Pragma("unroll") for (int k = 0; k < 2; ++k) \
;         acc[ai][bj][m][n] = __builtin_amdgcn_mfma_f32_16x16x32_bf16(Bt[n][k], At[m][k], acc[ai][bj][m][n], 0, 0, 0); __builtin_amdgcn_s_setprio(0); } while (0)
; #define PG8_WAIT_V(n) asm volatile("s_waitcnt vmcnt(" #n ")" ::: "memory")
; #define PG8_WAIT_L(n) asm volatile("s_waitcnt lgkmcnt(" #n ")" ::: "memory")
; #define PG8_BAR __builtin_amdgcn_s_barrier()
; #define PG8_SCHED __builtin_amdgcn_sched_barrier(0)
;     ...
;             PG8_WAIT_V(8); PG8_WAIT_L(0); PG8_BAR; PG8_MMA(1, 0, At, B0); PG8_MMA(1, 1, At, B1); PG8_BAR; PG8_SCHED;
;             PG8_LDB(B0, 1, 0); PG8_LDB(B1, 1, 1); PG8_SCHED; PG8_LDA(At, 1, 0); PG8_STAGE(PG8_SA(0, 1), a2 + hstep, voffA);
;             PG8_WAIT_V(8); PG8_WAIT_L(0); PG8_BAR; PG8_MMA(0, 0, At, B0); PG8_MMA(0, 1, At, B1); PG8_BAR; PG8_SCHED;
	v_mfma_f32_16x16x32_bf16 v[64:67], v[108:111], v[164:167], v[64:67]
	v_mfma_f32_16x16x32_bf16 v[60:63], v[128:131], v[164:167], v[60:63]
	v_mfma_f32_16x16x32_bf16 v[48:51], v[108:111], v[172:175], v[48:51]
	v_mfma_f32_16x16x32_bf16 v[44:47], v[128:131], v[172:175], v[44:47]
	v_mfma_f32_16x16x32_bf16 v[32:35], v[108:111], v[180:183], v[32:35]
	v_mfma_f32_16x16x32_bf16 v[28:31], v[128:131], v[180:183], v[28:31]
	v_mfma_f32_16x16x32_bf16 v[16:19], v[108:111], v[206:209], v[16:19]
	v_mfma_f32_16x16x32_bf16 v[12:15], v[128:131], v[206:209], v[12:15]
	v_mfma_f32_16x16x32_bf16 v[64:67], v[112:115], v[168:171], v[64:67]
	v_mfma_f32_16x16x32_bf16 v[60:63], v[136:139], v[168:171], v[60:63]
	v_mfma_f32_16x16x32_bf16 v[48:51], v[112:115], v[176:179], v[48:51]
	v_mfma_f32_16x16x32_bf16 v[44:47], v[136:139], v[176:179], v[44:47]
	v_mfma_f32_16x16x32_bf16 v[32:35], v[112:115], v[184:187], v[32:35]
	v_mfma_f32_16x16x32_bf16 v[28:31], v[136:139], v[184:187], v[28:31]
	v_mfma_f32_16x16x32_bf16 v[16:19], v[112:115], v[210:213], v[16:19]
	v_mfma_f32_16x16x32_bf16 v[12:15], v[136:139], v[210:213], v[12:15]
	s_setprio 0
	s_setprio 1
	v_mfma_f32_16x16x32_bf16 v[56:59], v[148:151], v[164:167], v[56:59]
	v_mfma_f32_16x16x32_bf16 v[52:55], v[156:159], v[164:167], v[52:55]
	v_mfma_f32_16x16x32_bf16 v[40:43], v[148:151], v[172:175], v[40:43]
	v_mfma_f32_16x16x32_bf16 v[36:39], v[156:159], v[172:175], v[36:39]
	v_mfma_f32_16x16x32_bf16 v[24:27], v[148:151], v[180:183], v[24:27]
	v_mfma_f32_16x16x32_bf16 v[20:23], v[156:159], v[180:183], v[20:23]
	v_mfma_f32_16x16x32_bf16 v[8:11], v[148:151], v[206:209], v[8:11]
	v_mfma_f32_16x16x32_bf16 v[4:7], v[156:159], v[206:209], v[4:7]
	v_mfma_f32_16x16x32_bf16 v[56:59], v[152:155], v[168:171], v[56:59]
	v_mfma_f32_16x16x32_bf16 v[52:55], v[160:163], v[168:171], v[52:55]
	v_mfma_f32_16x16x32_bf16 v[40:43], v[152:155], v[176:179], v[40:43]
	v_mfma_f32_16x16x32_bf16 v[36:39], v[160:163], v[176:179], v[36:39]
	v_mfma_f32_16x16x32_bf16 v[24:27], v[152:155], v[184:187], v[24:27]
	v_mfma_f32_16x16x32_bf16 v[20:23], v[160:163], v[184:187], v[20:23]
	v_mfma_f32_16x16x32_bf16 v[8:11], v[152:155], v[210:213], v[8:11]
	v_mfma_f32_16x16x32_bf16 v[4:7], v[160:163], v[210:213], v[4:7]
	s_barrier
	s_setprio 0
	s_add_i32 s50, 0, 0x18000
	s_add_i32 s51, 0, 0x1c000
	v_add_u32_e32 v136, s50, v233
	v_add_u32_e32 v160, s51, v233
	ds_read_b128 v[108:111], v136
	ds_read_b128 v[112:115], v136 offset:1024
	ds_read_b128 v[128:131], v136 offset:2048
	ds_read_b128 v[136:139], v136 offset:3072
	ds_read_b128 v[148:151], v160
	ds_read_b128 v[152:155], v160 offset:1024
	ds_read_b128 v[156:159], v160 offset:2048
	ds_read_b128 v[160:163], v160 offset:3072
	s_add_u32 s48, s68, 0x160000
	s_addc_u32 s49, s69, 0
	s_mov_b32 m0, s42
	v_lshl_add_u64 v[220:221], s[48:49], 0, v[192:193]
	ds_read_b128 v[164:167], v234 offset:32768
	ds_read_b128 v[168:171], v234 offset:33792
	ds_read_b128 v[172:175], v234 offset:34816
	ds_read_b128 v[176:179], v234 offset:35840
	ds_read_b128 v[180:183], v234 offset:36864
	ds_read_b128 v[184:187], v234 offset:37888
	ds_read_b128 v[206:209], v234 offset:38912
	ds_read_b128 v[210:213], v234 offset:39936
	global_load_lds_dwordx4 v[220:221], off
	v_lshl_add_u64 v[220:221], s[48:49], 0, v[190:191]
	s_mov_b32 m0, s52
	s_nop 0
	global_load_lds_dwordx4 v[220:221], off
	s_waitcnt vmcnt(8)
	s_waitcnt lgkmcnt(0)
	s_setprio 1
	s_barrier
	v_mfma_f32_16x16x32_bf16 v[144:147], v[108:111], v[164:167], v[144:147]
	v_mfma_f32_16x16x32_bf16 v[140:143], v[128:131], v[164:167], v[140:143]
	v_mfma_f32_16x16x32_bf16 v[120:123], v[108:111], v[172:175], v[120:123]
	v_mfma_f32_16x16x32_bf16 v[116:119], v[128:131], v[172:175], v[116:119]
	v_mfma_f32_16x16x32_bf16 v[96:99], v[108:111], v[180:183], v[96:99]
	v_mfma_f32_16x16x32_bf16 v[92:95], v[128:131], v[180:183], v[92:95]
	v_mfma_f32_16x16x32_bf16 v[80:83], v[108:111], v[206:209], v[80:83]
	v_mfma_f32_16x16x32_bf16 v[76:79], v[128:131], v[206:209], v[76:79]
	v_mfma_f32_16x16x32_bf16 v[144:147], v[112:115], v[168:171], v[144:147]
	v_mfma_f32_16x16x32_bf16 v[140:143], v[136:139], v[168:171], v[140:143]
	v_mfma_f32_16x16x32_bf16 v[120:123], v[112:115], v[176:179], v[120:123]
	v_mfma_f32_16x16x32_bf16 v[116:119], v[136:139], v[176:179], v[116:119]
	v_mfma_f32_16x16x32_bf16 v[96:99], v[112:115], v[184:187], v[96:99]
	v_mfma_f32_16x16x32_bf16 v[92:95], v[136:139], v[184:187], v[92:95]
	v_mfma_f32_16x16x32_bf16 v[80:83], v[112:115], v[210:213], v[80:83]
	v_mfma_f32_16x16x32_bf16 v[76:79], v[136:139], v[210:213], v[76:79]
	s_setprio 0
	s_setprio 1
	v_mfma_f32_16x16x32_bf16 v[132:135], v[148:151], v[164:167], v[132:135]
	v_mfma_f32_16x16x32_bf16 v[124:127], v[156:159], v[164:167], v[124:127]
	v_mfma_f32_16x16x32_bf16 v[104:107], v[148:151], v[172:175], v[104:107]
	v_mfma_f32_16x16x32_bf16 v[100:103], v[156:159], v[172:175], v[100:103]
	v_mfma_f32_16x16x32_bf16 v[88:91], v[148:151], v[180:183], v[88:91]
	v_mfma_f32_16x16x32_bf16 v[84:87], v[156:159], v[180:183], v[84:87]
	v_mfma_f32_16x16x32_bf16 v[72:75], v[148:151], v[206:209], v[72:75]
	v_mfma_f32_16x16x32_bf16 v[68:71], v[156:159], v[206:209], v[68:71]
	v_mfma_f32_16x16x32_bf16 v[132:135], v[152:155], v[168:171], v[132:135]
	v_mfma_f32_16x16x32_bf16 v[124:127], v[160:163], v[168:171], v[124:127]
	v_mfma_f32_16x16x32_bf16 v[104:107], v[152:155], v[176:179], v[104:107]
	v_mfma_f32_16x16x32_bf16 v[100:103], v[160:163], v[176:179], v[100:103]
	v_mfma_f32_16x16x32_bf16 v[88:91], v[152:155], v[184:187], v[88:91]
	v_mfma_f32_16x16x32_bf16 v[84:87], v[160:163], v[184:187], v[84:87]
	v_mfma_f32_16x16x32_bf16 v[72:75], v[152:155], v[210:213], v[72:75]
	v_mfma_f32_16x16x32_bf16 v[68:71], v[160:163], v[210:213], v[68:71]
	s_barrier
; #define PG8_STAGE(bufoff, gbase, voff) do { _Pragma("unroll") for (int _i = 0; _i < 2; ++_i) \
;         __builtin_amdgcn_global_load_lds((const unsigned*)((const char*)(gbase) + (voff)[_i]), (PG8_LAS unsigned*)(lds + (bufoff) + ldsw + _i * 8192), 16, 0, 0); } while (0)
; #define PG8_LDA(dst, b, h) do { _Pragma("unroll") for (int m = 0; m < 4; ++m) _Pragma("unroll") for (int k = 0; k < 2; ++k) dst[m][k] = *(const PG8_LAS bf16x8*)(lds + PG8_SA(b, h) + aoff + m * 2048 + k * 1024); } while (0)
; #define PG8_MMA(ai, bj, At, Bt) do { __builtin_amdgcn_s_setprio(1); _Pragma("unroll") for (int m = 0; m < 4; ++m) _Pragma("unroll") for (int n = 0; n < 2; ++n) _Pragma("unroll") for (int k = 0; k < 2; ++k) \
;         acc[ai][bj][m][n] = __builtin_amdgcn_mfma_f32_16x16x32_bf16(Bt[n][k], At[m][k], acc[ai][bj][m][n], 0, 0, 0); __builtin_amdgcn_s_setprio(0); } while (0)
; #define PG8_WAIT_V(n) asm volatile("s_waitcnt vmcnt(" #n ")" ::: "memory")
; #define PG8_WAIT_L(n) asm volatile("s_waitcnt lgkmcnt(" #n ")" ::: "memory")
; #define PG8_BAR __builtin_amdgcn_s_barrier()
; #define PG8_SCHED __builtin_amdgcn_sched_barrier(0)
;     ...
;             PG8_WAIT_V(8); PG8_WAIT_L(0); PG8_BAR; PG8_MMA(0, 0, At, B0); PG8_MMA(0, 1, At, B1); PG8_BAR; PG8_SCHED;
;             PG8_LDA(At, 1, 1); PG8_STAGE(PG8_SB(1, 0), b3, voffB); PG8_STAGE(PG8_SB(1, 1), b3 + hstep, voffB); PG8_STAGE(PG8_SA(1, 0), a3, voffA);
;             PG8_WAIT_V(8); PG8_WAIT_L(0); PG8_BAR; PG8_MMA(1, 0, At, B0); PG8_MMA(1, 1, At, B1); PG8_BAR; PG8_SCHED;
;     ...
;         if constexpr (ALIGN_EPI) { if (wr == 0) PG8_BAR; }
	s_setprio 0
	s_add_i32 s48, s50, s20
	v_lshl_add_u64 v[198:199], v[198:199], 0, s[66:67]
	s_mov_b32 m0, s48
	ds_read_b128 v[164:167], v234 offset:49152
	ds_read_b128 v[168:171], v234 offset:50176
	ds_read_b128 v[172:175], v234 offset:51200
	ds_read_b128 v[176:179], v234 offset:52224
	ds_read_b128 v[180:183], v234 offset:53248
	ds_read_b128 v[184:187], v234 offset:54272
	ds_read_b128 v[206:209], v234 offset:55296
	ds_read_b128 v[210:213], v234 offset:56320
	global_load_lds_dwordx4 v[198:199], off
	s_add_i32 m0, s48, 0x2000
	s_add_u32 s48, s62, 0x160080
	v_lshl_add_u64 v[198:199], v[214:215], 0, s[66:67]
	s_addc_u32 s49, s63, 0
	s_add_i32 s50, s51, s20
	global_load_lds_dwordx4 v[198:199], off
	v_lshl_add_u64 v[198:199], s[48:49], 0, v[200:201]
	s_mov_b32 m0, s50
	s_nop 0
	global_load_lds_dwordx4 v[198:199], off
	v_lshl_add_u64 v[198:199], s[48:49], 0, v[188:189]
	s_add_i32 m0, s50, 0x2000
	s_nop 0
	global_load_lds_dwordx4 v[198:199], off
	v_lshl_add_u64 v[198:199], v[216:217], 0, s[66:67]
	s_mov_b32 m0, s56
	s_nop 0
	global_load_lds_dwordx4 v[198:199], off
	v_lshl_add_u64 v[198:199], v[218:219], 0, s[66:67]
	s_mov_b32 m0, s58
	s_nop 0
	global_load_lds_dwordx4 v[198:199], off
	s_waitcnt vmcnt(8)
	s_waitcnt lgkmcnt(0)
	s_setprio 1
	s_barrier
	v_mfma_f32_16x16x32_bf16 v[64:67], v[108:111], v[164:167], v[64:67]
	v_mfma_f32_16x16x32_bf16 v[60:63], v[128:131], v[164:167], v[60:63]
	v_mfma_f32_16x16x32_bf16 v[48:51], v[108:111], v[172:175], v[48:51]
	v_mfma_f32_16x16x32_bf16 v[44:47], v[128:131], v[172:175], v[44:47]
	v_mfma_f32_16x16x32_bf16 v[32:35], v[108:111], v[180:183], v[32:35]
	v_mfma_f32_16x16x32_bf16 v[28:31], v[128:131], v[180:183], v[28:31]
	v_mfma_f32_16x16x32_bf16 v[16:19], v[108:111], v[206:209], v[16:19]
	v_mfma_f32_16x16x32_bf16 v[12:15], v[128:131], v[206:209], v[12:15]
	v_mfma_f32_16x16x32_bf16 v[64:67], v[112:115], v[168:171], v[64:67]
	v_mfma_f32_16x16x32_bf16 v[60:63], v[136:139], v[168:171], v[60:63]
	v_mfma_f32_16x16x32_bf16 v[48:51], v[112:115], v[176:179], v[48:51]
	v_mfma_f32_16x16x32_bf16 v[44:47], v[136:139], v[176:179], v[44:47]
	v_mfma_f32_16x16x32_bf16 v[32:35], v[112:115], v[184:187], v[32:35]
	v_mfma_f32_16x16x32_bf16 v[28:31], v[136:139], v[184:187], v[28:31]
	v_mfma_f32_16x16x32_bf16 v[16:19], v[112:115], v[210:213], v[16:19]
	v_mfma_f32_16x16x32_bf16 v[12:15], v[136:139], v[210:213], v[12:15]
	s_setprio 0
	s_setprio 1
	v_mfma_f32_16x16x32_bf16 v[56:59], v[148:151], v[164:167], v[56:59]
	v_mfma_f32_16x16x32_bf16 v[52:55], v[156:159], v[164:167], v[52:55]
	v_mfma_f32_16x16x32_bf16 v[40:43], v[148:151], v[172:175], v[40:43]
	v_mfma_f32_16x16x32_bf16 v[36:39], v[156:159], v[172:175], v[36:39]
	v_mfma_f32_16x16x32_bf16 v[24:27], v[148:151], v[180:183], v[24:27]
	v_mfma_f32_16x16x32_bf16 v[20:23], v[156:159], v[180:183], v[20:23]
	v_mfma_f32_16x16x32_bf16 v[8:11], v[148:151], v[206:209], v[8:11]
	v_mfma_f32_16x16x32_bf16 v[4:7], v[156:159], v[206:209], v[4:7]
	v_mfma_f32_16x16x32_bf16 v[56:59], v[152:155], v[168:171], v[56:59]
	v_mfma_f32_16x16x32_bf16 v[52:55], v[160:163], v[168:171], v[52:55]
	v_mfma_f32_16x16x32_bf16 v[40:43], v[152:155], v[176:179], v[40:43]
	v_mfma_f32_16x16x32_bf16 v[36:39], v[160:163], v[176:179], v[36:39]
	v_mfma_f32_16x16x32_bf16 v[24:27], v[152:155], v[184:187], v[24:27]
	v_mfma_f32_16x16x32_bf16 v[20:23], v[160:163], v[184:187], v[20:23]
	v_mfma_f32_16x16x32_bf16 v[8:11], v[152:155], v[210:213], v[8:11]
	v_mfma_f32_16x16x32_bf16 v[4:7], v[160:163], v[210:213], v[4:7]
	s_barrier
	s_setprio 0
	s_add_i32 s77, s77, 2
	s_add_u32 s75, s75, 0x100
	s_addc_u32 s76, s76, 0
	s_cmpk_gt_u32 s77, 0x55
	s_mov_b64 s[50:51], s[60:61]
	s_cbranch_scc0 .LBB0_1254
	s_and_b64 vcc, exec, s[12:13]
	s_cbranch_vccz .LBB0_1257
	s_barrier
